# all six 256-wide GEMM bodies: LDS-DMA m0 = s_add_u32 m0, wave_base_sgpr(s32), const (156 sites; the v_add / v_readfirstlane / s_mov chains and 61 dead adds removed)
# baseline (speedup 1.0000x reference)
; DI void lds_barrier() { asm volatile("s_waitcnt lgkmcnt(0)\n\ts_barrier" ::: "memory"); }
; DI int tid512() { int t = threadIdx.x; asm volatile("" : "+v"(t)); return t; }
; #define G_WAIT_V(n) asm volatile("s_waitcnt vmcnt(" #n ")" ::: "memory")
; #define G_BAR __builtin_amdgcn_s_barrier()
;     ...
;   const int t = tid512();
;   const int wid = t >> 6, lane = t & 63, wr = wid >> 2, wc = wid & 3, fr = lane & 15, fq = lane >> 4;
;   int r0, c0, r1, c1;
;   g_stage_rc(t * 16, r0, c0); g_stage_rc(t * 16 + 8192, r1, c1);
;   const int oa0 = r0 * LDA + c0, oa1 = r1 * LDA + c1, ob0 = r0 * LDB + c0, ob1 = r1 * LDB + c1;
;   const int obr = fr * 64 + fq * 16, rdo = obr ^ (((obr >> 9) & 1) << 5);
;   bf16x8 At[4][2], B0[2][2], B1[2][2];
;   constexpr int nt = K / 64;
;   lds_barrier();
;   G_STAGE(G_SB(0, 0), B, ob0, ob1, LDB, 0, KB(0)); G_STAGE(G_SA(0, 0), A, oa0, oa1, LDA, 0, KA(0));
;   G_STAGE(G_SB(0, 1), B, ob0, ob1, LDB, 128, KB(0)); G_STAGE(G_SA(0, 1), A, oa0, oa1, LDA, 128, KA(0));
;   if (wr == 1) G_BAR;
;   G_WAIT_V(4); G_BAR;
;   G_STAGE(G_SB(1, 0), B, ob0, ob1, LDB, 0, KB(1)); G_STAGE(G_SA(1, 0), A, oa0, oa1, LDA, 0, KA(1)); G_STAGE(G_SB(1, 1), B, ob0, ob1, LDB, 128, KB(1));
;   G_WAIT_V(6); G_BAR;
; DI void f3_phase(PREF p, int l, unsigned char* lds_all) {
;     ...
;       f32x4 acc[2][2][4][2]; zero_acc256(acc);
;       gemm256<1024, 1024, 1024>(acc, p.X + (size_t)mt * 256 * 1024, W + O_PLEG + (size_t)dt * 256 * 1024, shm, p);
.LBB0_37:
	s_lshr_b32 s0, s16, 2
	s_and_b32 s36, s0, 8
	s_lshl_b32 s0, s36, 2
	s_sub_i32 s0, s16, s0
	s_and_b32 s37, s16, 7
	s_ashr_i32 s18, s0, 3
	s_or_b32 s0, s37, s47
	v_mov_b32_e32 v0, v168
	s_or_b32 s35, s0, s36
	s_lshl_b32 s0, s35, 19
	v_lshlrev_b32_e32 v143, 4, v0
	s_nop 0
	v_readfirstlane_b32 s32, v143
	v_and_b32_e32 v2, 32, v0
	v_lshrrev_b32_e32 v4, 1, v0
	v_bitop3_b32 v2, v143, v2, 48 bitop3:0x6c
	s_add_u32 s16, s8, s0
	v_ashrrev_i32_e32 v10, 3, v0
	v_bfe_u32 v13, v0, 2, 4
	s_mov_b32 s0, 0x3ffff0
	v_and_b32_e32 v11, 32, v4
	v_lshrrev_b32_e32 v12, 1, v2
	v_add_u32_e32 v144, 0x2000, v143
	s_addc_u32 s17, s9, 0
	s_ashr_i32 s19, s18, 31
	v_and_or_b32 v3, v10, s0, v13
	v_or_b32_e32 v2, v12, v11
	v_ashrrev_i32_e32 v15, 7, v144
	s_lshl_b64 s[20:21], s[18:19], 19
	v_and_or_b32 v4, v15, s0, v13
	v_lshl_or_b32 v132, v3, 10, v2
	s_add_u32 s22, s28, s20
	v_lshl_or_b32 v130, v4, 10, v2
	v_ashrrev_i32_e32 v133, 31, v132
	s_addc_u32 s23, s29, s21
	v_lshlrev_b64 v[16:17], 1, v[132:133]
	v_ashrrev_i32_e32 v131, 31, v130
	s_waitcnt lgkmcnt(0)
	s_barrier
	v_lshl_add_u64 v[2:3], s[22:23], 0, v[16:17]
	s_add_u32 m0, s32, 0x10000
	v_lshlrev_b64 v[18:19], 1, v[130:131]
	global_load_lds_dwordx4 v[2:3], off
	v_lshl_add_u64 v[6:7], s[22:23], 0, v[18:19]
	s_add_u32 m0, s32, 0x12000
	s_nop 0
	global_load_lds_dwordx4 v[6:7], off
	v_lshl_add_u64 v[8:9], s[16:17], 0, v[16:17]
	s_mov_b32 m0, s32
	s_nop 0
	global_load_lds_dwordx4 v[8:9], off
	s_add_u32 m0, s32, 0x2000
	s_add_u32 s0, s22, 0x40000
	v_lshl_add_u64 v[4:5], s[16:17], 0, v[18:19]
	s_addc_u32 s1, s23, 0
	global_load_lds_dwordx4 v[4:5], off
	v_lshl_add_u64 v[20:21], s[0:1], 0, v[16:17]
	s_add_u32 m0, s32, 0x14000
	s_nop 0
	global_load_lds_dwordx4 v[20:21], off
	v_lshl_add_u64 v[20:21], s[0:1], 0, v[18:19]
	s_add_u32 m0, s32, 0x16000
	s_add_u32 s0, s16, 0x40000
	s_addc_u32 s1, s17, 0
	global_load_lds_dwordx4 v[20:21], off
	v_lshl_add_u64 v[16:17], s[0:1], 0, v[16:17]
	s_add_u32 m0, s32, 0x4000
	v_add_u32_e32 v152, 0x6000, v143
	global_load_lds_dwordx4 v[16:17], off
	v_lshl_add_u64 v[16:17], s[0:1], 0, v[18:19]
	v_readfirstlane_b32 s0, v152
	s_add_u32 m0, s32, 0x6000
	v_ashrrev_i32_e32 v14, 8, v0
	global_load_lds_dwordx4 v[16:17], off
	v_cmp_eq_u32_e32 vcc, 1, v14
	s_and_saveexec_b64 s[24:25], vcc
	s_cbranch_execz .LBB0_39
	s_barrier
.LBB0_39:
	s_or_b64 exec, exec, s[24:25]
	v_lshl_add_u64 v[2:3], v[2:3], 0, s[76:77]
	s_add_u32 m0, s32, 0x18000
	s_waitcnt vmcnt(4)
	s_barrier
	global_load_lds_dwordx4 v[2:3], off
	v_lshl_add_u64 v[2:3], v[6:7], 0, s[76:77]
	s_add_u32 m0, s32, 0x1a000
	s_nop 0
	global_load_lds_dwordx4 v[2:3], off
	v_lshl_add_u64 v[2:3], v[8:9], 0, s[76:77]
	s_add_u32 m0, s32, 0x8000
	s_nop 0
	global_load_lds_dwordx4 v[2:3], off
	s_add_u32 m0, s32, 0xa000
	s_add_u32 s0, s22, 0x40080
	v_lshl_add_u64 v[2:3], v[4:5], 0, s[76:77]
	s_addc_u32 s1, s23, 0
	global_load_lds_dwordx4 v[2:3], off
	v_lshl_add_u64 v[2:3], v[132:133], 1, s[0:1]
	s_add_u32 m0, s32, 0x1c000
	s_nop 0
	global_load_lds_dwordx4 v[2:3], off
	v_lshl_add_u64 v[2:3], v[130:131], 1, s[0:1]
	s_add_u32 m0, s32, 0x1e000
	v_lshlrev_b32_e32 v17, 6, v0
	global_load_lds_dwordx4 v[2:3], off
	v_and_b32_e32 v16, 48, v0
	v_and_b32_e32 v18, 0x3c0, v17
	v_lshlrev_b32_e32 v20, 2, v0
	v_or_b32_e32 v19, v18, v16
	v_and_b32_e32 v20, 32, v20
	s_mov_b32 s0, 0x14000
	v_bitop3_b32 v8, v19, s0, v20 bitop3:0xde
	s_mov_b32 s0, 0x18000
	v_bitop3_b32 v9, v19, s0, v20 bitop3:0xde
	s_mov_b32 s0, 0x1c000
	v_lshlrev_b32_e32 v2, 10, v15
	v_lshlrev_b32_e32 v5, 10, v10
	v_lshlrev_b32_e32 v7, 13, v14
	v_bitop3_b32 v14, v19, s0, v20 bitop3:0xde
	s_add_i32 s0, s47, s36
	v_and_b32_e32 v2, 0xffffc000, v2
	v_lshlrev_b32_e32 v4, 10, v13
	v_and_b32_e32 v5, 0xffffc000, v5
	s_add_i32 s0, s0, s37
	v_or3_b32 v2, v12, v2, v4
	v_or3_b32 v4, v12, v5, v4
	s_lshl_b32 s0, s0, 19
	v_add_u32_e32 v2, v2, v11
	v_add_u32_e32 v4, v4, v11
	v_ashrrev_i32_e32 v3, 31, v2
	s_add_u32 s0, s8, s0
	v_ashrrev_i32_e32 v5, 31, v4
	v_lshlrev_b64 v[2:3], 1, v[2:3]
	s_addc_u32 s1, s9, 0
	v_lshlrev_b64 v[4:5], 1, v[4:5]
	v_lshl_add_u64 v[134:135], s[0:1], 0, v[2:3]
	v_lshl_add_u64 v[136:137], s[0:1], 0, v[4:5]
	s_add_u32 s0, s26, s20
	s_waitcnt vmcnt(6)
	s_addc_u32 s1, s27, s21
	v_bitop3_b32 v16, v18, v20, v16 bitop3:0x36
	v_bitop3_b32 v6, v19, s88, v20 bitop3:0xde
	v_and_b32_e32 v17, 0x3000, v17
	v_lshl_add_u64 v[138:139], s[0:1], 0, v[2:3]
	v_mov_b32_e32 v2, 0
	v_lshl_add_u64 v[140:141], s[0:1], 0, v[4:5]
	s_mov_b32 s22, -2
	s_mov_b64 s[20:21], 0
	v_add_u32_e32 v162, v6, v17
	v_add_u32_e32 v142, v16, v7
	v_add_u32_e32 v159, v8, v17
	v_add_u32_e32 v150, v9, v17
	v_add_u32_e32 v145, v14, v17
	v_mov_b32_e32 v3, v2
	v_mov_b32_e32 v4, v2
	v_mov_b32_e32 v5, v2
	v_mov_b32_e32 v6, v2
	v_mov_b32_e32 v7, v2
	v_mov_b32_e32 v8, v2
	v_mov_b32_e32 v9, v2
	v_mov_b32_e32 v10, v2
	v_mov_b32_e32 v11, v2
	v_mov_b32_e32 v12, v2
	v_mov_b32_e32 v13, v2
	v_mov_b32_e32 v14, v2
	v_mov_b32_e32 v15, v2
	v_mov_b32_e32 v16, v2
	v_mov_b32_e32 v17, v2
	v_mov_b32_e32 v18, v2
	v_mov_b32_e32 v19, v2
	v_mov_b32_e32 v20, v2
	v_mov_b32_e32 v21, v2
	v_mov_b32_e32 v22, v2
	v_mov_b32_e32 v23, v2
	v_mov_b32_e32 v24, v2
	v_mov_b32_e32 v25, v2
	v_mov_b32_e32 v26, v2
	v_mov_b32_e32 v27, v2
	v_mov_b32_e32 v28, v2
	v_mov_b32_e32 v29, v2
	v_mov_b32_e32 v30, v2
	v_mov_b32_e32 v31, v2
	v_mov_b32_e32 v32, v2
	v_mov_b32_e32 v33, v2
	v_mov_b32_e32 v34, v2
	v_mov_b32_e32 v35, v2
	v_mov_b32_e32 v36, v2
	v_mov_b32_e32 v37, v2
	v_mov_b32_e32 v38, v2
	v_mov_b32_e32 v39, v2
	v_mov_b32_e32 v40, v2
	v_mov_b32_e32 v41, v2
	v_mov_b32_e32 v42, v2
	v_mov_b32_e32 v43, v2
	v_mov_b32_e32 v44, v2
	v_mov_b32_e32 v45, v2
	v_mov_b32_e32 v46, v2
	v_mov_b32_e32 v47, v2
; #define G_LDA(dst, b, h)                                                                                                  \
;   _Pragma("unroll") for (int m = 0; m < 4; ++m) _Pragma("unroll") for (int k = 0; k < 2; ++k)                             \
;       dst[m][k] = *(const bf16x8*)((const char*)G_SA(b, h) + ((wr * 4 + m) * 2 + k) * 1024 + rdo)
; #define G_LDB(dst, b, h)                                                                                                  \
;   _Pragma("unroll") for (int n = 0; n < 2; ++n) _Pragma("unroll") for (int k = 0; k < 2; ++k)                             \
;       dst[n][k] = *(const bf16x8*)((const char*)G_SB(b, h) + ((wc * 2 + n) * 2 + k) * 1024 + rdo)
; #define G_WAIT_L(n) asm volatile("s_waitcnt lgkmcnt(" #n ")" ::: "memory")
; #define G_BAR __builtin_amdgcn_s_barrier()
; #define G_SCHED __builtin_amdgcn_sched_barrier(0)
;     ...
;   for (int tt = 0; tt < nt - 2; tt += 2) {
;     G_LDB(B0, 0, 0); G_SCHED; G_LDA(At, 0, 0); G_STAGE(G_SA(1, 1), A, oa0, oa1, LDA, 128, KA(tt + 1));
;     G_WAIT_L(8); G_BAR; G_WAIT_L(0); G_MMA(0, 0, At, B0); G_BAR; G_SCHED;
;     G_LDB(B1, 0, 1); G_STAGE(G_SB(0, 0), B, ob0, ob1, LDB, 0, KB(tt + 2));
;     G_BAR; G_WAIT_L(0); G_MMA(0, 1, At, B1); G_BAR;
; DI void zero_acc256(f32x4 (&a)[2][2][4][2]) {
; #pragma unroll
;   for (int i = 0; i < 2; ++i)
; #pragma unroll
;     for (int j = 0; j < 2; ++j)
; #pragma unroll
;       for (int m = 0; m < 4; ++m)
; #pragma unroll
;         for (int n = 0; n < 2; ++n)
; #pragma unroll
;           for (int e = 0; e < 4; ++e) a[i][j][m][n][e] = 0.f;
; }
	v_mov_b32_e32 v48, v2
	v_mov_b32_e32 v49, v2
	v_mov_b32_e32 v50, v2
	v_mov_b32_e32 v51, v2
	v_mov_b32_e32 v52, v2
	v_mov_b32_e32 v53, v2
	v_mov_b32_e32 v54, v2
	v_mov_b32_e32 v55, v2
	v_mov_b32_e32 v56, v2
	v_mov_b32_e32 v57, v2
	v_mov_b32_e32 v62, v2
	v_mov_b32_e32 v63, v2
	v_mov_b32_e32 v64, v2
	v_mov_b32_e32 v65, v2
	v_mov_b32_e32 v78, v2
	v_mov_b32_e32 v79, v2
	v_mov_b32_e32 v80, v2
	v_mov_b32_e32 v81, v2
	v_mov_b32_e32 v94, v2
	v_mov_b32_e32 v95, v2
	v_mov_b32_e32 v96, v2
	v_mov_b32_e32 v97, v2
	v_mov_b32_e32 v98, v2
	v_mov_b32_e32 v99, v2
	v_mov_b32_e32 v100, v2
	v_mov_b32_e32 v101, v2
	v_mov_b32_e32 v102, v2
	v_mov_b32_e32 v103, v2
	v_mov_b32_e32 v104, v2
	v_mov_b32_e32 v105, v2
	v_mov_b32_e32 v106, v2
	v_mov_b32_e32 v107, v2
	v_mov_b32_e32 v108, v2
	v_mov_b32_e32 v109, v2
	v_mov_b32_e32 v110, v2
	v_mov_b32_e32 v111, v2
	v_mov_b32_e32 v112, v2
	v_mov_b32_e32 v113, v2
	v_mov_b32_e32 v114, v2
	v_mov_b32_e32 v115, v2
	v_mov_b32_e32 v116, v2
	v_mov_b32_e32 v117, v2
	v_mov_b32_e32 v118, v2
	v_mov_b32_e32 v119, v2
	v_mov_b32_e32 v120, v2
	v_mov_b32_e32 v121, v2
	v_mov_b32_e32 v122, v2
	v_mov_b32_e32 v123, v2
	v_mov_b32_e32 v124, v2
	v_mov_b32_e32 v125, v2
	v_mov_b32_e32 v126, v2
	v_mov_b32_e32 v127, v2
	v_mov_b32_e32 v128, v2
	v_mov_b32_e32 v129, v2
	v_mov_b32_e32 v58, v2
	v_mov_b32_e32 v59, v2
	v_mov_b32_e32 v60, v2
	v_mov_b32_e32 v61, v2
	v_mov_b32_e32 v66, v2
	v_mov_b32_e32 v67, v2
	v_mov_b32_e32 v68, v2
	v_mov_b32_e32 v69, v2
	v_mov_b32_e32 v70, v2
	v_mov_b32_e32 v71, v2
	v_mov_b32_e32 v72, v2
	v_mov_b32_e32 v73, v2
	v_mov_b32_e32 v74, v2
	v_mov_b32_e32 v75, v2
	v_mov_b32_e32 v76, v2
	v_mov_b32_e32 v77, v2
	v_mov_b32_e32 v82, v2
	v_mov_b32_e32 v83, v2
	v_mov_b32_e32 v84, v2
	v_mov_b32_e32 v85, v2
	v_mov_b32_e32 v86, v2
	v_mov_b32_e32 v87, v2
	v_mov_b32_e32 v88, v2
	v_mov_b32_e32 v89, v2
	v_mov_b32_e32 v90, v2
	v_mov_b32_e32 v91, v2
	v_mov_b32_e32 v92, v2
	v_mov_b32_e32 v93, v2
	s_mov_b64 s[24:25], 0x12f0100
	s_mov_b64 s[36:37], 0x12b0180
	s_mov_b64 s[40:41], 0x12f0180
	s_barrier
.LBB0_40:
	ds_read_b128 v[164:167], v162
	ds_read_b128 v[182:185], v162 offset:1024
	ds_read_b128 v[186:189], v162 offset:2048
	ds_read_b128 v[190:193], v162 offset:3072
	v_lshl_add_u64 v[242:243], v[136:137], 0, s[20:21]
	v_lshl_add_u64 v[226:227], v[242:243], 0, s[78:79]
	s_add_u32 m0, s32, 0xc000
	v_lshl_add_u64 v[244:245], v[134:135], 0, s[20:21]
	ds_read_b128 v[194:197], v142
	ds_read_b128 v[198:201], v142 offset:1024
	ds_read_b128 v[202:205], v142 offset:2048
	ds_read_b128 v[206:209], v142 offset:3072
	ds_read_b128 v[210:213], v142 offset:4096
	ds_read_b128 v[214:217], v142 offset:5120
	ds_read_b128 v[218:221], v142 offset:6144
	ds_read_b128 v[222:225], v142 offset:7168
	global_load_lds_dwordx4 v[226:227], off
	s_add_u32 m0, s32, 0xe000
	v_lshl_add_u64 v[226:227], v[244:245], 0, s[78:79]
	global_load_lds_dwordx4 v[226:227], off
	s_waitcnt lgkmcnt(8)
	s_barrier
	s_waitcnt lgkmcnt(0)
	v_mfma_f32_16x16x32_bf16 v[126:129], v[194:197], v[164:167], v[126:129]
	v_mfma_f32_16x16x32_bf16 v[122:125], v[194:197], v[186:189], v[122:125]
	v_mfma_f32_16x16x32_bf16 v[118:121], v[202:205], v[164:167], v[118:121]
	v_mfma_f32_16x16x32_bf16 v[114:117], v[202:205], v[186:189], v[114:117]
	v_mfma_f32_16x16x32_bf16 v[110:113], v[210:213], v[164:167], v[110:113]
	v_mfma_f32_16x16x32_bf16 v[106:109], v[210:213], v[186:189], v[106:109]
	v_mfma_f32_16x16x32_bf16 v[102:105], v[218:221], v[164:167], v[102:105]
	v_mfma_f32_16x16x32_bf16 v[98:101], v[218:221], v[186:189], v[98:101]
	v_mfma_f32_16x16x32_bf16 v[126:129], v[198:201], v[182:185], v[126:129]
	v_mfma_f32_16x16x32_bf16 v[122:125], v[198:201], v[190:193], v[122:125]
	v_mfma_f32_16x16x32_bf16 v[118:121], v[206:209], v[182:185], v[118:121]
	v_mfma_f32_16x16x32_bf16 v[114:117], v[206:209], v[190:193], v[114:117]
	v_mfma_f32_16x16x32_bf16 v[110:113], v[214:217], v[182:185], v[110:113]
	v_mfma_f32_16x16x32_bf16 v[106:109], v[214:217], v[190:193], v[106:109]
	v_mfma_f32_16x16x32_bf16 v[102:105], v[222:225], v[182:185], v[102:105]
	v_mfma_f32_16x16x32_bf16 v[98:101], v[222:225], v[190:193], v[98:101]
	s_barrier
	v_lshl_add_u64 v[246:247], v[140:141], 0, s[20:21]
	v_lshl_add_u64 v[248:249], v[246:247], 0, s[42:43]
	s_add_u32 m0, s32, 0x10000
	ds_read_b128 v[226:229], v159
	ds_read_b128 v[230:233], v159 offset:1024
	ds_read_b128 v[234:237], v159 offset:2048
	ds_read_b128 v[238:241], v159 offset:3072
	global_load_lds_dwordx4 v[248:249], off
	v_lshl_add_u64 v[248:249], v[138:139], 0, s[20:21]
	s_add_u32 m0, s32, 0x12000
	v_lshl_add_u64 v[250:251], v[248:249], 0, s[42:43]
	global_load_lds_dwordx4 v[250:251], off
	s_barrier
	s_waitcnt lgkmcnt(0)
	v_mfma_f32_16x16x32_bf16 v[94:97], v[194:197], v[226:229], v[94:97]
	v_mfma_f32_16x16x32_bf16 v[78:81], v[194:197], v[234:237], v[78:81]
	v_mfma_f32_16x16x32_bf16 v[62:65], v[202:205], v[226:229], v[62:65]
	v_mfma_f32_16x16x32_bf16 v[54:57], v[202:205], v[234:237], v[54:57]
	v_mfma_f32_16x16x32_bf16 v[50:53], v[210:213], v[226:229], v[50:53]
	v_mfma_f32_16x16x32_bf16 v[46:49], v[210:213], v[234:237], v[46:49]
	v_mfma_f32_16x16x32_bf16 v[42:45], v[218:221], v[226:229], v[42:45]
	v_mfma_f32_16x16x32_bf16 v[38:41], v[218:221], v[234:237], v[38:41]
	v_mfma_f32_16x16x32_bf16 v[94:97], v[198:201], v[230:233], v[94:97]
	v_mfma_f32_16x16x32_bf16 v[78:81], v[198:201], v[238:241], v[78:81]
	v_mfma_f32_16x16x32_bf16 v[62:65], v[206:209], v[230:233], v[62:65]
	v_mfma_f32_16x16x32_bf16 v[54:57], v[206:209], v[238:241], v[54:57]
	v_mfma_f32_16x16x32_bf16 v[50:53], v[214:217], v[230:233], v[50:53]
	v_mfma_f32_16x16x32_bf16 v[46:49], v[214:217], v[238:241], v[46:49]
	v_mfma_f32_16x16x32_bf16 v[42:45], v[222:225], v[230:233], v[42:45]
	v_mfma_f32_16x16x32_bf16 v[38:41], v[222:225], v[238:241], v[38:41]
	v_lshl_add_u64 v[250:251], v[242:243], 0, s[82:83]
	s_mov_b32 m0, s32
	s_barrier
; #define G_LDA(dst, b, h)                                                                                                  \
;   _Pragma("unroll") for (int m = 0; m < 4; ++m) _Pragma("unroll") for (int k = 0; k < 2; ++k)                             \
;       dst[m][k] = *(const bf16x8*)((const char*)G_SA(b, h) + ((wr * 4 + m) * 2 + k) * 1024 + rdo)
; #define G_LDB(dst, b, h)                                                                                                  \
;   _Pragma("unroll") for (int n = 0; n < 2; ++n) _Pragma("unroll") for (int k = 0; k < 2; ++k)                             \
;       dst[n][k] = *(const bf16x8*)((const char*)G_SB(b, h) + ((wc * 2 + n) * 2 + k) * 1024 + rdo)
; #define G_WAIT_V(n) asm volatile("s_waitcnt vmcnt(" #n ")" ::: "memory")
; #define G_WAIT_L(n) asm volatile("s_waitcnt lgkmcnt(" #n ")" ::: "memory")
; #define G_BAR __builtin_amdgcn_s_barrier()
; #define G_SCHED __builtin_amdgcn_sched_barrier(0)
;     ...
;     G_LDA(At, 0, 1); G_STAGE(G_SA(0, 0), A, oa0, oa1, LDA, 0, KA(tt + 2));
;     G_BAR; G_WAIT_L(0); G_MMA(1, 0, At, B0); G_BAR; G_SCHED;
;     G_STAGE(G_SB(0, 1), B, ob0, ob1, LDB, 128, KB(tt + 2));
;     G_WAIT_V(6); G_BAR; G_MMA(1, 1, At, B1); G_BAR;
;     G_LDB(B0, 1, 0); G_SCHED; G_LDA(At, 1, 0); G_STAGE(G_SA(0, 1), A, oa0, oa1, LDA, 128, KA(tt + 2));
;     G_WAIT_L(8); G_BAR; G_WAIT_L(0); G_MMA(0, 0, At, B0); G_BAR; G_SCHED;
;     G_LDB(B1, 1, 1); G_STAGE(G_SB(1, 0), B, ob0, ob1, LDB, 0, KB(tt + 3));
	ds_read_b128 v[194:197], v142 offset:16384
	ds_read_b128 v[198:201], v142 offset:17408
	ds_read_b128 v[202:205], v142 offset:18432
	ds_read_b128 v[206:209], v142 offset:19456
	ds_read_b128 v[210:213], v142 offset:20480
	ds_read_b128 v[214:217], v142 offset:21504
	ds_read_b128 v[218:221], v142 offset:22528
	ds_read_b128 v[222:225], v142 offset:23552
	global_load_lds_dwordx4 v[250:251], off
	s_add_u32 m0, s32, 0x2000
	v_lshl_add_u64 v[250:251], v[244:245], 0, s[82:83]
	global_load_lds_dwordx4 v[250:251], off
	s_barrier
	s_waitcnt lgkmcnt(0)
	v_mfma_f32_16x16x32_bf16 v[34:37], v[194:197], v[164:167], v[34:37]
	v_mfma_f32_16x16x32_bf16 v[30:33], v[194:197], v[186:189], v[30:33]
	v_mfma_f32_16x16x32_bf16 v[26:29], v[202:205], v[164:167], v[26:29]
	v_mfma_f32_16x16x32_bf16 v[22:25], v[202:205], v[186:189], v[22:25]
	v_mfma_f32_16x16x32_bf16 v[18:21], v[210:213], v[164:167], v[18:21]
	v_mfma_f32_16x16x32_bf16 v[14:17], v[210:213], v[186:189], v[14:17]
	v_mfma_f32_16x16x32_bf16 v[10:13], v[218:221], v[164:167], v[10:13]
	v_mfma_f32_16x16x32_bf16 v[6:9], v[218:221], v[186:189], v[6:9]
	v_mfma_f32_16x16x32_bf16 v[34:37], v[198:201], v[182:185], v[34:37]
	v_mfma_f32_16x16x32_bf16 v[30:33], v[198:201], v[190:193], v[30:33]
	v_mfma_f32_16x16x32_bf16 v[26:29], v[206:209], v[182:185], v[26:29]
	v_mfma_f32_16x16x32_bf16 v[22:25], v[206:209], v[190:193], v[22:25]
	v_mfma_f32_16x16x32_bf16 v[18:21], v[214:217], v[182:185], v[18:21]
	v_mfma_f32_16x16x32_bf16 v[14:17], v[214:217], v[190:193], v[14:17]
	v_mfma_f32_16x16x32_bf16 v[10:13], v[222:225], v[182:185], v[10:13]
	v_mfma_f32_16x16x32_bf16 v[6:9], v[222:225], v[190:193], v[6:9]
	s_barrier
	v_lshl_add_u64 v[164:165], v[246:247], 0, s[24:25]
	s_add_u32 m0, s32, 0x14000
	s_nop 0
	global_load_lds_dwordx4 v[164:165], off
	s_add_u32 m0, s32, 0x16000
	v_lshl_add_u64 v[164:165], v[248:249], 0, s[24:25]
	global_load_lds_dwordx4 v[164:165], off
	s_waitcnt vmcnt(6)
	s_barrier
	v_mfma_f32_16x16x32_bf16 v[2:5], v[194:197], v[226:229], v[2:5]
	v_mfma_f32_16x16x32_bf16 v[58:61], v[194:197], v[234:237], v[58:61]
	v_mfma_f32_16x16x32_bf16 v[66:69], v[202:205], v[226:229], v[66:69]
	v_mfma_f32_16x16x32_bf16 v[70:73], v[202:205], v[234:237], v[70:73]
	v_mfma_f32_16x16x32_bf16 v[74:77], v[210:213], v[226:229], v[74:77]
	v_mfma_f32_16x16x32_bf16 v[82:85], v[210:213], v[234:237], v[82:85]
	v_mfma_f32_16x16x32_bf16 v[86:89], v[218:221], v[226:229], v[86:89]
	v_mfma_f32_16x16x32_bf16 v[90:93], v[218:221], v[234:237], v[90:93]
	v_mfma_f32_16x16x32_bf16 v[2:5], v[198:201], v[230:233], v[2:5]
	v_mfma_f32_16x16x32_bf16 v[58:61], v[198:201], v[238:241], v[58:61]
	v_mfma_f32_16x16x32_bf16 v[66:69], v[206:209], v[230:233], v[66:69]
	v_mfma_f32_16x16x32_bf16 v[70:73], v[206:209], v[238:241], v[70:73]
	v_mfma_f32_16x16x32_bf16 v[74:77], v[214:217], v[230:233], v[74:77]
	v_mfma_f32_16x16x32_bf16 v[82:85], v[214:217], v[238:241], v[82:85]
	v_mfma_f32_16x16x32_bf16 v[86:89], v[222:225], v[230:233], v[86:89]
	v_mfma_f32_16x16x32_bf16 v[90:93], v[222:225], v[238:241], v[90:93]
	s_barrier
	ds_read_b128 v[164:167], v150
	ds_read_b128 v[182:185], v150 offset:1024
	ds_read_b128 v[186:189], v150 offset:2048
	ds_read_b128 v[190:193], v150 offset:3072
	v_lshl_add_u64 v[226:227], v[242:243], 0, s[86:87]
	s_add_u32 m0, s32, 0x4000
	ds_read_b128 v[194:197], v142 offset:32768
	ds_read_b128 v[198:201], v142 offset:33792
	ds_read_b128 v[202:205], v142 offset:34816
	ds_read_b128 v[206:209], v142 offset:35840
	ds_read_b128 v[210:213], v142 offset:36864
	ds_read_b128 v[214:217], v142 offset:37888
	ds_read_b128 v[218:221], v142 offset:38912
	ds_read_b128 v[222:225], v142 offset:39936
	global_load_lds_dwordx4 v[226:227], off
	s_add_u32 m0, s32, 0x6000
	v_lshl_add_u64 v[226:227], v[244:245], 0, s[86:87]
	global_load_lds_dwordx4 v[226:227], off
	s_waitcnt lgkmcnt(8)
	s_barrier
	s_waitcnt lgkmcnt(0)
	v_mfma_f32_16x16x32_bf16 v[126:129], v[194:197], v[164:167], v[126:129]
	v_mfma_f32_16x16x32_bf16 v[122:125], v[194:197], v[186:189], v[122:125]
	v_mfma_f32_16x16x32_bf16 v[118:121], v[202:205], v[164:167], v[118:121]
	v_mfma_f32_16x16x32_bf16 v[114:117], v[202:205], v[186:189], v[114:117]
	v_mfma_f32_16x16x32_bf16 v[110:113], v[210:213], v[164:167], v[110:113]
	v_mfma_f32_16x16x32_bf16 v[106:109], v[210:213], v[186:189], v[106:109]
	v_mfma_f32_16x16x32_bf16 v[102:105], v[218:221], v[164:167], v[102:105]
	v_mfma_f32_16x16x32_bf16 v[98:101], v[218:221], v[186:189], v[98:101]
	v_mfma_f32_16x16x32_bf16 v[126:129], v[198:201], v[182:185], v[126:129]
	v_mfma_f32_16x16x32_bf16 v[122:125], v[198:201], v[190:193], v[122:125]
	v_mfma_f32_16x16x32_bf16 v[118:121], v[206:209], v[182:185], v[118:121]
	v_mfma_f32_16x16x32_bf16 v[114:117], v[206:209], v[190:193], v[114:117]
	v_mfma_f32_16x16x32_bf16 v[110:113], v[214:217], v[182:185], v[110:113]
	v_mfma_f32_16x16x32_bf16 v[106:109], v[214:217], v[190:193], v[106:109]
	v_mfma_f32_16x16x32_bf16 v[102:105], v[222:225], v[182:185], v[102:105]
	v_mfma_f32_16x16x32_bf16 v[98:101], v[222:225], v[190:193], v[98:101]
	s_barrier
	v_lshl_add_u64 v[250:251], v[246:247], 0, s[36:37]
	s_add_u32 m0, s32, 0x18000
	ds_read_b128 v[226:229], v145
	ds_read_b128 v[230:233], v145 offset:1024
	ds_read_b128 v[234:237], v145 offset:2048
	ds_read_b128 v[238:241], v145 offset:3072
	global_load_lds_dwordx4 v[250:251], off
	s_add_u32 m0, s32, 0x1a000
	v_lshl_add_u64 v[250:251], v[248:249], 0, s[36:37]
	global_load_lds_dwordx4 v[250:251], off
	s_barrier
; #define G_LDA(dst, b, h)                                                                                                  \
;   _Pragma("unroll") for (int m = 0; m < 4; ++m) _Pragma("unroll") for (int k = 0; k < 2; ++k)                             \
;       dst[m][k] = *(const bf16x8*)((const char*)G_SA(b, h) + ((wr * 4 + m) * 2 + k) * 1024 + rdo)
; #define G_LDB(dst, b, h)                                                                                                  \
;   _Pragma("unroll") for (int n = 0; n < 2; ++n) _Pragma("unroll") for (int k = 0; k < 2; ++k)                             \
;       dst[n][k] = *(const bf16x8*)((const char*)G_SB(b, h) + ((wc * 2 + n) * 2 + k) * 1024 + rdo)
; #define G_WAIT_V(n) asm volatile("s_waitcnt vmcnt(" #n ")" ::: "memory")
; #define G_WAIT_L(n) asm volatile("s_waitcnt lgkmcnt(" #n ")" ::: "memory")
; #define G_BAR __builtin_amdgcn_s_barrier()
; #define G_SCHED __builtin_amdgcn_sched_barrier(0)
; DI void br_flush(PREF p, f32x4 (&acc)[2][2][4][2], int slot) { br_store(p, acc, slot); zero_acc256(acc); }
;     ...
;     G_BAR; G_WAIT_L(0); G_MMA(0, 1, At, B1); G_BAR;
;     G_LDA(At, 1, 1); G_STAGE(G_SA(1, 0), A, oa0, oa1, LDA, 0, KA(tt + 3));
;     G_BAR; G_WAIT_L(0); G_MMA(1, 0, At, B0); G_BAR; G_SCHED;
;     G_STAGE(G_SB(1, 1), B, ob0, ob1, LDB, 128, KB(tt + 3));
;     G_WAIT_V(6); G_BAR; G_MMA(1, 1, At, B1); G_BAR;
;     if (MODE && ((tt + 1) & 3) == 3) br_flush(p, acc, (tt + 1) >> 2);
;   }
;   {
;     G_LDB(B0, 0, 0); G_LDA(At, 0, 0); G_STAGE(G_SA(1, 1), A, oa0, oa1, LDA, 128, KA(nt - 1));
	s_waitcnt lgkmcnt(0)
	v_mfma_f32_16x16x32_bf16 v[94:97], v[194:197], v[226:229], v[94:97]
	v_mfma_f32_16x16x32_bf16 v[78:81], v[194:197], v[234:237], v[78:81]
	v_mfma_f32_16x16x32_bf16 v[62:65], v[202:205], v[226:229], v[62:65]
	v_mfma_f32_16x16x32_bf16 v[54:57], v[202:205], v[234:237], v[54:57]
	v_mfma_f32_16x16x32_bf16 v[50:53], v[210:213], v[226:229], v[50:53]
	v_mfma_f32_16x16x32_bf16 v[46:49], v[210:213], v[234:237], v[46:49]
	v_mfma_f32_16x16x32_bf16 v[42:45], v[218:221], v[226:229], v[42:45]
	v_mfma_f32_16x16x32_bf16 v[38:41], v[218:221], v[234:237], v[38:41]
	v_mfma_f32_16x16x32_bf16 v[94:97], v[198:201], v[230:233], v[94:97]
	v_mfma_f32_16x16x32_bf16 v[78:81], v[198:201], v[238:241], v[78:81]
	v_mfma_f32_16x16x32_bf16 v[62:65], v[206:209], v[230:233], v[62:65]
	v_mfma_f32_16x16x32_bf16 v[54:57], v[206:209], v[238:241], v[54:57]
	v_mfma_f32_16x16x32_bf16 v[50:53], v[214:217], v[230:233], v[50:53]
	v_mfma_f32_16x16x32_bf16 v[46:49], v[214:217], v[238:241], v[46:49]
	v_mfma_f32_16x16x32_bf16 v[42:45], v[222:225], v[230:233], v[42:45]
	v_mfma_f32_16x16x32_bf16 v[38:41], v[222:225], v[238:241], v[38:41]
	v_lshl_add_u64 v[242:243], v[242:243], 0, s[90:91]
	s_add_u32 m0, s32, 0x8000
	s_barrier
	ds_read_b128 v[194:197], v142 offset:49152
	ds_read_b128 v[198:201], v142 offset:50176
	ds_read_b128 v[202:205], v142 offset:51200
	ds_read_b128 v[206:209], v142 offset:52224
	ds_read_b128 v[210:213], v142 offset:53248
	ds_read_b128 v[214:217], v142 offset:54272
	ds_read_b128 v[218:221], v142 offset:55296
	ds_read_b128 v[222:225], v142 offset:56320
	global_load_lds_dwordx4 v[242:243], off
	s_add_u32 m0, s32, 0xa000
	v_lshl_add_u64 v[242:243], v[244:245], 0, s[90:91]
	global_load_lds_dwordx4 v[242:243], off
	s_barrier
	s_waitcnt lgkmcnt(0)
	v_mfma_f32_16x16x32_bf16 v[34:37], v[194:197], v[164:167], v[34:37]
	v_mfma_f32_16x16x32_bf16 v[30:33], v[194:197], v[186:189], v[30:33]
	v_mfma_f32_16x16x32_bf16 v[26:29], v[202:205], v[164:167], v[26:29]
	v_mfma_f32_16x16x32_bf16 v[22:25], v[202:205], v[186:189], v[22:25]
	v_mfma_f32_16x16x32_bf16 v[18:21], v[210:213], v[164:167], v[18:21]
	v_mfma_f32_16x16x32_bf16 v[14:17], v[210:213], v[186:189], v[14:17]
	v_mfma_f32_16x16x32_bf16 v[10:13], v[218:221], v[164:167], v[10:13]
	v_mfma_f32_16x16x32_bf16 v[6:9], v[218:221], v[186:189], v[6:9]
	v_mfma_f32_16x16x32_bf16 v[34:37], v[198:201], v[182:185], v[34:37]
	v_mfma_f32_16x16x32_bf16 v[30:33], v[198:201], v[190:193], v[30:33]
	v_mfma_f32_16x16x32_bf16 v[26:29], v[206:209], v[182:185], v[26:29]
	v_mfma_f32_16x16x32_bf16 v[22:25], v[206:209], v[190:193], v[22:25]
	v_mfma_f32_16x16x32_bf16 v[18:21], v[214:217], v[182:185], v[18:21]
	v_mfma_f32_16x16x32_bf16 v[14:17], v[214:217], v[190:193], v[14:17]
	v_mfma_f32_16x16x32_bf16 v[10:13], v[222:225], v[182:185], v[10:13]
	v_mfma_f32_16x16x32_bf16 v[6:9], v[222:225], v[190:193], v[6:9]
	s_barrier
	v_lshl_add_u64 v[164:165], v[246:247], 0, s[40:41]
	s_add_u32 m0, s32, 0x1c000
	s_nop 0
	global_load_lds_dwordx4 v[164:165], off
	s_add_u32 m0, s32, 0x1e000
	v_lshl_add_u64 v[164:165], v[248:249], 0, s[40:41]
	global_load_lds_dwordx4 v[164:165], off
	s_waitcnt vmcnt(6)
	s_barrier
	v_mfma_f32_16x16x32_bf16 v[2:5], v[194:197], v[226:229], v[2:5]
	v_mfma_f32_16x16x32_bf16 v[58:61], v[194:197], v[234:237], v[58:61]
	v_mfma_f32_16x16x32_bf16 v[66:69], v[202:205], v[226:229], v[66:69]
	v_mfma_f32_16x16x32_bf16 v[70:73], v[202:205], v[234:237], v[70:73]
	v_mfma_f32_16x16x32_bf16 v[74:77], v[210:213], v[226:229], v[74:77]
	v_mfma_f32_16x16x32_bf16 v[82:85], v[210:213], v[234:237], v[82:85]
	v_mfma_f32_16x16x32_bf16 v[86:89], v[218:221], v[226:229], v[86:89]
	v_mfma_f32_16x16x32_bf16 v[90:93], v[218:221], v[234:237], v[90:93]
	v_mfma_f32_16x16x32_bf16 v[2:5], v[198:201], v[230:233], v[2:5]
	v_mfma_f32_16x16x32_bf16 v[58:61], v[198:201], v[238:241], v[58:61]
	v_mfma_f32_16x16x32_bf16 v[66:69], v[206:209], v[230:233], v[66:69]
	v_mfma_f32_16x16x32_bf16 v[70:73], v[206:209], v[238:241], v[70:73]
	v_mfma_f32_16x16x32_bf16 v[74:77], v[214:217], v[230:233], v[74:77]
	v_mfma_f32_16x16x32_bf16 v[82:85], v[214:217], v[238:241], v[82:85]
	v_mfma_f32_16x16x32_bf16 v[86:89], v[222:225], v[230:233], v[86:89]
	v_mfma_f32_16x16x32_bf16 v[90:93], v[222:225], v[238:241], v[90:93]
	s_add_i32 s22, s22, 2
	s_add_u32 s20, s20, 0x100
	s_addc_u32 s21, s21, 0
	s_cmp_lt_u32 s22, 12
	s_barrier
	s_cbranch_scc1 .LBB0_40
	s_add_u32 s0, s16, 0x40780
	s_addc_u32 s1, s17, 0
	v_lshl_add_u64 v[132:133], v[132:133], 1, s[0:1]
	s_add_u32 m0, s32, 0xc000
	v_lshl_add_u64 v[130:131], v[130:131], 1, s[0:1]
	ds_read_b128 v[134:137], v162
	ds_read_b128 v[138:141], v162 offset:1024
	ds_read_b128 v[146:149], v162 offset:2048
	ds_read_b128 v[152:155], v162 offset:3072
	ds_read_b128 v[164:167], v142
	ds_read_b128 v[182:185], v142 offset:1024
	ds_read_b128 v[186:189], v142 offset:2048
	ds_read_b128 v[190:193], v142 offset:3072
	ds_read_b128 v[194:197], v142 offset:4096
	ds_read_b128 v[198:201], v142 offset:5120
	ds_read_b128 v[202:205], v142 offset:6144
	ds_read_b128 v[206:209], v142 offset:7168
	global_load_lds_dwordx4 v[132:133], off
	s_add_u32 m0, s32, 0xe000
	s_nop 0
	global_load_lds_dwordx4 v[130:131], off
	s_barrier
; #define G_LDA(dst, b, h)                                                                                                  \
;   _Pragma("unroll") for (int m = 0; m < 4; ++m) _Pragma("unroll") for (int k = 0; k < 2; ++k)                             \
;       dst[m][k] = *(const bf16x8*)((const char*)G_SA(b, h) + ((wr * 4 + m) * 2 + k) * 1024 + rdo)
; #define G_LDB(dst, b, h)                                                                                                  \
;   _Pragma("unroll") for (int n = 0; n < 2; ++n) _Pragma("unroll") for (int k = 0; k < 2; ++k)                             \
;       dst[n][k] = *(const bf16x8*)((const char*)G_SB(b, h) + ((wc * 2 + n) * 2 + k) * 1024 + rdo)
; #define G_WAIT_V(n) asm volatile("s_waitcnt vmcnt(" #n ")" ::: "memory")
; #define G_WAIT_L(n) asm volatile("s_waitcnt lgkmcnt(" #n ")" ::: "memory")
; #define G_BAR __builtin_amdgcn_s_barrier()
;     ...
;     G_BAR; G_WAIT_L(0); G_MMA(0, 0, At, B0); G_BAR;
;     G_LDB(B1, 0, 1); G_BAR; G_WAIT_L(0); G_MMA(0, 1, At, B1); G_BAR;
;     G_LDA(At, 0, 1); G_WAIT_V(4); G_BAR; G_WAIT_L(0); G_MMA(1, 0, At, B0); G_MMA(1, 1, At, B1); G_BAR;
;   }
;   {
;     G_LDB(B0, 1, 0); G_LDA(At, 1, 0); G_WAIT_V(2); G_BAR; G_WAIT_L(0); G_MMA(0, 0, At, B0); G_BAR;
	s_waitcnt lgkmcnt(0)
	v_mfma_f32_16x16x32_bf16 v[126:129], v[164:167], v[134:137], v[126:129]
	v_mfma_f32_16x16x32_bf16 v[122:125], v[164:167], v[146:149], v[122:125]
	v_mfma_f32_16x16x32_bf16 v[110:113], v[194:197], v[134:137], v[110:113]
	v_mfma_f32_16x16x32_bf16 v[102:105], v[202:205], v[134:137], v[102:105]
	v_mfma_f32_16x16x32_bf16 v[126:129], v[182:185], v[138:141], v[126:129]
	v_mfma_f32_16x16x32_bf16 v[122:125], v[182:185], v[152:155], v[122:125]
	v_mfma_f32_16x16x32_bf16 v[118:121], v[186:189], v[134:137], v[118:121]
	v_mfma_f32_16x16x32_bf16 v[114:117], v[186:189], v[146:149], v[114:117]
	v_mfma_f32_16x16x32_bf16 v[110:113], v[198:201], v[138:141], v[110:113]
	v_mfma_f32_16x16x32_bf16 v[106:109], v[194:197], v[146:149], v[106:109]
	v_mfma_f32_16x16x32_bf16 v[102:105], v[206:209], v[138:141], v[102:105]
	v_mfma_f32_16x16x32_bf16 v[98:101], v[202:205], v[146:149], v[98:101]
	v_mfma_f32_16x16x32_bf16 v[130:133], v[190:193], v[138:141], v[118:121]
	v_mfma_f32_16x16x32_bf16 v[210:213], v[190:193], v[152:155], v[114:117]
	v_mfma_f32_16x16x32_bf16 v[214:217], v[198:201], v[152:155], v[106:109]
	v_mfma_f32_16x16x32_bf16 v[218:221], v[206:209], v[152:155], v[98:101]
	s_barrier
	s_nop 1
	s_nop 0
	ds_read_b128 v[98:101], v159
	ds_read_b128 v[106:109], v159 offset:1024
	ds_read_b128 v[114:117], v159 offset:2048
	ds_read_b128 v[118:121], v159 offset:3072
	s_barrier
	s_waitcnt lgkmcnt(0)
	v_mfma_f32_16x16x32_bf16 v[94:97], v[164:167], v[98:101], v[94:97]
	v_mfma_f32_16x16x32_bf16 v[78:81], v[164:167], v[114:117], v[78:81]
	v_mfma_f32_16x16x32_bf16 v[62:65], v[186:189], v[98:101], v[62:65]
	v_mfma_f32_16x16x32_bf16 v[54:57], v[186:189], v[114:117], v[54:57]
	v_mfma_f32_16x16x32_bf16 v[50:53], v[194:197], v[98:101], v[50:53]
	v_mfma_f32_16x16x32_bf16 v[46:49], v[194:197], v[114:117], v[46:49]
	v_mfma_f32_16x16x32_bf16 v[42:45], v[202:205], v[98:101], v[42:45]
	v_mfma_f32_16x16x32_bf16 v[38:41], v[202:205], v[114:117], v[38:41]
	v_mfma_f32_16x16x32_bf16 v[94:97], v[182:185], v[106:109], v[94:97]
	v_mfma_f32_16x16x32_bf16 v[78:81], v[182:185], v[118:121], v[78:81]
	v_mfma_f32_16x16x32_bf16 v[62:65], v[190:193], v[106:109], v[62:65]
	v_mfma_f32_16x16x32_bf16 v[54:57], v[190:193], v[118:121], v[54:57]
	v_mfma_f32_16x16x32_bf16 v[50:53], v[198:201], v[106:109], v[50:53]
	v_mfma_f32_16x16x32_bf16 v[46:49], v[198:201], v[118:121], v[46:49]
	v_mfma_f32_16x16x32_bf16 v[42:45], v[206:209], v[106:109], v[42:45]
	v_mfma_f32_16x16x32_bf16 v[38:41], v[206:209], v[118:121], v[38:41]
	s_barrier
	ds_read_b128 v[156:159], v142 offset:16384
	ds_read_b128 v[164:167], v142 offset:17408
	ds_read_b128 v[182:185], v142 offset:18432
	ds_read_b128 v[186:189], v142 offset:19456
	ds_read_b128 v[190:193], v142 offset:20480
	ds_read_b128 v[194:197], v142 offset:21504
	ds_read_b128 v[198:201], v142 offset:22528
	ds_read_b128 v[202:205], v142 offset:23552
	s_waitcnt vmcnt(4)
	s_barrier
	s_waitcnt lgkmcnt(0)
	v_mfma_f32_16x16x32_bf16 v[34:37], v[156:159], v[134:137], v[34:37]
	v_mfma_f32_16x16x32_bf16 v[30:33], v[156:159], v[146:149], v[30:33]
	v_mfma_f32_16x16x32_bf16 v[26:29], v[182:185], v[134:137], v[26:29]
	v_mfma_f32_16x16x32_bf16 v[22:25], v[182:185], v[146:149], v[22:25]
	v_mfma_f32_16x16x32_bf16 v[18:21], v[190:193], v[134:137], v[18:21]
	v_mfma_f32_16x16x32_bf16 v[14:17], v[190:193], v[146:149], v[14:17]
	v_mfma_f32_16x16x32_bf16 v[10:13], v[198:201], v[134:137], v[10:13]
	v_mfma_f32_16x16x32_bf16 v[6:9], v[198:201], v[146:149], v[6:9]
	v_mfma_f32_16x16x32_bf16 v[34:37], v[164:167], v[138:141], v[34:37]
	v_mfma_f32_16x16x32_bf16 v[30:33], v[164:167], v[152:155], v[30:33]
	v_mfma_f32_16x16x32_bf16 v[26:29], v[186:189], v[138:141], v[26:29]
	v_mfma_f32_16x16x32_bf16 v[22:25], v[186:189], v[152:155], v[22:25]
	v_mfma_f32_16x16x32_bf16 v[18:21], v[194:197], v[138:141], v[18:21]
	v_mfma_f32_16x16x32_bf16 v[14:17], v[194:197], v[152:155], v[14:17]
	v_mfma_f32_16x16x32_bf16 v[10:13], v[202:205], v[138:141], v[10:13]
	v_mfma_f32_16x16x32_bf16 v[6:9], v[202:205], v[152:155], v[6:9]
	v_mfma_f32_16x16x32_bf16 v[58:61], v[156:159], v[114:117], v[58:61]
	v_mfma_f32_16x16x32_bf16 v[134:137], v[164:167], v[118:121], v[58:61]
	v_mfma_f32_16x16x32_bf16 v[58:61], v[182:185], v[98:101], v[66:69]
	v_mfma_f32_16x16x32_bf16 v[138:141], v[186:189], v[106:109], v[58:61]
	v_mfma_f32_16x16x32_bf16 v[58:61], v[182:185], v[114:117], v[70:73]
	v_mfma_f32_16x16x32_bf16 v[146:149], v[186:189], v[118:121], v[58:61]
	v_mfma_f32_16x16x32_bf16 v[58:61], v[190:193], v[98:101], v[74:77]
	v_mfma_f32_16x16x32_bf16 v[152:155], v[194:197], v[106:109], v[58:61]
	v_mfma_f32_16x16x32_bf16 v[58:61], v[190:193], v[114:117], v[82:85]
	v_mfma_f32_16x16x32_bf16 v[2:5], v[156:159], v[98:101], v[2:5]
	v_mfma_f32_16x16x32_bf16 v[156:159], v[194:197], v[118:121], v[58:61]
	v_mfma_f32_16x16x32_bf16 v[58:61], v[198:201], v[98:101], v[86:89]
	v_mfma_f32_16x16x32_bf16 v[2:5], v[164:167], v[106:109], v[2:5]
	v_mfma_f32_16x16x32_bf16 v[164:167], v[202:205], v[106:109], v[58:61]
	v_mfma_f32_16x16x32_bf16 v[58:61], v[198:201], v[114:117], v[90:93]
	v_mfma_f32_16x16x32_bf16 v[182:185], v[202:205], v[118:121], v[58:61]
	s_barrier
	ds_read_b128 v[186:189], v150
	ds_read_b128 v[190:193], v150 offset:1024
	ds_read_b128 v[194:197], v150 offset:2048
	ds_read_b128 v[198:201], v150 offset:3072
	s_nop 0
	s_nop 0
	ds_read_b128 v[58:61], v142 offset:32768
	ds_read_b128 v[66:69], v142 offset:33792
	ds_read_b128 v[70:73], v142 offset:34816
	ds_read_b128 v[74:77], v142 offset:35840
	ds_read_b128 v[202:205], v142 offset:36864
	ds_read_b128 v[206:209], v142 offset:37888
	ds_read_b128 v[222:225], v142 offset:38912
	ds_read_b128 v[226:229], v142 offset:39936
	s_waitcnt vmcnt(2)
	s_barrier
; #define G_LDA(dst, b, h)                                                                                                  \
;   _Pragma("unroll") for (int m = 0; m < 4; ++m) _Pragma("unroll") for (int k = 0; k < 2; ++k)                             \
;       dst[m][k] = *(const bf16x8*)((const char*)G_SA(b, h) + ((wr * 4 + m) * 2 + k) * 1024 + rdo)
; #define G_LDB(dst, b, h)                                                                                                  \
;   _Pragma("unroll") for (int n = 0; n < 2; ++n) _Pragma("unroll") for (int k = 0; k < 2; ++k)                             \
;       dst[n][k] = *(const bf16x8*)((const char*)G_SB(b, h) + ((wc * 2 + n) * 2 + k) * 1024 + rdo)
; #define G_WAIT_V(n) asm volatile("s_waitcnt vmcnt(" #n ")" ::: "memory")
; #define G_WAIT_L(n) asm volatile("s_waitcnt lgkmcnt(" #n ")" ::: "memory")
; #define G_BAR __builtin_amdgcn_s_barrier()
;     ...
;     G_LDB(B0, 1, 0); G_LDA(At, 1, 0); G_WAIT_V(2); G_BAR; G_WAIT_L(0); G_MMA(0, 0, At, B0); G_BAR;
;     G_LDB(B1, 1, 1); G_WAIT_V(0); G_BAR; G_WAIT_L(0); G_MMA(0, 1, At, B1); G_BAR;
;     G_LDA(At, 1, 1); G_BAR; G_WAIT_L(0); G_MMA(1, 0, At, B0); G_MMA(1, 1, At, B1); G_BAR;
;   }
;   if (wr == 0) G_BAR;
	s_waitcnt lgkmcnt(0)
	v_mfma_f32_16x16x32_bf16 v[82:85], v[58:61], v[186:189], v[126:129]
	v_mfma_f32_16x16x32_bf16 v[118:121], v[66:69], v[190:193], v[82:85]
	v_mfma_f32_16x16x32_bf16 v[82:85], v[58:61], v[194:197], v[122:125]
	v_mfma_f32_16x16x32_bf16 v[126:129], v[66:69], v[198:201], v[82:85]
	v_mfma_f32_16x16x32_bf16 v[82:85], v[70:73], v[186:189], v[130:133]
	v_mfma_f32_16x16x32_bf16 v[114:117], v[74:77], v[190:193], v[82:85]
	v_mfma_f32_16x16x32_bf16 v[82:85], v[70:73], v[194:197], v[210:213]
	v_mfma_f32_16x16x32_bf16 v[122:125], v[74:77], v[198:201], v[82:85]
	v_mfma_f32_16x16x32_bf16 v[82:85], v[202:205], v[186:189], v[110:113]
	v_mfma_f32_16x16x32_bf16 v[106:109], v[206:209], v[190:193], v[82:85]
	v_mfma_f32_16x16x32_bf16 v[82:85], v[202:205], v[194:197], v[214:217]
	v_mfma_f32_16x16x32_bf16 v[110:113], v[206:209], v[198:201], v[82:85]
	v_mfma_f32_16x16x32_bf16 v[82:85], v[222:225], v[186:189], v[102:105]
	v_mfma_f32_16x16x32_bf16 v[98:101], v[226:229], v[190:193], v[82:85]
	v_mfma_f32_16x16x32_bf16 v[82:85], v[222:225], v[194:197], v[218:221]
	v_mfma_f32_16x16x32_bf16 v[102:105], v[226:229], v[198:201], v[82:85]
	s_barrier
	ds_read_b128 v[130:133], v145
	ds_read_b128 v[210:213], v145 offset:1024
	ds_read_b128 v[214:217], v145 offset:2048
	ds_read_b128 v[218:221], v145 offset:3072
	s_waitcnt vmcnt(0)
	s_barrier
	s_waitcnt lgkmcnt(0)
	v_mfma_f32_16x16x32_bf16 v[82:85], v[58:61], v[130:133], v[94:97]
	v_mfma_f32_16x16x32_bf16 v[58:61], v[58:61], v[214:217], v[78:81]
	v_mfma_f32_16x16x32_bf16 v[94:97], v[66:69], v[218:221], v[58:61]
	v_mfma_f32_16x16x32_bf16 v[58:61], v[70:73], v[130:133], v[62:65]
	v_mfma_f32_16x16x32_bf16 v[54:57], v[70:73], v[214:217], v[54:57]
	v_mfma_f32_16x16x32_bf16 v[50:53], v[202:205], v[130:133], v[50:53]
	v_mfma_f32_16x16x32_bf16 v[46:49], v[202:205], v[214:217], v[46:49]
	v_mfma_f32_16x16x32_bf16 v[42:45], v[222:225], v[130:133], v[42:45]
	v_mfma_f32_16x16x32_bf16 v[38:41], v[222:225], v[214:217], v[38:41]
	v_mfma_f32_16x16x32_bf16 v[86:89], v[66:69], v[210:213], v[82:85]
	v_mfma_f32_16x16x32_bf16 v[82:85], v[74:77], v[210:213], v[58:61]
	v_mfma_f32_16x16x32_bf16 v[90:93], v[74:77], v[218:221], v[54:57]
	v_mfma_f32_16x16x32_bf16 v[74:77], v[206:209], v[210:213], v[50:53]
	v_mfma_f32_16x16x32_bf16 v[78:81], v[206:209], v[218:221], v[46:49]
	v_mfma_f32_16x16x32_bf16 v[66:69], v[226:229], v[210:213], v[42:45]
	v_mfma_f32_16x16x32_bf16 v[70:73], v[226:229], v[218:221], v[38:41]
	s_barrier
	ds_read_b128 v[202:205], v142 offset:49152
	ds_read_b128 v[206:209], v142 offset:50176
	ds_read_b128 v[222:225], v142 offset:51200
	ds_read_b128 v[226:229], v142 offset:52224
	ds_read_b128 v[230:233], v142 offset:53248
	ds_read_b128 v[234:237], v142 offset:54272
	ds_read_b128 v[238:241], v142 offset:55296
	ds_read_b128 v[142:145], v142 offset:56320
	s_barrier
	s_waitcnt lgkmcnt(0)
	v_mfma_f32_16x16x32_bf16 v[34:37], v[202:205], v[186:189], v[34:37]
	v_mfma_f32_16x16x32_bf16 v[30:33], v[202:205], v[194:197], v[30:33]
	v_mfma_f32_16x16x32_bf16 v[26:29], v[222:225], v[186:189], v[26:29]
	v_mfma_f32_16x16x32_bf16 v[22:25], v[222:225], v[194:197], v[22:25]
	v_mfma_f32_16x16x32_bf16 v[18:21], v[230:233], v[186:189], v[18:21]
	v_mfma_f32_16x16x32_bf16 v[14:17], v[230:233], v[194:197], v[14:17]
	v_mfma_f32_16x16x32_bf16 v[10:13], v[238:241], v[186:189], v[10:13]
	v_mfma_f32_16x16x32_bf16 v[6:9], v[238:241], v[194:197], v[6:9]
	v_mfma_f32_16x16x32_bf16 v[54:57], v[206:209], v[190:193], v[34:37]
	v_mfma_f32_16x16x32_bf16 v[62:65], v[206:209], v[198:201], v[30:33]
	v_mfma_f32_16x16x32_bf16 v[50:53], v[226:229], v[190:193], v[26:29]
	v_mfma_f32_16x16x32_bf16 v[58:61], v[226:229], v[198:201], v[22:25]
	v_mfma_f32_16x16x32_bf16 v[42:45], v[234:237], v[190:193], v[18:21]
	v_mfma_f32_16x16x32_bf16 v[46:49], v[234:237], v[198:201], v[14:17]
	v_mfma_f32_16x16x32_bf16 v[34:37], v[142:145], v[190:193], v[10:13]
	v_mfma_f32_16x16x32_bf16 v[38:41], v[142:145], v[198:201], v[6:9]
	v_mfma_f32_16x16x32_bf16 v[2:5], v[202:205], v[130:133], v[2:5]
	v_mfma_f32_16x16x32_bf16 v[22:25], v[206:209], v[210:213], v[2:5]
	v_mfma_f32_16x16x32_bf16 v[2:5], v[202:205], v[214:217], v[134:137]
	v_mfma_f32_16x16x32_bf16 v[30:33], v[206:209], v[218:221], v[2:5]
	v_mfma_f32_16x16x32_bf16 v[2:5], v[222:225], v[130:133], v[138:141]
	v_mfma_f32_16x16x32_bf16 v[18:21], v[226:229], v[210:213], v[2:5]
	v_mfma_f32_16x16x32_bf16 v[2:5], v[222:225], v[214:217], v[146:149]
	v_mfma_f32_16x16x32_bf16 v[26:29], v[226:229], v[218:221], v[2:5]
	v_mfma_f32_16x16x32_bf16 v[2:5], v[230:233], v[130:133], v[152:155]
	v_mfma_f32_16x16x32_bf16 v[10:13], v[234:237], v[210:213], v[2:5]
	v_mfma_f32_16x16x32_bf16 v[2:5], v[230:233], v[214:217], v[156:159]
	v_mfma_f32_16x16x32_bf16 v[14:17], v[234:237], v[218:221], v[2:5]
	v_mfma_f32_16x16x32_bf16 v[2:5], v[238:241], v[130:133], v[164:167]
	v_mfma_f32_16x16x32_bf16 v[6:9], v[238:241], v[214:217], v[182:185]
	v_mfma_f32_16x16x32_bf16 v[2:5], v[142:145], v[210:213], v[2:5]
	v_mfma_f32_16x16x32_bf16 v[6:9], v[142:145], v[218:221], v[6:9]
	v_cmp_gt_u32_e32 vcc, s67, v0
	s_barrier
	s_and_saveexec_b64 s[16:17], vcc
	s_cbranch_execz .LBB0_43
	s_barrier
; DI float sigm(float x) { return 1.f / (1.f + __expf(-x)); }
; DI u32x4 pack8(const float* f) { u32x4 o; o.x = pack2(f[0], f[1]); o.y = pack2(f[2], f[3]); o.z = pack2(f[4], f[5]); o.w = pack2(f[6], f[7]); return o; }
; DI void lds_barrier() { asm volatile("s_waitcnt lgkmcnt(0)\n\ts_barrier" ::: "memory"); }
; DI int tid512() { int t = threadIdx.x; asm volatile("" : "+v"(t)); return t; }
; template <int AI, int BJ>
; DI void stage_q(const f32x4 (&acc)[2][2][4][2], float* Cs) {
;   const int t = tid512(), wid = t >> 6, lane = t & 63, wr = wid >> 2, wc = wid & 3, fr = lane & 15, fq = lane >> 4;
;   lds_barrier();
; #pragma unroll
;   for (int m = 0; m < 4; ++m)
; #pragma unroll
;     for (int n = 0; n < 2; ++n)
; #pragma unroll
;       for (int j = 0; j < 4; ++j) Cs[(wr * 64 + m * 16 + fq * 4 + j) * CST + wc * 32 + n * 16 + fr] = acc[AI][BJ][m][n][j];
;   lds_barrier();
; }
; template <int AI, int BJ, int PASS>
; DI void f3_proc(PREF p, const f32x4 (&acc)[2][2][4][2], int mt, int dt, float* Cs, const u32x4 (&g)[4]) {
;   const int t = tid512();
;   const int row0 = mt * 256 + AI * 128, col0 = dt * 256 + BJ * 128;
;   const int c = (t & 15) * 8;
;   stage_q<AI, BJ>(acc, Cs);
; #pragma unroll
;   for (int q = 0; q < 4; ++q) {
;     int r = (t >> 4) + 32 * q;
;     float v[8]; ld8(Cs + r * CST + c, v);
;     if (PASS == 0) {
; #pragma unroll
;       for (int j = 0; j < 8; ++j) v[j] = sigm(v[j]);
;     } else {
;       float gf[8]; unpack8(g[q], gf);
; #pragma unroll
;       for (int j = 0; j < 8; ++j) v[j] *= gf[j];
;     }
;     *(u32x4*)((u16*)p.fbuf + (size_t)(row0 + r) * 1024 + col0 + c) = pack8(v);
;   }
.LBB0_43:
	s_or_b64 exec, exec, s[16:17]
	v_mov_b32_e32 v132, v168
	s_lshl_b32 s24, s35, 8
	v_lshlrev_b32_e32 v0, 3, v132
	v_and_b32_e32 v133, 0x78, v0
	v_mov_b32_e32 v0, v168
	s_waitcnt lgkmcnt(0)
	s_barrier
	s_nop 0
	v_and_b32_e32 v130, 15, v0
	v_lshrrev_b32_e32 v131, 2, v0
	v_lshlrev_b32_e32 v0, 1, v0
	v_lshlrev_b32_e32 v130, 2, v130
	v_and_b32_e32 v131, 0xfffffcc, v131
	v_and_or_b32 v0, v0, s89, v130
	v_mad_u64_u32 v[130:131], s[0:1], v131, s92, v[0:1]
	v_add_u32_e32 v0, 0x400, v130
	ds_write2_b32 v130, v118, v126 offset1:16
	ds_write2_b32 v130, v119, v127 offset0:132 offset1:148
	ds_write2_b32 v0, v120, v128 offset0:8 offset1:24
	ds_write2_b32 v0, v121, v129 offset0:140 offset1:156
	v_add_u32_e32 v0, 0x2000, v130
	ds_write2_b32 v0, v114, v122 offset0:64 offset1:80
	ds_write2_b32 v0, v115, v123 offset0:196 offset1:212
	v_add_u32_e32 v0, 0x2400, v130
	ds_write2_b32 v0, v116, v124 offset0:72 offset1:88
	ds_write2_b32 v0, v117, v125 offset0:204 offset1:220
	v_add_u32_e32 v0, 0x4000, v130
	ds_write2_b32 v0, v106, v110 offset0:128 offset1:144
	v_add_u32_e32 v0, 0x4400, v130
	ds_write2_b32 v0, v107, v111 offset0:4 offset1:20
	ds_write2_b32 v0, v108, v112 offset0:136 offset1:152
	v_add_u32_e32 v0, 0x4800, v130
	ds_write2_b32 v0, v109, v113 offset0:12 offset1:28
	v_add_u32_e32 v0, 0x6000, v130
	ds_write2_b32 v0, v98, v102 offset0:192 offset1:208
	v_add_u32_e32 v0, 0x6400, v130
	ds_write2_b32 v0, v99, v103 offset0:68 offset1:84
	ds_write2_b32 v0, v100, v104 offset0:200 offset1:216
	v_add_u32_e32 v0, 0x6800, v130
	v_ashrrev_i32_e32 v100, 4, v132
	ds_write2_b32 v0, v101, v105 offset0:76 offset1:92
	v_mul_lo_u32 v0, v100, s92
	s_waitcnt lgkmcnt(0)
	s_barrier
	v_lshl_add_u32 v102, v133, 2, v0
	s_waitcnt vmcnt(0)
	ds_read_b128 v[104:107], v102
	ds_read_b128 v[108:111], v102 offset:16
	s_lshl_b32 s0, s18, 8
	s_ashr_i32 s1, s0, 31
	s_lshl_b64 s[0:1], s[0:1], 1
	s_waitcnt lgkmcnt(1)
	v_mul_f32_e32 v0, 0xbfb8aa3b, v104
	v_exp_f32_e32 v0, v0
	s_add_u32 s16, s14, s0
	s_addc_u32 s17, s15, s1
	v_mul_f32_e32 v105, 0xbfb8aa3b, v105
	v_add_f32_e32 v101, 1.0, v0
	v_lshlrev_b32_e32 v0, 1, v133
	v_lshl_add_u64 v[98:99], s[16:17], 0, v[0:1]
	v_exp_f32_e32 v105, v105
	s_nop 0
	v_add_f32_e32 v103, 1.0, v105
	v_rcp_f32_e32 v0, v101
	v_mul_f32_e32 v106, 0xbfb8aa3b, v106
	v_exp_f32_e32 v106, v106
	s_nop 0
	v_add_f32_e32 v105, 1.0, v106
	v_rcp_f32_e32 v101, v103
	v_mul_f32_e32 v107, 0xbfb8aa3b, v107
	v_exp_f32_e32 v107, v107
	s_nop 0
	v_add_f32_e32 v106, 1.0, v107
	s_waitcnt lgkmcnt(0)
	v_mul_f32_e32 v108, 0xbfb8aa3b, v108
	v_exp_f32_e32 v108, v108
	v_rcp_f32_e32 v103, v105
	v_add_f32_e32 v107, 1.0, v108
	v_rcp_f32_e32 v113, v106
	v_mul_f32_e32 v106, 0xbfb8aa3b, v109
	v_exp_f32_e32 v106, v106
	s_nop 0
	v_add_f32_e32 v106, 1.0, v106
	v_rcp_f32_e32 v112, v107
	v_mul_f32_e32 v107, 0xbfb8aa3b, v110
	v_exp_f32_e32 v107, v107
	s_nop 0
	v_add_f32_e32 v107, 1.0, v107
	v_rcp_f32_e32 v114, v106
	v_mul_f32_e32 v106, 0xbfb8aa3b, v111
	v_exp_f32_e32 v106, v106
	s_nop 0
	v_add_f32_e32 v106, 1.0, v106
	v_rcp_f32_e32 v111, v107
	v_cvt_pk_bf16_f32 v110, v112, v114
	v_rcp_f32_e32 v116, v106
	ds_read_b128 v[104:107], v102 offset:16896
	v_cvt_pk_bf16_f32 v108, v0, v101
	v_cvt_pk_bf16_f32 v109, v103, v113
	ds_read_b128 v[112:115], v102 offset:16912
	v_add_u32_e32 v100, s24, v100
	s_waitcnt lgkmcnt(1)
	v_mul_f32_e32 v0, 0xbfb8aa3b, v104
	v_exp_f32_e32 v0, v0
	v_ashrrev_i32_e32 v101, 31, v100
	v_cvt_pk_bf16_f32 v111, v111, v116
	v_lshlrev_b64 v[116:117], 11, v[100:101]
	v_add_f32_e32 v0, 1.0, v0
	v_mul_f32_e32 v105, 0xbfb8aa3b, v105
	v_lshl_add_u64 v[116:117], v[98:99], 0, v[116:117]
	v_exp_f32_e32 v105, v105
	global_store_dwordx4 v[116:117], v[108:111], off
	v_mul_f32_e32 v106, 0xbfb8aa3b, v106
	v_exp_f32_e32 v106, v106
	v_add_f32_e32 v103, 1.0, v105
	v_rcp_f32_e32 v0, v0
	v_mul_f32_e32 v107, 0xbfb8aa3b, v107
	v_add_f32_e32 v105, 1.0, v106
	v_rcp_f32_e32 v101, v103
	v_exp_f32_e32 v107, v107
	s_nop 0
	v_add_f32_e32 v106, 1.0, v107
	s_waitcnt lgkmcnt(0)
	v_mul_f32_e32 v108, 0xbfb8aa3b, v112
	v_exp_f32_e32 v108, v108
	v_rcp_f32_e32 v103, v105
	v_add_f32_e32 v107, 1.0, v108
	v_rcp_f32_e32 v109, v106
	v_mul_f32_e32 v106, 0xbfb8aa3b, v113
	v_exp_f32_e32 v106, v106
	s_nop 0
	v_add_f32_e32 v106, 1.0, v106
	v_rcp_f32_e32 v110, v107
	v_mul_f32_e32 v107, 0xbfb8aa3b, v114
	v_exp_f32_e32 v107, v107
	s_nop 0
	v_add_f32_e32 v107, 1.0, v107
	v_rcp_f32_e32 v111, v106
	v_mul_f32_e32 v106, 0xbfb8aa3b, v115
	v_exp_f32_e32 v106, v106
	s_nop 0
	v_add_f32_e32 v106, 1.0, v106
	v_rcp_f32_e32 v116, v107
	v_cvt_pk_bf16_f32 v109, v103, v109
	v_rcp_f32_e32 v117, v106
	ds_read_b128 v[104:107], v102 offset:33792
	ds_read_b128 v[112:115], v102 offset:33808
	v_cvt_pk_bf16_f32 v108, v0, v101
	v_cvt_pk_bf16_f32 v110, v110, v111
	v_cvt_pk_bf16_f32 v111, v116, v117
	s_waitcnt lgkmcnt(1)
	v_mul_f32_e32 v0, 0xbfb8aa3b, v104
	v_exp_f32_e32 v0, v0
	v_add_u32_e32 v116, 32, v100
	v_ashrrev_i32_e32 v117, 31, v116
	v_lshlrev_b64 v[116:117], 11, v[116:117]
	v_add_f32_e32 v0, 1.0, v0
	v_mul_f32_e32 v105, 0xbfb8aa3b, v105
	v_lshl_add_u64 v[116:117], v[98:99], 0, v[116:117]
	v_exp_f32_e32 v105, v105
	global_store_dwordx4 v[116:117], v[108:111], off
	v_mul_f32_e32 v106, 0xbfb8aa3b, v106
	v_exp_f32_e32 v106, v106
	v_add_f32_e32 v104, 1.0, v105
	v_rcp_f32_e32 v0, v0
	v_mul_f32_e32 v107, 0xbfb8aa3b, v107
	v_add_f32_e32 v105, 1.0, v106
	v_exp_f32_e32 v107, v107
	v_rcp_f32_e32 v101, v104
	v_add_f32_e32 v106, 1.0, v107
	s_waitcnt lgkmcnt(0)
; DI float sigm(float x) { return 1.f / (1.f + __expf(-x)); }
; DI u32x4 pack8(const float* f) { u32x4 o; o.x = pack2(f[0], f[1]); o.y = pack2(f[2], f[3]); o.z = pack2(f[4], f[5]); o.w = pack2(f[6], f[7]); return o; }
; DI void lds_barrier() { asm volatile("s_waitcnt lgkmcnt(0)\n\ts_barrier" ::: "memory"); }
; DI int tid512() { int t = threadIdx.x; asm volatile("" : "+v"(t)); return t; }
; template <int AI, int BJ>
; DI void stage_q(const f32x4 (&acc)[2][2][4][2], float* Cs) {
;   const int t = tid512(), wid = t >> 6, lane = t & 63, wr = wid >> 2, wc = wid & 3, fr = lane & 15, fq = lane >> 4;
;   lds_barrier();
; #pragma unroll
;   for (int m = 0; m < 4; ++m)
; #pragma unroll
;     for (int n = 0; n < 2; ++n)
; #pragma unroll
;       for (int j = 0; j < 4; ++j) Cs[(wr * 64 + m * 16 + fq * 4 + j) * CST + wc * 32 + n * 16 + fr] = acc[AI][BJ][m][n][j];
;   lds_barrier();
; }
; template <int AI, int BJ, int PASS>
; DI void f3_proc(PREF p, const f32x4 (&acc)[2][2][4][2], int mt, int dt, float* Cs, const u32x4 (&g)[4]) {
;   const int t = tid512();
;   const int row0 = mt * 256 + AI * 128, col0 = dt * 256 + BJ * 128;
;   const int c = (t & 15) * 8;
;   stage_q<AI, BJ>(acc, Cs);
; #pragma unroll
;   for (int q = 0; q < 4; ++q) {
;     int r = (t >> 4) + 32 * q;
;     float v[8]; ld8(Cs + r * CST + c, v);
;     if (PASS == 0) {
; #pragma unroll
;       for (int j = 0; j < 8; ++j) v[j] = sigm(v[j]);
;     } else {
;       float gf[8]; unpack8(g[q], gf);
; #pragma unroll
;       for (int j = 0; j < 8; ++j) v[j] *= gf[j];
;     }
;     *(u32x4*)((u16*)p.fbuf + (size_t)(row0 + r) * 1024 + col0 + c) = pack8(v);
;   }
	v_mul_f32_e32 v108, 0xbfb8aa3b, v112
	v_exp_f32_e32 v108, v108
	v_rcp_f32_e32 v103, v105
	v_add_f32_e32 v107, 1.0, v108
	v_rcp_f32_e32 v109, v106
	v_mul_f32_e32 v106, 0xbfb8aa3b, v113
	v_exp_f32_e32 v106, v106
	s_nop 0
	v_add_f32_e32 v106, 1.0, v106
	v_rcp_f32_e32 v110, v107
	v_mul_f32_e32 v107, 0xbfb8aa3b, v114
	v_exp_f32_e32 v107, v107
	s_nop 0
	v_add_f32_e32 v107, 1.0, v107
	v_rcp_f32_e32 v111, v106
	v_mul_f32_e32 v106, 0xbfb8aa3b, v115
	v_exp_f32_e32 v106, v106
	s_nop 0
	v_add_f32_e32 v106, 1.0, v106
	v_rcp_f32_e32 v116, v107
	v_cvt_pk_bf16_f32 v109, v103, v109
	v_rcp_f32_e32 v117, v106
	ds_read_b128 v[104:107], v102 offset:50688
	ds_read_b128 v[112:115], v102 offset:50704
	v_cvt_pk_bf16_f32 v108, v0, v101
	v_add_u32_e32 v102, 64, v100
	v_ashrrev_i32_e32 v103, 31, v102
	s_waitcnt lgkmcnt(1)
	v_mul_f32_e32 v0, 0xbfb8aa3b, v104
	v_exp_f32_e32 v0, v0
	v_lshlrev_b64 v[102:103], 11, v[102:103]
	v_lshl_add_u64 v[102:103], v[98:99], 0, v[102:103]
	v_cvt_pk_bf16_f32 v110, v110, v111
	v_add_f32_e32 v0, 1.0, v0
	v_cvt_pk_bf16_f32 v111, v116, v117
	global_store_dwordx4 v[102:103], v[108:111], off
	v_mul_f32_e32 v105, 0xbfb8aa3b, v105
	v_exp_f32_e32 v105, v105
	s_nop 0
	v_add_f32_e32 v102, 1.0, v105
	v_mul_f32_e32 v104, 0xbfb8aa3b, v106
	v_rcp_f32_e32 v0, v0
	v_exp_f32_e32 v104, v104
	s_nop 0
	v_add_f32_e32 v104, 1.0, v104
	v_rcp_f32_e32 v101, v102
	v_mul_f32_e32 v107, 0xbfb8aa3b, v107
	v_exp_f32_e32 v107, v107
	s_nop 0
	v_add_f32_e32 v105, 1.0, v107
	s_waitcnt lgkmcnt(0)
	v_mul_f32_e32 v106, 0xbfb8aa3b, v112
	v_rcp_f32_e32 v103, v104
	v_exp_f32_e32 v106, v106
	s_nop 0
	v_add_f32_e32 v106, 1.0, v106
	v_rcp_f32_e32 v104, v105
	v_mul_f32_e32 v108, 0xbfb8aa3b, v113
	v_exp_f32_e32 v108, v108
	s_nop 0
	v_add_f32_e32 v107, 1.0, v108
	v_rcp_f32_e32 v105, v106
	v_mul_f32_e32 v109, 0xbfb8aa3b, v114
	v_exp_f32_e32 v109, v109
	s_nop 0
	v_add_f32_e32 v108, 1.0, v109
	v_rcp_f32_e32 v106, v107
	v_mul_f32_e32 v110, 0xbfb8aa3b, v115
	v_exp_f32_e32 v110, v110
	s_nop 0
	v_add_f32_e32 v109, 1.0, v110
	v_rcp_f32_e32 v107, v108
	v_add_u32_e32 v100, 0x60, v100
	v_rcp_f32_e32 v108, v109
	v_cvt_pk_bf16_f32 v102, v0, v101
	v_ashrrev_i32_e32 v101, 31, v100
	v_lshlrev_b64 v[100:101], 11, v[100:101]
	v_lshl_add_u64 v[98:99], v[98:99], 0, v[100:101]
	v_mov_b32_e32 v100, v168
	v_cvt_pk_bf16_f32 v103, v103, v104
	v_cvt_pk_bf16_f32 v104, v105, v106
	v_cvt_pk_bf16_f32 v105, v107, v108
	global_store_dwordx4 v[98:99], v[102:105], off
	s_or_b32 s25, s24, 0x80
	v_lshlrev_b32_e32 v0, 3, v100
	v_and_b32_e32 v101, 0x78, v0
	v_mov_b32_e32 v0, v168
	s_waitcnt lgkmcnt(0)
	s_barrier
	s_nop 0
	v_and_b32_e32 v98, 15, v0
	v_lshrrev_b32_e32 v99, 2, v0
	v_lshlrev_b32_e32 v0, 1, v0
	v_lshlrev_b32_e32 v98, 2, v98
	v_and_b32_e32 v99, 0xfffffcc, v99
	v_and_or_b32 v0, v0, s89, v98
	v_mad_u64_u32 v[98:99], s[0:1], v99, s92, v[0:1]
	v_add_u32_e32 v0, 0x400, v98
	ds_write2_b32 v98, v86, v94 offset1:16
	ds_write2_b32 v98, v87, v95 offset0:132 offset1:148
	ds_write2_b32 v0, v88, v96 offset0:8 offset1:24
	ds_write2_b32 v0, v89, v97 offset0:140 offset1:156
	v_add_u32_e32 v0, 0x2000, v98
	ds_write2_b32 v0, v82, v90 offset0:64 offset1:80
	ds_write2_b32 v0, v83, v91 offset0:196 offset1:212
	v_add_u32_e32 v0, 0x2400, v98
	ds_write2_b32 v0, v84, v92 offset0:72 offset1:88
	ds_write2_b32 v0, v85, v93 offset0:204 offset1:220
	v_add_u32_e32 v0, 0x4000, v98
	ds_write2_b32 v0, v74, v78 offset0:128 offset1:144
	v_add_u32_e32 v0, 0x4400, v98
	ds_write2_b32 v0, v75, v79 offset0:4 offset1:20
	ds_write2_b32 v0, v76, v80 offset0:136 offset1:152
	v_add_u32_e32 v0, 0x4800, v98
	ds_write2_b32 v0, v77, v81 offset0:12 offset1:28
	v_add_u32_e32 v0, 0x6000, v98
	ds_write2_b32 v0, v66, v70 offset0:192 offset1:208
	v_add_u32_e32 v0, 0x6400, v98
	ds_write2_b32 v0, v67, v71 offset0:68 offset1:84
	ds_write2_b32 v0, v68, v72 offset0:200 offset1:216
	v_add_u32_e32 v0, 0x6800, v98
	ds_write2_b32 v0, v69, v73 offset0:76 offset1:92
	v_ashrrev_i32_e32 v0, 4, v100
	v_mul_lo_u32 v66, v0, s92
	s_waitcnt lgkmcnt(0)
	s_barrier
	v_lshl_add_u32 v68, v101, 2, v66
	ds_read_b128 v[70:73], v68
	ds_read_b128 v[74:77], v68 offset:16
	s_waitcnt lgkmcnt(1)
	v_mul_f32_e32 v66, 0xbfb8aa3b, v70
	v_exp_f32_e32 v66, v66
	v_mul_f32_e32 v71, 0xbfb8aa3b, v71
	v_exp_f32_e32 v71, v71
	v_mul_f32_e32 v72, 0xbfb8aa3b, v72
	v_add_f32_e32 v66, 1.0, v66
	v_exp_f32_e32 v72, v72
	v_mul_f32_e32 v73, 0xbfb8aa3b, v73
	v_exp_f32_e32 v73, v73
	v_add_f32_e32 v70, 1.0, v71
	v_rcp_f32_e32 v66, v66
	s_waitcnt lgkmcnt(0)
	v_mul_f32_e32 v74, 0xbfb8aa3b, v74
	v_add_f32_e32 v71, 1.0, v72
	v_rcp_f32_e32 v67, v70
	v_exp_f32_e32 v74, v74
	v_add_f32_e32 v72, 1.0, v73
	v_rcp_f32_e32 v69, v71
	v_mul_f32_e32 v75, 0xbfb8aa3b, v75
	v_add_f32_e32 v73, 1.0, v74
	v_rcp_f32_e32 v71, v72
	v_exp_f32_e32 v75, v75
	s_nop 0
	v_add_f32_e32 v74, 1.0, v75
	v_rcp_f32_e32 v72, v73
	v_mul_f32_e32 v76, 0xbfb8aa3b, v76
	v_exp_f32_e32 v76, v76
	s_nop 0
	v_add_f32_e32 v75, 1.0, v76
	v_rcp_f32_e32 v73, v74
	v_mul_f32_e32 v77, 0xbfb8aa3b, v77
	v_exp_f32_e32 v77, v77
	s_nop 0
	v_add_f32_e32 v76, 1.0, v77
	v_rcp_f32_e32 v78, v75
	v_cvt_pk_bf16_f32 v72, v72, v73
	v_rcp_f32_e32 v79, v76
	ds_read_b128 v[74:77], v68 offset:16896
	v_cvt_pk_bf16_f32 v70, v66, v67
	v_cvt_pk_bf16_f32 v73, v78, v79
	v_add_u32_e32 v66, s24, v0
	ds_read_b128 v[78:81], v68 offset:16912
	s_waitcnt lgkmcnt(1)
; DI float sigm(float x) { return 1.f / (1.f + __expf(-x)); }
; DI u32x4 pack8(const float* f) { u32x4 o; o.x = pack2(f[0], f[1]); o.y = pack2(f[2], f[3]); o.z = pack2(f[4], f[5]); o.w = pack2(f[6], f[7]); return o; }
; DI void lds_barrier() { asm volatile("s_waitcnt lgkmcnt(0)\n\ts_barrier" ::: "memory"); }
; DI int tid512() { int t = threadIdx.x; asm volatile("" : "+v"(t)); return t; }
; template <int AI, int BJ>
; DI void stage_q(const f32x4 (&acc)[2][2][4][2], float* Cs) {
;   const int t = tid512(), wid = t >> 6, lane = t & 63, wr = wid >> 2, wc = wid & 3, fr = lane & 15, fq = lane >> 4;
;   lds_barrier();
; #pragma unroll
;   for (int m = 0; m < 4; ++m)
; #pragma unroll
;     for (int n = 0; n < 2; ++n)
; #pragma unroll
;       for (int j = 0; j < 4; ++j) Cs[(wr * 64 + m * 16 + fq * 4 + j) * CST + wc * 32 + n * 16 + fr] = acc[AI][BJ][m][n][j];
;   lds_barrier();
; }
; template <int AI, int BJ, int PASS>
; DI void f3_proc(PREF p, const f32x4 (&acc)[2][2][4][2], int mt, int dt, float* Cs, const u32x4 (&g)[4]) {
;   const int t = tid512();
;   const int row0 = mt * 256 + AI * 128, col0 = dt * 256 + BJ * 128;
;   const int c = (t & 15) * 8;
;   stage_q<AI, BJ>(acc, Cs);
; #pragma unroll
;   for (int q = 0; q < 4; ++q) {
;     int r = (t >> 4) + 32 * q;
;     float v[8]; ld8(Cs + r * CST + c, v);
;     if (PASS == 0) {
; #pragma unroll
;       for (int j = 0; j < 8; ++j) v[j] = sigm(v[j]);
;     } else {
;       float gf[8]; unpack8(g[q], gf);
; #pragma unroll
;       for (int j = 0; j < 8; ++j) v[j] *= gf[j];
;     }
;     *(u32x4*)((u16*)p.fbuf + (size_t)(row0 + r) * 1024 + col0 + c) = pack8(v);
;   }
	v_mul_f32_e32 v0, 0xbfb8aa3b, v74
	v_exp_f32_e32 v0, v0
	v_ashrrev_i32_e32 v67, 31, v66
	v_lshlrev_b64 v[82:83], 11, v[66:67]
	v_cvt_pk_bf16_f32 v71, v69, v71
	v_add_f32_e32 v67, 1.0, v0
	v_lshl_add_u64 v[82:83], s[16:17], 0, v[82:83]
	v_lshlrev_b32_e32 v0, 1, v101
	v_lshl_add_u64 v[82:83], v[82:83], 0, v[0:1]
	global_store_dwordx4 v[82:83], v[70:73], off offset:256
	v_add_u32_e32 v82, 32, v66
	v_ashrrev_i32_e32 v83, 31, v82
	v_mul_f32_e32 v72, 0xbfb8aa3b, v75
	v_exp_f32_e32 v72, v72
	s_nop 0
	v_add_f32_e32 v70, 1.0, v72
	v_rcp_f32_e32 v67, v67
	v_mul_f32_e32 v74, 0xbfb8aa3b, v76
	v_exp_f32_e32 v74, v74
	s_nop 0
	v_add_f32_e32 v72, 1.0, v74
	v_mul_f32_e32 v73, 0xbfb8aa3b, v77
	v_rcp_f32_e32 v69, v70
	v_exp_f32_e32 v73, v73
	s_nop 0
	v_add_f32_e32 v73, 1.0, v73
	v_rcp_f32_e32 v71, v72
	s_waitcnt lgkmcnt(0)
	v_mul_f32_e32 v75, 0xbfb8aa3b, v78
	v_exp_f32_e32 v75, v75
	s_nop 0
	v_add_f32_e32 v74, 1.0, v75
	v_rcp_f32_e32 v72, v73
	v_mul_f32_e32 v76, 0xbfb8aa3b, v79
	v_exp_f32_e32 v76, v76
	s_nop 0
	v_add_f32_e32 v75, 1.0, v76
	v_rcp_f32_e32 v73, v74
	v_mul_f32_e32 v77, 0xbfb8aa3b, v80
	v_exp_f32_e32 v77, v77
	s_nop 0
	v_add_f32_e32 v76, 1.0, v77
	v_rcp_f32_e32 v78, v75
	v_mul_f32_e32 v75, 0xbfb8aa3b, v81
	v_exp_f32_e32 v75, v75
	s_nop 0
	v_add_f32_e32 v75, 1.0, v75
	v_rcp_f32_e32 v79, v76
	v_cvt_pk_bf16_f32 v71, v71, v72
	v_rcp_f32_e32 v80, v75
	ds_read_b128 v[74:77], v68 offset:33792
	v_cvt_pk_bf16_f32 v70, v67, v69
	v_cvt_pk_bf16_f32 v72, v73, v78
	v_cvt_pk_bf16_f32 v73, v79, v80
	ds_read_b128 v[78:81], v68 offset:33808
	s_waitcnt lgkmcnt(1)
	v_mul_f32_e32 v67, 0xbfb8aa3b, v74
	v_exp_f32_e32 v67, v67
	v_lshlrev_b64 v[82:83], 11, v[82:83]
	v_lshl_add_u64 v[82:83], s[16:17], 0, v[82:83]
	v_lshl_add_u64 v[82:83], v[82:83], 0, v[0:1]
	v_add_f32_e32 v67, 1.0, v67
	global_store_dwordx4 v[82:83], v[70:73], off offset:256
	s_nop 1
	v_mul_f32_e32 v72, 0xbfb8aa3b, v75
	v_exp_f32_e32 v72, v72
	s_nop 0
	v_add_f32_e32 v70, 1.0, v72
	v_rcp_f32_e32 v67, v67
	v_mul_f32_e32 v74, 0xbfb8aa3b, v76
	v_exp_f32_e32 v74, v74
	s_nop 0
	v_add_f32_e32 v72, 1.0, v74
	v_mul_f32_e32 v73, 0xbfb8aa3b, v77
	v_rcp_f32_e32 v69, v70
	v_exp_f32_e32 v73, v73
	s_nop 0
	v_add_f32_e32 v73, 1.0, v73
	v_rcp_f32_e32 v71, v72
	s_waitcnt lgkmcnt(0)
	v_mul_f32_e32 v75, 0xbfb8aa3b, v78
	v_exp_f32_e32 v75, v75
	s_nop 0
	v_add_f32_e32 v74, 1.0, v75
	v_rcp_f32_e32 v72, v73
	v_mul_f32_e32 v76, 0xbfb8aa3b, v79
	v_exp_f32_e32 v76, v76
	s_nop 0
	v_add_f32_e32 v75, 1.0, v76
	v_rcp_f32_e32 v73, v74
	v_mul_f32_e32 v77, 0xbfb8aa3b, v80
	v_exp_f32_e32 v77, v77
	s_nop 0
	v_add_f32_e32 v76, 1.0, v77
	v_rcp_f32_e32 v78, v75
	v_mul_f32_e32 v75, 0xbfb8aa3b, v81
	v_exp_f32_e32 v75, v75
	s_nop 0
	v_add_f32_e32 v75, 1.0, v75
	v_rcp_f32_e32 v79, v76
	v_cvt_pk_bf16_f32 v71, v71, v72
	v_rcp_f32_e32 v80, v75
	ds_read_b128 v[74:77], v68 offset:50688
	v_cvt_pk_bf16_f32 v70, v67, v69
	v_cvt_pk_bf16_f32 v72, v73, v78
	v_cvt_pk_bf16_f32 v73, v79, v80
	ds_read_b128 v[78:81], v68 offset:50704
	s_waitcnt lgkmcnt(1)
	v_mul_f32_e32 v67, 0xbfb8aa3b, v74
	v_exp_f32_e32 v67, v67
	v_add_u32_e32 v68, 64, v66
	v_ashrrev_i32_e32 v69, 31, v68
	v_lshlrev_b64 v[68:69], 11, v[68:69]
	v_add_f32_e32 v67, 1.0, v67
	v_lshl_add_u64 v[68:69], s[16:17], 0, v[68:69]
	v_lshl_add_u64 v[68:69], v[68:69], 0, v[0:1]
	global_store_dwordx4 v[68:69], v[70:73], off offset:256
	s_nop 1
	v_mul_f32_e32 v70, 0xbfb8aa3b, v75
	s_nop 0
	v_exp_f32_e32 v70, v70
	s_nop 0
	v_add_f32_e32 v70, 1.0, v70
	v_rcp_f32_e32 v67, v67
	v_mul_f32_e32 v73, 0xbfb8aa3b, v76
	v_exp_f32_e32 v73, v73
	s_nop 0
	v_add_f32_e32 v71, 1.0, v73
	v_mul_f32_e32 v72, 0xbfb8aa3b, v77
	v_exp_f32_e32 v72, v72
	v_rcp_f32_e32 v68, v70
	v_add_f32_e32 v72, 1.0, v72
	s_waitcnt lgkmcnt(0)
	v_mul_f32_e32 v74, 0xbfb8aa3b, v78
	v_exp_f32_e32 v74, v74
	v_rcp_f32_e32 v69, v71
	v_add_f32_e32 v73, 1.0, v74
	v_mul_f32_e32 v75, 0xbfb8aa3b, v79
	v_exp_f32_e32 v75, v75
	v_rcp_f32_e32 v70, v72
	v_add_f32_e32 v74, 1.0, v75
	v_mul_f32_e32 v76, 0xbfb8aa3b, v80
	v_exp_f32_e32 v76, v76
	v_rcp_f32_e32 v71, v73
	v_add_f32_e32 v75, 1.0, v76
	v_mul_f32_e32 v77, 0xbfb8aa3b, v81
	v_exp_f32_e32 v77, v77
	v_rcp_f32_e32 v72, v74
	v_add_f32_e32 v76, 1.0, v77
	v_rcp_f32_e32 v73, v75
	v_add_u32_e32 v66, 0x60, v66
	v_cvt_pk_bf16_f32 v68, v67, v68
	v_ashrrev_i32_e32 v67, 31, v66
	v_lshlrev_b64 v[66:67], 11, v[66:67]
	v_lshl_add_u64 v[66:67], s[16:17], 0, v[66:67]
	v_lshl_add_u64 v[66:67], v[66:67], 0, v[0:1]
	v_rcp_f32_e32 v74, v76
	v_cvt_pk_bf16_f32 v69, v69, v70
	v_cvt_pk_bf16_f32 v70, v71, v72
	v_cvt_pk_bf16_f32 v71, v73, v74
	global_store_dwordx4 v[66:67], v[68:71], off offset:256
	s_nop 1
	v_mov_b32_e32 v68, v168
	s_nop 0
	v_lshlrev_b32_e32 v0, 3, v68
	v_and_b32_e32 v69, 0x78, v0
	v_mov_b32_e32 v0, v168
	s_waitcnt lgkmcnt(0)
	s_barrier
	s_nop 0
	v_and_b32_e32 v66, 15, v0
	v_lshrrev_b32_e32 v67, 2, v0
	v_lshlrev_b32_e32 v0, 1, v0
	v_lshlrev_b32_e32 v66, 2, v66
	v_and_b32_e32 v67, 0xfffffcc, v67
	v_and_or_b32 v0, v0, s89, v66
	v_mad_u64_u32 v[66:67], s[0:1], v67, s92, v[0:1]
	v_add_u32_e32 v0, 0x400, v66
	ds_write2_b32 v66, v54, v62 offset1:16
	ds_write2_b32 v66, v55, v63 offset0:132 offset1:148
	ds_write2_b32 v0, v56, v64 offset0:8 offset1:24
	ds_write2_b32 v0, v57, v65 offset0:140 offset1:156
	v_add_u32_e32 v0, 0x2000, v66
	ds_write2_b32 v0, v50, v58 offset0:64 offset1:80
	ds_write2_b32 v0, v51, v59 offset0:196 offset1:212
	v_add_u32_e32 v0, 0x2400, v66
	ds_write2_b32 v0, v52, v60 offset0:72 offset1:88
	ds_write2_b32 v0, v53, v61 offset0:204 offset1:220
	v_add_u32_e32 v0, 0x4000, v66
	ds_write2_b32 v0, v42, v46 offset0:128 offset1:144
	v_add_u32_e32 v0, 0x4400, v66
	ds_write2_b32 v0, v43, v47 offset0:4 offset1:20
	ds_write2_b32 v0, v44, v48 offset0:136 offset1:152
	v_add_u32_e32 v0, 0x4800, v66
	ds_write2_b32 v0, v45, v49 offset0:12 offset1:28
	v_add_u32_e32 v0, 0x6000, v66
	ds_write2_b32 v0, v34, v38 offset0:192 offset1:208
	v_add_u32_e32 v0, 0x6400, v66
	ds_write2_b32 v0, v35, v39 offset0:68 offset1:84
	ds_write2_b32 v0, v36, v40 offset0:200 offset1:216
	v_add_u32_e32 v0, 0x6800, v66
	v_ashrrev_i32_e32 v36, 4, v68
	ds_write2_b32 v0, v37, v41 offset0:76 offset1:92
	v_mul_lo_u32 v0, v36, s92
	s_waitcnt lgkmcnt(0)
	s_barrier
; DI float sigm(float x) { return 1.f / (1.f + __expf(-x)); }
; DI u32x4 pack8(const float* f) { u32x4 o; o.x = pack2(f[0], f[1]); o.y = pack2(f[2], f[3]); o.z = pack2(f[4], f[5]); o.w = pack2(f[6], f[7]); return o; }
; DI void lds_barrier() { asm volatile("s_waitcnt lgkmcnt(0)\n\ts_barrier" ::: "memory"); }
; DI int tid512() { int t = threadIdx.x; asm volatile("" : "+v"(t)); return t; }
; template <int AI, int BJ>
; DI void stage_q(const f32x4 (&acc)[2][2][4][2], float* Cs) {
;   const int t = tid512(), wid = t >> 6, lane = t & 63, wr = wid >> 2, wc = wid & 3, fr = lane & 15, fq = lane >> 4;
;   lds_barrier();
; #pragma unroll
;   for (int m = 0; m < 4; ++m)
; #pragma unroll
;     for (int n = 0; n < 2; ++n)
; #pragma unroll
;       for (int j = 0; j < 4; ++j) Cs[(wr * 64 + m * 16 + fq * 4 + j) * CST + wc * 32 + n * 16 + fr] = acc[AI][BJ][m][n][j];
;   lds_barrier();
; }
; template <int AI, int BJ, int PASS>
; DI void f3_proc(PREF p, const f32x4 (&acc)[2][2][4][2], int mt, int dt, float* Cs, const u32x4 (&g)[4]) {
;   const int t = tid512();
;   const int row0 = mt * 256 + AI * 128, col0 = dt * 256 + BJ * 128;
;   const int c = (t & 15) * 8;
;   stage_q<AI, BJ>(acc, Cs);
; #pragma unroll
;   for (int q = 0; q < 4; ++q) {
;     int r = (t >> 4) + 32 * q;
;     float v[8]; ld8(Cs + r * CST + c, v);
;     if (PASS == 0) {
; #pragma unroll
;       for (int j = 0; j < 8; ++j) v[j] = sigm(v[j]);
;     } else {
;       float gf[8]; unpack8(g[q], gf);
; #pragma unroll
;       for (int j = 0; j < 8; ++j) v[j] *= gf[j];
;     }
;     *(u32x4*)((u16*)p.fbuf + (size_t)(row0 + r) * 1024 + col0 + c) = pack8(v);
;   }
	v_lshl_add_u32 v38, v69, 2, v0
	ds_read_b128 v[40:43], v38
	ds_read_b128 v[44:47], v38 offset:16
	v_add_u32_e32 v36, s25, v36
	s_waitcnt lgkmcnt(1)
	v_mul_f32_e32 v0, 0xbfb8aa3b, v40
	v_exp_f32_e32 v0, v0
	v_mul_f32_e32 v41, 0xbfb8aa3b, v41
	v_exp_f32_e32 v41, v41
	v_mul_f32_e32 v42, 0xbfb8aa3b, v42
	v_add_f32_e32 v37, 1.0, v0
	v_lshlrev_b32_e32 v0, 1, v69
	v_lshl_add_u64 v[34:35], s[16:17], 0, v[0:1]
	v_exp_f32_e32 v42, v42
	v_add_f32_e32 v39, 1.0, v41
	v_rcp_f32_e32 v0, v37
	v_mul_f32_e32 v43, 0xbfb8aa3b, v43
	v_add_f32_e32 v41, 1.0, v42
	v_rcp_f32_e32 v37, v39
	v_exp_f32_e32 v43, v43
	s_nop 0
	v_add_f32_e32 v42, 1.0, v43
	s_waitcnt lgkmcnt(0)
	v_mul_f32_e32 v44, 0xbfb8aa3b, v44
	v_exp_f32_e32 v44, v44
	v_rcp_f32_e32 v39, v41
	v_add_f32_e32 v43, 1.0, v44
	v_rcp_f32_e32 v49, v42
	v_mul_f32_e32 v42, 0xbfb8aa3b, v45
	v_exp_f32_e32 v42, v42
	s_nop 0
	v_add_f32_e32 v42, 1.0, v42
	v_rcp_f32_e32 v48, v43
	v_mul_f32_e32 v43, 0xbfb8aa3b, v46
	v_exp_f32_e32 v43, v43
	s_nop 0
	v_add_f32_e32 v43, 1.0, v43
	v_rcp_f32_e32 v50, v42
	v_mul_f32_e32 v42, 0xbfb8aa3b, v47
	v_exp_f32_e32 v42, v42
	s_nop 0
	v_add_f32_e32 v42, 1.0, v42
	v_rcp_f32_e32 v47, v43
	v_cvt_pk_bf16_f32 v46, v48, v50
	v_rcp_f32_e32 v52, v42
	ds_read_b128 v[40:43], v38 offset:16896
	v_cvt_pk_bf16_f32 v44, v0, v37
	v_cvt_pk_bf16_f32 v45, v39, v49
	ds_read_b128 v[48:51], v38 offset:16912
	v_ashrrev_i32_e32 v37, 31, v36
	s_waitcnt lgkmcnt(1)
	v_mul_f32_e32 v0, 0xbfb8aa3b, v40
	v_exp_f32_e32 v0, v0
	v_cvt_pk_bf16_f32 v47, v47, v52
	v_lshlrev_b64 v[52:53], 11, v[36:37]
	v_mul_f32_e32 v41, 0xbfb8aa3b, v41
	v_add_f32_e32 v0, 1.0, v0
	v_lshl_add_u64 v[52:53], v[34:35], 0, v[52:53]
	v_exp_f32_e32 v41, v41
	global_store_dwordx4 v[52:53], v[44:47], off
	v_add_f32_e32 v39, 1.0, v41
	v_rcp_f32_e32 v0, v0
	v_mul_f32_e32 v42, 0xbfb8aa3b, v42
	v_exp_f32_e32 v42, v42
	s_nop 0
	v_add_f32_e32 v41, 1.0, v42
	v_rcp_f32_e32 v37, v39
	v_mul_f32_e32 v43, 0xbfb8aa3b, v43
	v_exp_f32_e32 v43, v43
	s_nop 0
	v_add_f32_e32 v42, 1.0, v43
	s_waitcnt lgkmcnt(0)
	v_mul_f32_e32 v44, 0xbfb8aa3b, v48
	v_exp_f32_e32 v44, v44
	v_rcp_f32_e32 v39, v41
	v_add_f32_e32 v43, 1.0, v44
	v_rcp_f32_e32 v45, v42
	v_mul_f32_e32 v42, 0xbfb8aa3b, v49
	v_exp_f32_e32 v42, v42
	s_nop 0
	v_add_f32_e32 v42, 1.0, v42
	v_rcp_f32_e32 v46, v43
	v_mul_f32_e32 v43, 0xbfb8aa3b, v50
	v_exp_f32_e32 v43, v43
	s_nop 0
	v_add_f32_e32 v43, 1.0, v43
	v_rcp_f32_e32 v47, v42
	v_mul_f32_e32 v42, 0xbfb8aa3b, v51
	v_exp_f32_e32 v42, v42
	s_nop 0
	v_add_f32_e32 v42, 1.0, v42
	v_rcp_f32_e32 v52, v43
	v_cvt_pk_bf16_f32 v45, v39, v45
	v_rcp_f32_e32 v53, v42
	ds_read_b128 v[40:43], v38 offset:33792
	ds_read_b128 v[48:51], v38 offset:33808
	v_cvt_pk_bf16_f32 v44, v0, v37
	v_cvt_pk_bf16_f32 v46, v46, v47
	v_cvt_pk_bf16_f32 v47, v52, v53
	s_waitcnt lgkmcnt(1)
	v_mul_f32_e32 v0, 0xbfb8aa3b, v40
	v_exp_f32_e32 v0, v0
	v_add_u32_e32 v52, 32, v36
	v_ashrrev_i32_e32 v53, 31, v52
	v_lshlrev_b64 v[52:53], 11, v[52:53]
	v_add_f32_e32 v0, 1.0, v0
	v_mul_f32_e32 v41, 0xbfb8aa3b, v41
	v_lshl_add_u64 v[52:53], v[34:35], 0, v[52:53]
	v_exp_f32_e32 v41, v41
	global_store_dwordx4 v[52:53], v[44:47], off
	v_mul_f32_e32 v42, 0xbfb8aa3b, v42
	v_exp_f32_e32 v42, v42
	v_add_f32_e32 v40, 1.0, v41
	v_rcp_f32_e32 v0, v0
	v_mul_f32_e32 v43, 0xbfb8aa3b, v43
	v_add_f32_e32 v41, 1.0, v42
	v_exp_f32_e32 v43, v43
	v_rcp_f32_e32 v37, v40
	v_add_f32_e32 v42, 1.0, v43
	s_waitcnt lgkmcnt(0)
	v_mul_f32_e32 v44, 0xbfb8aa3b, v48
	v_exp_f32_e32 v44, v44
	v_rcp_f32_e32 v39, v41
	v_add_f32_e32 v43, 1.0, v44
	v_rcp_f32_e32 v45, v42
	v_mul_f32_e32 v42, 0xbfb8aa3b, v49
	v_exp_f32_e32 v42, v42
	s_nop 0
	v_add_f32_e32 v42, 1.0, v42
	v_rcp_f32_e32 v46, v43
	v_mul_f32_e32 v43, 0xbfb8aa3b, v50
	v_exp_f32_e32 v43, v43
	s_nop 0
	v_add_f32_e32 v43, 1.0, v43
	v_rcp_f32_e32 v47, v42
	v_mul_f32_e32 v42, 0xbfb8aa3b, v51
	v_exp_f32_e32 v42, v42
	s_nop 0
	v_add_f32_e32 v42, 1.0, v42
	v_rcp_f32_e32 v52, v43
	v_cvt_pk_bf16_f32 v45, v39, v45
	v_rcp_f32_e32 v53, v42
	ds_read_b128 v[40:43], v38 offset:50688
	ds_read_b128 v[48:51], v38 offset:50704
	v_cvt_pk_bf16_f32 v44, v0, v37
	v_add_u32_e32 v38, 64, v36
	v_ashrrev_i32_e32 v39, 31, v38
	s_waitcnt lgkmcnt(1)
	v_mul_f32_e32 v0, 0xbfb8aa3b, v40
	v_exp_f32_e32 v0, v0
	v_lshlrev_b64 v[38:39], 11, v[38:39]
	v_lshl_add_u64 v[38:39], v[34:35], 0, v[38:39]
	v_cvt_pk_bf16_f32 v46, v46, v47
	v_add_f32_e32 v0, 1.0, v0
	v_cvt_pk_bf16_f32 v47, v52, v53
	global_store_dwordx4 v[38:39], v[44:47], off
	v_mul_f32_e32 v41, 0xbfb8aa3b, v41
	v_exp_f32_e32 v41, v41
	s_nop 0
	v_add_f32_e32 v38, 1.0, v41
	v_mul_f32_e32 v40, 0xbfb8aa3b, v42
	v_rcp_f32_e32 v0, v0
	v_exp_f32_e32 v40, v40
	s_nop 0
	v_add_f32_e32 v40, 1.0, v40
	v_rcp_f32_e32 v37, v38
	v_mul_f32_e32 v43, 0xbfb8aa3b, v43
	v_exp_f32_e32 v43, v43
	s_nop 0
	v_add_f32_e32 v41, 1.0, v43
	s_waitcnt lgkmcnt(0)
	v_mul_f32_e32 v42, 0xbfb8aa3b, v48
	v_rcp_f32_e32 v39, v40
	v_exp_f32_e32 v42, v42
	s_nop 0
	v_add_f32_e32 v42, 1.0, v42
	v_rcp_f32_e32 v40, v41
	v_mul_f32_e32 v44, 0xbfb8aa3b, v49
	v_exp_f32_e32 v44, v44
	s_nop 0
	v_add_f32_e32 v43, 1.0, v44
	v_rcp_f32_e32 v41, v42
	v_mul_f32_e32 v45, 0xbfb8aa3b, v50
	v_exp_f32_e32 v45, v45
	s_nop 0
	v_add_f32_e32 v44, 1.0, v45
	v_rcp_f32_e32 v42, v43
	v_mul_f32_e32 v46, 0xbfb8aa3b, v51
	v_exp_f32_e32 v46, v46
	s_nop 0
	v_add_f32_e32 v45, 1.0, v46
	v_rcp_f32_e32 v43, v44
	v_add_u32_e32 v36, 0x60, v36
	v_rcp_f32_e32 v44, v45
	v_cvt_pk_bf16_f32 v38, v0, v37
	v_ashrrev_i32_e32 v37, 31, v36
	v_lshlrev_b64 v[36:37], 11, v[36:37]
	v_lshl_add_u64 v[34:35], v[34:35], 0, v[36:37]
	v_mov_b32_e32 v36, v168
	v_cvt_pk_bf16_f32 v39, v39, v40
	v_cvt_pk_bf16_f32 v40, v41, v42
	v_cvt_pk_bf16_f32 v41, v43, v44
	global_store_dwordx4 v[34:35], v[38:41], off
	s_nop 0
	v_lshlrev_b32_e32 v0, 3, v36
	v_and_b32_e32 v37, 0x78, v0
	v_mov_b32_e32 v0, v168
	s_waitcnt lgkmcnt(0)
	s_barrier
; DI float sigm(float x) { return 1.f / (1.f + __expf(-x)); }
; DI u32x4 pack8(const float* f) { u32x4 o; o.x = pack2(f[0], f[1]); o.y = pack2(f[2], f[3]); o.z = pack2(f[4], f[5]); o.w = pack2(f[6], f[7]); return o; }
; DI void lds_barrier() { asm volatile("s_waitcnt lgkmcnt(0)\n\ts_barrier" ::: "memory"); }
; DI int tid512() { int t = threadIdx.x; asm volatile("" : "+v"(t)); return t; }
; template <int AI, int BJ>
; DI void stage_q(const f32x4 (&acc)[2][2][4][2], float* Cs) {
;   const int t = tid512(), wid = t >> 6, lane = t & 63, wr = wid >> 2, wc = wid & 3, fr = lane & 15, fq = lane >> 4;
;   lds_barrier();
; #pragma unroll
;   for (int m = 0; m < 4; ++m)
; #pragma unroll
;     for (int n = 0; n < 2; ++n)
; #pragma unroll
;       for (int j = 0; j < 4; ++j) Cs[(wr * 64 + m * 16 + fq * 4 + j) * CST + wc * 32 + n * 16 + fr] = acc[AI][BJ][m][n][j];
;   lds_barrier();
; }
; template <int AI, int BJ, int PASS>
; DI void f3_proc(PREF p, const f32x4 (&acc)[2][2][4][2], int mt, int dt, float* Cs, const u32x4 (&g)[4]) {
;   const int t = tid512();
;   const int row0 = mt * 256 + AI * 128, col0 = dt * 256 + BJ * 128;
;   const int c = (t & 15) * 8;
;   stage_q<AI, BJ>(acc, Cs);
; #pragma unroll
;   for (int q = 0; q < 4; ++q) {
;     int r = (t >> 4) + 32 * q;
;     float v[8]; ld8(Cs + r * CST + c, v);
;     if (PASS == 0) {
; #pragma unroll
;       for (int j = 0; j < 8; ++j) v[j] = sigm(v[j]);
;     } else {
;       float gf[8]; unpack8(g[q], gf);
; #pragma unroll
;       for (int j = 0; j < 8; ++j) v[j] *= gf[j];
;     }
;     *(u32x4*)((u16*)p.fbuf + (size_t)(row0 + r) * 1024 + col0 + c) = pack8(v);
;   }
	s_nop 0
	v_and_b32_e32 v34, 15, v0
	v_lshrrev_b32_e32 v35, 2, v0
	v_lshlrev_b32_e32 v0, 1, v0
	v_lshlrev_b32_e32 v34, 2, v34
	v_and_b32_e32 v35, 0xfffffcc, v35
	v_and_or_b32 v0, v0, s89, v34
	v_mad_u64_u32 v[34:35], s[0:1], v35, s92, v[0:1]
	v_add_u32_e32 v0, 0x400, v34
	ds_write2_b32 v34, v22, v30 offset1:16
	ds_write2_b32 v34, v23, v31 offset0:132 offset1:148
	ds_write2_b32 v0, v24, v32 offset0:8 offset1:24
	ds_write2_b32 v0, v25, v33 offset0:140 offset1:156
	v_add_u32_e32 v0, 0x2000, v34
	ds_write2_b32 v0, v18, v26 offset0:64 offset1:80
	ds_write2_b32 v0, v19, v27 offset0:196 offset1:212
	v_add_u32_e32 v0, 0x2400, v34
	ds_write2_b32 v0, v20, v28 offset0:72 offset1:88
	ds_write2_b32 v0, v21, v29 offset0:204 offset1:220
	v_add_u32_e32 v0, 0x4000, v34
	ds_write2_b32 v0, v10, v14 offset0:128 offset1:144
	v_add_u32_e32 v0, 0x4400, v34
	ds_write2_b32 v0, v11, v15 offset0:4 offset1:20
	ds_write2_b32 v0, v12, v16 offset0:136 offset1:152
	v_add_u32_e32 v0, 0x4800, v34
	ds_write2_b32 v0, v13, v17 offset0:12 offset1:28
	v_add_u32_e32 v0, 0x6000, v34
	ds_write2_b32 v0, v2, v6 offset0:192 offset1:208
	v_add_u32_e32 v0, 0x6400, v34
	ds_write2_b32 v0, v3, v7 offset0:68 offset1:84
	ds_write2_b32 v0, v4, v8 offset0:200 offset1:216
	v_add_u32_e32 v0, 0x6800, v34
	ds_write2_b32 v0, v5, v9 offset0:76 offset1:92
	v_ashrrev_i32_e32 v0, 4, v36
	v_mul_lo_u32 v2, v0, s92
	s_waitcnt lgkmcnt(0)
	s_barrier
	v_lshl_add_u32 v4, v37, 2, v2
	ds_read_b128 v[6:9], v4
	ds_read_b128 v[10:13], v4 offset:16
	s_waitcnt lgkmcnt(1)
	v_mul_f32_e32 v2, 0xbfb8aa3b, v6
	v_exp_f32_e32 v2, v2
	v_mul_f32_e32 v7, 0xbfb8aa3b, v7
	v_exp_f32_e32 v7, v7
	v_mul_f32_e32 v8, 0xbfb8aa3b, v8
	v_add_f32_e32 v2, 1.0, v2
	v_exp_f32_e32 v8, v8
	v_mul_f32_e32 v9, 0xbfb8aa3b, v9
	v_exp_f32_e32 v9, v9
	v_add_f32_e32 v6, 1.0, v7
	v_rcp_f32_e32 v2, v2
	s_waitcnt lgkmcnt(0)
	v_mul_f32_e32 v10, 0xbfb8aa3b, v10
	v_add_f32_e32 v7, 1.0, v8
	v_rcp_f32_e32 v3, v6
	v_exp_f32_e32 v10, v10
	v_add_f32_e32 v8, 1.0, v9
	v_rcp_f32_e32 v5, v7
	v_mul_f32_e32 v11, 0xbfb8aa3b, v11
	v_add_f32_e32 v9, 1.0, v10
	v_rcp_f32_e32 v7, v8
	v_exp_f32_e32 v11, v11
	s_nop 0
	v_add_f32_e32 v10, 1.0, v11
	v_rcp_f32_e32 v8, v9
	v_mul_f32_e32 v12, 0xbfb8aa3b, v12
	v_exp_f32_e32 v12, v12
	s_nop 0
	v_add_f32_e32 v11, 1.0, v12
	v_rcp_f32_e32 v9, v10
	v_mul_f32_e32 v13, 0xbfb8aa3b, v13
	v_exp_f32_e32 v13, v13
	s_nop 0
	v_add_f32_e32 v12, 1.0, v13
	v_rcp_f32_e32 v14, v11
	v_cvt_pk_bf16_f32 v8, v8, v9
	v_rcp_f32_e32 v15, v12
	ds_read_b128 v[10:13], v4 offset:16896
	v_cvt_pk_bf16_f32 v6, v2, v3
	v_cvt_pk_bf16_f32 v9, v14, v15
	v_add_u32_e32 v2, s25, v0
	ds_read_b128 v[14:17], v4 offset:16912
	s_waitcnt lgkmcnt(1)
	v_mul_f32_e32 v0, 0xbfb8aa3b, v10
	v_exp_f32_e32 v0, v0
	v_ashrrev_i32_e32 v3, 31, v2
	v_lshlrev_b64 v[18:19], 11, v[2:3]
	v_cvt_pk_bf16_f32 v7, v5, v7
	v_add_f32_e32 v3, 1.0, v0
	v_lshl_add_u64 v[18:19], s[16:17], 0, v[18:19]
	v_lshlrev_b32_e32 v0, 1, v37
	v_lshl_add_u64 v[18:19], v[18:19], 0, v[0:1]
	global_store_dwordx4 v[18:19], v[6:9], off offset:256
	v_add_u32_e32 v18, 32, v2
	v_ashrrev_i32_e32 v19, 31, v18
	v_mul_f32_e32 v8, 0xbfb8aa3b, v11
	v_exp_f32_e32 v8, v8
	s_nop 0
	v_add_f32_e32 v6, 1.0, v8
	v_rcp_f32_e32 v3, v3
	v_mul_f32_e32 v10, 0xbfb8aa3b, v12
	v_exp_f32_e32 v10, v10
	s_nop 0
	v_add_f32_e32 v8, 1.0, v10
	v_mul_f32_e32 v9, 0xbfb8aa3b, v13
	v_rcp_f32_e32 v5, v6
	v_exp_f32_e32 v9, v9
	s_nop 0
	v_add_f32_e32 v9, 1.0, v9
	v_rcp_f32_e32 v7, v8
	s_waitcnt lgkmcnt(0)
	v_mul_f32_e32 v11, 0xbfb8aa3b, v14
	v_exp_f32_e32 v11, v11
	s_nop 0
	v_add_f32_e32 v10, 1.0, v11
	v_rcp_f32_e32 v8, v9
	v_mul_f32_e32 v12, 0xbfb8aa3b, v15
	v_exp_f32_e32 v12, v12
	s_nop 0
	v_add_f32_e32 v11, 1.0, v12
	v_rcp_f32_e32 v9, v10
	v_mul_f32_e32 v13, 0xbfb8aa3b, v16
	v_exp_f32_e32 v13, v13
	s_nop 0
	v_add_f32_e32 v12, 1.0, v13
	v_rcp_f32_e32 v14, v11
	v_mul_f32_e32 v11, 0xbfb8aa3b, v17
	v_exp_f32_e32 v11, v11
	s_nop 0
	v_add_f32_e32 v11, 1.0, v11
	v_rcp_f32_e32 v15, v12
	v_cvt_pk_bf16_f32 v7, v7, v8
	v_rcp_f32_e32 v16, v11
	ds_read_b128 v[10:13], v4 offset:33792
	v_cvt_pk_bf16_f32 v6, v3, v5
	v_cvt_pk_bf16_f32 v8, v9, v14
	v_cvt_pk_bf16_f32 v9, v15, v16
	ds_read_b128 v[14:17], v4 offset:33808
	s_waitcnt lgkmcnt(1)
	v_mul_f32_e32 v3, 0xbfb8aa3b, v10
	v_exp_f32_e32 v3, v3
	v_lshlrev_b64 v[18:19], 11, v[18:19]
	v_lshl_add_u64 v[18:19], s[16:17], 0, v[18:19]
	v_lshl_add_u64 v[18:19], v[18:19], 0, v[0:1]
	v_add_f32_e32 v3, 1.0, v3
	global_store_dwordx4 v[18:19], v[6:9], off offset:256
	s_nop 1
	v_mul_f32_e32 v8, 0xbfb8aa3b, v11
	v_exp_f32_e32 v8, v8
	s_nop 0
	v_add_f32_e32 v6, 1.0, v8
	v_rcp_f32_e32 v3, v3
	v_mul_f32_e32 v10, 0xbfb8aa3b, v12
	v_exp_f32_e32 v10, v10
	s_nop 0
	v_add_f32_e32 v8, 1.0, v10
	v_mul_f32_e32 v9, 0xbfb8aa3b, v13
	v_rcp_f32_e32 v5, v6
	v_exp_f32_e32 v9, v9
	s_nop 0
	v_add_f32_e32 v9, 1.0, v9
	v_rcp_f32_e32 v7, v8
	s_waitcnt lgkmcnt(0)
	v_mul_f32_e32 v11, 0xbfb8aa3b, v14
	v_exp_f32_e32 v11, v11
	s_nop 0
	v_add_f32_e32 v10, 1.0, v11
	v_rcp_f32_e32 v8, v9
	v_mul_f32_e32 v12, 0xbfb8aa3b, v15
	v_exp_f32_e32 v12, v12
	s_nop 0
	v_add_f32_e32 v11, 1.0, v12
	v_rcp_f32_e32 v9, v10
	v_mul_f32_e32 v13, 0xbfb8aa3b, v16
	v_exp_f32_e32 v13, v13
	s_nop 0
	v_add_f32_e32 v12, 1.0, v13
	v_rcp_f32_e32 v14, v11
	v_mul_f32_e32 v11, 0xbfb8aa3b, v17
	v_exp_f32_e32 v11, v11
	s_nop 0
	v_add_f32_e32 v11, 1.0, v11
	v_rcp_f32_e32 v15, v12
	v_cvt_pk_bf16_f32 v7, v7, v8
	v_rcp_f32_e32 v16, v11
	ds_read_b128 v[10:13], v4 offset:50688
	v_cvt_pk_bf16_f32 v6, v3, v5
	v_cvt_pk_bf16_f32 v8, v9, v14
	v_cvt_pk_bf16_f32 v9, v15, v16
	ds_read_b128 v[14:17], v4 offset:50704
	s_waitcnt lgkmcnt(1)
; DI float sigm(float x) { return 1.f / (1.f + __expf(-x)); }
; DI u32x4 pack8(const float* f) { u32x4 o; o.x = pack2(f[0], f[1]); o.y = pack2(f[2], f[3]); o.z = pack2(f[4], f[5]); o.w = pack2(f[6], f[7]); return o; }
; DI void lds_barrier() { asm volatile("s_waitcnt lgkmcnt(0)\n\ts_barrier" ::: "memory"); }
; DI int tid512() { int t = threadIdx.x; asm volatile("" : "+v"(t)); return t; }
; #define G_WAIT_V(n) asm volatile("s_waitcnt vmcnt(" #n ")" ::: "memory")
; #define G_BAR __builtin_amdgcn_s_barrier()
;     ...
;   const int t = tid512();
;   const int wid = t >> 6, lane = t & 63, wr = wid >> 2, wc = wid & 3, fr = lane & 15, fq = lane >> 4;
;   int r0, c0, r1, c1;
;   g_stage_rc(t * 16, r0, c0); g_stage_rc(t * 16 + 8192, r1, c1);
;   const int oa0 = r0 * LDA + c0, oa1 = r1 * LDA + c1, ob0 = r0 * LDB + c0, ob1 = r1 * LDB + c1;
;   const int obr = fr * 64 + fq * 16, rdo = obr ^ (((obr >> 9) & 1) << 5);
;   bf16x8 At[4][2], B0[2][2], B1[2][2];
;   constexpr int nt = K / 64;
;   lds_barrier();
;   G_STAGE(G_SB(0, 0), B, ob0, ob1, LDB, 0, KB(0)); G_STAGE(G_SA(0, 0), A, oa0, oa1, LDA, 0, KA(0));
;   G_STAGE(G_SB(0, 1), B, ob0, ob1, LDB, 128, KB(0)); G_STAGE(G_SA(0, 1), A, oa0, oa1, LDA, 128, KA(0));
;   if (wr == 1) G_BAR;
;   G_WAIT_V(4); G_BAR;
;   G_STAGE(G_SB(1, 0), B, ob0, ob1, LDB, 0, KB(1)); G_STAGE(G_SA(1, 0), A, oa0, oa1, LDA, 0, KA(1)); G_STAGE(G_SB(1, 1), B, ob0, ob1, LDB, 128, KB(1));
;   G_WAIT_V(6); G_BAR;
; template <int AI, int BJ, int PASS>
; DI void f3_proc(PREF p, const f32x4 (&acc)[2][2][4][2], int mt, int dt, float* Cs, const u32x4 (&g)[4]) {
;   const int t = tid512();
;   const int row0 = mt * 256 + AI * 128, col0 = dt * 256 + BJ * 128;
;   const int c = (t & 15) * 8;
;   stage_q<AI, BJ>(acc, Cs);
; #pragma unroll
;   for (int q = 0; q < 4; ++q) {
;     int r = (t >> 4) + 32 * q;
;     float v[8]; ld8(Cs + r * CST + c, v);
;     if (PASS == 0) {
; #pragma unroll
;       for (int j = 0; j < 8; ++j) v[j] = sigm(v[j]);
;     } else {
;       float gf[8]; unpack8(g[q], gf);
; #pragma unroll
;       for (int j = 0; j < 8; ++j) v[j] *= gf[j];
;     }
;     *(u32x4*)((u16*)p.fbuf + (size_t)(row0 + r) * 1024 + col0 + c) = pack8(v);
;   }
	v_mul_f32_e32 v3, 0xbfb8aa3b, v10
	v_exp_f32_e32 v3, v3
	v_add_u32_e32 v4, 64, v2
	v_ashrrev_i32_e32 v5, 31, v4
	v_lshlrev_b64 v[4:5], 11, v[4:5]
	v_add_f32_e32 v3, 1.0, v3
	v_lshl_add_u64 v[4:5], s[16:17], 0, v[4:5]
	v_lshl_add_u64 v[4:5], v[4:5], 0, v[0:1]
	global_store_dwordx4 v[4:5], v[6:9], off offset:256
	s_nop 1
	v_mul_f32_e32 v6, 0xbfb8aa3b, v11
	s_nop 0
	v_exp_f32_e32 v6, v6
	s_nop 0
	v_add_f32_e32 v6, 1.0, v6
	v_rcp_f32_e32 v3, v3
	v_mul_f32_e32 v9, 0xbfb8aa3b, v12
	v_exp_f32_e32 v9, v9
	s_nop 0
	v_add_f32_e32 v7, 1.0, v9
	v_mul_f32_e32 v8, 0xbfb8aa3b, v13
	v_exp_f32_e32 v8, v8
	v_rcp_f32_e32 v4, v6
	v_add_f32_e32 v8, 1.0, v8
	s_waitcnt lgkmcnt(0)
	v_mul_f32_e32 v10, 0xbfb8aa3b, v14
	v_exp_f32_e32 v10, v10
	v_rcp_f32_e32 v5, v7
	v_add_f32_e32 v9, 1.0, v10
	v_mul_f32_e32 v11, 0xbfb8aa3b, v15
	v_exp_f32_e32 v11, v11
	v_rcp_f32_e32 v6, v8
	v_add_f32_e32 v10, 1.0, v11
	v_mul_f32_e32 v12, 0xbfb8aa3b, v16
	v_exp_f32_e32 v12, v12
	v_rcp_f32_e32 v7, v9
	v_add_f32_e32 v11, 1.0, v12
	v_mul_f32_e32 v13, 0xbfb8aa3b, v17
	v_exp_f32_e32 v13, v13
	v_rcp_f32_e32 v8, v10
	v_add_f32_e32 v12, 1.0, v13
	v_rcp_f32_e32 v9, v11
	v_add_u32_e32 v2, 0x60, v2
	v_cvt_pk_bf16_f32 v4, v3, v4
	v_ashrrev_i32_e32 v3, 31, v2
	v_lshlrev_b64 v[2:3], 11, v[2:3]
	v_lshl_add_u64 v[2:3], s[16:17], 0, v[2:3]
	v_lshl_add_u64 v[2:3], v[2:3], 0, v[0:1]
	s_lshl_b32 s0, s35, 17
	v_mov_b32_e32 v0, v168
	v_rcp_f32_e32 v10, v12
	v_cvt_pk_bf16_f32 v5, v5, v6
	v_cvt_pk_bf16_f32 v6, v7, v8
	v_cvt_pk_bf16_f32 v7, v9, v10
	global_store_dwordx4 v[2:3], v[4:7], off offset:256
	s_add_u32 s20, s10, s0
	s_addc_u32 s21, s11, 0
	v_lshlrev_b32_e32 v18, 4, v0
	s_nop 0
	v_readfirstlane_b32 s32, v18
	v_and_b32_e32 v2, 32, v0
	s_lshl_b64 s[0:1], s[18:19], 17
	v_bitop3_b32 v2, v18, v2, 48 bitop3:0x6c
	s_add_u32 s18, s30, s0
	v_lshrrev_b32_e32 v3, 3, v0
	v_bfe_u32 v4, v0, 2, 4
	s_mov_b32 s0, 0xfffff0
	v_lshrrev_b32_e32 v5, 1, v0
	v_lshrrev_b32_e32 v2, 1, v2
	v_add_u32_e32 v19, 0x2000, v18
	v_and_or_b32 v3, v3, s0, v4
	v_and_or_b32 v5, v5, 32, v2
	v_lshrrev_b32_e32 v2, 7, v19
	v_and_or_b32 v4, v2, s0, v4
	v_lshl_or_b32 v2, v3, 8, v5
	v_lshl_or_b32 v4, v4, 8, v5
	v_ashrrev_i32_e32 v3, 31, v2
	s_addc_u32 s19, s31, s1
	v_lshlrev_b64 v[2:3], 1, v[2:3]
	v_ashrrev_i32_e32 v5, 31, v4
	s_waitcnt lgkmcnt(0)
	s_barrier
	v_lshl_add_u64 v[6:7], s[18:19], 0, v[2:3]
	s_add_u32 m0, s32, 0x10000
	v_lshlrev_b64 v[4:5], 1, v[4:5]
	global_load_lds_dwordx4 v[6:7], off
	v_lshl_add_u64 v[8:9], s[18:19], 0, v[4:5]
	s_add_u32 m0, s32, 0x12000
	s_nop 0
	global_load_lds_dwordx4 v[8:9], off
	v_lshl_add_u64 v[10:11], s[20:21], 0, v[2:3]
	s_mov_b32 m0, s32
	s_nop 0
	global_load_lds_dwordx4 v[10:11], off
	s_add_u32 m0, s32, 0x2000
	s_add_u32 s0, s18, 0x10000
	v_lshl_add_u64 v[14:15], s[20:21], 0, v[4:5]
	s_addc_u32 s1, s19, 0
	global_load_lds_dwordx4 v[14:15], off
	v_lshl_add_u64 v[12:13], s[0:1], 0, v[2:3]
	s_add_u32 m0, s32, 0x14000
	s_nop 0
	global_load_lds_dwordx4 v[12:13], off
	v_lshl_add_u64 v[12:13], s[0:1], 0, v[4:5]
	s_add_u32 m0, s32, 0x16000
	s_add_u32 s0, s20, 0x10000
	v_add_u32_e32 v16, 0x4000, v18
	s_addc_u32 s1, s21, 0
	global_load_lds_dwordx4 v[12:13], off
	v_lshl_add_u64 v[12:13], s[0:1], 0, v[2:3]
	s_add_u32 m0, s32, 0x4000
	v_add_u32_e32 v17, 0x6000, v18
	global_load_lds_dwordx4 v[12:13], off
	v_lshl_add_u64 v[12:13], s[0:1], 0, v[4:5]
	v_readfirstlane_b32 s0, v17
	s_add_u32 m0, s32, 0x6000
	s_nop 0
	global_load_lds_dwordx4 v[12:13], off
	v_ashrrev_i32_e32 v12, 8, v0
	v_cmp_eq_u32_e32 vcc, 1, v12
	s_and_saveexec_b64 s[22:23], vcc
	s_cbranch_execz .LBB0_45
	s_barrier
.LBB0_45:
	s_or_b64 exec, exec, s[22:23]
	v_add_u32_e32 v13, 0x18000, v18
	v_lshl_add_u64 v[24:25], v[6:7], 0, s[76:77]
	v_readfirstlane_b32 s37, v13
	v_add_u32_e32 v13, 0x1a000, v18
	s_mov_b32 m0, s37
	v_readfirstlane_b32 s40, v13
	v_add_u32_e32 v13, 0x8000, v18
	s_waitcnt vmcnt(4)
	s_barrier
	global_load_lds_dwordx4 v[24:25], off
	v_lshl_add_u64 v[24:25], v[8:9], 0, s[76:77]
	s_mov_b32 m0, s40
	v_readfirstlane_b32 s35, v13
	v_add_u32_e32 v13, 0xa000, v18
	global_load_lds_dwordx4 v[24:25], off
	v_lshl_add_u64 v[24:25], v[10:11], 0, s[76:77]
	s_mov_b32 m0, s35
	v_readfirstlane_b32 s36, v13
	s_add_u32 s0, s18, 0x10080
	v_add_u32_e32 v13, 0x1c000, v18
	global_load_lds_dwordx4 v[24:25], off
	v_lshl_add_u64 v[24:25], v[14:15], 0, s[76:77]
	s_mov_b32 m0, s36
	s_addc_u32 s1, s19, 0
	v_readfirstlane_b32 s22, v13
	v_add_u32_e32 v13, 0x1e000, v18
	global_load_lds_dwordx4 v[24:25], off
	v_lshl_add_u64 v[24:25], s[0:1], 0, v[2:3]
	s_mov_b32 m0, s22
	v_readfirstlane_b32 s23, v13
	global_load_lds_dwordx4 v[24:25], off
	v_lshl_add_u64 v[24:25], s[0:1], 0, v[4:5]
	s_mov_b32 m0, s23
	v_lshlrev_b32_e32 v26, 2, v0
	global_load_lds_dwordx4 v[24:25], off
	v_lshlrev_b32_e32 v24, 6, v0
	v_and_b32_e32 v13, 48, v0
	v_and_b32_e32 v25, 0x3c0, v24
	v_and_b32_e32 v41, 32, v26
	v_or_b32_e32 v40, v25, v13
	v_bitop3_b32 v13, v25, v41, v13 bitop3:0x36
	s_movk_i32 s0, 0x3000
	v_and_or_b32 v162, v24, s0, v13
	s_add_u32 s0, s20, 0x10080
	s_addc_u32 s1, s21, 0
	v_lshl_add_u64 v[72:73], s[0:1], 0, v[2:3]
	v_lshl_add_u64 v[74:75], s[0:1], 0, v[4:5]
	s_add_u32 s0, s18, 0x10100
	s_addc_u32 s1, s19, 0
	v_or_b32_e32 v230, 0x10000, v162
	v_or_b32_e32 v232, 0x10800, v162
	s_waitcnt vmcnt(6)
	s_barrier
; #define G_LDA(dst, b, h)                                                                                                  \
;   _Pragma("unroll") for (int m = 0; m < 4; ++m) _Pragma("unroll") for (int k = 0; k < 2; ++k)                             \
;       dst[m][k] = *(const bf16x8*)((const char*)G_SA(b, h) + ((wr * 4 + m) * 2 + k) * 1024 + rdo)
; #define G_LDB(dst, b, h)                                                                                                  \
;   _Pragma("unroll") for (int n = 0; n < 2; ++n) _Pragma("unroll") for (int k = 0; k < 2; ++k)                             \
;       dst[n][k] = *(const bf16x8*)((const char*)G_SB(b, h) + ((wc * 2 + n) * 2 + k) * 1024 + rdo)
; #define G_WAIT_L(n) asm volatile("s_waitcnt lgkmcnt(" #n ")" ::: "memory")
; #define G_BAR __builtin_amdgcn_s_barrier()
; #define G_SCHED __builtin_amdgcn_sched_barrier(0)
;     ...
;   for (int tt = 0; tt < nt - 2; tt += 2) {
;     G_LDB(B0, 0, 0); G_SCHED; G_LDA(At, 0, 0); G_STAGE(G_SA(1, 1), A, oa0, oa1, LDA, 128, KA(tt + 1));
;     G_WAIT_L(8); G_BAR; G_WAIT_L(0); G_MMA(0, 0, At, B0); G_BAR; G_SCHED;
;     G_LDB(B1, 0, 1); G_STAGE(G_SB(0, 0), B, ob0, ob1, LDB, 0, KB(tt + 2));
;     G_BAR; G_WAIT_L(0); G_MMA(0, 1, At, B1); G_BAR;
;     G_LDA(At, 0, 1); G_STAGE(G_SA(0, 0), A, oa0, oa1, LDA, 0, KA(tt + 2));
;     G_BAR; G_WAIT_L(0); G_MMA(1, 0, At, B0); G_BAR; G_SCHED;
	v_lshl_add_u64 v[160:161], s[0:1], 0, v[2:3]
	v_lshl_add_u64 v[194:195], s[0:1], 0, v[4:5]
	s_add_u32 s0, s20, 0x10100
	v_or_b32_e32 v231, 0x10400, v162
	ds_read_b128 v[24:27], v230
	ds_read_b128 v[28:31], v231
	v_or_b32_e32 v233, 0x10c00, v162
	ds_read_b128 v[32:35], v232
	ds_read_b128 v[36:39], v233
	s_addc_u32 s1, s21, 0
	v_lshl_add_u64 v[214:215], s[0:1], 0, v[2:3]
	v_lshl_add_u64 v[216:217], s[0:1], 0, v[4:5]
	s_add_u32 s0, s18, 0x10180
	s_addc_u32 s1, s19, 0
	v_lshlrev_b32_e32 v42, 13, v12
	v_lshl_add_u64 v[120:121], v[6:7], 0, s[82:83]
	v_lshl_add_u64 v[122:123], v[8:9], 0, s[82:83]
	v_lshl_add_u64 v[152:153], v[10:11], 0, s[82:83]
	v_lshl_add_u64 v[226:227], v[6:7], 0, s[90:91]
	v_lshl_add_u64 v[228:229], v[8:9], 0, s[90:91]
	v_lshl_add_u64 v[12:13], v[10:11], 0, s[90:91]
	v_lshl_add_u64 v[10:11], v[14:15], 0, s[90:91]
	v_lshl_add_u64 v[8:9], s[0:1], 0, v[2:3]
	v_lshl_add_u64 v[6:7], s[0:1], 0, v[4:5]
	v_lshl_add_u64 v[154:155], v[14:15], 0, s[82:83]
	v_add_u32_e32 v14, 0xc000, v18
	v_bitop3_b32 v242, v40, v42, v41 bitop3:0xde
	v_readfirstlane_b32 s19, v14
	v_add_u32_e32 v14, 0xe000, v18
	s_mov_b32 m0, s19
	v_readfirstlane_b32 s18, v14
	ds_read_b128 v[40:43], v242
	ds_read_b128 v[44:47], v242 offset:1024
	ds_read_b128 v[48:51], v242 offset:2048
	ds_read_b128 v[52:55], v242 offset:3072
	ds_read_b128 v[56:59], v242 offset:4096
	ds_read_b128 v[60:63], v242 offset:5120
	ds_read_b128 v[64:67], v242 offset:6144
	ds_read_b128 v[68:71], v242 offset:7168
	global_load_lds_dwordx4 v[72:73], off
	s_mov_b32 m0, s18
	s_nop 0
	global_load_lds_dwordx4 v[74:75], off
	s_waitcnt lgkmcnt(8)
	s_barrier
	s_waitcnt lgkmcnt(0)
	v_mfma_f32_16x16x32_bf16 v[72:75], v[40:43], v[24:27], 0
	v_mfma_f32_16x16x32_bf16 v[76:79], v[40:43], v[32:35], 0
	v_mfma_f32_16x16x32_bf16 v[80:83], v[48:51], v[24:27], 0
	v_mfma_f32_16x16x32_bf16 v[84:87], v[48:51], v[32:35], 0
	v_mfma_f32_16x16x32_bf16 v[88:91], v[56:59], v[24:27], 0
	v_mfma_f32_16x16x32_bf16 v[92:95], v[56:59], v[32:35], 0
	v_mfma_f32_16x16x32_bf16 v[96:99], v[64:67], v[24:27], 0
	v_mfma_f32_16x16x32_bf16 v[100:103], v[64:67], v[32:35], 0
	v_mfma_f32_16x16x32_bf16 v[72:75], v[44:47], v[28:31], v[72:75]
	v_mfma_f32_16x16x32_bf16 v[76:79], v[44:47], v[36:39], v[76:79]
	v_mfma_f32_16x16x32_bf16 v[80:83], v[52:55], v[28:31], v[80:83]
	v_mfma_f32_16x16x32_bf16 v[84:87], v[52:55], v[36:39], v[84:87]
	v_mfma_f32_16x16x32_bf16 v[88:91], v[60:63], v[28:31], v[88:91]
	v_mfma_f32_16x16x32_bf16 v[92:95], v[60:63], v[36:39], v[92:95]
	v_mfma_f32_16x16x32_bf16 v[96:99], v[68:71], v[28:31], v[96:99]
	v_mfma_f32_16x16x32_bf16 v[100:103], v[68:71], v[36:39], v[100:103]
	s_barrier
	v_or_b32_e32 v234, 0x14000, v162
	v_or_b32_e32 v236, 0x14800, v162
	s_add_u32 m0, s32, 0x10000
	v_or_b32_e32 v235, 0x14400, v162
	ds_read_b128 v[104:107], v234
	ds_read_b128 v[108:111], v235
	v_or_b32_e32 v237, 0x14c00, v162
	ds_read_b128 v[112:115], v236
	ds_read_b128 v[116:119], v237
	global_load_lds_dwordx4 v[120:121], off
	s_add_u32 m0, s32, 0x12000
	s_nop 0
	global_load_lds_dwordx4 v[122:123], off
	s_barrier
	s_waitcnt lgkmcnt(0)
	v_mfma_f32_16x16x32_bf16 v[120:123], v[40:43], v[104:107], 0
	v_mfma_f32_16x16x32_bf16 v[40:43], v[40:43], v[112:115], 0
	v_mfma_f32_16x16x32_bf16 v[120:123], v[44:47], v[108:111], v[120:123]
	v_mfma_f32_16x16x32_bf16 v[40:43], v[44:47], v[116:119], v[40:43]
	v_mfma_f32_16x16x32_bf16 v[44:47], v[48:51], v[104:107], 0
	v_mfma_f32_16x16x32_bf16 v[48:51], v[48:51], v[112:115], 0
	v_mfma_f32_16x16x32_bf16 v[44:47], v[52:55], v[108:111], v[44:47]
	v_mfma_f32_16x16x32_bf16 v[48:51], v[52:55], v[116:119], v[48:51]
	v_mfma_f32_16x16x32_bf16 v[52:55], v[56:59], v[104:107], 0
	v_mfma_f32_16x16x32_bf16 v[56:59], v[56:59], v[112:115], 0
	v_mfma_f32_16x16x32_bf16 v[52:55], v[60:63], v[108:111], v[52:55]
	v_mfma_f32_16x16x32_bf16 v[56:59], v[60:63], v[116:119], v[56:59]
	v_mfma_f32_16x16x32_bf16 v[60:63], v[64:67], v[104:107], 0
	v_mfma_f32_16x16x32_bf16 v[64:67], v[64:67], v[112:115], 0
	v_mfma_f32_16x16x32_bf16 v[60:63], v[68:71], v[108:111], v[60:63]
	v_mfma_f32_16x16x32_bf16 v[64:67], v[68:71], v[116:119], v[64:67]
	s_mov_b32 m0, s32
	s_barrier
	ds_read_b128 v[68:71], v242 offset:16384
	ds_read_b128 v[124:127], v242 offset:17408
	ds_read_b128 v[128:131], v242 offset:18432
	ds_read_b128 v[132:135], v242 offset:19456
	ds_read_b128 v[136:139], v242 offset:20480
	ds_read_b128 v[140:143], v242 offset:21504
	ds_read_b128 v[144:147], v242 offset:22528
	ds_read_b128 v[148:151], v242 offset:23552
	global_load_lds_dwordx4 v[152:153], off
	s_add_u32 m0, s32, 0x2000
	s_nop 0
	global_load_lds_dwordx4 v[154:155], off
	s_barrier
	s_waitcnt lgkmcnt(0)
	v_mfma_f32_16x16x32_bf16 v[152:155], v[68:71], v[24:27], 0
	v_mfma_f32_16x16x32_bf16 v[164:167], v[128:131], v[24:27], 0
	v_mfma_f32_16x16x32_bf16 v[186:189], v[136:139], v[24:27], 0
	v_mfma_f32_16x16x32_bf16 v[22:25], v[144:147], v[24:27], 0
	v_mfma_f32_16x16x32_bf16 v[152:155], v[124:127], v[28:31], v[152:155]
	v_mfma_f32_16x16x32_bf16 v[164:167], v[132:135], v[28:31], v[164:167]
	v_mfma_f32_16x16x32_bf16 v[186:189], v[140:143], v[28:31], v[186:189]
	v_mfma_f32_16x16x32_bf16 v[22:25], v[148:151], v[28:31], v[22:25]
	v_mfma_f32_16x16x32_bf16 v[26:29], v[144:147], v[32:35], 0
	v_mfma_f32_16x16x32_bf16 v[156:159], v[68:71], v[32:35], 0
	v_mfma_f32_16x16x32_bf16 v[182:185], v[128:131], v[32:35], 0
	v_mfma_f32_16x16x32_bf16 v[190:193], v[136:139], v[32:35], 0
	v_mfma_f32_16x16x32_bf16 v[26:29], v[148:151], v[36:39], v[26:29]
	v_mfma_f32_16x16x32_bf16 v[156:159], v[124:127], v[36:39], v[156:159]
	v_mfma_f32_16x16x32_bf16 v[182:185], v[132:135], v[36:39], v[182:185]
	v_mfma_f32_16x16x32_bf16 v[190:193], v[140:143], v[36:39], v[190:193]
	s_barrier
; #define G_LDA(dst, b, h)                                                                                                  \
;   _Pragma("unroll") for (int m = 0; m < 4; ++m) _Pragma("unroll") for (int k = 0; k < 2; ++k)                             \
;       dst[m][k] = *(const bf16x8*)((const char*)G_SA(b, h) + ((wr * 4 + m) * 2 + k) * 1024 + rdo)
; #define G_LDB(dst, b, h)                                                                                                  \
;   _Pragma("unroll") for (int n = 0; n < 2; ++n) _Pragma("unroll") for (int k = 0; k < 2; ++k)                             \
;       dst[n][k] = *(const bf16x8*)((const char*)G_SB(b, h) + ((wc * 2 + n) * 2 + k) * 1024 + rdo)
; #define G_WAIT_V(n) asm volatile("s_waitcnt vmcnt(" #n ")" ::: "memory")
; #define G_WAIT_L(n) asm volatile("s_waitcnt lgkmcnt(" #n ")" ::: "memory")
; #define G_BAR __builtin_amdgcn_s_barrier()
; #define G_SCHED __builtin_amdgcn_sched_barrier(0)
;     ...
;     G_STAGE(G_SB(0, 1), B, ob0, ob1, LDB, 128, KB(tt + 2));
;     G_WAIT_V(6); G_BAR; G_MMA(1, 1, At, B1); G_BAR;
;     G_LDB(B0, 1, 0); G_SCHED; G_LDA(At, 1, 0); G_STAGE(G_SA(0, 1), A, oa0, oa1, LDA, 128, KA(tt + 2));
;     G_WAIT_L(8); G_BAR; G_WAIT_L(0); G_MMA(0, 0, At, B0); G_BAR; G_SCHED;
;     G_LDB(B1, 1, 1); G_STAGE(G_SB(1, 0), B, ob0, ob1, LDB, 0, KB(tt + 3));
;     G_BAR; G_WAIT_L(0); G_MMA(0, 1, At, B1); G_BAR;
;     G_LDA(At, 1, 1); G_STAGE(G_SA(1, 0), A, oa0, oa1, LDA, 0, KA(tt + 3));
;     G_BAR; G_WAIT_L(0); G_MMA(1, 0, At, B0); G_BAR; G_SCHED;
;     G_STAGE(G_SB(1, 1), B, ob0, ob1, LDB, 128, KB(tt + 3));
;     G_WAIT_V(6); G_BAR; G_MMA(1, 1, At, B1); G_BAR;
	s_add_u32 m0, s32, 0x14000
	s_nop 0
	global_load_lds_dwordx4 v[160:161], off
	s_add_u32 m0, s32, 0x16000
	s_nop 0
	global_load_lds_dwordx4 v[194:195], off
	s_waitcnt vmcnt(6)
	s_barrier
	v_mfma_f32_16x16x32_bf16 v[18:21], v[68:71], v[104:107], 0
	v_mfma_f32_16x16x32_bf16 v[30:33], v[68:71], v[112:115], 0
	v_mfma_f32_16x16x32_bf16 v[18:21], v[124:127], v[108:111], v[18:21]
	v_mfma_f32_16x16x32_bf16 v[30:33], v[124:127], v[116:119], v[30:33]
	v_mfma_f32_16x16x32_bf16 v[34:37], v[128:131], v[104:107], 0
	v_mfma_f32_16x16x32_bf16 v[124:127], v[136:139], v[104:107], 0
	v_mfma_f32_16x16x32_bf16 v[104:107], v[144:147], v[104:107], 0
	v_mfma_f32_16x16x32_bf16 v[34:37], v[132:135], v[108:111], v[34:37]
	v_mfma_f32_16x16x32_bf16 v[68:71], v[128:131], v[112:115], 0
	v_mfma_f32_16x16x32_bf16 v[124:127], v[140:143], v[108:111], v[124:127]
	v_mfma_f32_16x16x32_bf16 v[128:131], v[136:139], v[112:115], 0
	v_mfma_f32_16x16x32_bf16 v[104:107], v[148:151], v[108:111], v[104:107]
	v_mfma_f32_16x16x32_bf16 v[108:111], v[144:147], v[112:115], 0
	v_mfma_f32_16x16x32_bf16 v[68:71], v[132:135], v[116:119], v[68:71]
	v_mfma_f32_16x16x32_bf16 v[128:131], v[140:143], v[116:119], v[128:131]
	v_mfma_f32_16x16x32_bf16 v[108:111], v[148:151], v[116:119], v[108:111]
	v_or_b32_e32 v160, 0x18000, v162
	v_or_b32_e32 v238, 0x18800, v162
	s_barrier
	v_or_b32_e32 v161, 0x18400, v162
	ds_read_b128 v[112:115], v160
	ds_read_b128 v[116:119], v161
	v_or_b32_e32 v239, 0x18c00, v162
	ds_read_b128 v[132:135], v238
	ds_read_b128 v[136:139], v239
	v_readfirstlane_b32 s0, v16
	s_mov_b32 m0, s0
	v_readfirstlane_b32 s0, v17
	ds_read_b128 v[140:143], v242 offset:32768
	ds_read_b128 v[144:147], v242 offset:33792
	ds_read_b128 v[148:151], v242 offset:34816
	ds_read_b128 v[194:197], v242 offset:35840
	ds_read_b128 v[198:201], v242 offset:36864
	ds_read_b128 v[202:205], v242 offset:37888
	ds_read_b128 v[206:209], v242 offset:38912
	ds_read_b128 v[210:213], v242 offset:39936
	global_load_lds_dwordx4 v[214:215], off
	s_mov_b32 m0, s0
	s_nop 0
	global_load_lds_dwordx4 v[216:217], off
	s_waitcnt lgkmcnt(8)
	s_barrier
	s_waitcnt lgkmcnt(0)
	v_mfma_f32_16x16x32_bf16 v[14:17], v[140:143], v[112:115], v[72:75]
	v_mfma_f32_16x16x32_bf16 v[72:75], v[140:143], v[132:135], v[76:79]
	v_mfma_f32_16x16x32_bf16 v[76:79], v[148:151], v[112:115], v[80:83]
	v_mfma_f32_16x16x32_bf16 v[80:83], v[148:151], v[132:135], v[84:87]
	v_mfma_f32_16x16x32_bf16 v[84:87], v[198:201], v[112:115], v[88:91]
	v_mfma_f32_16x16x32_bf16 v[88:91], v[198:201], v[132:135], v[92:95]
	v_mfma_f32_16x16x32_bf16 v[92:95], v[206:209], v[112:115], v[96:99]
	v_mfma_f32_16x16x32_bf16 v[96:99], v[206:209], v[132:135], v[100:103]
	v_mfma_f32_16x16x32_bf16 v[14:17], v[144:147], v[116:119], v[14:17]
	v_mfma_f32_16x16x32_bf16 v[72:75], v[144:147], v[136:139], v[72:75]
	v_mfma_f32_16x16x32_bf16 v[76:79], v[194:197], v[116:119], v[76:79]
	v_mfma_f32_16x16x32_bf16 v[80:83], v[194:197], v[136:139], v[80:83]
	v_mfma_f32_16x16x32_bf16 v[84:87], v[202:205], v[116:119], v[84:87]
	v_mfma_f32_16x16x32_bf16 v[88:91], v[202:205], v[136:139], v[88:91]
	v_mfma_f32_16x16x32_bf16 v[92:95], v[210:213], v[116:119], v[92:95]
	v_mfma_f32_16x16x32_bf16 v[96:99], v[210:213], v[136:139], v[96:99]
	s_barrier
	v_or_b32_e32 v240, 0x1c000, v162
	v_or_b32_e32 v243, 0x1c800, v162
	s_mov_b32 m0, s37
	v_or_b32_e32 v241, 0x1c400, v162
	ds_read_b128 v[100:103], v240
	ds_read_b128 v[214:217], v241
	v_or_b32_e32 v162, 0x1cc00, v162
	ds_read_b128 v[218:221], v243
	ds_read_b128 v[222:225], v162
	global_load_lds_dwordx4 v[226:227], off
	s_mov_b32 m0, s40
	s_nop 0
	global_load_lds_dwordx4 v[228:229], off
	s_barrier
	s_waitcnt lgkmcnt(0)
	v_mfma_f32_16x16x32_bf16 v[120:123], v[140:143], v[100:103], v[120:123]
	v_mfma_f32_16x16x32_bf16 v[38:41], v[140:143], v[218:221], v[40:43]
	v_mfma_f32_16x16x32_bf16 v[42:45], v[148:151], v[100:103], v[44:47]
	v_mfma_f32_16x16x32_bf16 v[46:49], v[148:151], v[218:221], v[48:51]
	v_mfma_f32_16x16x32_bf16 v[50:53], v[198:201], v[100:103], v[52:55]
	v_mfma_f32_16x16x32_bf16 v[54:57], v[198:201], v[218:221], v[56:59]
	v_mfma_f32_16x16x32_bf16 v[58:61], v[206:209], v[100:103], v[60:63]
	v_mfma_f32_16x16x32_bf16 v[62:65], v[206:209], v[218:221], v[64:67]
	v_mfma_f32_16x16x32_bf16 v[120:123], v[144:147], v[214:217], v[120:123]
	v_mfma_f32_16x16x32_bf16 v[38:41], v[144:147], v[222:225], v[38:41]
	v_mfma_f32_16x16x32_bf16 v[42:45], v[194:197], v[214:217], v[42:45]
	v_mfma_f32_16x16x32_bf16 v[46:49], v[194:197], v[222:225], v[46:49]
	v_mfma_f32_16x16x32_bf16 v[50:53], v[202:205], v[214:217], v[50:53]
	v_mfma_f32_16x16x32_bf16 v[54:57], v[202:205], v[222:225], v[54:57]
	v_mfma_f32_16x16x32_bf16 v[58:61], v[210:213], v[214:217], v[58:61]
	v_mfma_f32_16x16x32_bf16 v[62:65], v[210:213], v[222:225], v[62:65]
	s_mov_b32 m0, s35
	s_barrier
	ds_read_b128 v[140:143], v242 offset:49152
	ds_read_b128 v[144:147], v242 offset:50176
	ds_read_b128 v[148:151], v242 offset:51200
	ds_read_b128 v[194:197], v242 offset:52224
	ds_read_b128 v[198:201], v242 offset:53248
	ds_read_b128 v[202:205], v242 offset:54272
	ds_read_b128 v[206:209], v242 offset:55296
	ds_read_b128 v[210:213], v242 offset:56320
	global_load_lds_dwordx4 v[12:13], off
	s_mov_b32 m0, s36
	s_nop 0
	global_load_lds_dwordx4 v[10:11], off
	s_barrier
; #define G_LDA(dst, b, h)                                                                                                  \
;   _Pragma("unroll") for (int m = 0; m < 4; ++m) _Pragma("unroll") for (int k = 0; k < 2; ++k)                             \
;       dst[m][k] = *(const bf16x8*)((const char*)G_SA(b, h) + ((wr * 4 + m) * 2 + k) * 1024 + rdo)
; #define G_LDB(dst, b, h)                                                                                                  \
;   _Pragma("unroll") for (int n = 0; n < 2; ++n) _Pragma("unroll") for (int k = 0; k < 2; ++k)                             \
;       dst[n][k] = *(const bf16x8*)((const char*)G_SB(b, h) + ((wc * 2 + n) * 2 + k) * 1024 + rdo)
; #define G_WAIT_V(n) asm volatile("s_waitcnt vmcnt(" #n ")" ::: "memory")
; #define G_WAIT_L(n) asm volatile("s_waitcnt lgkmcnt(" #n ")" ::: "memory")
; #define G_BAR __builtin_amdgcn_s_barrier()
; DI void br_flush(PREF p, f32x4 (&acc)[2][2][4][2], int slot) { br_store(p, acc, slot); zero_acc256(acc); }
;     ...
;     G_WAIT_V(6); G_BAR; G_MMA(1, 1, At, B1); G_BAR;
;     if (MODE && ((tt + 1) & 3) == 3) br_flush(p, acc, (tt + 1) >> 2);
;   }
;   {
;     G_LDB(B0, 0, 0); G_LDA(At, 0, 0); G_STAGE(G_SA(1, 1), A, oa0, oa1, LDA, 128, KA(nt - 1));
;     G_BAR; G_WAIT_L(0); G_MMA(0, 0, At, B0); G_BAR;
;     G_LDB(B1, 0, 1); G_BAR; G_WAIT_L(0); G_MMA(0, 1, At, B1); G_BAR;
;     G_LDA(At, 0, 1); G_WAIT_V(4); G_BAR; G_WAIT_L(0); G_MMA(1, 0, At, B0); G_MMA(1, 1, At, B1); G_BAR;
	s_waitcnt lgkmcnt(0)
	v_mfma_f32_16x16x32_bf16 v[10:13], v[140:143], v[112:115], v[152:155]
	v_mfma_f32_16x16x32_bf16 v[22:25], v[206:209], v[112:115], v[22:25]
	v_mfma_f32_16x16x32_bf16 v[26:29], v[206:209], v[132:135], v[26:29]
	v_mfma_f32_16x16x32_bf16 v[10:13], v[144:147], v[116:119], v[10:13]
	v_mfma_f32_16x16x32_bf16 v[152:155], v[140:143], v[132:135], v[156:159]
	v_mfma_f32_16x16x32_bf16 v[156:159], v[148:151], v[112:115], v[164:167]
	v_mfma_f32_16x16x32_bf16 v[164:167], v[148:151], v[132:135], v[182:185]
	v_mfma_f32_16x16x32_bf16 v[182:185], v[198:201], v[112:115], v[186:189]
	v_mfma_f32_16x16x32_bf16 v[186:189], v[198:201], v[132:135], v[190:193]
	v_mfma_f32_16x16x32_bf16 v[22:25], v[210:213], v[116:119], v[22:25]
	v_mfma_f32_16x16x32_bf16 v[26:29], v[210:213], v[136:139], v[26:29]
	v_mfma_f32_16x16x32_bf16 v[152:155], v[144:147], v[136:139], v[152:155]
	v_mfma_f32_16x16x32_bf16 v[156:159], v[194:197], v[116:119], v[156:159]
	v_mfma_f32_16x16x32_bf16 v[164:167], v[194:197], v[136:139], v[164:167]
	v_mfma_f32_16x16x32_bf16 v[182:185], v[202:205], v[116:119], v[182:185]
	v_mfma_f32_16x16x32_bf16 v[186:189], v[202:205], v[136:139], v[186:189]
	s_barrier
	s_mov_b32 m0, s22
	s_nop 0
	global_load_lds_dwordx4 v[8:9], off
	s_mov_b32 m0, s23
	s_nop 0
	global_load_lds_dwordx4 v[6:7], off
	s_waitcnt vmcnt(6)
	s_barrier
	v_mfma_f32_16x16x32_bf16 v[6:9], v[140:143], v[100:103], v[18:21]
	v_mfma_f32_16x16x32_bf16 v[18:21], v[140:143], v[218:221], v[30:33]
	v_mfma_f32_16x16x32_bf16 v[30:33], v[148:151], v[100:103], v[34:37]
	v_mfma_f32_16x16x32_bf16 v[34:37], v[148:151], v[218:221], v[68:71]
	v_mfma_f32_16x16x32_bf16 v[66:69], v[198:201], v[100:103], v[124:127]
	v_mfma_f32_16x16x32_bf16 v[100:103], v[206:209], v[100:103], v[104:107]
	v_mfma_f32_16x16x32_bf16 v[104:107], v[206:209], v[218:221], v[108:111]
	v_mfma_f32_16x16x32_bf16 v[6:9], v[144:147], v[214:217], v[6:9]
	v_mfma_f32_16x16x32_bf16 v[18:21], v[144:147], v[222:225], v[18:21]
	v_mfma_f32_16x16x32_bf16 v[30:33], v[194:197], v[214:217], v[30:33]
	v_mfma_f32_16x16x32_bf16 v[34:37], v[194:197], v[222:225], v[34:37]
	v_mfma_f32_16x16x32_bf16 v[66:69], v[202:205], v[214:217], v[66:69]
	v_mfma_f32_16x16x32_bf16 v[112:115], v[198:201], v[218:221], v[128:131]
	v_mfma_f32_16x16x32_bf16 v[100:103], v[210:213], v[214:217], v[100:103]
	v_mfma_f32_16x16x32_bf16 v[104:107], v[210:213], v[222:225], v[104:107]
	v_mfma_f32_16x16x32_bf16 v[112:115], v[202:205], v[222:225], v[112:115]
	s_add_u32 s0, s20, 0x10180
	s_addc_u32 s1, s21, 0
	s_mov_b32 m0, s19
	v_lshl_add_u64 v[2:3], s[0:1], 0, v[2:3]
	s_barrier
	ds_read_b128 v[108:111], v230
	ds_read_b128 v[116:119], v231
	ds_read_b128 v[124:127], v232
	ds_read_b128 v[128:131], v233
	ds_read_b128 v[132:135], v242
	ds_read_b128 v[136:139], v242 offset:1024
	ds_read_b128 v[140:143], v242 offset:2048
	ds_read_b128 v[144:147], v242 offset:3072
	ds_read_b128 v[148:151], v242 offset:4096
	ds_read_b128 v[190:193], v242 offset:5120
	ds_read_b128 v[194:197], v242 offset:6144
	ds_read_b128 v[198:201], v242 offset:7168
	global_load_lds_dwordx4 v[2:3], off
	s_mov_b32 m0, s18
	v_lshl_add_u64 v[2:3], s[0:1], 0, v[4:5]
	global_load_lds_dwordx4 v[2:3], off
	s_barrier
	s_waitcnt lgkmcnt(0)
	v_mfma_f32_16x16x32_bf16 v[2:5], v[132:135], v[108:111], v[14:17]
	v_mfma_f32_16x16x32_bf16 v[14:17], v[132:135], v[124:127], v[72:75]
	v_mfma_f32_16x16x32_bf16 v[70:73], v[140:143], v[108:111], v[76:79]
	v_mfma_f32_16x16x32_bf16 v[74:77], v[140:143], v[124:127], v[80:83]
	v_mfma_f32_16x16x32_bf16 v[78:81], v[148:151], v[108:111], v[84:87]
	v_mfma_f32_16x16x32_bf16 v[82:85], v[148:151], v[124:127], v[88:91]
	v_mfma_f32_16x16x32_bf16 v[86:89], v[194:197], v[108:111], v[92:95]
	v_mfma_f32_16x16x32_bf16 v[90:93], v[194:197], v[124:127], v[96:99]
	v_mfma_f32_16x16x32_bf16 v[2:5], v[136:139], v[116:119], v[2:5]
	v_mfma_f32_16x16x32_bf16 v[14:17], v[136:139], v[128:131], v[14:17]
	v_mfma_f32_16x16x32_bf16 v[70:73], v[144:147], v[116:119], v[70:73]
	v_mfma_f32_16x16x32_bf16 v[74:77], v[144:147], v[128:131], v[74:77]
	v_mfma_f32_16x16x32_bf16 v[78:81], v[190:193], v[116:119], v[78:81]
	v_mfma_f32_16x16x32_bf16 v[82:85], v[190:193], v[128:131], v[82:85]
	v_mfma_f32_16x16x32_bf16 v[86:89], v[198:201], v[116:119], v[86:89]
	v_mfma_f32_16x16x32_bf16 v[90:93], v[198:201], v[128:131], v[90:93]
	s_barrier
	ds_read_b128 v[94:97], v234
	ds_read_b128 v[202:205], v235
	ds_read_b128 v[206:209], v236
	ds_read_b128 v[210:213], v237
	s_barrier
	s_waitcnt lgkmcnt(0)
	v_mfma_f32_16x16x32_bf16 v[38:41], v[132:135], v[206:209], v[38:41]
	v_mfma_f32_16x16x32_bf16 v[42:45], v[140:143], v[94:97], v[42:45]
	v_mfma_f32_16x16x32_bf16 v[46:49], v[140:143], v[206:209], v[46:49]
	v_mfma_f32_16x16x32_bf16 v[50:53], v[148:151], v[94:97], v[50:53]
	v_mfma_f32_16x16x32_bf16 v[54:57], v[148:151], v[206:209], v[54:57]
	v_mfma_f32_16x16x32_bf16 v[58:61], v[194:197], v[94:97], v[58:61]
	v_mfma_f32_16x16x32_bf16 v[62:65], v[194:197], v[206:209], v[62:65]
	v_mfma_f32_16x16x32_bf16 v[120:123], v[132:135], v[94:97], v[120:123]
	v_mfma_f32_16x16x32_bf16 v[38:41], v[136:139], v[210:213], v[38:41]
	v_mfma_f32_16x16x32_bf16 v[42:45], v[144:147], v[202:205], v[42:45]
	v_mfma_f32_16x16x32_bf16 v[46:49], v[144:147], v[210:213], v[46:49]
	v_mfma_f32_16x16x32_bf16 v[50:53], v[190:193], v[202:205], v[50:53]
	v_mfma_f32_16x16x32_bf16 v[54:57], v[190:193], v[210:213], v[54:57]
	v_mfma_f32_16x16x32_bf16 v[58:61], v[198:201], v[202:205], v[58:61]
	v_mfma_f32_16x16x32_bf16 v[62:65], v[198:201], v[210:213], v[62:65]
	v_mfma_f32_16x16x32_bf16 v[214:217], v[136:139], v[202:205], v[120:123]
	s_barrier
; #define G_LDA(dst, b, h)                                                                                                  \
;   _Pragma("unroll") for (int m = 0; m < 4; ++m) _Pragma("unroll") for (int k = 0; k < 2; ++k)                             \
;       dst[m][k] = *(const bf16x8*)((const char*)G_SA(b, h) + ((wr * 4 + m) * 2 + k) * 1024 + rdo)
; #define G_LDB(dst, b, h)                                                                                                  \
;   _Pragma("unroll") for (int n = 0; n < 2; ++n) _Pragma("unroll") for (int k = 0; k < 2; ++k)                             \
;       dst[n][k] = *(const bf16x8*)((const char*)G_SB(b, h) + ((wc * 2 + n) * 2 + k) * 1024 + rdo)
; #define G_WAIT_V(n) asm volatile("s_waitcnt vmcnt(" #n ")" ::: "memory")
; #define G_WAIT_L(n) asm volatile("s_waitcnt lgkmcnt(" #n ")" ::: "memory")
; #define G_BAR __builtin_amdgcn_s_barrier()
;     ...
;     G_LDA(At, 0, 1); G_WAIT_V(4); G_BAR; G_WAIT_L(0); G_MMA(1, 0, At, B0); G_MMA(1, 1, At, B1); G_BAR;
;   }
;   {
;     G_LDB(B0, 1, 0); G_LDA(At, 1, 0); G_WAIT_V(2); G_BAR; G_WAIT_L(0); G_MMA(0, 0, At, B0); G_BAR;
;     G_LDB(B1, 1, 1); G_WAIT_V(0); G_BAR; G_WAIT_L(0); G_MMA(0, 1, At, B1); G_BAR;
	s_nop 0
	ds_read_b128 v[120:123], v242 offset:16384
	ds_read_b128 v[132:135], v242 offset:17408
	ds_read_b128 v[136:139], v242 offset:18432
	ds_read_b128 v[140:143], v242 offset:19456
	ds_read_b128 v[144:147], v242 offset:20480
	ds_read_b128 v[148:151], v242 offset:21504
	ds_read_b128 v[190:193], v242 offset:22528
	ds_read_b128 v[194:197], v242 offset:23552
	s_waitcnt vmcnt(4)
	s_barrier
	s_waitcnt lgkmcnt(0)
	v_mfma_f32_16x16x32_bf16 v[10:13], v[120:123], v[108:111], v[10:13]
	v_mfma_f32_16x16x32_bf16 v[22:25], v[190:193], v[108:111], v[22:25]
	v_mfma_f32_16x16x32_bf16 v[26:29], v[190:193], v[124:127], v[26:29]
	v_mfma_f32_16x16x32_bf16 v[10:13], v[132:135], v[116:119], v[10:13]
	v_mfma_f32_16x16x32_bf16 v[152:155], v[120:123], v[124:127], v[152:155]
	v_mfma_f32_16x16x32_bf16 v[156:159], v[136:139], v[108:111], v[156:159]
	v_mfma_f32_16x16x32_bf16 v[164:167], v[136:139], v[124:127], v[164:167]
	v_mfma_f32_16x16x32_bf16 v[182:185], v[144:147], v[108:111], v[182:185]
	v_mfma_f32_16x16x32_bf16 v[186:189], v[144:147], v[124:127], v[186:189]
	v_mfma_f32_16x16x32_bf16 v[22:25], v[194:197], v[116:119], v[22:25]
	v_mfma_f32_16x16x32_bf16 v[26:29], v[194:197], v[128:131], v[26:29]
	v_mfma_f32_16x16x32_bf16 v[152:155], v[132:135], v[128:131], v[152:155]
	v_mfma_f32_16x16x32_bf16 v[156:159], v[140:143], v[116:119], v[156:159]
	v_mfma_f32_16x16x32_bf16 v[164:167], v[140:143], v[128:131], v[164:167]
	v_mfma_f32_16x16x32_bf16 v[182:185], v[148:151], v[116:119], v[182:185]
	v_mfma_f32_16x16x32_bf16 v[186:189], v[148:151], v[128:131], v[186:189]
	v_mfma_f32_16x16x32_bf16 v[30:33], v[136:139], v[94:97], v[30:33]
	v_mfma_f32_16x16x32_bf16 v[126:129], v[140:143], v[202:205], v[30:33]
	v_mfma_f32_16x16x32_bf16 v[30:33], v[136:139], v[206:209], v[34:37]
	v_mfma_f32_16x16x32_bf16 v[198:201], v[140:143], v[210:213], v[30:33]
	v_mfma_f32_16x16x32_bf16 v[30:33], v[144:147], v[94:97], v[66:69]
	v_mfma_f32_16x16x32_bf16 v[218:221], v[148:151], v[202:205], v[30:33]
	v_mfma_f32_16x16x32_bf16 v[30:33], v[144:147], v[206:209], v[112:115]
	v_mfma_f32_16x16x32_bf16 v[6:9], v[120:123], v[94:97], v[6:9]
	v_mfma_f32_16x16x32_bf16 v[18:21], v[120:123], v[206:209], v[18:21]
	v_mfma_f32_16x16x32_bf16 v[110:113], v[148:151], v[210:213], v[30:33]
	v_mfma_f32_16x16x32_bf16 v[30:33], v[190:193], v[94:97], v[100:103]
	v_mfma_f32_16x16x32_bf16 v[6:9], v[132:135], v[202:205], v[6:9]
	v_mfma_f32_16x16x32_bf16 v[18:21], v[132:135], v[210:213], v[18:21]
	v_mfma_f32_16x16x32_bf16 v[114:117], v[194:197], v[202:205], v[30:33]
	v_mfma_f32_16x16x32_bf16 v[30:33], v[190:193], v[206:209], v[104:107]
	v_mfma_f32_16x16x32_bf16 v[102:105], v[194:197], v[210:213], v[30:33]
	s_barrier
	s_nop 4
	s_nop 0
	ds_read_b128 v[30:33], v160
	ds_read_b128 v[34:37], v161
	ds_read_b128 v[146:149], v238
	ds_read_b128 v[190:193], v239
	ds_read_b128 v[66:69], v242 offset:32768
	ds_read_b128 v[94:97], v242 offset:33792
	ds_read_b128 v[194:197], v242 offset:34816
	ds_read_b128 v[202:205], v242 offset:35840
	ds_read_b128 v[206:209], v242 offset:36864
	ds_read_b128 v[210:213], v242 offset:37888
	ds_read_b128 v[222:225], v242 offset:38912
	ds_read_b128 v[226:229], v242 offset:39936
	s_waitcnt vmcnt(2)
	s_barrier
	s_waitcnt lgkmcnt(0)
	v_mfma_f32_16x16x32_bf16 v[2:5], v[66:69], v[30:33], v[2:5]
	v_mfma_f32_16x16x32_bf16 v[134:137], v[94:97], v[34:37], v[2:5]
	v_mfma_f32_16x16x32_bf16 v[2:5], v[66:69], v[146:149], v[14:17]
	v_mfma_f32_16x16x32_bf16 v[142:145], v[94:97], v[190:193], v[2:5]
	v_mfma_f32_16x16x32_bf16 v[2:5], v[194:197], v[30:33], v[70:73]
	v_mfma_f32_16x16x32_bf16 v[130:133], v[202:205], v[34:37], v[2:5]
	v_mfma_f32_16x16x32_bf16 v[2:5], v[194:197], v[146:149], v[74:77]
	v_mfma_f32_16x16x32_bf16 v[138:141], v[202:205], v[190:193], v[2:5]
	v_mfma_f32_16x16x32_bf16 v[2:5], v[206:209], v[30:33], v[78:81]
	v_mfma_f32_16x16x32_bf16 v[118:121], v[210:213], v[34:37], v[2:5]
	v_mfma_f32_16x16x32_bf16 v[2:5], v[206:209], v[146:149], v[82:85]
	v_mfma_f32_16x16x32_bf16 v[122:125], v[210:213], v[190:193], v[2:5]
	v_mfma_f32_16x16x32_bf16 v[2:5], v[222:225], v[30:33], v[86:89]
	v_mfma_f32_16x16x32_bf16 v[98:101], v[226:229], v[34:37], v[2:5]
	v_mfma_f32_16x16x32_bf16 v[2:5], v[222:225], v[146:149], v[90:93]
	v_mfma_f32_16x16x32_bf16 v[106:109], v[226:229], v[190:193], v[2:5]
	s_barrier
; #define G_LDA(dst, b, h)                                                                                                  \
;   _Pragma("unroll") for (int m = 0; m < 4; ++m) _Pragma("unroll") for (int k = 0; k < 2; ++k)                             \
;       dst[m][k] = *(const bf16x8*)((const char*)G_SA(b, h) + ((wr * 4 + m) * 2 + k) * 1024 + rdo)
; #define G_LDB(dst, b, h)                                                                                                  \
;   _Pragma("unroll") for (int n = 0; n < 2; ++n) _Pragma("unroll") for (int k = 0; k < 2; ++k)                             \
;       dst[n][k] = *(const bf16x8*)((const char*)G_SB(b, h) + ((wc * 2 + n) * 2 + k) * 1024 + rdo)
; #define G_WAIT_V(n) asm volatile("s_waitcnt vmcnt(" #n ")" ::: "memory")
; #define G_WAIT_L(n) asm volatile("s_waitcnt lgkmcnt(" #n ")" ::: "memory")
; #define G_BAR __builtin_amdgcn_s_barrier()
;     ...
;     G_LDB(B1, 1, 1); G_WAIT_V(0); G_BAR; G_WAIT_L(0); G_MMA(0, 1, At, B1); G_BAR;
;     G_LDA(At, 1, 1); G_BAR; G_WAIT_L(0); G_MMA(1, 0, At, B0); G_MMA(1, 1, At, B1); G_BAR;
;   }
;   if (wr == 0) G_BAR;
	s_nop 4
	s_nop 0
	ds_read_b128 v[2:5], v240
	ds_read_b128 v[230:233], v241
	ds_read_b128 v[234:237], v243
	ds_read_b128 v[238:241], v162
	s_waitcnt vmcnt(0)
	s_barrier
	s_waitcnt lgkmcnt(0)
	v_mfma_f32_16x16x32_bf16 v[14:17], v[66:69], v[2:5], v[214:217]
	v_mfma_f32_16x16x32_bf16 v[86:89], v[94:97], v[230:233], v[14:17]
	v_mfma_f32_16x16x32_bf16 v[14:17], v[66:69], v[234:237], v[38:41]
	v_mfma_f32_16x16x32_bf16 v[94:97], v[94:97], v[238:241], v[14:17]
	v_mfma_f32_16x16x32_bf16 v[14:17], v[194:197], v[2:5], v[42:45]
	v_mfma_f32_16x16x32_bf16 v[82:85], v[202:205], v[230:233], v[14:17]
	v_mfma_f32_16x16x32_bf16 v[14:17], v[194:197], v[234:237], v[46:49]
	v_mfma_f32_16x16x32_bf16 v[90:93], v[202:205], v[238:241], v[14:17]
	v_mfma_f32_16x16x32_bf16 v[14:17], v[206:209], v[2:5], v[50:53]
	v_mfma_f32_16x16x32_bf16 v[74:77], v[210:213], v[230:233], v[14:17]
	v_mfma_f32_16x16x32_bf16 v[14:17], v[206:209], v[234:237], v[54:57]
	v_mfma_f32_16x16x32_bf16 v[78:81], v[210:213], v[238:241], v[14:17]
	v_mfma_f32_16x16x32_bf16 v[14:17], v[222:225], v[2:5], v[58:61]
	v_mfma_f32_16x16x32_bf16 v[66:69], v[226:229], v[230:233], v[14:17]
	v_mfma_f32_16x16x32_bf16 v[14:17], v[222:225], v[234:237], v[62:65]
	v_mfma_f32_16x16x32_bf16 v[70:73], v[226:229], v[238:241], v[14:17]
	s_barrier
	s_nop 4
	s_nop 0
	ds_read_b128 v[14:17], v242 offset:49152
	ds_read_b128 v[194:197], v242 offset:50176
	ds_read_b128 v[202:205], v242 offset:51200
	ds_read_b128 v[206:209], v242 offset:52224
	ds_read_b128 v[210:213], v242 offset:53248
	ds_read_b128 v[214:217], v242 offset:54272
	ds_read_b128 v[222:225], v242 offset:55296
	ds_read_b128 v[226:229], v242 offset:56320
	s_barrier
	s_waitcnt lgkmcnt(0)
	v_mfma_f32_16x16x32_bf16 v[10:13], v[14:17], v[30:33], v[10:13]
	v_mfma_f32_16x16x32_bf16 v[54:57], v[194:197], v[34:37], v[10:13]
	v_mfma_f32_16x16x32_bf16 v[10:13], v[14:17], v[146:149], v[152:155]
	v_mfma_f32_16x16x32_bf16 v[62:65], v[194:197], v[190:193], v[10:13]
	v_mfma_f32_16x16x32_bf16 v[10:13], v[202:205], v[30:33], v[156:159]
	v_mfma_f32_16x16x32_bf16 v[50:53], v[206:209], v[34:37], v[10:13]
	v_mfma_f32_16x16x32_bf16 v[10:13], v[202:205], v[146:149], v[164:167]
	v_mfma_f32_16x16x32_bf16 v[58:61], v[206:209], v[190:193], v[10:13]
	v_mfma_f32_16x16x32_bf16 v[10:13], v[210:213], v[30:33], v[182:185]
	v_mfma_f32_16x16x32_bf16 v[42:45], v[214:217], v[34:37], v[10:13]
	v_mfma_f32_16x16x32_bf16 v[10:13], v[210:213], v[146:149], v[186:189]
	v_mfma_f32_16x16x32_bf16 v[46:49], v[214:217], v[190:193], v[10:13]
	v_mfma_f32_16x16x32_bf16 v[10:13], v[222:225], v[30:33], v[22:25]
	v_mfma_f32_16x16x32_bf16 v[34:37], v[226:229], v[34:37], v[10:13]
	v_mfma_f32_16x16x32_bf16 v[10:13], v[222:225], v[146:149], v[26:29]
	v_mfma_f32_16x16x32_bf16 v[38:41], v[226:229], v[190:193], v[10:13]
	v_mfma_f32_16x16x32_bf16 v[6:9], v[14:17], v[2:5], v[6:9]
	v_mfma_f32_16x16x32_bf16 v[22:25], v[194:197], v[230:233], v[6:9]
	v_mfma_f32_16x16x32_bf16 v[6:9], v[14:17], v[234:237], v[18:21]
	v_mfma_f32_16x16x32_bf16 v[30:33], v[194:197], v[238:241], v[6:9]
	v_mfma_f32_16x16x32_bf16 v[6:9], v[202:205], v[2:5], v[126:129]
	v_mfma_f32_16x16x32_bf16 v[18:21], v[206:209], v[230:233], v[6:9]
	v_mfma_f32_16x16x32_bf16 v[6:9], v[202:205], v[234:237], v[198:201]
	v_mfma_f32_16x16x32_bf16 v[26:29], v[206:209], v[238:241], v[6:9]
	v_mfma_f32_16x16x32_bf16 v[6:9], v[210:213], v[2:5], v[218:221]
	v_mfma_f32_16x16x32_bf16 v[10:13], v[214:217], v[230:233], v[6:9]
	v_mfma_f32_16x16x32_bf16 v[6:9], v[210:213], v[234:237], v[110:113]
	v_mfma_f32_16x16x32_bf16 v[14:17], v[214:217], v[238:241], v[6:9]
	v_mfma_f32_16x16x32_bf16 v[2:5], v[222:225], v[2:5], v[114:117]
	v_mfma_f32_16x16x32_bf16 v[6:9], v[222:225], v[234:237], v[102:105]
	v_mfma_f32_16x16x32_bf16 v[2:5], v[226:229], v[230:233], v[2:5]
	v_mfma_f32_16x16x32_bf16 v[6:9], v[226:229], v[238:241], v[6:9]
	v_cmp_gt_u32_e32 vcc, s67, v0
	s_barrier
	s_and_saveexec_b64 s[18:19], vcc
	s_cbranch_execz .LBB0_36
	s_barrier
	s_branch .LBB0_36

; DI void lds_barrier() { asm volatile("s_waitcnt lgkmcnt(0)\n\ts_barrier" ::: "memory"); }
; DI int tid512() { int t = threadIdx.x; asm volatile("" : "+v"(t)); return t; }
; #define G_WAIT_V(n) asm volatile("s_waitcnt vmcnt(" #n ")" ::: "memory")
; #define G_BAR __builtin_amdgcn_s_barrier()
;     ...
;   const int t = tid512();
;   const int wid = t >> 6, lane = t & 63, wr = wid >> 2, wc = wid & 3, fr = lane & 15, fq = lane >> 4;
;   int r0, c0, r1, c1;
;   g_stage_rc(t * 16, r0, c0); g_stage_rc(t * 16 + 8192, r1, c1);
;   const int oa0 = r0 * LDA + c0, oa1 = r1 * LDA + c1, ob0 = r0 * LDB + c0, ob1 = r1 * LDB + c1;
;   const int obr = fr * 64 + fq * 16, rdo = obr ^ (((obr >> 9) & 1) << 5);
;   bf16x8 At[4][2], B0[2][2], B1[2][2];
;   constexpr int nt = K / 64;
;   lds_barrier();
;   G_STAGE(G_SB(0, 0), B, ob0, ob1, LDB, 0, KB(0)); G_STAGE(G_SA(0, 0), A, oa0, oa1, LDA, 0, KA(0));
;   G_STAGE(G_SB(0, 1), B, ob0, ob1, LDB, 128, KB(0)); G_STAGE(G_SA(0, 1), A, oa0, oa1, LDA, 128, KA(0));
;   if (wr == 1) G_BAR;
;   G_WAIT_V(4); G_BAR;
;   G_STAGE(G_SB(1, 0), B, ob0, ob1, LDB, 0, KB(1)); G_STAGE(G_SA(1, 0), A, oa0, oa1, LDA, 0, KA(1)); G_STAGE(G_SB(1, 1), B, ob0, ob1, LDB, 128, KB(1));
;   G_WAIT_V(6); G_BAR;
.LBB0_63:
	s_lshr_b32 s0, s9, 2
	s_and_b32 s36, s0, 8
	s_lshl_b32 s0, s36, 2
	s_sub_i32 s0, s9, s0
	s_and_b32 s37, s9, 7
	s_ashr_i32 s8, s0, 3
	s_or_b32 s0, s37, s47
	v_mov_b32_e32 v0, v168
	s_or_b32 s35, s0, s36
	s_lshl_b32 s0, s35, 19
	v_lshlrev_b32_e32 v143, 4, v0
	s_nop 0
	v_readfirstlane_b32 s32, v143
	v_and_b32_e32 v2, 32, v0
	v_lshrrev_b32_e32 v4, 1, v0
	v_bitop3_b32 v2, v143, v2, 48 bitop3:0x6c
	s_add_u32 s20, s10, s0
	v_ashrrev_i32_e32 v10, 3, v0
	v_bfe_u32 v13, v0, 2, 4
	s_mov_b32 s0, 0x3ffff0
	v_and_b32_e32 v11, 32, v4
	v_lshrrev_b32_e32 v12, 1, v2
	v_add_u32_e32 v144, 0x2000, v143
	s_addc_u32 s21, s11, 0
	s_ashr_i32 s9, s8, 31
	v_and_or_b32 v3, v10, s0, v13
	v_or_b32_e32 v2, v12, v11
	v_ashrrev_i32_e32 v15, 7, v144
	s_lshl_b64 s[22:23], s[8:9], 19
	v_and_or_b32 v4, v15, s0, v13
	v_lshl_or_b32 v132, v3, 10, v2
	s_add_u32 s24, s30, s22
	v_lshl_or_b32 v130, v4, 10, v2
	v_ashrrev_i32_e32 v133, 31, v132
	s_addc_u32 s25, s31, s23
	v_lshlrev_b64 v[16:17], 1, v[132:133]
	v_ashrrev_i32_e32 v131, 31, v130
	s_waitcnt lgkmcnt(0)
	s_barrier
	v_lshl_add_u64 v[2:3], s[24:25], 0, v[16:17]
	s_add_u32 m0, s32, 0x10000
	v_lshlrev_b64 v[18:19], 1, v[130:131]
	global_load_lds_dwordx4 v[2:3], off
	v_lshl_add_u64 v[6:7], s[24:25], 0, v[18:19]
	s_add_u32 m0, s32, 0x12000
	s_nop 0
	global_load_lds_dwordx4 v[6:7], off
	v_lshl_add_u64 v[8:9], s[20:21], 0, v[16:17]
	s_mov_b32 m0, s32
	s_nop 0
	global_load_lds_dwordx4 v[8:9], off
	s_add_u32 m0, s32, 0x2000
	s_add_u32 s0, s24, 0x40000
	v_lshl_add_u64 v[4:5], s[20:21], 0, v[18:19]
	s_addc_u32 s1, s25, 0
	global_load_lds_dwordx4 v[4:5], off
	v_lshl_add_u64 v[20:21], s[0:1], 0, v[16:17]
	s_add_u32 m0, s32, 0x14000
	s_nop 0
	global_load_lds_dwordx4 v[20:21], off
	v_lshl_add_u64 v[20:21], s[0:1], 0, v[18:19]
	s_add_u32 m0, s32, 0x16000
	s_add_u32 s0, s20, 0x40000
	v_add_u32_e32 v151, 0x4000, v143
	s_addc_u32 s1, s21, 0
	v_readfirstlane_b32 s9, v151
	global_load_lds_dwordx4 v[20:21], off
	v_lshl_add_u64 v[16:17], s[0:1], 0, v[16:17]
	s_add_u32 m0, s32, 0x4000
	v_add_u32_e32 v152, 0x6000, v143
	global_load_lds_dwordx4 v[16:17], off
	v_lshl_add_u64 v[16:17], s[0:1], 0, v[18:19]
	v_readfirstlane_b32 s0, v152
	s_add_u32 m0, s32, 0x6000
	v_ashrrev_i32_e32 v14, 8, v0
	global_load_lds_dwordx4 v[16:17], off
	v_cmp_eq_u32_e32 vcc, 1, v14
	s_and_saveexec_b64 s[26:27], vcc
	s_cbranch_execz .LBB0_65
	s_barrier
.LBB0_65:
	s_or_b64 exec, exec, s[26:27]
	v_lshl_add_u64 v[2:3], v[2:3], 0, s[76:77]
	s_add_u32 m0, s32, 0x18000
	s_waitcnt vmcnt(4)
	s_barrier
	global_load_lds_dwordx4 v[2:3], off
	v_lshl_add_u64 v[2:3], v[6:7], 0, s[76:77]
	s_add_u32 m0, s32, 0x1a000
	s_nop 0
	global_load_lds_dwordx4 v[2:3], off
	v_lshl_add_u64 v[2:3], v[8:9], 0, s[76:77]
	s_add_u32 m0, s32, 0x8000
	s_nop 0
	global_load_lds_dwordx4 v[2:3], off
	s_add_u32 m0, s32, 0xa000
	s_add_u32 s0, s24, 0x40080
	v_lshl_add_u64 v[2:3], v[4:5], 0, s[76:77]
	s_addc_u32 s1, s25, 0
	global_load_lds_dwordx4 v[2:3], off
	v_lshl_add_u64 v[2:3], v[132:133], 1, s[0:1]
	s_add_u32 m0, s32, 0x1c000
	s_nop 0
	global_load_lds_dwordx4 v[2:3], off
	v_lshl_add_u64 v[2:3], v[130:131], 1, s[0:1]
	s_add_u32 m0, s32, 0x1e000
	v_lshlrev_b32_e32 v17, 6, v0
	global_load_lds_dwordx4 v[2:3], off
	v_and_b32_e32 v16, 48, v0
	v_and_b32_e32 v18, 0x3c0, v17
	v_lshlrev_b32_e32 v20, 2, v0
	v_or_b32_e32 v19, v18, v16
	v_and_b32_e32 v20, 32, v20
	s_mov_b32 s0, 0x14000
	v_bitop3_b32 v8, v19, s0, v20 bitop3:0xde
	s_mov_b32 s0, 0x18000
	v_bitop3_b32 v9, v19, s0, v20 bitop3:0xde
	s_mov_b32 s0, 0x1c000
	v_lshlrev_b32_e32 v2, 10, v15
	v_lshlrev_b32_e32 v5, 10, v10
	v_lshlrev_b32_e32 v7, 13, v14
	v_bitop3_b32 v14, v19, s0, v20 bitop3:0xde
	s_add_i32 s0, s47, s36
	v_and_b32_e32 v2, 0xffffc000, v2
	v_lshlrev_b32_e32 v4, 10, v13
	v_and_b32_e32 v5, 0xffffc000, v5
	s_add_i32 s0, s0, s37
	v_or3_b32 v2, v12, v2, v4
	v_or3_b32 v4, v12, v5, v4
	s_lshl_b32 s0, s0, 19
	v_add_u32_e32 v2, v2, v11
	v_add_u32_e32 v4, v4, v11
	v_ashrrev_i32_e32 v3, 31, v2
	s_add_u32 s0, s10, s0
	v_ashrrev_i32_e32 v5, 31, v4
	v_lshlrev_b64 v[2:3], 1, v[2:3]
	s_addc_u32 s1, s11, 0
	v_lshlrev_b64 v[4:5], 1, v[4:5]
	v_lshl_add_u64 v[134:135], s[0:1], 0, v[2:3]
	v_lshl_add_u64 v[136:137], s[0:1], 0, v[4:5]
	s_add_u32 s0, s28, s22
	s_waitcnt vmcnt(6)
	s_addc_u32 s1, s29, s23
	v_bitop3_b32 v16, v18, v20, v16 bitop3:0x36
	v_bitop3_b32 v6, v19, s88, v20 bitop3:0xde
	v_and_b32_e32 v17, 0x3000, v17
	v_lshl_add_u64 v[138:139], s[0:1], 0, v[2:3]
	v_mov_b32_e32 v2, 0
	v_lshl_add_u64 v[140:141], s[0:1], 0, v[4:5]
	s_mov_b32 s9, -2
	s_mov_b64 s[22:23], 0
	v_add_u32_e32 v160, v6, v17
	v_add_u32_e32 v142, v16, v7
	v_add_u32_e32 v158, v8, v17
	v_add_u32_e32 v149, v9, v17
	v_add_u32_e32 v145, v14, v17
	v_mov_b32_e32 v3, v2
	v_mov_b32_e32 v4, v2
	v_mov_b32_e32 v5, v2
	v_mov_b32_e32 v6, v2
	v_mov_b32_e32 v7, v2
	v_mov_b32_e32 v8, v2
	v_mov_b32_e32 v9, v2
	v_mov_b32_e32 v10, v2
	v_mov_b32_e32 v11, v2
	v_mov_b32_e32 v12, v2
	v_mov_b32_e32 v13, v2
	v_mov_b32_e32 v14, v2
	v_mov_b32_e32 v15, v2
	v_mov_b32_e32 v16, v2
	v_mov_b32_e32 v17, v2
	v_mov_b32_e32 v18, v2
	v_mov_b32_e32 v19, v2
	v_mov_b32_e32 v20, v2
	v_mov_b32_e32 v21, v2
	v_mov_b32_e32 v22, v2
	v_mov_b32_e32 v23, v2
	v_mov_b32_e32 v24, v2
	v_mov_b32_e32 v25, v2
	v_mov_b32_e32 v26, v2
	v_mov_b32_e32 v27, v2
	v_mov_b32_e32 v28, v2
	v_mov_b32_e32 v29, v2
	v_mov_b32_e32 v30, v2
	v_mov_b32_e32 v31, v2
	v_mov_b32_e32 v32, v2
	v_mov_b32_e32 v33, v2
	v_mov_b32_e32 v34, v2
	v_mov_b32_e32 v35, v2
	v_mov_b32_e32 v36, v2
	v_mov_b32_e32 v37, v2
	v_mov_b32_e32 v38, v2
	v_mov_b32_e32 v39, v2
	v_mov_b32_e32 v40, v2
	v_mov_b32_e32 v41, v2
	v_mov_b32_e32 v42, v2
	v_mov_b32_e32 v43, v2
	v_mov_b32_e32 v44, v2
; #define G_LDA(dst, b, h)                                                                                                  \
;   _Pragma("unroll") for (int m = 0; m < 4; ++m) _Pragma("unroll") for (int k = 0; k < 2; ++k)                             \
;       dst[m][k] = *(const bf16x8*)((const char*)G_SA(b, h) + ((wr * 4 + m) * 2 + k) * 1024 + rdo)
; #define G_LDB(dst, b, h)                                                                                                  \
;   _Pragma("unroll") for (int n = 0; n < 2; ++n) _Pragma("unroll") for (int k = 0; k < 2; ++k)                             \
;       dst[n][k] = *(const bf16x8*)((const char*)G_SB(b, h) + ((wc * 2 + n) * 2 + k) * 1024 + rdo)
; #define G_WAIT_L(n) asm volatile("s_waitcnt lgkmcnt(" #n ")" ::: "memory")
; #define G_BAR __builtin_amdgcn_s_barrier()
; #define G_SCHED __builtin_amdgcn_sched_barrier(0)
;     ...
;   for (int tt = 0; tt < nt - 2; tt += 2) {
;     G_LDB(B0, 0, 0); G_SCHED; G_LDA(At, 0, 0); G_STAGE(G_SA(1, 1), A, oa0, oa1, LDA, 128, KA(tt + 1));
;     G_WAIT_L(8); G_BAR; G_WAIT_L(0); G_MMA(0, 0, At, B0); G_BAR; G_SCHED;
;     G_LDB(B1, 0, 1); G_STAGE(G_SB(0, 0), B, ob0, ob1, LDB, 0, KB(tt + 2));
;     G_BAR; G_WAIT_L(0); G_MMA(0, 1, At, B1); G_BAR;
; DI void zero_acc256(f32x4 (&a)[2][2][4][2]) {
; #pragma unroll
;   for (int i = 0; i < 2; ++i)
; #pragma unroll
;     for (int j = 0; j < 2; ++j)
; #pragma unroll
;       for (int m = 0; m < 4; ++m)
; #pragma unroll
;         for (int n = 0; n < 2; ++n)
; #pragma unroll
;           for (int e = 0; e < 4; ++e) a[i][j][m][n][e] = 0.f;
; }
	v_mov_b32_e32 v45, v2
	v_mov_b32_e32 v46, v2
	v_mov_b32_e32 v47, v2
	v_mov_b32_e32 v48, v2
	v_mov_b32_e32 v49, v2
	v_mov_b32_e32 v50, v2
	v_mov_b32_e32 v51, v2
	v_mov_b32_e32 v52, v2
	v_mov_b32_e32 v53, v2
	v_mov_b32_e32 v54, v2
	v_mov_b32_e32 v55, v2
	v_mov_b32_e32 v56, v2
	v_mov_b32_e32 v57, v2
	v_mov_b32_e32 v58, v2
	v_mov_b32_e32 v59, v2
	v_mov_b32_e32 v60, v2
	v_mov_b32_e32 v61, v2
	v_mov_b32_e32 v62, v2
	v_mov_b32_e32 v63, v2
	v_mov_b32_e32 v64, v2
	v_mov_b32_e32 v65, v2
	v_mov_b32_e32 v66, v2
	v_mov_b32_e32 v67, v2
	v_mov_b32_e32 v68, v2
	v_mov_b32_e32 v69, v2
	v_mov_b32_e32 v70, v2
	v_mov_b32_e32 v71, v2
	v_mov_b32_e32 v72, v2
	v_mov_b32_e32 v73, v2
	v_mov_b32_e32 v74, v2
	v_mov_b32_e32 v75, v2
	v_mov_b32_e32 v76, v2
	v_mov_b32_e32 v77, v2
	v_mov_b32_e32 v78, v2
	v_mov_b32_e32 v79, v2
	v_mov_b32_e32 v80, v2
	v_mov_b32_e32 v81, v2
	v_mov_b32_e32 v82, v2
	v_mov_b32_e32 v83, v2
	v_mov_b32_e32 v84, v2
	v_mov_b32_e32 v85, v2
	v_mov_b32_e32 v86, v2
	v_mov_b32_e32 v87, v2
	v_mov_b32_e32 v88, v2
	v_mov_b32_e32 v89, v2
	v_mov_b32_e32 v90, v2
	v_mov_b32_e32 v91, v2
	v_mov_b32_e32 v92, v2
	v_mov_b32_e32 v93, v2
	v_mov_b32_e32 v94, v2
	v_mov_b32_e32 v95, v2
	v_mov_b32_e32 v96, v2
	v_mov_b32_e32 v97, v2
	v_mov_b32_e32 v98, v2
	v_mov_b32_e32 v99, v2
	v_mov_b32_e32 v100, v2
	v_mov_b32_e32 v101, v2
	v_mov_b32_e32 v102, v2
	v_mov_b32_e32 v103, v2
	v_mov_b32_e32 v104, v2
	v_mov_b32_e32 v105, v2
	v_mov_b32_e32 v106, v2
	v_mov_b32_e32 v107, v2
	v_mov_b32_e32 v108, v2
	v_mov_b32_e32 v109, v2
	v_mov_b32_e32 v110, v2
	v_mov_b32_e32 v111, v2
	v_mov_b32_e32 v112, v2
	v_mov_b32_e32 v113, v2
	v_mov_b32_e32 v114, v2
	v_mov_b32_e32 v115, v2
	v_mov_b32_e32 v116, v2
	v_mov_b32_e32 v117, v2
	v_mov_b32_e32 v118, v2
	v_mov_b32_e32 v119, v2
	v_mov_b32_e32 v120, v2
	v_mov_b32_e32 v121, v2
	v_mov_b32_e32 v122, v2
	v_mov_b32_e32 v123, v2
	v_mov_b32_e32 v124, v2
	v_mov_b32_e32 v125, v2
	v_mov_b32_e32 v126, v2
	v_mov_b32_e32 v127, v2
	v_mov_b32_e32 v128, v2
	v_mov_b32_e32 v129, v2
	s_mov_b64 s[24:25], 0x1070100
	s_mov_b64 s[26:27], 0x1030180
	s_mov_b64 s[36:37], 0x1070180
	s_barrier
.LBB0_66:
	ds_read_b128 v[164:167], v160
	ds_read_b128 v[182:185], v160 offset:1024
	ds_read_b128 v[186:189], v160 offset:2048
	ds_read_b128 v[190:193], v160 offset:3072
	v_lshl_add_u64 v[242:243], v[136:137], 0, s[22:23]
	v_lshl_add_u64 v[226:227], v[242:243], 0, s[78:79]
	s_add_u32 m0, s32, 0xc000
	v_lshl_add_u64 v[244:245], v[134:135], 0, s[22:23]
	ds_read_b128 v[194:197], v142
	ds_read_b128 v[198:201], v142 offset:1024
	ds_read_b128 v[202:205], v142 offset:2048
	ds_read_b128 v[206:209], v142 offset:3072
	ds_read_b128 v[210:213], v142 offset:4096
	ds_read_b128 v[214:217], v142 offset:5120
	ds_read_b128 v[218:221], v142 offset:6144
	ds_read_b128 v[222:225], v142 offset:7168
	global_load_lds_dwordx4 v[226:227], off
	s_add_u32 m0, s32, 0xe000
	v_lshl_add_u64 v[226:227], v[244:245], 0, s[78:79]
	global_load_lds_dwordx4 v[226:227], off
	s_waitcnt lgkmcnt(8)
	s_barrier
	s_waitcnt lgkmcnt(0)
	v_mfma_f32_16x16x32_bf16 v[126:129], v[194:197], v[164:167], v[126:129]
	v_mfma_f32_16x16x32_bf16 v[122:125], v[194:197], v[186:189], v[122:125]
	v_mfma_f32_16x16x32_bf16 v[118:121], v[202:205], v[164:167], v[118:121]
	v_mfma_f32_16x16x32_bf16 v[114:117], v[202:205], v[186:189], v[114:117]
	v_mfma_f32_16x16x32_bf16 v[110:113], v[210:213], v[164:167], v[110:113]
	v_mfma_f32_16x16x32_bf16 v[106:109], v[210:213], v[186:189], v[106:109]
	v_mfma_f32_16x16x32_bf16 v[102:105], v[218:221], v[164:167], v[102:105]
	v_mfma_f32_16x16x32_bf16 v[98:101], v[218:221], v[186:189], v[98:101]
	v_mfma_f32_16x16x32_bf16 v[126:129], v[198:201], v[182:185], v[126:129]
	v_mfma_f32_16x16x32_bf16 v[122:125], v[198:201], v[190:193], v[122:125]
	v_mfma_f32_16x16x32_bf16 v[118:121], v[206:209], v[182:185], v[118:121]
	v_mfma_f32_16x16x32_bf16 v[114:117], v[206:209], v[190:193], v[114:117]
	v_mfma_f32_16x16x32_bf16 v[110:113], v[214:217], v[182:185], v[110:113]
	v_mfma_f32_16x16x32_bf16 v[106:109], v[214:217], v[190:193], v[106:109]
	v_mfma_f32_16x16x32_bf16 v[102:105], v[222:225], v[182:185], v[102:105]
	v_mfma_f32_16x16x32_bf16 v[98:101], v[222:225], v[190:193], v[98:101]
	s_barrier
	v_lshl_add_u64 v[246:247], v[140:141], 0, s[22:23]
	v_lshl_add_u64 v[248:249], v[246:247], 0, s[48:49]
	s_add_u32 m0, s32, 0x10000
	ds_read_b128 v[226:229], v158
	ds_read_b128 v[230:233], v158 offset:1024
	ds_read_b128 v[234:237], v158 offset:2048
	ds_read_b128 v[238:241], v158 offset:3072
	global_load_lds_dwordx4 v[248:249], off
	v_lshl_add_u64 v[248:249], v[138:139], 0, s[22:23]
	s_add_u32 m0, s32, 0x12000
	v_lshl_add_u64 v[250:251], v[248:249], 0, s[48:49]
	global_load_lds_dwordx4 v[250:251], off
	s_barrier
	s_waitcnt lgkmcnt(0)
	v_mfma_f32_16x16x32_bf16 v[94:97], v[194:197], v[226:229], v[94:97]
	v_mfma_f32_16x16x32_bf16 v[90:93], v[194:197], v[234:237], v[90:93]
	v_mfma_f32_16x16x32_bf16 v[86:89], v[202:205], v[226:229], v[86:89]
	v_mfma_f32_16x16x32_bf16 v[82:85], v[202:205], v[234:237], v[82:85]
	v_mfma_f32_16x16x32_bf16 v[78:81], v[210:213], v[226:229], v[78:81]
	v_mfma_f32_16x16x32_bf16 v[74:77], v[210:213], v[234:237], v[74:77]
	v_mfma_f32_16x16x32_bf16 v[70:73], v[218:221], v[226:229], v[70:73]
	v_mfma_f32_16x16x32_bf16 v[66:69], v[218:221], v[234:237], v[66:69]
	v_mfma_f32_16x16x32_bf16 v[94:97], v[198:201], v[230:233], v[94:97]
	v_mfma_f32_16x16x32_bf16 v[90:93], v[198:201], v[238:241], v[90:93]
	v_mfma_f32_16x16x32_bf16 v[86:89], v[206:209], v[230:233], v[86:89]
	v_mfma_f32_16x16x32_bf16 v[82:85], v[206:209], v[238:241], v[82:85]
	v_mfma_f32_16x16x32_bf16 v[78:81], v[214:217], v[230:233], v[78:81]
	v_mfma_f32_16x16x32_bf16 v[74:77], v[214:217], v[238:241], v[74:77]
	v_mfma_f32_16x16x32_bf16 v[70:73], v[222:225], v[230:233], v[70:73]
	v_mfma_f32_16x16x32_bf16 v[66:69], v[222:225], v[238:241], v[66:69]
	v_lshl_add_u64 v[250:251], v[242:243], 0, s[82:83]
	s_mov_b32 m0, s32
	s_barrier
; #define G_LDA(dst, b, h)                                                                                                  \
;   _Pragma("unroll") for (int m = 0; m < 4; ++m) _Pragma("unroll") for (int k = 0; k < 2; ++k)                             \
;       dst[m][k] = *(const bf16x8*)((const char*)G_SA(b, h) + ((wr * 4 + m) * 2 + k) * 1024 + rdo)
; #define G_LDB(dst, b, h)                                                                                                  \
;   _Pragma("unroll") for (int n = 0; n < 2; ++n) _Pragma("unroll") for (int k = 0; k < 2; ++k)                             \
;       dst[n][k] = *(const bf16x8*)((const char*)G_SB(b, h) + ((wc * 2 + n) * 2 + k) * 1024 + rdo)
; #define G_WAIT_V(n) asm volatile("s_waitcnt vmcnt(" #n ")" ::: "memory")
; #define G_WAIT_L(n) asm volatile("s_waitcnt lgkmcnt(" #n ")" ::: "memory")
; #define G_BAR __builtin_amdgcn_s_barrier()
; #define G_SCHED __builtin_amdgcn_sched_barrier(0)
;     ...
;     G_LDA(At, 0, 1); G_STAGE(G_SA(0, 0), A, oa0, oa1, LDA, 0, KA(tt + 2));
;     G_BAR; G_WAIT_L(0); G_MMA(1, 0, At, B0); G_BAR; G_SCHED;
;     G_STAGE(G_SB(0, 1), B, ob0, ob1, LDB, 128, KB(tt + 2));
;     G_WAIT_V(6); G_BAR; G_MMA(1, 1, At, B1); G_BAR;
;     G_LDB(B0, 1, 0); G_SCHED; G_LDA(At, 1, 0); G_STAGE(G_SA(0, 1), A, oa0, oa1, LDA, 128, KA(tt + 2));
;     G_WAIT_L(8); G_BAR; G_WAIT_L(0); G_MMA(0, 0, At, B0); G_BAR; G_SCHED;
;     G_LDB(B1, 1, 1); G_STAGE(G_SB(1, 0), B, ob0, ob1, LDB, 0, KB(tt + 3));
	ds_read_b128 v[194:197], v142 offset:16384
	ds_read_b128 v[198:201], v142 offset:17408
	ds_read_b128 v[202:205], v142 offset:18432
	ds_read_b128 v[206:209], v142 offset:19456
	ds_read_b128 v[210:213], v142 offset:20480
	ds_read_b128 v[214:217], v142 offset:21504
	ds_read_b128 v[218:221], v142 offset:22528
	ds_read_b128 v[222:225], v142 offset:23552
	global_load_lds_dwordx4 v[250:251], off
	s_add_u32 m0, s32, 0x2000
	v_lshl_add_u64 v[250:251], v[244:245], 0, s[82:83]
	global_load_lds_dwordx4 v[250:251], off
	s_barrier
	s_waitcnt lgkmcnt(0)
	v_mfma_f32_16x16x32_bf16 v[62:65], v[194:197], v[164:167], v[62:65]
	v_mfma_f32_16x16x32_bf16 v[58:61], v[194:197], v[186:189], v[58:61]
	v_mfma_f32_16x16x32_bf16 v[54:57], v[202:205], v[164:167], v[54:57]
	v_mfma_f32_16x16x32_bf16 v[50:53], v[202:205], v[186:189], v[50:53]
	v_mfma_f32_16x16x32_bf16 v[46:49], v[210:213], v[164:167], v[46:49]
	v_mfma_f32_16x16x32_bf16 v[42:45], v[210:213], v[186:189], v[42:45]
	v_mfma_f32_16x16x32_bf16 v[38:41], v[218:221], v[164:167], v[38:41]
	v_mfma_f32_16x16x32_bf16 v[34:37], v[218:221], v[186:189], v[34:37]
	v_mfma_f32_16x16x32_bf16 v[62:65], v[198:201], v[182:185], v[62:65]
	v_mfma_f32_16x16x32_bf16 v[58:61], v[198:201], v[190:193], v[58:61]
	v_mfma_f32_16x16x32_bf16 v[54:57], v[206:209], v[182:185], v[54:57]
	v_mfma_f32_16x16x32_bf16 v[50:53], v[206:209], v[190:193], v[50:53]
	v_mfma_f32_16x16x32_bf16 v[46:49], v[214:217], v[182:185], v[46:49]
	v_mfma_f32_16x16x32_bf16 v[42:45], v[214:217], v[190:193], v[42:45]
	v_mfma_f32_16x16x32_bf16 v[38:41], v[222:225], v[182:185], v[38:41]
	v_mfma_f32_16x16x32_bf16 v[34:37], v[222:225], v[190:193], v[34:37]
	s_barrier
	v_lshl_add_u64 v[164:165], v[246:247], 0, s[24:25]
	s_add_u32 m0, s32, 0x14000
	s_nop 0
	global_load_lds_dwordx4 v[164:165], off
	s_add_u32 m0, s32, 0x16000
	v_lshl_add_u64 v[164:165], v[248:249], 0, s[24:25]
	global_load_lds_dwordx4 v[164:165], off
	s_waitcnt vmcnt(6)
	s_barrier
	v_mfma_f32_16x16x32_bf16 v[30:33], v[194:197], v[226:229], v[30:33]
	v_mfma_f32_16x16x32_bf16 v[26:29], v[194:197], v[234:237], v[26:29]
	v_mfma_f32_16x16x32_bf16 v[22:25], v[202:205], v[226:229], v[22:25]
	v_mfma_f32_16x16x32_bf16 v[18:21], v[202:205], v[234:237], v[18:21]
	v_mfma_f32_16x16x32_bf16 v[14:17], v[210:213], v[226:229], v[14:17]
	v_mfma_f32_16x16x32_bf16 v[10:13], v[210:213], v[234:237], v[10:13]
	v_mfma_f32_16x16x32_bf16 v[6:9], v[218:221], v[226:229], v[6:9]
	v_mfma_f32_16x16x32_bf16 v[2:5], v[218:221], v[234:237], v[2:5]
	v_mfma_f32_16x16x32_bf16 v[30:33], v[198:201], v[230:233], v[30:33]
	v_mfma_f32_16x16x32_bf16 v[26:29], v[198:201], v[238:241], v[26:29]
	v_mfma_f32_16x16x32_bf16 v[22:25], v[206:209], v[230:233], v[22:25]
	v_mfma_f32_16x16x32_bf16 v[18:21], v[206:209], v[238:241], v[18:21]
	v_mfma_f32_16x16x32_bf16 v[14:17], v[214:217], v[230:233], v[14:17]
	v_mfma_f32_16x16x32_bf16 v[10:13], v[214:217], v[238:241], v[10:13]
	v_mfma_f32_16x16x32_bf16 v[6:9], v[222:225], v[230:233], v[6:9]
	v_mfma_f32_16x16x32_bf16 v[2:5], v[222:225], v[238:241], v[2:5]
	s_barrier
	ds_read_b128 v[164:167], v149
	ds_read_b128 v[182:185], v149 offset:1024
	ds_read_b128 v[186:189], v149 offset:2048
	ds_read_b128 v[190:193], v149 offset:3072
	v_lshl_add_u64 v[226:227], v[242:243], 0, s[86:87]
	s_add_u32 m0, s32, 0x4000
	ds_read_b128 v[194:197], v142 offset:32768
	ds_read_b128 v[198:201], v142 offset:33792
	ds_read_b128 v[202:205], v142 offset:34816
	ds_read_b128 v[206:209], v142 offset:35840
	ds_read_b128 v[210:213], v142 offset:36864
	ds_read_b128 v[214:217], v142 offset:37888
	ds_read_b128 v[218:221], v142 offset:38912
	ds_read_b128 v[222:225], v142 offset:39936
	global_load_lds_dwordx4 v[226:227], off
	s_add_u32 m0, s32, 0x6000
	v_lshl_add_u64 v[226:227], v[244:245], 0, s[86:87]
	global_load_lds_dwordx4 v[226:227], off
	s_waitcnt lgkmcnt(8)
	s_barrier
	s_waitcnt lgkmcnt(0)
	v_mfma_f32_16x16x32_bf16 v[126:129], v[194:197], v[164:167], v[126:129]
	v_mfma_f32_16x16x32_bf16 v[122:125], v[194:197], v[186:189], v[122:125]
	v_mfma_f32_16x16x32_bf16 v[118:121], v[202:205], v[164:167], v[118:121]
	v_mfma_f32_16x16x32_bf16 v[114:117], v[202:205], v[186:189], v[114:117]
	v_mfma_f32_16x16x32_bf16 v[110:113], v[210:213], v[164:167], v[110:113]
	v_mfma_f32_16x16x32_bf16 v[106:109], v[210:213], v[186:189], v[106:109]
	v_mfma_f32_16x16x32_bf16 v[102:105], v[218:221], v[164:167], v[102:105]
	v_mfma_f32_16x16x32_bf16 v[98:101], v[218:221], v[186:189], v[98:101]
	v_mfma_f32_16x16x32_bf16 v[126:129], v[198:201], v[182:185], v[126:129]
	v_mfma_f32_16x16x32_bf16 v[122:125], v[198:201], v[190:193], v[122:125]
	v_mfma_f32_16x16x32_bf16 v[118:121], v[206:209], v[182:185], v[118:121]
	v_mfma_f32_16x16x32_bf16 v[114:117], v[206:209], v[190:193], v[114:117]
	v_mfma_f32_16x16x32_bf16 v[110:113], v[214:217], v[182:185], v[110:113]
	v_mfma_f32_16x16x32_bf16 v[106:109], v[214:217], v[190:193], v[106:109]
	v_mfma_f32_16x16x32_bf16 v[102:105], v[222:225], v[182:185], v[102:105]
	v_mfma_f32_16x16x32_bf16 v[98:101], v[222:225], v[190:193], v[98:101]
	s_barrier
	v_lshl_add_u64 v[250:251], v[246:247], 0, s[26:27]
	s_add_u32 m0, s32, 0x18000
	ds_read_b128 v[226:229], v145
	ds_read_b128 v[230:233], v145 offset:1024
	ds_read_b128 v[234:237], v145 offset:2048
	ds_read_b128 v[238:241], v145 offset:3072
	global_load_lds_dwordx4 v[250:251], off
	s_add_u32 m0, s32, 0x1a000
	v_lshl_add_u64 v[250:251], v[248:249], 0, s[26:27]
	global_load_lds_dwordx4 v[250:251], off
	s_barrier
; #define G_LDA(dst, b, h)                                                                                                  \
;   _Pragma("unroll") for (int m = 0; m < 4; ++m) _Pragma("unroll") for (int k = 0; k < 2; ++k)                             \
;       dst[m][k] = *(const bf16x8*)((const char*)G_SA(b, h) + ((wr * 4 + m) * 2 + k) * 1024 + rdo)
; #define G_LDB(dst, b, h)                                                                                                  \
;   _Pragma("unroll") for (int n = 0; n < 2; ++n) _Pragma("unroll") for (int k = 0; k < 2; ++k)                             \
;       dst[n][k] = *(const bf16x8*)((const char*)G_SB(b, h) + ((wc * 2 + n) * 2 + k) * 1024 + rdo)
; #define G_WAIT_V(n) asm volatile("s_waitcnt vmcnt(" #n ")" ::: "memory")
; #define G_WAIT_L(n) asm volatile("s_waitcnt lgkmcnt(" #n ")" ::: "memory")
; #define G_BAR __builtin_amdgcn_s_barrier()
; #define G_SCHED __builtin_amdgcn_sched_barrier(0)
; DI void br_flush(PREF p, f32x4 (&acc)[2][2][4][2], int slot) { br_store(p, acc, slot); zero_acc256(acc); }
;     ...
;     G_LDB(B1, 1, 1); G_STAGE(G_SB(1, 0), B, ob0, ob1, LDB, 0, KB(tt + 3));
;     G_BAR; G_WAIT_L(0); G_MMA(0, 1, At, B1); G_BAR;
;     G_LDA(At, 1, 1); G_STAGE(G_SA(1, 0), A, oa0, oa1, LDA, 0, KA(tt + 3));
;     G_BAR; G_WAIT_L(0); G_MMA(1, 0, At, B0); G_BAR; G_SCHED;
;     G_STAGE(G_SB(1, 1), B, ob0, ob1, LDB, 128, KB(tt + 3));
;     G_WAIT_V(6); G_BAR; G_MMA(1, 1, At, B1); G_BAR;
;     if (MODE && ((tt + 1) & 3) == 3) br_flush(p, acc, (tt + 1) >> 2);
;   }
;   {
;     G_LDB(B0, 0, 0); G_LDA(At, 0, 0); G_STAGE(G_SA(1, 1), A, oa0, oa1, LDA, 128, KA(nt - 1));
;     G_BAR; G_WAIT_L(0); G_MMA(0, 0, At, B0); G_BAR;
;     G_LDB(B1, 0, 1); G_BAR; G_WAIT_L(0); G_MMA(0, 1, At, B1); G_BAR;
;     G_LDA(At, 0, 1); G_WAIT_V(4); G_BAR; G_WAIT_L(0); G_MMA(1, 0, At, B0); G_MMA(1, 1, At, B1); G_BAR;
	s_waitcnt lgkmcnt(0)
	v_mfma_f32_16x16x32_bf16 v[94:97], v[194:197], v[226:229], v[94:97]
	v_mfma_f32_16x16x32_bf16 v[90:93], v[194:197], v[234:237], v[90:93]
	v_mfma_f32_16x16x32_bf16 v[86:89], v[202:205], v[226:229], v[86:89]
	v_mfma_f32_16x16x32_bf16 v[82:85], v[202:205], v[234:237], v[82:85]
	v_mfma_f32_16x16x32_bf16 v[78:81], v[210:213], v[226:229], v[78:81]
	v_mfma_f32_16x16x32_bf16 v[74:77], v[210:213], v[234:237], v[74:77]
	v_mfma_f32_16x16x32_bf16 v[70:73], v[218:221], v[226:229], v[70:73]
	v_mfma_f32_16x16x32_bf16 v[66:69], v[218:221], v[234:237], v[66:69]
	v_mfma_f32_16x16x32_bf16 v[94:97], v[198:201], v[230:233], v[94:97]
	v_mfma_f32_16x16x32_bf16 v[90:93], v[198:201], v[238:241], v[90:93]
	v_mfma_f32_16x16x32_bf16 v[86:89], v[206:209], v[230:233], v[86:89]
	v_mfma_f32_16x16x32_bf16 v[82:85], v[206:209], v[238:241], v[82:85]
	v_mfma_f32_16x16x32_bf16 v[78:81], v[214:217], v[230:233], v[78:81]
	v_mfma_f32_16x16x32_bf16 v[74:77], v[214:217], v[238:241], v[74:77]
	v_mfma_f32_16x16x32_bf16 v[70:73], v[222:225], v[230:233], v[70:73]
	v_mfma_f32_16x16x32_bf16 v[66:69], v[222:225], v[238:241], v[66:69]
	v_lshl_add_u64 v[242:243], v[242:243], 0, s[90:91]
	s_add_u32 m0, s32, 0x8000
	s_barrier
	ds_read_b128 v[194:197], v142 offset:49152
	ds_read_b128 v[198:201], v142 offset:50176
	ds_read_b128 v[202:205], v142 offset:51200
	ds_read_b128 v[206:209], v142 offset:52224
	ds_read_b128 v[210:213], v142 offset:53248
	ds_read_b128 v[214:217], v142 offset:54272
	ds_read_b128 v[218:221], v142 offset:55296
	ds_read_b128 v[222:225], v142 offset:56320
	global_load_lds_dwordx4 v[242:243], off
	s_add_u32 m0, s32, 0xa000
	v_lshl_add_u64 v[242:243], v[244:245], 0, s[90:91]
	global_load_lds_dwordx4 v[242:243], off
	s_barrier
	s_waitcnt lgkmcnt(0)
	v_mfma_f32_16x16x32_bf16 v[62:65], v[194:197], v[164:167], v[62:65]
	v_mfma_f32_16x16x32_bf16 v[58:61], v[194:197], v[186:189], v[58:61]
	v_mfma_f32_16x16x32_bf16 v[54:57], v[202:205], v[164:167], v[54:57]
	v_mfma_f32_16x16x32_bf16 v[50:53], v[202:205], v[186:189], v[50:53]
	v_mfma_f32_16x16x32_bf16 v[46:49], v[210:213], v[164:167], v[46:49]
	v_mfma_f32_16x16x32_bf16 v[42:45], v[210:213], v[186:189], v[42:45]
	v_mfma_f32_16x16x32_bf16 v[38:41], v[218:221], v[164:167], v[38:41]
	v_mfma_f32_16x16x32_bf16 v[34:37], v[218:221], v[186:189], v[34:37]
	v_mfma_f32_16x16x32_bf16 v[62:65], v[198:201], v[182:185], v[62:65]
	v_mfma_f32_16x16x32_bf16 v[58:61], v[198:201], v[190:193], v[58:61]
	v_mfma_f32_16x16x32_bf16 v[54:57], v[206:209], v[182:185], v[54:57]
	v_mfma_f32_16x16x32_bf16 v[50:53], v[206:209], v[190:193], v[50:53]
	v_mfma_f32_16x16x32_bf16 v[46:49], v[214:217], v[182:185], v[46:49]
	v_mfma_f32_16x16x32_bf16 v[42:45], v[214:217], v[190:193], v[42:45]
	v_mfma_f32_16x16x32_bf16 v[38:41], v[222:225], v[182:185], v[38:41]
	v_mfma_f32_16x16x32_bf16 v[34:37], v[222:225], v[190:193], v[34:37]
	s_barrier
	v_lshl_add_u64 v[164:165], v[246:247], 0, s[36:37]
	s_add_u32 m0, s32, 0x1c000
	s_nop 0
	global_load_lds_dwordx4 v[164:165], off
	s_add_u32 m0, s32, 0x1e000
	v_lshl_add_u64 v[164:165], v[248:249], 0, s[36:37]
	global_load_lds_dwordx4 v[164:165], off
	s_waitcnt vmcnt(6)
	s_barrier
	v_mfma_f32_16x16x32_bf16 v[30:33], v[194:197], v[226:229], v[30:33]
	v_mfma_f32_16x16x32_bf16 v[26:29], v[194:197], v[234:237], v[26:29]
	v_mfma_f32_16x16x32_bf16 v[22:25], v[202:205], v[226:229], v[22:25]
	v_mfma_f32_16x16x32_bf16 v[18:21], v[202:205], v[234:237], v[18:21]
	v_mfma_f32_16x16x32_bf16 v[14:17], v[210:213], v[226:229], v[14:17]
	v_mfma_f32_16x16x32_bf16 v[10:13], v[210:213], v[234:237], v[10:13]
	v_mfma_f32_16x16x32_bf16 v[6:9], v[218:221], v[226:229], v[6:9]
	v_mfma_f32_16x16x32_bf16 v[2:5], v[218:221], v[234:237], v[2:5]
	v_mfma_f32_16x16x32_bf16 v[30:33], v[198:201], v[230:233], v[30:33]
	v_mfma_f32_16x16x32_bf16 v[26:29], v[198:201], v[238:241], v[26:29]
	v_mfma_f32_16x16x32_bf16 v[22:25], v[206:209], v[230:233], v[22:25]
	v_mfma_f32_16x16x32_bf16 v[18:21], v[206:209], v[238:241], v[18:21]
	v_mfma_f32_16x16x32_bf16 v[14:17], v[214:217], v[230:233], v[14:17]
	v_mfma_f32_16x16x32_bf16 v[10:13], v[214:217], v[238:241], v[10:13]
	v_mfma_f32_16x16x32_bf16 v[6:9], v[222:225], v[230:233], v[6:9]
	v_mfma_f32_16x16x32_bf16 v[2:5], v[222:225], v[238:241], v[2:5]
	s_add_i32 s9, s9, 2
	s_add_u32 s22, s22, 0x100
	s_addc_u32 s23, s23, 0
	s_cmp_lt_u32 s9, 12
	s_barrier
	s_cbranch_scc1 .LBB0_66
	s_add_u32 s0, s20, 0x40780
	s_addc_u32 s1, s21, 0
	v_lshl_add_u64 v[132:133], v[132:133], 1, s[0:1]
	s_add_u32 m0, s32, 0xc000
	v_lshl_add_u64 v[130:131], v[130:131], 1, s[0:1]
	ds_read_b128 v[134:137], v160
	ds_read_b128 v[138:141], v160 offset:1024
	ds_read_b128 v[150:153], v160 offset:2048
	ds_read_b128 v[154:157], v160 offset:3072
	ds_read_b128 v[164:167], v142
	ds_read_b128 v[182:185], v142 offset:1024
	ds_read_b128 v[186:189], v142 offset:2048
	ds_read_b128 v[190:193], v142 offset:3072
	ds_read_b128 v[194:197], v142 offset:4096
	ds_read_b128 v[198:201], v142 offset:5120
	ds_read_b128 v[202:205], v142 offset:6144
	ds_read_b128 v[206:209], v142 offset:7168
	global_load_lds_dwordx4 v[132:133], off
	s_add_u32 m0, s32, 0xe000
	s_nop 0
	global_load_lds_dwordx4 v[130:131], off
	s_barrier
; #define G_LDA(dst, b, h)                                                                                                  \
;   _Pragma("unroll") for (int m = 0; m < 4; ++m) _Pragma("unroll") for (int k = 0; k < 2; ++k)                             \
;       dst[m][k] = *(const bf16x8*)((const char*)G_SA(b, h) + ((wr * 4 + m) * 2 + k) * 1024 + rdo)
; #define G_LDB(dst, b, h)                                                                                                  \
;   _Pragma("unroll") for (int n = 0; n < 2; ++n) _Pragma("unroll") for (int k = 0; k < 2; ++k)                             \
;       dst[n][k] = *(const bf16x8*)((const char*)G_SB(b, h) + ((wc * 2 + n) * 2 + k) * 1024 + rdo)
; #define G_WAIT_V(n) asm volatile("s_waitcnt vmcnt(" #n ")" ::: "memory")
; #define G_WAIT_L(n) asm volatile("s_waitcnt lgkmcnt(" #n ")" ::: "memory")
; #define G_BAR __builtin_amdgcn_s_barrier()
;     ...
;     G_LDB(B0, 0, 0); G_LDA(At, 0, 0); G_STAGE(G_SA(1, 1), A, oa0, oa1, LDA, 128, KA(nt - 1));
;     G_BAR; G_WAIT_L(0); G_MMA(0, 0, At, B0); G_BAR;
;     G_LDB(B1, 0, 1); G_BAR; G_WAIT_L(0); G_MMA(0, 1, At, B1); G_BAR;
;     G_LDA(At, 0, 1); G_WAIT_V(4); G_BAR; G_WAIT_L(0); G_MMA(1, 0, At, B0); G_MMA(1, 1, At, B1); G_BAR;
	s_waitcnt lgkmcnt(0)
	v_mfma_f32_16x16x32_bf16 v[126:129], v[164:167], v[134:137], v[126:129]
	v_mfma_f32_16x16x32_bf16 v[122:125], v[164:167], v[150:153], v[122:125]
	v_mfma_f32_16x16x32_bf16 v[110:113], v[194:197], v[134:137], v[110:113]
	v_mfma_f32_16x16x32_bf16 v[102:105], v[202:205], v[134:137], v[102:105]
	v_mfma_f32_16x16x32_bf16 v[126:129], v[182:185], v[138:141], v[126:129]
	v_mfma_f32_16x16x32_bf16 v[122:125], v[182:185], v[154:157], v[122:125]
	v_mfma_f32_16x16x32_bf16 v[118:121], v[186:189], v[134:137], v[118:121]
	v_mfma_f32_16x16x32_bf16 v[114:117], v[186:189], v[150:153], v[114:117]
	v_mfma_f32_16x16x32_bf16 v[110:113], v[198:201], v[138:141], v[110:113]
	v_mfma_f32_16x16x32_bf16 v[106:109], v[194:197], v[150:153], v[106:109]
	v_mfma_f32_16x16x32_bf16 v[102:105], v[206:209], v[138:141], v[102:105]
	v_mfma_f32_16x16x32_bf16 v[98:101], v[202:205], v[150:153], v[98:101]
	v_mfma_f32_16x16x32_bf16 v[130:133], v[190:193], v[138:141], v[118:121]
	v_mfma_f32_16x16x32_bf16 v[210:213], v[190:193], v[154:157], v[114:117]
	v_mfma_f32_16x16x32_bf16 v[214:217], v[198:201], v[154:157], v[106:109]
	v_mfma_f32_16x16x32_bf16 v[218:221], v[206:209], v[154:157], v[98:101]
	s_barrier
	s_nop 1
	s_nop 0
	ds_read_b128 v[98:101], v158
	ds_read_b128 v[106:109], v158 offset:1024
	ds_read_b128 v[114:117], v158 offset:2048
	ds_read_b128 v[118:121], v158 offset:3072
	s_barrier
	s_waitcnt lgkmcnt(0)
	v_mfma_f32_16x16x32_bf16 v[94:97], v[164:167], v[98:101], v[94:97]
	v_mfma_f32_16x16x32_bf16 v[90:93], v[164:167], v[114:117], v[90:93]
	v_mfma_f32_16x16x32_bf16 v[78:81], v[194:197], v[98:101], v[78:81]
	v_mfma_f32_16x16x32_bf16 v[70:73], v[202:205], v[98:101], v[70:73]
	v_mfma_f32_16x16x32_bf16 v[94:97], v[182:185], v[106:109], v[94:97]
	v_mfma_f32_16x16x32_bf16 v[90:93], v[182:185], v[118:121], v[90:93]
	v_mfma_f32_16x16x32_bf16 v[86:89], v[186:189], v[98:101], v[86:89]
	v_mfma_f32_16x16x32_bf16 v[82:85], v[186:189], v[114:117], v[82:85]
	v_mfma_f32_16x16x32_bf16 v[78:81], v[198:201], v[106:109], v[78:81]
	v_mfma_f32_16x16x32_bf16 v[74:77], v[194:197], v[114:117], v[74:77]
	v_mfma_f32_16x16x32_bf16 v[70:73], v[206:209], v[106:109], v[70:73]
	v_mfma_f32_16x16x32_bf16 v[66:69], v[202:205], v[114:117], v[66:69]
	v_mfma_f32_16x16x32_bf16 v[158:161], v[190:193], v[106:109], v[86:89]
	v_mfma_f32_16x16x32_bf16 v[164:167], v[190:193], v[118:121], v[82:85]
	v_mfma_f32_16x16x32_bf16 v[182:185], v[198:201], v[118:121], v[74:77]
	v_mfma_f32_16x16x32_bf16 v[186:189], v[206:209], v[118:121], v[66:69]
	s_barrier
	s_nop 1
	s_nop 0
	ds_read_b128 v[66:69], v142 offset:16384
	ds_read_b128 v[74:77], v142 offset:17408
	ds_read_b128 v[82:85], v142 offset:18432
	ds_read_b128 v[86:89], v142 offset:19456
	ds_read_b128 v[190:193], v142 offset:20480
	ds_read_b128 v[194:197], v142 offset:21504
	ds_read_b128 v[198:201], v142 offset:22528
	ds_read_b128 v[202:205], v142 offset:23552
	s_waitcnt vmcnt(4)
	s_barrier
	s_waitcnt lgkmcnt(0)
	v_mfma_f32_16x16x32_bf16 v[62:65], v[66:69], v[134:137], v[62:65]
	v_mfma_f32_16x16x32_bf16 v[58:61], v[66:69], v[150:153], v[58:61]
	v_mfma_f32_16x16x32_bf16 v[46:49], v[190:193], v[134:137], v[46:49]
	v_mfma_f32_16x16x32_bf16 v[38:41], v[198:201], v[134:137], v[38:41]
	v_mfma_f32_16x16x32_bf16 v[62:65], v[74:77], v[138:141], v[62:65]
	v_mfma_f32_16x16x32_bf16 v[58:61], v[74:77], v[154:157], v[58:61]
	v_mfma_f32_16x16x32_bf16 v[54:57], v[82:85], v[134:137], v[54:57]
	v_mfma_f32_16x16x32_bf16 v[50:53], v[82:85], v[150:153], v[50:53]
	v_mfma_f32_16x16x32_bf16 v[46:49], v[194:197], v[138:141], v[46:49]
	v_mfma_f32_16x16x32_bf16 v[42:45], v[190:193], v[150:153], v[42:45]
	v_mfma_f32_16x16x32_bf16 v[38:41], v[202:205], v[138:141], v[38:41]
	v_mfma_f32_16x16x32_bf16 v[34:37], v[198:201], v[150:153], v[34:37]
	v_mfma_f32_16x16x32_bf16 v[206:209], v[86:89], v[138:141], v[54:57]
	v_mfma_f32_16x16x32_bf16 v[222:225], v[86:89], v[154:157], v[50:53]
	v_mfma_f32_16x16x32_bf16 v[226:229], v[194:197], v[154:157], v[42:45]
	v_mfma_f32_16x16x32_bf16 v[134:137], v[202:205], v[154:157], v[34:37]
	v_mfma_f32_16x16x32_bf16 v[30:33], v[66:69], v[98:101], v[30:33]
	v_mfma_f32_16x16x32_bf16 v[26:29], v[66:69], v[114:117], v[26:29]
	v_mfma_f32_16x16x32_bf16 v[14:17], v[190:193], v[98:101], v[14:17]
	v_mfma_f32_16x16x32_bf16 v[6:9], v[198:201], v[98:101], v[6:9]
	v_mfma_f32_16x16x32_bf16 v[30:33], v[74:77], v[106:109], v[30:33]
	v_mfma_f32_16x16x32_bf16 v[26:29], v[74:77], v[118:121], v[26:29]
	v_mfma_f32_16x16x32_bf16 v[22:25], v[82:85], v[98:101], v[22:25]
	v_mfma_f32_16x16x32_bf16 v[18:21], v[82:85], v[114:117], v[18:21]
	v_mfma_f32_16x16x32_bf16 v[14:17], v[194:197], v[106:109], v[14:17]
	v_mfma_f32_16x16x32_bf16 v[10:13], v[190:193], v[114:117], v[10:13]
	v_mfma_f32_16x16x32_bf16 v[6:9], v[202:205], v[106:109], v[6:9]
	v_mfma_f32_16x16x32_bf16 v[2:5], v[198:201], v[114:117], v[2:5]
	v_mfma_f32_16x16x32_bf16 v[138:141], v[86:89], v[106:109], v[22:25]
	v_mfma_f32_16x16x32_bf16 v[150:153], v[86:89], v[118:121], v[18:21]
	v_mfma_f32_16x16x32_bf16 v[154:157], v[194:197], v[118:121], v[10:13]
	v_mfma_f32_16x16x32_bf16 v[190:193], v[202:205], v[118:121], v[2:5]
	s_barrier
; #define G_LDA(dst, b, h)                                                                                                  \
;   _Pragma("unroll") for (int m = 0; m < 4; ++m) _Pragma("unroll") for (int k = 0; k < 2; ++k)                             \
;       dst[m][k] = *(const bf16x8*)((const char*)G_SA(b, h) + ((wr * 4 + m) * 2 + k) * 1024 + rdo)
; #define G_LDB(dst, b, h)                                                                                                  \
;   _Pragma("unroll") for (int n = 0; n < 2; ++n) _Pragma("unroll") for (int k = 0; k < 2; ++k)                             \
;       dst[n][k] = *(const bf16x8*)((const char*)G_SB(b, h) + ((wc * 2 + n) * 2 + k) * 1024 + rdo)
; #define G_WAIT_V(n) asm volatile("s_waitcnt vmcnt(" #n ")" ::: "memory")
; #define G_WAIT_L(n) asm volatile("s_waitcnt lgkmcnt(" #n ")" ::: "memory")
; #define G_BAR __builtin_amdgcn_s_barrier()
;     ...
;     G_LDB(B0, 1, 0); G_LDA(At, 1, 0); G_WAIT_V(2); G_BAR; G_WAIT_L(0); G_MMA(0, 0, At, B0); G_BAR;
;     G_LDB(B1, 1, 1); G_WAIT_V(0); G_BAR; G_WAIT_L(0); G_MMA(0, 1, At, B1); G_BAR;
;     G_LDA(At, 1, 1); G_BAR; G_WAIT_L(0); G_MMA(1, 0, At, B0); G_MMA(1, 1, At, B1); G_BAR;
;   }
;   if (wr == 0) G_BAR;
	s_nop 1
	s_nop 0
	ds_read_b128 v[2:5], v149
	ds_read_b128 v[10:13], v149 offset:1024
	ds_read_b128 v[18:21], v149 offset:2048
	ds_read_b128 v[22:25], v149 offset:3072
	ds_read_b128 v[34:37], v142 offset:32768
	ds_read_b128 v[42:45], v142 offset:33792
	ds_read_b128 v[50:53], v142 offset:34816
	ds_read_b128 v[54:57], v142 offset:35840
	ds_read_b128 v[66:69], v142 offset:36864
	ds_read_b128 v[146:149], v142 offset:37888
	ds_read_b128 v[194:197], v142 offset:38912
	ds_read_b128 v[198:201], v142 offset:39936
	s_waitcnt vmcnt(2)
	s_barrier
	s_waitcnt lgkmcnt(0)
	v_mfma_f32_16x16x32_bf16 v[74:77], v[34:37], v[2:5], v[126:129]
	v_mfma_f32_16x16x32_bf16 v[118:121], v[42:45], v[10:13], v[74:77]
	v_mfma_f32_16x16x32_bf16 v[74:77], v[34:37], v[18:21], v[122:125]
	v_mfma_f32_16x16x32_bf16 v[126:129], v[42:45], v[22:25], v[74:77]
	v_mfma_f32_16x16x32_bf16 v[74:77], v[50:53], v[2:5], v[130:133]
	v_mfma_f32_16x16x32_bf16 v[114:117], v[54:57], v[10:13], v[74:77]
	v_mfma_f32_16x16x32_bf16 v[74:77], v[50:53], v[18:21], v[210:213]
	v_mfma_f32_16x16x32_bf16 v[122:125], v[54:57], v[22:25], v[74:77]
	v_mfma_f32_16x16x32_bf16 v[74:77], v[66:69], v[2:5], v[110:113]
	v_mfma_f32_16x16x32_bf16 v[106:109], v[146:149], v[10:13], v[74:77]
	v_mfma_f32_16x16x32_bf16 v[74:77], v[66:69], v[18:21], v[214:217]
	v_mfma_f32_16x16x32_bf16 v[110:113], v[146:149], v[22:25], v[74:77]
	v_mfma_f32_16x16x32_bf16 v[74:77], v[194:197], v[2:5], v[102:105]
	v_mfma_f32_16x16x32_bf16 v[98:101], v[198:201], v[10:13], v[74:77]
	v_mfma_f32_16x16x32_bf16 v[74:77], v[194:197], v[18:21], v[218:221]
	v_mfma_f32_16x16x32_bf16 v[102:105], v[198:201], v[22:25], v[74:77]
	s_barrier
	ds_read_b128 v[130:133], v145
	ds_read_b128 v[202:205], v145 offset:1024
	ds_read_b128 v[210:213], v145 offset:2048
	ds_read_b128 v[214:217], v145 offset:3072
	s_waitcnt vmcnt(0)
	s_barrier
	s_waitcnt lgkmcnt(0)
	v_mfma_f32_16x16x32_bf16 v[74:77], v[34:37], v[130:133], v[94:97]
	v_mfma_f32_16x16x32_bf16 v[34:37], v[34:37], v[210:213], v[90:93]
	v_mfma_f32_16x16x32_bf16 v[94:97], v[42:45], v[214:217], v[34:37]
	v_mfma_f32_16x16x32_bf16 v[34:37], v[50:53], v[130:133], v[158:161]
	v_mfma_f32_16x16x32_bf16 v[82:85], v[54:57], v[202:205], v[34:37]
	v_mfma_f32_16x16x32_bf16 v[34:37], v[50:53], v[210:213], v[164:167]
	v_mfma_f32_16x16x32_bf16 v[90:93], v[54:57], v[214:217], v[34:37]
	v_mfma_f32_16x16x32_bf16 v[34:37], v[66:69], v[130:133], v[78:81]
	v_mfma_f32_16x16x32_bf16 v[86:89], v[42:45], v[202:205], v[74:77]
	v_mfma_f32_16x16x32_bf16 v[74:77], v[146:149], v[202:205], v[34:37]
	v_mfma_f32_16x16x32_bf16 v[34:37], v[66:69], v[210:213], v[182:185]
	v_mfma_f32_16x16x32_bf16 v[78:81], v[146:149], v[214:217], v[34:37]
	v_mfma_f32_16x16x32_bf16 v[34:37], v[194:197], v[130:133], v[70:73]
	v_mfma_f32_16x16x32_bf16 v[66:69], v[198:201], v[202:205], v[34:37]
	v_mfma_f32_16x16x32_bf16 v[34:37], v[194:197], v[210:213], v[186:189]
	v_mfma_f32_16x16x32_bf16 v[70:73], v[198:201], v[214:217], v[34:37]
	s_barrier
	ds_read_b128 v[144:147], v142 offset:49152
	ds_read_b128 v[158:161], v142 offset:50176
	ds_read_b128 v[164:167], v142 offset:51200
	ds_read_b128 v[182:185], v142 offset:52224
	ds_read_b128 v[186:189], v142 offset:53248
	ds_read_b128 v[194:197], v142 offset:54272
	ds_read_b128 v[198:201], v142 offset:55296
	ds_read_b128 v[218:221], v142 offset:56320
	s_barrier
	s_waitcnt lgkmcnt(0)
	v_mfma_f32_16x16x32_bf16 v[34:37], v[144:147], v[2:5], v[62:65]
	v_mfma_f32_16x16x32_bf16 v[54:57], v[158:161], v[10:13], v[34:37]
	v_mfma_f32_16x16x32_bf16 v[34:37], v[144:147], v[18:21], v[58:61]
	v_mfma_f32_16x16x32_bf16 v[62:65], v[158:161], v[22:25], v[34:37]
	v_mfma_f32_16x16x32_bf16 v[34:37], v[164:167], v[2:5], v[206:209]
	v_mfma_f32_16x16x32_bf16 v[50:53], v[182:185], v[10:13], v[34:37]
	v_mfma_f32_16x16x32_bf16 v[34:37], v[164:167], v[18:21], v[222:225]
	v_mfma_f32_16x16x32_bf16 v[58:61], v[182:185], v[22:25], v[34:37]
	v_mfma_f32_16x16x32_bf16 v[34:37], v[186:189], v[2:5], v[46:49]
	v_mfma_f32_16x16x32_bf16 v[42:45], v[194:197], v[10:13], v[34:37]
	v_mfma_f32_16x16x32_bf16 v[34:37], v[186:189], v[18:21], v[226:229]
	v_mfma_f32_16x16x32_bf16 v[2:5], v[198:201], v[2:5], v[38:41]
	v_mfma_f32_16x16x32_bf16 v[46:49], v[194:197], v[22:25], v[34:37]
	v_mfma_f32_16x16x32_bf16 v[34:37], v[218:221], v[10:13], v[2:5]
	v_mfma_f32_16x16x32_bf16 v[2:5], v[198:201], v[18:21], v[134:137]
	v_mfma_f32_16x16x32_bf16 v[38:41], v[218:221], v[22:25], v[2:5]
	v_mfma_f32_16x16x32_bf16 v[2:5], v[144:147], v[130:133], v[30:33]
	v_mfma_f32_16x16x32_bf16 v[22:25], v[158:161], v[202:205], v[2:5]
	v_mfma_f32_16x16x32_bf16 v[2:5], v[144:147], v[210:213], v[26:29]
	v_mfma_f32_16x16x32_bf16 v[30:33], v[158:161], v[214:217], v[2:5]
	v_mfma_f32_16x16x32_bf16 v[2:5], v[164:167], v[130:133], v[138:141]
	v_mfma_f32_16x16x32_bf16 v[18:21], v[182:185], v[202:205], v[2:5]
	v_mfma_f32_16x16x32_bf16 v[2:5], v[164:167], v[210:213], v[150:153]
	v_mfma_f32_16x16x32_bf16 v[26:29], v[182:185], v[214:217], v[2:5]
	v_mfma_f32_16x16x32_bf16 v[2:5], v[186:189], v[130:133], v[14:17]
	v_mfma_f32_16x16x32_bf16 v[10:13], v[194:197], v[202:205], v[2:5]
	v_mfma_f32_16x16x32_bf16 v[2:5], v[186:189], v[210:213], v[154:157]
	v_mfma_f32_16x16x32_bf16 v[14:17], v[194:197], v[214:217], v[2:5]
	v_mfma_f32_16x16x32_bf16 v[2:5], v[198:201], v[130:133], v[6:9]
	v_mfma_f32_16x16x32_bf16 v[6:9], v[198:201], v[210:213], v[190:193]
	v_mfma_f32_16x16x32_bf16 v[2:5], v[218:221], v[202:205], v[2:5]
	v_mfma_f32_16x16x32_bf16 v[6:9], v[218:221], v[214:217], v[6:9]
	v_cmp_gt_u32_e32 vcc, s67, v0
	s_barrier
	s_and_saveexec_b64 s[20:21], vcc
	s_cbranch_execz .LBB0_69
	s_barrier

; DI void lds_barrier() { asm volatile("s_waitcnt lgkmcnt(0)\n\ts_barrier" ::: "memory"); }
; DI int tid512() { int t = threadIdx.x; asm volatile("" : "+v"(t)); return t; }
; #define G_WAIT_V(n) asm volatile("s_waitcnt vmcnt(" #n ")" ::: "memory")
; #define G_BAR __builtin_amdgcn_s_barrier()
;     ...
;   const int t = tid512();
;   const int wid = t >> 6, lane = t & 63, wr = wid >> 2, wc = wid & 3, fr = lane & 15, fq = lane >> 4;
;   int r0, c0, r1, c1;
;   g_stage_rc(t * 16, r0, c0); g_stage_rc(t * 16 + 8192, r1, c1);
;   const int oa0 = r0 * LDA + c0, oa1 = r1 * LDA + c1, ob0 = r0 * LDB + c0, ob1 = r1 * LDB + c1;
;   const int obr = fr * 64 + fq * 16, rdo = obr ^ (((obr >> 9) & 1) << 5);
;   bf16x8 At[4][2], B0[2][2], B1[2][2];
;   constexpr int nt = K / 64;
;   lds_barrier();
;   G_STAGE(G_SB(0, 0), B, ob0, ob1, LDB, 0, KB(0)); G_STAGE(G_SA(0, 0), A, oa0, oa1, LDA, 0, KA(0));
;   G_STAGE(G_SB(0, 1), B, ob0, ob1, LDB, 128, KB(0)); G_STAGE(G_SA(0, 1), A, oa0, oa1, LDA, 128, KA(0));
;   if (wr == 1) G_BAR;
;   G_WAIT_V(4); G_BAR;
;   G_STAGE(G_SB(1, 0), B, ob0, ob1, LDB, 0, KB(1)); G_STAGE(G_SA(1, 0), A, oa0, oa1, LDA, 0, KA(1)); G_STAGE(G_SB(1, 1), B, ob0, ob1, LDB, 128, KB(1));
;   G_WAIT_V(6); G_BAR;
; DI void zero_acc256(f32x4 (&a)[2][2][4][2]) {
; #pragma unroll
;   for (int i = 0; i < 2; ++i)
; #pragma unroll
;     for (int j = 0; j < 2; ++j)
; #pragma unroll
;       for (int m = 0; m < 4; ++m)
; #pragma unroll
;         for (int n = 0; n < 2; ++n)
; #pragma unroll
;           for (int e = 0; e < 4; ++e) a[i][j][m][n][e] = 0.f;
; }
.LBB0_102:
	s_lshl_b32 s52, s23, 6
	s_add_u32 s0, s52, s28
	v_mov_b32_e32 v0, v168
	s_addc_u32 s1, 0, s29
	s_lshl_b64 s[0:1], s[0:1], 11
	v_lshlrev_b32_e32 v143, 4, v0
	s_nop 0
	v_readfirstlane_b32 s32, v143
	v_and_b32_e32 v2, 32, v0
	v_lshrrev_b32_e32 v4, 1, v0
	v_bitop3_b32 v2, v143, v2, 48 bitop3:0x6c
	s_add_u32 s8, s65, s0
	v_ashrrev_i32_e32 v10, 3, v0
	v_bfe_u32 v13, v0, 2, 4
	s_mov_b32 s0, 0x3ffff0
	v_and_b32_e32 v11, 32, v4
	v_lshrrev_b32_e32 v12, 1, v2
	v_add_u32_e32 v144, 0x2000, v143
	v_and_or_b32 v3, v10, s0, v13
	v_or_b32_e32 v2, v12, v11
	v_ashrrev_i32_e32 v15, 7, v144
	v_and_or_b32 v4, v15, s0, v13
	v_lshl_or_b32 v132, v3, 10, v2
	v_lshl_or_b32 v130, v4, 10, v2
	v_bfe_u32 v182, v3, 4, 1
	v_lshlrev_b32_e32 v182, 20, v182
	v_lshrrev_b32_e32 v184, 5, v3
	v_lshlrev_b32_e32 v184, 4, v184
	v_and_b32_e32 v183, 15, v3
	v_add_u32_e32 v184, v184, v183
	v_lshl_or_b32 v182, v184, 10, v182
	v_or_b32_e32 v182, v182, v2
	v_lshlrev_b32_e32 v182, 1, v182
	v_mov_b32_e32 v183, 0
	v_add_u32_e32 v184, 0x10000, v182
	v_mov_b32_e32 v185, 0
	v_ashrrev_i32_e32 v133, 31, v132
	s_addc_u32 s9, s68, s1
	v_lshlrev_b64 v[16:17], 1, v[132:133]
	v_ashrrev_i32_e32 v131, 31, v130
	s_waitcnt lgkmcnt(0)
	s_barrier
	v_lshl_add_u64 v[2:3], s[8:9], 0, v[182:183]
	s_add_u32 m0, s32, 0x10000
	v_lshlrev_b64 v[18:19], 1, v[130:131]
	global_load_lds_dwordx4 v[2:3], off
	v_lshl_add_u64 v[6:7], s[8:9], 0, v[184:185]
	s_add_u32 m0, s32, 0x12000
	s_nop 0
	global_load_lds_dwordx4 v[6:7], off
	v_lshl_add_u64 v[8:9], s[26:27], 0, v[16:17]
	s_mov_b32 m0, s32
	s_nop 0
	global_load_lds_dwordx4 v[8:9], off
	s_add_u32 m0, s32, 0x2000
	s_add_u32 s0, s8, 0x400000
	v_lshl_add_u64 v[4:5], s[26:27], 0, v[18:19]
	s_addc_u32 s1, s9, 0
	global_load_lds_dwordx4 v[4:5], off
	v_lshl_add_u64 v[20:21], s[0:1], 0, v[182:183]
	s_add_u32 m0, s32, 0x14000
	s_nop 0
	global_load_lds_dwordx4 v[20:21], off
	v_lshl_add_u64 v[20:21], s[0:1], 0, v[184:185]
	s_add_u32 m0, s32, 0x16000
	v_add_u32_e32 v152, 0x6000, v143
	global_load_lds_dwordx4 v[20:21], off
	v_lshl_add_u64 v[16:17], s[30:31], 0, v[16:17]
	s_add_u32 m0, s32, 0x4000
	v_readfirstlane_b32 s0, v152
	global_load_lds_dwordx4 v[16:17], off
	v_lshl_add_u64 v[16:17], s[30:31], 0, v[18:19]
	s_add_u32 m0, s32, 0x6000
	v_ashrrev_i32_e32 v14, 8, v0
	global_load_lds_dwordx4 v[16:17], off
	v_cmp_eq_u32_e32 vcc, 1, v14
	s_and_saveexec_b64 s[10:11], vcc
	s_cbranch_execz .LBB0_104
	s_barrier
.LBB0_104:
	s_or_b64 exec, exec, s[10:11]
	v_lshl_add_u64 v[2:3], v[2:3], 0, s[76:77]
	s_add_u32 m0, s32, 0x18000
	s_waitcnt vmcnt(4)
	s_barrier
	global_load_lds_dwordx4 v[2:3], off
	v_lshl_add_u64 v[2:3], v[6:7], 0, s[76:77]
	s_add_u32 m0, s32, 0x1a000
	s_nop 0
	global_load_lds_dwordx4 v[2:3], off
	v_lshl_add_u64 v[2:3], v[8:9], 0, s[76:77]
	s_add_u32 m0, s32, 0x8000
	s_nop 0
	global_load_lds_dwordx4 v[2:3], off
	s_add_u32 m0, s32, 0xa000
	s_add_u32 s0, s8, 0x400080
	v_lshl_add_u64 v[2:3], v[4:5], 0, s[76:77]
	s_addc_u32 s1, s9, 0
	global_load_lds_dwordx4 v[2:3], off
	v_lshl_add_u64 v[2:3], v[182:183], 0, s[0:1]
	s_add_u32 m0, s32, 0x1c000
	s_nop 0
	global_load_lds_dwordx4 v[2:3], off
	v_lshl_add_u64 v[2:3], v[184:185], 0, s[0:1]
	s_add_u32 m0, s32, 0x1e000
	v_lshlrev_b32_e32 v17, 6, v0
	global_load_lds_dwordx4 v[2:3], off
	v_lshlrev_b32_e32 v2, 10, v15
	v_and_b32_e32 v2, 0xffffc000, v2
	v_lshlrev_b32_e32 v4, 10, v13
	v_lshlrev_b32_e32 v5, 10, v10
	v_and_b32_e32 v16, 48, v0
	v_and_b32_e32 v18, 0x3c0, v17
	v_lshlrev_b32_e32 v20, 2, v0
	v_or3_b32 v2, v12, v2, v4
	v_and_b32_e32 v5, 0xffffc000, v5
	v_or_b32_e32 v19, v18, v16
	v_and_b32_e32 v20, 32, v20
	s_mov_b32 s0, 0x14000
	v_add_u32_e32 v2, v2, v11
	v_or3_b32 v4, v12, v5, v4
	v_bitop3_b32 v8, v19, s0, v20 bitop3:0xde
	s_mov_b32 s0, 0x18000
	v_ashrrev_i32_e32 v3, 31, v2
	v_add_u32_e32 v4, v4, v11
	s_waitcnt vmcnt(6)
	v_bitop3_b32 v9, v19, s0, v20 bitop3:0xde
	s_mov_b32 s0, 0x1c000
	v_lshlrev_b64 v[2:3], 1, v[2:3]
	v_ashrrev_i32_e32 v5, 31, v4
	v_bitop3_b32 v16, v18, v20, v16 bitop3:0x36
	v_bitop3_b32 v6, v19, s88, v20 bitop3:0xde
	v_lshlrev_b32_e32 v7, 13, v14
	v_bitop3_b32 v14, v19, s0, v20 bitop3:0xde
	v_and_b32_e32 v17, 0x3000, v17
	v_lshl_add_u64 v[134:135], s[26:27], 0, v[2:3]
	v_lshlrev_b64 v[4:5], 1, v[4:5]
	v_lshl_add_u64 v[138:139], s[40:41], 0, v[184:185]
	v_mov_b32_e32 v2, 0
	v_lshl_add_u64 v[136:137], s[26:27], 0, v[4:5]
	v_lshl_add_u64 v[140:141], s[40:41], 0, v[182:183]
	s_mov_b32 s10, -2
	s_mov_b64 s[8:9], 0
	v_add_u32_e32 v160, v6, v17
	v_add_u32_e32 v142, v16, v7
	v_add_u32_e32 v158, v8, v17
	v_add_u32_e32 v148, v9, v17
	v_add_u32_e32 v145, v14, v17
	v_mov_b32_e32 v3, v2
	v_mov_b32_e32 v4, v2
	v_mov_b32_e32 v5, v2
	v_mov_b32_e32 v6, v2
	v_mov_b32_e32 v7, v2
	v_mov_b32_e32 v8, v2
	v_mov_b32_e32 v9, v2
	v_mov_b32_e32 v10, v2
	v_mov_b32_e32 v11, v2
	v_mov_b32_e32 v12, v2
	v_mov_b32_e32 v13, v2
	v_mov_b32_e32 v14, v2
	v_mov_b32_e32 v15, v2
	v_mov_b32_e32 v16, v2
	v_mov_b32_e32 v17, v2
	v_mov_b32_e32 v18, v2
	v_mov_b32_e32 v19, v2
	v_mov_b32_e32 v20, v2
	v_mov_b32_e32 v21, v2
	v_mov_b32_e32 v22, v2
	v_mov_b32_e32 v23, v2
	v_mov_b32_e32 v24, v2
	v_mov_b32_e32 v25, v2
	v_mov_b32_e32 v26, v2
	v_mov_b32_e32 v27, v2
	v_mov_b32_e32 v28, v2
	v_mov_b32_e32 v29, v2
	v_mov_b32_e32 v30, v2
	v_mov_b32_e32 v31, v2
	v_mov_b32_e32 v32, v2
	v_mov_b32_e32 v33, v2
	v_mov_b32_e32 v34, v2
	v_mov_b32_e32 v35, v2
	v_mov_b32_e32 v36, v2
	v_mov_b32_e32 v37, v2
	v_mov_b32_e32 v38, v2
	v_mov_b32_e32 v39, v2
	v_mov_b32_e32 v40, v2
	v_mov_b32_e32 v41, v2
	v_mov_b32_e32 v42, v2
	v_mov_b32_e32 v43, v2
	v_mov_b32_e32 v44, v2
	v_mov_b32_e32 v45, v2
	v_mov_b32_e32 v46, v2
	v_mov_b32_e32 v47, v2
	v_mov_b32_e32 v48, v2
	v_mov_b32_e32 v49, v2
; #define G_LDA(dst, b, h)                                                                                                  \
;   _Pragma("unroll") for (int m = 0; m < 4; ++m) _Pragma("unroll") for (int k = 0; k < 2; ++k)                             \
;       dst[m][k] = *(const bf16x8*)((const char*)G_SA(b, h) + ((wr * 4 + m) * 2 + k) * 1024 + rdo)
; #define G_LDB(dst, b, h)                                                                                                  \
;   _Pragma("unroll") for (int n = 0; n < 2; ++n) _Pragma("unroll") for (int k = 0; k < 2; ++k)                             \
;       dst[n][k] = *(const bf16x8*)((const char*)G_SB(b, h) + ((wc * 2 + n) * 2 + k) * 1024 + rdo)
; #define G_WAIT_L(n) asm volatile("s_waitcnt lgkmcnt(" #n ")" ::: "memory")
; #define G_BAR __builtin_amdgcn_s_barrier()
; #define G_SCHED __builtin_amdgcn_sched_barrier(0)
;     ...
;   for (int tt = 0; tt < nt - 2; tt += 2) {
;     G_LDB(B0, 0, 0); G_SCHED; G_LDA(At, 0, 0); G_STAGE(G_SA(1, 1), A, oa0, oa1, LDA, 128, KA(tt + 1));
;     G_WAIT_L(8); G_BAR; G_WAIT_L(0); G_MMA(0, 0, At, B0); G_BAR; G_SCHED;
;     G_LDB(B1, 0, 1); G_STAGE(G_SB(0, 0), B, ob0, ob1, LDB, 0, KB(tt + 2));
;     G_BAR; G_WAIT_L(0); G_MMA(0, 1, At, B1); G_BAR;
;     G_LDA(At, 0, 1); G_STAGE(G_SA(0, 0), A, oa0, oa1, LDA, 0, KA(tt + 2));
;     G_BAR; G_WAIT_L(0); G_MMA(1, 0, At, B0); G_BAR; G_SCHED;
; DI void zero_acc256(f32x4 (&a)[2][2][4][2]) {
; #pragma unroll
;   for (int i = 0; i < 2; ++i)
; #pragma unroll
;     for (int j = 0; j < 2; ++j)
; #pragma unroll
;       for (int m = 0; m < 4; ++m)
; #pragma unroll
;         for (int n = 0; n < 2; ++n)
; #pragma unroll
;           for (int e = 0; e < 4; ++e) a[i][j][m][n][e] = 0.f;
; }
	v_mov_b32_e32 v50, v2
	v_mov_b32_e32 v51, v2
	v_mov_b32_e32 v52, v2
	v_mov_b32_e32 v53, v2
	v_mov_b32_e32 v54, v2
	v_mov_b32_e32 v55, v2
	v_mov_b32_e32 v56, v2
	v_mov_b32_e32 v57, v2
	v_mov_b32_e32 v58, v2
	v_mov_b32_e32 v59, v2
	v_mov_b32_e32 v60, v2
	v_mov_b32_e32 v61, v2
	v_mov_b32_e32 v62, v2
	v_mov_b32_e32 v63, v2
	v_mov_b32_e32 v64, v2
	v_mov_b32_e32 v65, v2
	v_mov_b32_e32 v66, v2
	v_mov_b32_e32 v67, v2
	v_mov_b32_e32 v68, v2
	v_mov_b32_e32 v69, v2
	v_mov_b32_e32 v70, v2
	v_mov_b32_e32 v71, v2
	v_mov_b32_e32 v72, v2
	v_mov_b32_e32 v73, v2
	v_mov_b32_e32 v74, v2
	v_mov_b32_e32 v75, v2
	v_mov_b32_e32 v76, v2
	v_mov_b32_e32 v77, v2
	v_mov_b32_e32 v78, v2
	v_mov_b32_e32 v79, v2
	v_mov_b32_e32 v80, v2
	v_mov_b32_e32 v81, v2
	v_mov_b32_e32 v82, v2
	v_mov_b32_e32 v83, v2
	v_mov_b32_e32 v84, v2
	v_mov_b32_e32 v85, v2
	v_mov_b32_e32 v86, v2
	v_mov_b32_e32 v87, v2
	v_mov_b32_e32 v88, v2
	v_mov_b32_e32 v89, v2
	v_mov_b32_e32 v90, v2
	v_mov_b32_e32 v91, v2
	v_mov_b32_e32 v92, v2
	v_mov_b32_e32 v93, v2
	v_mov_b32_e32 v94, v2
	v_mov_b32_e32 v95, v2
	v_mov_b32_e32 v96, v2
	v_mov_b32_e32 v97, v2
	v_mov_b32_e32 v98, v2
	v_mov_b32_e32 v99, v2
	v_mov_b32_e32 v100, v2
	v_mov_b32_e32 v101, v2
	v_mov_b32_e32 v102, v2
	v_mov_b32_e32 v103, v2
	v_mov_b32_e32 v104, v2
	v_mov_b32_e32 v105, v2
	v_mov_b32_e32 v106, v2
	v_mov_b32_e32 v107, v2
	v_mov_b32_e32 v108, v2
	v_mov_b32_e32 v109, v2
	v_mov_b32_e32 v110, v2
	v_mov_b32_e32 v111, v2
	v_mov_b32_e32 v112, v2
	v_mov_b32_e32 v113, v2
	v_mov_b32_e32 v114, v2
	v_mov_b32_e32 v115, v2
	v_mov_b32_e32 v116, v2
	v_mov_b32_e32 v117, v2
	v_mov_b32_e32 v118, v2
	v_mov_b32_e32 v119, v2
	v_mov_b32_e32 v120, v2
	v_mov_b32_e32 v121, v2
	v_mov_b32_e32 v122, v2
	v_mov_b32_e32 v123, v2
	v_mov_b32_e32 v124, v2
	v_mov_b32_e32 v125, v2
	v_mov_b32_e32 v126, v2
	v_mov_b32_e32 v127, v2
	v_mov_b32_e32 v128, v2
	v_mov_b32_e32 v129, v2
	s_barrier
.LBB0_105:
	ds_read_b128 v[164:167], v160
	ds_read_b128 v[182:185], v160 offset:1024
	ds_read_b128 v[186:189], v160 offset:2048
	ds_read_b128 v[190:193], v160 offset:3072
	v_lshl_add_u64 v[242:243], v[136:137], 0, s[8:9]
	v_lshl_add_u64 v[226:227], v[242:243], 0, s[78:79]
	s_add_u32 m0, s32, 0xc000
	v_lshl_add_u64 v[244:245], v[134:135], 0, s[8:9]
	ds_read_b128 v[194:197], v142
	ds_read_b128 v[198:201], v142 offset:1024
	ds_read_b128 v[202:205], v142 offset:2048
	ds_read_b128 v[206:209], v142 offset:3072
	ds_read_b128 v[210:213], v142 offset:4096
	ds_read_b128 v[214:217], v142 offset:5120
	ds_read_b128 v[218:221], v142 offset:6144
	ds_read_b128 v[222:225], v142 offset:7168
	global_load_lds_dwordx4 v[226:227], off
	s_add_u32 m0, s32, 0xe000
	v_lshl_add_u64 v[226:227], v[244:245], 0, s[78:79]
	global_load_lds_dwordx4 v[226:227], off
	s_waitcnt lgkmcnt(8)
	s_barrier
	s_waitcnt lgkmcnt(0)
	v_mfma_f32_16x16x32_bf16 v[126:129], v[194:197], v[164:167], v[126:129]
	v_mfma_f32_16x16x32_bf16 v[122:125], v[194:197], v[186:189], v[122:125]
	v_mfma_f32_16x16x32_bf16 v[118:121], v[202:205], v[164:167], v[118:121]
	v_mfma_f32_16x16x32_bf16 v[114:117], v[202:205], v[186:189], v[114:117]
	v_mfma_f32_16x16x32_bf16 v[110:113], v[210:213], v[164:167], v[110:113]
	v_mfma_f32_16x16x32_bf16 v[106:109], v[210:213], v[186:189], v[106:109]
	v_mfma_f32_16x16x32_bf16 v[102:105], v[218:221], v[164:167], v[102:105]
	v_mfma_f32_16x16x32_bf16 v[98:101], v[218:221], v[186:189], v[98:101]
	v_mfma_f32_16x16x32_bf16 v[126:129], v[198:201], v[182:185], v[126:129]
	v_mfma_f32_16x16x32_bf16 v[122:125], v[198:201], v[190:193], v[122:125]
	v_mfma_f32_16x16x32_bf16 v[118:121], v[206:209], v[182:185], v[118:121]
	v_mfma_f32_16x16x32_bf16 v[114:117], v[206:209], v[190:193], v[114:117]
	v_mfma_f32_16x16x32_bf16 v[110:113], v[214:217], v[182:185], v[110:113]
	v_mfma_f32_16x16x32_bf16 v[106:109], v[214:217], v[190:193], v[106:109]
	v_mfma_f32_16x16x32_bf16 v[102:105], v[222:225], v[182:185], v[102:105]
	v_mfma_f32_16x16x32_bf16 v[98:101], v[222:225], v[190:193], v[98:101]
	s_barrier
	v_lshl_add_u64 v[246:247], v[140:141], 0, s[8:9]
	v_lshl_add_u64 v[248:249], v[246:247], 0, s[50:51]
	s_add_u32 m0, s32, 0x10000
	ds_read_b128 v[226:229], v158
	ds_read_b128 v[230:233], v158 offset:1024
	ds_read_b128 v[234:237], v158 offset:2048
	ds_read_b128 v[238:241], v158 offset:3072
	global_load_lds_dwordx4 v[248:249], off
	v_lshl_add_u64 v[248:249], v[138:139], 0, s[8:9]
	s_add_u32 m0, s32, 0x12000
	v_lshl_add_u64 v[250:251], v[248:249], 0, s[50:51]
	global_load_lds_dwordx4 v[250:251], off
	s_barrier
	s_waitcnt lgkmcnt(0)
	v_mfma_f32_16x16x32_bf16 v[94:97], v[194:197], v[226:229], v[94:97]
	v_mfma_f32_16x16x32_bf16 v[90:93], v[194:197], v[234:237], v[90:93]
	v_mfma_f32_16x16x32_bf16 v[86:89], v[202:205], v[226:229], v[86:89]
	v_mfma_f32_16x16x32_bf16 v[82:85], v[202:205], v[234:237], v[82:85]
	v_mfma_f32_16x16x32_bf16 v[78:81], v[210:213], v[226:229], v[78:81]
	v_mfma_f32_16x16x32_bf16 v[74:77], v[210:213], v[234:237], v[74:77]
	v_mfma_f32_16x16x32_bf16 v[70:73], v[218:221], v[226:229], v[70:73]
	v_mfma_f32_16x16x32_bf16 v[66:69], v[218:221], v[234:237], v[66:69]
	v_mfma_f32_16x16x32_bf16 v[94:97], v[198:201], v[230:233], v[94:97]
	v_mfma_f32_16x16x32_bf16 v[90:93], v[198:201], v[238:241], v[90:93]
	v_mfma_f32_16x16x32_bf16 v[86:89], v[206:209], v[230:233], v[86:89]
	v_mfma_f32_16x16x32_bf16 v[82:85], v[206:209], v[238:241], v[82:85]
	v_mfma_f32_16x16x32_bf16 v[78:81], v[214:217], v[230:233], v[78:81]
	v_mfma_f32_16x16x32_bf16 v[74:77], v[214:217], v[238:241], v[74:77]
	v_mfma_f32_16x16x32_bf16 v[70:73], v[222:225], v[230:233], v[70:73]
	v_mfma_f32_16x16x32_bf16 v[66:69], v[222:225], v[238:241], v[66:69]
	v_lshl_add_u64 v[250:251], v[242:243], 0, s[82:83]
	s_mov_b32 m0, s32
	s_barrier
; #define G_LDA(dst, b, h)                                                                                                  \
;   _Pragma("unroll") for (int m = 0; m < 4; ++m) _Pragma("unroll") for (int k = 0; k < 2; ++k)                             \
;       dst[m][k] = *(const bf16x8*)((const char*)G_SA(b, h) + ((wr * 4 + m) * 2 + k) * 1024 + rdo)
; #define G_LDB(dst, b, h)                                                                                                  \
;   _Pragma("unroll") for (int n = 0; n < 2; ++n) _Pragma("unroll") for (int k = 0; k < 2; ++k)                             \
;       dst[n][k] = *(const bf16x8*)((const char*)G_SB(b, h) + ((wc * 2 + n) * 2 + k) * 1024 + rdo)
; #define G_WAIT_V(n) asm volatile("s_waitcnt vmcnt(" #n ")" ::: "memory")
; #define G_WAIT_L(n) asm volatile("s_waitcnt lgkmcnt(" #n ")" ::: "memory")
; #define G_BAR __builtin_amdgcn_s_barrier()
; #define G_SCHED __builtin_amdgcn_sched_barrier(0)
;     ...
;     G_LDA(At, 0, 1); G_STAGE(G_SA(0, 0), A, oa0, oa1, LDA, 0, KA(tt + 2));
;     G_BAR; G_WAIT_L(0); G_MMA(1, 0, At, B0); G_BAR; G_SCHED;
;     G_STAGE(G_SB(0, 1), B, ob0, ob1, LDB, 128, KB(tt + 2));
;     G_WAIT_V(6); G_BAR; G_MMA(1, 1, At, B1); G_BAR;
;     G_LDB(B0, 1, 0); G_SCHED; G_LDA(At, 1, 0); G_STAGE(G_SA(0, 1), A, oa0, oa1, LDA, 128, KA(tt + 2));
;     G_WAIT_L(8); G_BAR; G_WAIT_L(0); G_MMA(0, 0, At, B0); G_BAR; G_SCHED;
;     G_LDB(B1, 1, 1); G_STAGE(G_SB(1, 0), B, ob0, ob1, LDB, 0, KB(tt + 3));
	ds_read_b128 v[194:197], v142 offset:16384
	ds_read_b128 v[198:201], v142 offset:17408
	ds_read_b128 v[202:205], v142 offset:18432
	ds_read_b128 v[206:209], v142 offset:19456
	ds_read_b128 v[210:213], v142 offset:20480
	ds_read_b128 v[214:217], v142 offset:21504
	ds_read_b128 v[218:221], v142 offset:22528
	ds_read_b128 v[222:225], v142 offset:23552
	global_load_lds_dwordx4 v[250:251], off
	s_add_u32 m0, s32, 0x2000
	v_lshl_add_u64 v[250:251], v[244:245], 0, s[82:83]
	global_load_lds_dwordx4 v[250:251], off
	s_barrier
	s_waitcnt lgkmcnt(0)
	v_mfma_f32_16x16x32_bf16 v[62:65], v[194:197], v[164:167], v[62:65]
	v_mfma_f32_16x16x32_bf16 v[58:61], v[194:197], v[186:189], v[58:61]
	v_mfma_f32_16x16x32_bf16 v[54:57], v[202:205], v[164:167], v[54:57]
	v_mfma_f32_16x16x32_bf16 v[50:53], v[202:205], v[186:189], v[50:53]
	v_mfma_f32_16x16x32_bf16 v[46:49], v[210:213], v[164:167], v[46:49]
	v_mfma_f32_16x16x32_bf16 v[42:45], v[210:213], v[186:189], v[42:45]
	v_mfma_f32_16x16x32_bf16 v[38:41], v[218:221], v[164:167], v[38:41]
	v_mfma_f32_16x16x32_bf16 v[34:37], v[218:221], v[186:189], v[34:37]
	v_mfma_f32_16x16x32_bf16 v[62:65], v[198:201], v[182:185], v[62:65]
	v_mfma_f32_16x16x32_bf16 v[58:61], v[198:201], v[190:193], v[58:61]
	v_mfma_f32_16x16x32_bf16 v[54:57], v[206:209], v[182:185], v[54:57]
	v_mfma_f32_16x16x32_bf16 v[50:53], v[206:209], v[190:193], v[50:53]
	v_mfma_f32_16x16x32_bf16 v[46:49], v[214:217], v[182:185], v[46:49]
	v_mfma_f32_16x16x32_bf16 v[42:45], v[214:217], v[190:193], v[42:45]
	v_mfma_f32_16x16x32_bf16 v[38:41], v[222:225], v[182:185], v[38:41]
	v_mfma_f32_16x16x32_bf16 v[34:37], v[222:225], v[190:193], v[34:37]
	s_barrier
	v_lshl_add_u64 v[164:165], v[246:247], 0, s[38:39]
	s_add_u32 m0, s32, 0x14000
	s_nop 0
	global_load_lds_dwordx4 v[164:165], off
	s_add_u32 m0, s32, 0x16000
	v_lshl_add_u64 v[164:165], v[248:249], 0, s[38:39]
	global_load_lds_dwordx4 v[164:165], off
	s_waitcnt vmcnt(6)
	s_barrier
	v_mfma_f32_16x16x32_bf16 v[30:33], v[194:197], v[226:229], v[30:33]
	v_mfma_f32_16x16x32_bf16 v[26:29], v[194:197], v[234:237], v[26:29]
	v_mfma_f32_16x16x32_bf16 v[22:25], v[202:205], v[226:229], v[22:25]
	v_mfma_f32_16x16x32_bf16 v[18:21], v[202:205], v[234:237], v[18:21]
	v_mfma_f32_16x16x32_bf16 v[14:17], v[210:213], v[226:229], v[14:17]
	v_mfma_f32_16x16x32_bf16 v[10:13], v[210:213], v[234:237], v[10:13]
	v_mfma_f32_16x16x32_bf16 v[6:9], v[218:221], v[226:229], v[6:9]
	v_mfma_f32_16x16x32_bf16 v[2:5], v[218:221], v[234:237], v[2:5]
	v_mfma_f32_16x16x32_bf16 v[30:33], v[198:201], v[230:233], v[30:33]
	v_mfma_f32_16x16x32_bf16 v[26:29], v[198:201], v[238:241], v[26:29]
	v_mfma_f32_16x16x32_bf16 v[22:25], v[206:209], v[230:233], v[22:25]
	v_mfma_f32_16x16x32_bf16 v[18:21], v[206:209], v[238:241], v[18:21]
	v_mfma_f32_16x16x32_bf16 v[14:17], v[214:217], v[230:233], v[14:17]
	v_mfma_f32_16x16x32_bf16 v[10:13], v[214:217], v[238:241], v[10:13]
	v_mfma_f32_16x16x32_bf16 v[6:9], v[222:225], v[230:233], v[6:9]
	v_mfma_f32_16x16x32_bf16 v[2:5], v[222:225], v[238:241], v[2:5]
	s_barrier
	ds_read_b128 v[164:167], v148
	ds_read_b128 v[182:185], v148 offset:1024
	ds_read_b128 v[186:189], v148 offset:2048
	ds_read_b128 v[190:193], v148 offset:3072
	v_lshl_add_u64 v[226:227], v[242:243], 0, s[86:87]
	s_add_u32 m0, s32, 0x4000
	ds_read_b128 v[194:197], v142 offset:32768
	ds_read_b128 v[198:201], v142 offset:33792
	ds_read_b128 v[202:205], v142 offset:34816
	ds_read_b128 v[206:209], v142 offset:35840
	ds_read_b128 v[210:213], v142 offset:36864
	ds_read_b128 v[214:217], v142 offset:37888
	ds_read_b128 v[218:221], v142 offset:38912
	ds_read_b128 v[222:225], v142 offset:39936
	global_load_lds_dwordx4 v[226:227], off
	s_add_u32 m0, s32, 0x6000
	v_lshl_add_u64 v[226:227], v[244:245], 0, s[86:87]
	global_load_lds_dwordx4 v[226:227], off
	s_waitcnt lgkmcnt(8)
	s_barrier
	s_waitcnt lgkmcnt(0)
	v_mfma_f32_16x16x32_bf16 v[126:129], v[194:197], v[164:167], v[126:129]
	v_mfma_f32_16x16x32_bf16 v[122:125], v[194:197], v[186:189], v[122:125]
	v_mfma_f32_16x16x32_bf16 v[118:121], v[202:205], v[164:167], v[118:121]
	v_mfma_f32_16x16x32_bf16 v[114:117], v[202:205], v[186:189], v[114:117]
	v_mfma_f32_16x16x32_bf16 v[110:113], v[210:213], v[164:167], v[110:113]
	v_mfma_f32_16x16x32_bf16 v[106:109], v[210:213], v[186:189], v[106:109]
	v_mfma_f32_16x16x32_bf16 v[102:105], v[218:221], v[164:167], v[102:105]
	v_mfma_f32_16x16x32_bf16 v[98:101], v[218:221], v[186:189], v[98:101]
	v_mfma_f32_16x16x32_bf16 v[126:129], v[198:201], v[182:185], v[126:129]
	v_mfma_f32_16x16x32_bf16 v[122:125], v[198:201], v[190:193], v[122:125]
	v_mfma_f32_16x16x32_bf16 v[118:121], v[206:209], v[182:185], v[118:121]
	v_mfma_f32_16x16x32_bf16 v[114:117], v[206:209], v[190:193], v[114:117]
	v_mfma_f32_16x16x32_bf16 v[110:113], v[214:217], v[182:185], v[110:113]
	v_mfma_f32_16x16x32_bf16 v[106:109], v[214:217], v[190:193], v[106:109]
	v_mfma_f32_16x16x32_bf16 v[102:105], v[222:225], v[182:185], v[102:105]
	v_mfma_f32_16x16x32_bf16 v[98:101], v[222:225], v[190:193], v[98:101]
	s_barrier
	v_lshl_add_u64 v[250:251], v[246:247], 0, s[4:5]
	s_add_u32 m0, s32, 0x18000
	ds_read_b128 v[226:229], v145
	ds_read_b128 v[230:233], v145 offset:1024
	ds_read_b128 v[234:237], v145 offset:2048
	ds_read_b128 v[238:241], v145 offset:3072
	global_load_lds_dwordx4 v[250:251], off
	s_add_u32 m0, s32, 0x1a000
	v_lshl_add_u64 v[250:251], v[248:249], 0, s[4:5]
	global_load_lds_dwordx4 v[250:251], off
	s_barrier
; DI int tid512() { int t = threadIdx.x; asm volatile("" : "+v"(t)); return t; }
; #define G_LDA(dst, b, h)                                                                                                  \
;   _Pragma("unroll") for (int m = 0; m < 4; ++m) _Pragma("unroll") for (int k = 0; k < 2; ++k)                             \
;       dst[m][k] = *(const bf16x8*)((const char*)G_SA(b, h) + ((wr * 4 + m) * 2 + k) * 1024 + rdo)
; #define G_LDB(dst, b, h)                                                                                                  \
;   _Pragma("unroll") for (int n = 0; n < 2; ++n) _Pragma("unroll") for (int k = 0; k < 2; ++k)                             \
;       dst[n][k] = *(const bf16x8*)((const char*)G_SB(b, h) + ((wc * 2 + n) * 2 + k) * 1024 + rdo)
; #define G_WAIT_V(n) asm volatile("s_waitcnt vmcnt(" #n ")" ::: "memory")
; #define G_WAIT_L(n) asm volatile("s_waitcnt lgkmcnt(" #n ")" ::: "memory")
;     ...
;     G_LDB(B1, 1, 1); G_STAGE(G_SB(1, 0), B, ob0, ob1, LDB, 0, KB(tt + 3));
;     G_BAR; G_WAIT_L(0); G_MMA(0, 1, At, B1); G_BAR;
;     G_LDA(At, 1, 1); G_STAGE(G_SA(1, 0), A, oa0, oa1, LDA, 0, KA(tt + 3));
;     G_BAR; G_WAIT_L(0); G_MMA(1, 0, At, B0); G_BAR; G_SCHED;
;     G_STAGE(G_SB(1, 1), B, ob0, ob1, LDB, 128, KB(tt + 3));
;     G_WAIT_V(6); G_BAR; G_MMA(1, 1, At, B1); G_BAR;
;     if (MODE && ((tt + 1) & 3) == 3) br_flush(p, acc, (tt + 1) >> 2);
;   }
;   {
;     G_LDB(B0, 0, 0); G_LDA(At, 0, 0); G_STAGE(G_SA(1, 1), A, oa0, oa1, LDA, 128, KA(nt - 1));
; DI void gate_reg(PREF p, int l, int n, f32x4 (&acc)[2][2][4][2], int dt) {
;   const u32x4* sbn = merge_scratch(p, n);
;   u32x4* ssum = merge_scratch(p, 4);
;   const int t = tid512(), wid = t >> 6, lane = t & 63, wc = wid & 3, fr = lane & 15;
;   const float* bm = p.b_merge + (size_t)l * 4096 + n * 1024 + dt * 256 + wc * 32 + fr;
;   float bias[2][2];
; #pragma unroll
;   for (int bj = 0; bj < 2; ++bj)
; #pragma unroll
;     for (int nn = 0; nn < 2; ++nn) bias[bj][nn] = bm[bj * 128 + nn * 16];
; #pragma unroll
;   for (int ai = 0; ai < 2; ++ai)
; #pragma unroll
;     for (int bj = 0; bj < 2; ++bj) {
;       __builtin_amdgcn_sched_barrier(0);
;       u32x4 bn[4], pv[4];
; #pragma unroll
;       for (int m = 0; m < 4; ++m) {
;         bn[m] = sbn[((ai * 2 + bj) * 4 + m) * 64];
;         if (n > 0) pv[m] = ssum[((ai * 2 + bj) * 4 + m) * 64];
;       }
	s_waitcnt lgkmcnt(0)
	v_mfma_f32_16x16x32_bf16 v[94:97], v[194:197], v[226:229], v[94:97]
	v_mfma_f32_16x16x32_bf16 v[90:93], v[194:197], v[234:237], v[90:93]
	v_mfma_f32_16x16x32_bf16 v[86:89], v[202:205], v[226:229], v[86:89]
	v_mfma_f32_16x16x32_bf16 v[82:85], v[202:205], v[234:237], v[82:85]
	v_mfma_f32_16x16x32_bf16 v[78:81], v[210:213], v[226:229], v[78:81]
	v_mfma_f32_16x16x32_bf16 v[74:77], v[210:213], v[234:237], v[74:77]
	v_mfma_f32_16x16x32_bf16 v[70:73], v[218:221], v[226:229], v[70:73]
	v_mfma_f32_16x16x32_bf16 v[66:69], v[218:221], v[234:237], v[66:69]
	v_mfma_f32_16x16x32_bf16 v[94:97], v[198:201], v[230:233], v[94:97]
	v_mfma_f32_16x16x32_bf16 v[90:93], v[198:201], v[238:241], v[90:93]
	v_mfma_f32_16x16x32_bf16 v[86:89], v[206:209], v[230:233], v[86:89]
	v_mfma_f32_16x16x32_bf16 v[82:85], v[206:209], v[238:241], v[82:85]
	v_mfma_f32_16x16x32_bf16 v[78:81], v[214:217], v[230:233], v[78:81]
	v_mfma_f32_16x16x32_bf16 v[74:77], v[214:217], v[238:241], v[74:77]
	v_mfma_f32_16x16x32_bf16 v[70:73], v[222:225], v[230:233], v[70:73]
	v_mfma_f32_16x16x32_bf16 v[66:69], v[222:225], v[238:241], v[66:69]
	v_lshl_add_u64 v[242:243], v[242:243], 0, s[90:91]
	s_add_u32 m0, s32, 0x8000
	s_barrier
	ds_read_b128 v[194:197], v142 offset:49152
	ds_read_b128 v[198:201], v142 offset:50176
	ds_read_b128 v[202:205], v142 offset:51200
	ds_read_b128 v[206:209], v142 offset:52224
	ds_read_b128 v[210:213], v142 offset:53248
	ds_read_b128 v[214:217], v142 offset:54272
	ds_read_b128 v[218:221], v142 offset:55296
	ds_read_b128 v[222:225], v142 offset:56320
	global_load_lds_dwordx4 v[242:243], off
	s_add_u32 m0, s32, 0xa000
	v_lshl_add_u64 v[242:243], v[244:245], 0, s[90:91]
	global_load_lds_dwordx4 v[242:243], off
	s_barrier
	s_waitcnt lgkmcnt(0)
	v_mfma_f32_16x16x32_bf16 v[62:65], v[194:197], v[164:167], v[62:65]
	v_mfma_f32_16x16x32_bf16 v[58:61], v[194:197], v[186:189], v[58:61]
	v_mfma_f32_16x16x32_bf16 v[54:57], v[202:205], v[164:167], v[54:57]
	v_mfma_f32_16x16x32_bf16 v[50:53], v[202:205], v[186:189], v[50:53]
	v_mfma_f32_16x16x32_bf16 v[46:49], v[210:213], v[164:167], v[46:49]
	v_mfma_f32_16x16x32_bf16 v[42:45], v[210:213], v[186:189], v[42:45]
	v_mfma_f32_16x16x32_bf16 v[38:41], v[218:221], v[164:167], v[38:41]
	v_mfma_f32_16x16x32_bf16 v[34:37], v[218:221], v[186:189], v[34:37]
	v_mfma_f32_16x16x32_bf16 v[62:65], v[198:201], v[182:185], v[62:65]
	v_mfma_f32_16x16x32_bf16 v[58:61], v[198:201], v[190:193], v[58:61]
	v_mfma_f32_16x16x32_bf16 v[54:57], v[206:209], v[182:185], v[54:57]
	v_mfma_f32_16x16x32_bf16 v[50:53], v[206:209], v[190:193], v[50:53]
	v_mfma_f32_16x16x32_bf16 v[46:49], v[214:217], v[182:185], v[46:49]
	v_mfma_f32_16x16x32_bf16 v[42:45], v[214:217], v[190:193], v[42:45]
	v_mfma_f32_16x16x32_bf16 v[38:41], v[222:225], v[182:185], v[38:41]
	v_mfma_f32_16x16x32_bf16 v[34:37], v[222:225], v[190:193], v[34:37]
	s_barrier
	v_lshl_add_u64 v[164:165], v[246:247], 0, s[74:75]
	s_add_u32 m0, s32, 0x1c000
	s_nop 0
	global_load_lds_dwordx4 v[164:165], off
	s_add_u32 m0, s32, 0x1e000
	v_lshl_add_u64 v[164:165], v[248:249], 0, s[74:75]
	global_load_lds_dwordx4 v[164:165], off
	s_waitcnt vmcnt(6)
	s_barrier
	v_mfma_f32_16x16x32_bf16 v[30:33], v[194:197], v[226:229], v[30:33]
	v_mfma_f32_16x16x32_bf16 v[26:29], v[194:197], v[234:237], v[26:29]
	v_mfma_f32_16x16x32_bf16 v[22:25], v[202:205], v[226:229], v[22:25]
	v_mfma_f32_16x16x32_bf16 v[18:21], v[202:205], v[234:237], v[18:21]
	v_mfma_f32_16x16x32_bf16 v[14:17], v[210:213], v[226:229], v[14:17]
	v_mfma_f32_16x16x32_bf16 v[10:13], v[210:213], v[234:237], v[10:13]
	v_mfma_f32_16x16x32_bf16 v[6:9], v[218:221], v[226:229], v[6:9]
	v_mfma_f32_16x16x32_bf16 v[2:5], v[218:221], v[234:237], v[2:5]
	v_mfma_f32_16x16x32_bf16 v[30:33], v[198:201], v[230:233], v[30:33]
	v_mfma_f32_16x16x32_bf16 v[26:29], v[198:201], v[238:241], v[26:29]
	v_mfma_f32_16x16x32_bf16 v[22:25], v[206:209], v[230:233], v[22:25]
	v_mfma_f32_16x16x32_bf16 v[18:21], v[206:209], v[238:241], v[18:21]
	v_mfma_f32_16x16x32_bf16 v[14:17], v[214:217], v[230:233], v[14:17]
	v_mfma_f32_16x16x32_bf16 v[10:13], v[214:217], v[238:241], v[10:13]
	v_mfma_f32_16x16x32_bf16 v[6:9], v[222:225], v[230:233], v[6:9]
	v_mfma_f32_16x16x32_bf16 v[2:5], v[222:225], v[238:241], v[2:5]
	s_add_i32 s10, s10, 2
	s_add_u32 s8, s8, 0x100
	s_addc_u32 s9, s9, 0
	s_cmp_lt_u32 s10, 12
	s_barrier
	s_cbranch_scc1 .LBB0_105
	v_lshl_add_u64 v[132:133], v[132:133], 1, s[34:35]
	s_add_u32 m0, s32, 0xc000
	ds_read_b128 v[134:137], v160
	ds_read_b128 v[138:141], v160 offset:1024
	ds_read_b128 v[150:153], v160 offset:2048
	ds_read_b128 v[154:157], v160 offset:3072
	ds_read_b128 v[164:167], v142
	ds_read_b128 v[182:185], v142 offset:1024
	ds_read_b128 v[186:189], v142 offset:2048
	ds_read_b128 v[190:193], v142 offset:3072
	ds_read_b128 v[194:197], v142 offset:4096
	ds_read_b128 v[198:201], v142 offset:5120
	ds_read_b128 v[202:205], v142 offset:6144
	ds_read_b128 v[206:209], v142 offset:7168
	global_load_lds_dwordx4 v[132:133], off
	s_add_u32 m0, s32, 0xe000
	v_lshl_add_u64 v[130:131], v[130:131], 1, s[34:35]
	global_load_lds_dwordx4 v[130:131], off
	s_lshl_b32 s1, s23, 8
	s_add_u32 s98, s25, s1
	s_addc_u32 s99, s48, 0
	v_bfe_u32 v251, v168, 6, 2
	v_lshlrev_b32_e32 v248, 6, v251
	v_and_b32_e32 v250, 15, v168
	v_lshl_or_b32 v248, v250, 2, v248
	global_load_dword v170, v248, s[98:99]
	s_add_u32 s98, s98, 0x1000
	s_addc_u32 s99, s99, 0
	global_load_dword v252, v248, s[98:99]
	s_add_u32 s98, s98, 0x1000
	s_addc_u32 s99, s99, 0
	global_load_dword v253, v248, s[98:99]
	s_add_u32 s98, s98, 0x1000
	s_addc_u32 s99, s99, 0
	global_load_dword v162, v248, s[98:99]
	s_lshl_b32 s1, s23, 1
	v_lshrrev_b32_e32 v249, 1, v251
	v_add_u32_e32 v249, s1, v249
	v_and_b32_e32 v249, 3, v249
	v_lshrrev_b32_e32 v250, 8, v168
	v_lshl_add_u32 v249, v250, 2, v249
	v_lshlrev_b32_e32 v249, 14, v249
	v_and_b32_e32 v250, 63, v168
	v_lshl_or_b32 v249, v250, 4, v249
	v_and_b32_e32 v250, 1, v251
	v_lshl_or_b32 v249, v250, 3, v249
	s_lshr_b32 s1, s23, 1
	s_lshl_b32 s1, s1, 12
	s_add_u32 s20, s63, s1
	s_addc_u32 s21, s64, 0
	global_load_dwordx2 v[230:231], v249, s[20:21] offset:0
	global_load_dwordx2 v[238:239], v249, s[20:21] offset:1024
	s_add_u32 s20, s20, 0x20000
	s_addc_u32 s21, s21, 0
	global_load_dwordx2 v[232:233], v249, s[20:21] offset:0
	global_load_dwordx2 v[240:241], v249, s[20:21] offset:1024
	s_add_u32 s20, s20, 0x20000
	s_addc_u32 s21, s21, 0
	global_load_dwordx2 v[234:235], v249, s[20:21] offset:0
	global_load_dwordx2 v[242:243], v249, s[20:21] offset:1024
	s_add_u32 s20, s20, 0x20000
	s_addc_u32 s21, s21, 0
	global_load_dwordx2 v[236:237], v249, s[20:21] offset:0
	global_load_dwordx2 v[244:245], v249, s[20:21] offset:1024
	s_barrier
; #define G_LDA(dst, b, h)                                                                                                  \
;   _Pragma("unroll") for (int m = 0; m < 4; ++m) _Pragma("unroll") for (int k = 0; k < 2; ++k)                             \
;       dst[m][k] = *(const bf16x8*)((const char*)G_SA(b, h) + ((wr * 4 + m) * 2 + k) * 1024 + rdo)
; #define G_LDB(dst, b, h)                                                                                                  \
;   _Pragma("unroll") for (int n = 0; n < 2; ++n) _Pragma("unroll") for (int k = 0; k < 2; ++k)                             \
;       dst[n][k] = *(const bf16x8*)((const char*)G_SB(b, h) + ((wc * 2 + n) * 2 + k) * 1024 + rdo)
; #define G_WAIT_V(n) asm volatile("s_waitcnt vmcnt(" #n ")" ::: "memory")
; #define G_WAIT_L(n) asm volatile("s_waitcnt lgkmcnt(" #n ")" ::: "memory")
; #define G_BAR __builtin_amdgcn_s_barrier()
;     ...
;     G_LDB(B0, 0, 0); G_LDA(At, 0, 0); G_STAGE(G_SA(1, 1), A, oa0, oa1, LDA, 128, KA(nt - 1));
;     G_BAR; G_WAIT_L(0); G_MMA(0, 0, At, B0); G_BAR;
;     G_LDB(B1, 0, 1); G_BAR; G_WAIT_L(0); G_MMA(0, 1, At, B1); G_BAR;
;     G_LDA(At, 0, 1); G_WAIT_V(4); G_BAR; G_WAIT_L(0); G_MMA(1, 0, At, B0); G_MMA(1, 1, At, B1); G_BAR;
;   }
;   {
;     G_LDB(B0, 1, 0); G_LDA(At, 1, 0); G_WAIT_V(2); G_BAR; G_WAIT_L(0); G_MMA(0, 0, At, B0); G_BAR;
;     G_LDB(B1, 1, 1); G_WAIT_V(0); G_BAR; G_WAIT_L(0); G_MMA(0, 1, At, B1); G_BAR;
;     G_LDA(At, 1, 1); G_BAR; G_WAIT_L(0); G_MMA(1, 0, At, B0); G_MMA(1, 1, At, B1); G_BAR;
	s_waitcnt lgkmcnt(0)
	v_mfma_f32_16x16x32_bf16 v[126:129], v[164:167], v[134:137], v[126:129]
	v_mfma_f32_16x16x32_bf16 v[122:125], v[164:167], v[150:153], v[122:125]
	v_mfma_f32_16x16x32_bf16 v[114:117], v[186:189], v[150:153], v[114:117]
	v_mfma_f32_16x16x32_bf16 v[110:113], v[194:197], v[134:137], v[110:113]
	v_mfma_f32_16x16x32_bf16 v[106:109], v[194:197], v[150:153], v[106:109]
	v_mfma_f32_16x16x32_bf16 v[102:105], v[202:205], v[134:137], v[102:105]
	v_mfma_f32_16x16x32_bf16 v[98:101], v[202:205], v[150:153], v[98:101]
	v_mfma_f32_16x16x32_bf16 v[126:129], v[182:185], v[138:141], v[126:129]
	v_mfma_f32_16x16x32_bf16 v[122:125], v[182:185], v[154:157], v[122:125]
	v_mfma_f32_16x16x32_bf16 v[118:121], v[186:189], v[134:137], v[118:121]
	v_mfma_f32_16x16x32_bf16 v[114:117], v[190:193], v[154:157], v[114:117]
	v_mfma_f32_16x16x32_bf16 v[110:113], v[198:201], v[138:141], v[110:113]
	v_mfma_f32_16x16x32_bf16 v[106:109], v[198:201], v[154:157], v[106:109]
	v_mfma_f32_16x16x32_bf16 v[102:105], v[206:209], v[138:141], v[102:105]
	v_mfma_f32_16x16x32_bf16 v[98:101], v[206:209], v[154:157], v[98:101]
	v_mfma_f32_16x16x32_bf16 v[118:121], v[190:193], v[138:141], v[118:121]
	s_barrier
	ds_read_b128 v[130:133], v158
	ds_read_b128 v[210:213], v158 offset:1024
	ds_read_b128 v[214:217], v158 offset:2048
	ds_read_b128 v[158:161], v158 offset:3072
	s_barrier
	s_waitcnt lgkmcnt(0)
	v_mfma_f32_16x16x32_bf16 v[94:97], v[164:167], v[130:133], v[94:97]
	v_mfma_f32_16x16x32_bf16 v[90:93], v[164:167], v[214:217], v[90:93]
	v_mfma_f32_16x16x32_bf16 v[86:89], v[186:189], v[130:133], v[86:89]
	v_mfma_f32_16x16x32_bf16 v[82:85], v[186:189], v[214:217], v[82:85]
	v_mfma_f32_16x16x32_bf16 v[78:81], v[194:197], v[130:133], v[78:81]
	v_mfma_f32_16x16x32_bf16 v[74:77], v[194:197], v[214:217], v[74:77]
	v_mfma_f32_16x16x32_bf16 v[70:73], v[202:205], v[130:133], v[70:73]
	v_mfma_f32_16x16x32_bf16 v[66:69], v[202:205], v[214:217], v[66:69]
	v_mfma_f32_16x16x32_bf16 v[94:97], v[182:185], v[210:213], v[94:97]
	v_mfma_f32_16x16x32_bf16 v[90:93], v[182:185], v[158:161], v[90:93]
	v_mfma_f32_16x16x32_bf16 v[86:89], v[190:193], v[210:213], v[86:89]
	v_mfma_f32_16x16x32_bf16 v[82:85], v[190:193], v[158:161], v[82:85]
	v_mfma_f32_16x16x32_bf16 v[78:81], v[198:201], v[210:213], v[78:81]
	v_mfma_f32_16x16x32_bf16 v[74:77], v[198:201], v[158:161], v[74:77]
	v_mfma_f32_16x16x32_bf16 v[70:73], v[206:209], v[210:213], v[70:73]
	v_mfma_f32_16x16x32_bf16 v[66:69], v[206:209], v[158:161], v[66:69]
	s_barrier
	ds_read_b128 v[164:167], v142 offset:16384
	ds_read_b128 v[182:185], v142 offset:17408
	ds_read_b128 v[186:189], v142 offset:18432
	ds_read_b128 v[190:193], v142 offset:19456
	ds_read_b128 v[194:197], v142 offset:20480
	ds_read_b128 v[198:201], v142 offset:21504
	ds_read_b128 v[202:205], v142 offset:22528
	ds_read_b128 v[206:209], v142 offset:23552
	s_waitcnt vmcnt(16)
	s_barrier
	s_waitcnt lgkmcnt(0)
	v_mfma_f32_16x16x32_bf16 v[62:65], v[164:167], v[134:137], v[62:65]
	v_mfma_f32_16x16x32_bf16 v[58:61], v[164:167], v[150:153], v[58:61]
	v_mfma_f32_16x16x32_bf16 v[54:57], v[186:189], v[134:137], v[54:57]
	v_mfma_f32_16x16x32_bf16 v[50:53], v[186:189], v[150:153], v[50:53]
	v_mfma_f32_16x16x32_bf16 v[46:49], v[194:197], v[134:137], v[46:49]
	v_mfma_f32_16x16x32_bf16 v[38:41], v[202:205], v[134:137], v[38:41]
	v_mfma_f32_16x16x32_bf16 v[34:37], v[202:205], v[150:153], v[34:37]
	v_mfma_f32_16x16x32_bf16 v[62:65], v[182:185], v[138:141], v[62:65]
	v_mfma_f32_16x16x32_bf16 v[58:61], v[182:185], v[154:157], v[58:61]
	v_mfma_f32_16x16x32_bf16 v[54:57], v[190:193], v[138:141], v[54:57]
	v_mfma_f32_16x16x32_bf16 v[50:53], v[190:193], v[154:157], v[50:53]
	v_mfma_f32_16x16x32_bf16 v[46:49], v[198:201], v[138:141], v[46:49]
	v_mfma_f32_16x16x32_bf16 v[42:45], v[194:197], v[150:153], v[42:45]
	v_mfma_f32_16x16x32_bf16 v[38:41], v[206:209], v[138:141], v[38:41]
	v_mfma_f32_16x16x32_bf16 v[34:37], v[206:209], v[154:157], v[34:37]
	v_mfma_f32_16x16x32_bf16 v[42:45], v[198:201], v[154:157], v[42:45]
	v_mfma_f32_16x16x32_bf16 v[26:29], v[164:167], v[214:217], v[26:29]
	v_mfma_f32_16x16x32_bf16 v[22:25], v[186:189], v[130:133], v[22:25]
	v_mfma_f32_16x16x32_bf16 v[14:17], v[194:197], v[130:133], v[14:17]
	v_mfma_f32_16x16x32_bf16 v[10:13], v[194:197], v[214:217], v[10:13]
	v_mfma_f32_16x16x32_bf16 v[2:5], v[202:205], v[214:217], v[2:5]
	v_mfma_f32_16x16x32_bf16 v[30:33], v[164:167], v[130:133], v[30:33]
	v_mfma_f32_16x16x32_bf16 v[26:29], v[182:185], v[158:161], v[26:29]
	v_mfma_f32_16x16x32_bf16 v[22:25], v[190:193], v[210:213], v[22:25]
	v_mfma_f32_16x16x32_bf16 v[18:21], v[186:189], v[214:217], v[18:21]
	v_mfma_f32_16x16x32_bf16 v[14:17], v[198:201], v[210:213], v[14:17]
	v_mfma_f32_16x16x32_bf16 v[10:13], v[198:201], v[158:161], v[10:13]
	v_mfma_f32_16x16x32_bf16 v[6:9], v[202:205], v[130:133], v[6:9]
	v_mfma_f32_16x16x32_bf16 v[2:5], v[206:209], v[158:161], v[2:5]
	v_mfma_f32_16x16x32_bf16 v[30:33], v[182:185], v[210:213], v[30:33]
	v_mfma_f32_16x16x32_bf16 v[18:21], v[190:193], v[158:161], v[18:21]
	v_mfma_f32_16x16x32_bf16 v[6:9], v[206:209], v[210:213], v[6:9]
	s_barrier
	ds_read_b128 v[130:133], v148
	ds_read_b128 v[154:157], v148 offset:1024
	ds_read_b128 v[164:167], v148 offset:2048
	ds_read_b128 v[182:185], v148 offset:3072
	ds_read_b128 v[186:189], v142 offset:32768
	ds_read_b128 v[190:193], v142 offset:33792
	ds_read_b128 v[194:197], v142 offset:34816
	ds_read_b128 v[198:201], v142 offset:35840
	ds_read_b128 v[202:205], v142 offset:36864
	ds_read_b128 v[206:209], v142 offset:37888
	ds_read_b128 v[210:213], v142 offset:38912
	ds_read_b128 v[214:217], v142 offset:39936
	s_waitcnt vmcnt(14)
	s_barrier
; #define G_LDA(dst, b, h)                                                                                                  \
;   _Pragma("unroll") for (int m = 0; m < 4; ++m) _Pragma("unroll") for (int k = 0; k < 2; ++k)                             \
;       dst[m][k] = *(const bf16x8*)((const char*)G_SA(b, h) + ((wr * 4 + m) * 2 + k) * 1024 + rdo)
; #define G_LDB(dst, b, h)                                                                                                  \
;   _Pragma("unroll") for (int n = 0; n < 2; ++n) _Pragma("unroll") for (int k = 0; k < 2; ++k)                             \
;       dst[n][k] = *(const bf16x8*)((const char*)G_SB(b, h) + ((wc * 2 + n) * 2 + k) * 1024 + rdo)
; #define G_WAIT_V(n) asm volatile("s_waitcnt vmcnt(" #n ")" ::: "memory")
; #define G_WAIT_L(n) asm volatile("s_waitcnt lgkmcnt(" #n ")" ::: "memory")
; #define G_BAR __builtin_amdgcn_s_barrier()
;     ...
;     G_LDB(B0, 1, 0); G_LDA(At, 1, 0); G_WAIT_V(2); G_BAR; G_WAIT_L(0); G_MMA(0, 0, At, B0); G_BAR;
;     G_LDB(B1, 1, 1); G_WAIT_V(0); G_BAR; G_WAIT_L(0); G_MMA(0, 1, At, B1); G_BAR;
;     G_LDA(At, 1, 1); G_BAR; G_WAIT_L(0); G_MMA(1, 0, At, B0); G_MMA(1, 1, At, B1); G_BAR;
;   }
;   if (wr == 0) G_BAR;
	s_waitcnt lgkmcnt(0)
	v_mfma_f32_16x16x32_bf16 v[126:129], v[186:189], v[130:133], v[126:129]
	v_mfma_f32_16x16x32_bf16 v[122:125], v[186:189], v[164:167], v[122:125]
	v_mfma_f32_16x16x32_bf16 v[118:121], v[194:197], v[130:133], v[118:121]
	v_mfma_f32_16x16x32_bf16 v[114:117], v[194:197], v[164:167], v[114:117]
	v_mfma_f32_16x16x32_bf16 v[110:113], v[202:205], v[130:133], v[110:113]
	v_mfma_f32_16x16x32_bf16 v[106:109], v[202:205], v[164:167], v[106:109]
	v_mfma_f32_16x16x32_bf16 v[102:105], v[210:213], v[130:133], v[102:105]
	v_mfma_f32_16x16x32_bf16 v[98:101], v[210:213], v[164:167], v[98:101]
	v_mfma_f32_16x16x32_bf16 v[158:161], v[190:193], v[154:157], v[126:129]
	v_mfma_f32_16x16x32_bf16 v[150:153], v[190:193], v[182:185], v[122:125]
	v_mfma_f32_16x16x32_bf16 v[146:149], v[198:201], v[154:157], v[118:121]
	v_mfma_f32_16x16x32_bf16 v[138:141], v[198:201], v[182:185], v[114:117]
	v_mfma_f32_16x16x32_bf16 v[134:137], v[206:209], v[154:157], v[110:113]
	v_mfma_f32_16x16x32_bf16 v[126:129], v[206:209], v[182:185], v[106:109]
	v_mfma_f32_16x16x32_bf16 v[122:125], v[214:217], v[154:157], v[102:105]
	v_mfma_f32_16x16x32_bf16 v[114:117], v[214:217], v[182:185], v[98:101]
	s_barrier
	ds_read_b128 v[118:121], v145
	ds_read_b128 v[218:221], v145 offset:1024
	ds_read_b128 v[222:225], v145 offset:2048
	ds_read_b128 v[226:229], v145 offset:3072
	s_waitcnt vmcnt(12)
	s_barrier
	s_waitcnt lgkmcnt(0)
	v_mfma_f32_16x16x32_bf16 v[94:97], v[186:189], v[118:121], v[94:97]
	v_mfma_f32_16x16x32_bf16 v[90:93], v[186:189], v[222:225], v[90:93]
	v_mfma_f32_16x16x32_bf16 v[86:89], v[194:197], v[118:121], v[86:89]
	v_mfma_f32_16x16x32_bf16 v[82:85], v[194:197], v[222:225], v[82:85]
	v_mfma_f32_16x16x32_bf16 v[78:81], v[202:205], v[118:121], v[78:81]
	v_mfma_f32_16x16x32_bf16 v[74:77], v[202:205], v[222:225], v[74:77]
	v_mfma_f32_16x16x32_bf16 v[70:73], v[210:213], v[118:121], v[70:73]
	v_mfma_f32_16x16x32_bf16 v[66:69], v[210:213], v[222:225], v[66:69]
	v_mfma_f32_16x16x32_bf16 v[110:113], v[190:193], v[218:221], v[94:97]
	v_mfma_f32_16x16x32_bf16 v[106:109], v[190:193], v[226:229], v[90:93]
	v_mfma_f32_16x16x32_bf16 v[102:105], v[198:201], v[218:221], v[86:89]
	v_mfma_f32_16x16x32_bf16 v[98:101], v[198:201], v[226:229], v[82:85]
	v_mfma_f32_16x16x32_bf16 v[94:97], v[206:209], v[218:221], v[78:81]
	v_mfma_f32_16x16x32_bf16 v[90:93], v[206:209], v[226:229], v[74:77]
	v_mfma_f32_16x16x32_bf16 v[86:89], v[214:217], v[218:221], v[70:73]
	v_mfma_f32_16x16x32_bf16 v[82:85], v[214:217], v[226:229], v[66:69]
	s_barrier
	ds_read_b128 v[186:189], v142 offset:49152
	ds_read_b128 v[190:193], v142 offset:50176
	ds_read_b128 v[194:197], v142 offset:51200
	ds_read_b128 v[198:201], v142 offset:52224
	ds_read_b128 v[202:205], v142 offset:53248
	ds_read_b128 v[206:209], v142 offset:54272
	ds_read_b128 v[210:213], v142 offset:55296
	ds_read_b128 v[142:145], v142 offset:56320
	s_barrier
	s_waitcnt lgkmcnt(0)
	v_mfma_f32_16x16x32_bf16 v[62:65], v[186:189], v[130:133], v[62:65]
	v_mfma_f32_16x16x32_bf16 v[58:61], v[186:189], v[164:167], v[58:61]
	v_mfma_f32_16x16x32_bf16 v[54:57], v[194:197], v[130:133], v[54:57]
	v_mfma_f32_16x16x32_bf16 v[50:53], v[194:197], v[164:167], v[50:53]
	v_mfma_f32_16x16x32_bf16 v[46:49], v[202:205], v[130:133], v[46:49]
	v_mfma_f32_16x16x32_bf16 v[42:45], v[202:205], v[164:167], v[42:45]
	v_mfma_f32_16x16x32_bf16 v[38:41], v[210:213], v[130:133], v[38:41]
	v_mfma_f32_16x16x32_bf16 v[34:37], v[210:213], v[164:167], v[34:37]
	v_mfma_f32_16x16x32_bf16 v[78:81], v[190:193], v[154:157], v[62:65]
	v_mfma_f32_16x16x32_bf16 v[74:77], v[190:193], v[182:185], v[58:61]
	v_mfma_f32_16x16x32_bf16 v[70:73], v[198:201], v[154:157], v[54:57]
	v_mfma_f32_16x16x32_bf16 v[66:69], v[198:201], v[182:185], v[50:53]
	v_mfma_f32_16x16x32_bf16 v[62:65], v[206:209], v[154:157], v[46:49]
	v_mfma_f32_16x16x32_bf16 v[58:61], v[206:209], v[182:185], v[42:45]
	v_mfma_f32_16x16x32_bf16 v[54:57], v[142:145], v[154:157], v[38:41]
	v_mfma_f32_16x16x32_bf16 v[50:53], v[142:145], v[182:185], v[34:37]
	v_mfma_f32_16x16x32_bf16 v[30:33], v[186:189], v[118:121], v[30:33]
	v_mfma_f32_16x16x32_bf16 v[26:29], v[186:189], v[222:225], v[26:29]
	v_mfma_f32_16x16x32_bf16 v[22:25], v[194:197], v[118:121], v[22:25]
	v_mfma_f32_16x16x32_bf16 v[18:21], v[194:197], v[222:225], v[18:21]
	v_mfma_f32_16x16x32_bf16 v[14:17], v[202:205], v[118:121], v[14:17]
	v_mfma_f32_16x16x32_bf16 v[10:13], v[202:205], v[222:225], v[10:13]
	v_mfma_f32_16x16x32_bf16 v[6:9], v[210:213], v[118:121], v[6:9]
	v_mfma_f32_16x16x32_bf16 v[2:5], v[210:213], v[222:225], v[2:5]
	v_mfma_f32_16x16x32_bf16 v[46:49], v[190:193], v[218:221], v[30:33]
	v_mfma_f32_16x16x32_bf16 v[38:41], v[190:193], v[226:229], v[26:29]
	v_mfma_f32_16x16x32_bf16 v[34:37], v[198:201], v[218:221], v[22:25]
	v_mfma_f32_16x16x32_bf16 v[26:29], v[198:201], v[226:229], v[18:21]
	v_mfma_f32_16x16x32_bf16 v[22:25], v[206:209], v[218:221], v[14:17]
	v_mfma_f32_16x16x32_bf16 v[14:17], v[206:209], v[226:229], v[10:13]
	v_mfma_f32_16x16x32_bf16 v[10:13], v[142:145], v[218:221], v[6:9]
	v_mfma_f32_16x16x32_bf16 v[2:5], v[142:145], v[226:229], v[2:5]
	v_cmp_gt_u32_e32 vcc, s67, v0
	s_barrier
	s_and_saveexec_b64 s[8:9], vcc
	s_cbranch_execz .LBB0_108
	s_barrier
; DI float sigm(float x) { return 1.f / (1.f + __expf(-x)); }
; DI u32x4 pack8(const float* f) { u32x4 o; o.x = pack2(f[0], f[1]); o.y = pack2(f[2], f[3]); o.z = pack2(f[4], f[5]); o.w = pack2(f[6], f[7]); return o; }
; DI int tid512() { int t = threadIdx.x; asm volatile("" : "+v"(t)); return t; }
; DI u32x4* merge_scratch(PREF p, int region) { const int t = tid512(); return (u32x4*)p.fbuf + (size_t)blockIdx.x * 40960 + region * 8192 + (t >> 6) * 1024 + (t & 63); }
; DI void gate_reg(PREF p, int l, int n, f32x4 (&acc)[2][2][4][2], int dt) {
;   const u32x4* sbn = merge_scratch(p, n);
;   u32x4* ssum = merge_scratch(p, 4);
;   const int t = tid512(), wid = t >> 6, lane = t & 63, wc = wid & 3, fr = lane & 15;
;   const float* bm = p.b_merge + (size_t)l * 4096 + n * 1024 + dt * 256 + wc * 32 + fr;
;   float bias[2][2];
; #pragma unroll
;   for (int bj = 0; bj < 2; ++bj)
; #pragma unroll
;     for (int nn = 0; nn < 2; ++nn) bias[bj][nn] = bm[bj * 128 + nn * 16];
; #pragma unroll
;   for (int ai = 0; ai < 2; ++ai)
; #pragma unroll
;     for (int bj = 0; bj < 2; ++bj) {
;       __builtin_amdgcn_sched_barrier(0);
;       u32x4 bn[4], pv[4];
; #pragma unroll
;       for (int m = 0; m < 4; ++m) {
;         bn[m] = sbn[((ai * 2 + bj) * 4 + m) * 64];
;         if (n > 0) pv[m] = ssum[((ai * 2 + bj) * 4 + m) * 64];
;       }
; #pragma unroll
;       for (int m = 0; m < 4; ++m) {
;         float b[8]; unpack8(bn[m], b);
;         float v[8];
; #pragma unroll
;         for (int nn = 0; nn < 2; ++nn)
; #pragma unroll
;           for (int j = 0; j < 4; ++j) v[nn * 4 + j] = sigm(acc[ai][bj][m][nn][j] + bias[bj][nn]) * b[nn * 4 + j];
;         if (n > 0) {
;           float o[8]; unpack8(pv[m], o);
; #pragma unroll
;           for (int e = 0; e < 8; ++e) v[e] += o[e];
;         }
;         if (n < 3) ssum[((ai * 2 + bj) * 4 + m) * 64] = pack8(v);
; #pragma unroll
;         for (int nn = 0; nn < 2; ++nn)
; #pragma unroll
;           for (int j = 0; j < 4; ++j) acc[ai][bj][m][nn][j] = v[nn * 4 + j];
.LBB0_108:
	s_or_b64 exec, exec, s[8:9]
	s_lshl_b32 s0, s23, 8
	s_add_u32 s98, s25, s0
	s_addc_u32 s99, s48, 0
	s_lshr_b32 s0, s23, 1
	s_lshl_b32 s0, s0, 12
	s_add_u32 s8, s63, s0
	s_addc_u32 s9, s64, 0
	s_add_u32 s10, s8, 0x20000
	s_addc_u32 s11, s9, 0
	s_add_u32 s42, s8, 0x40000
	s_addc_u32 s43, s9, 0
	s_add_u32 s44, s8, 0x60000
	s_addc_u32 s45, s9, 0
	s_lshl_b32 s0, s23, 1
	v_bfe_u32 v155, v168, 6, 2
	v_lshlrev_b32_e32 v130, 6, v155
	v_and_b32_e32 v131, 15, v168
	v_lshl_or_b32 v130, v131, 2, v130
	v_lshrrev_b32_e32 v130, 1, v155
	v_add_u32_e32 v130, s0, v130
	v_and_b32_e32 v130, 3, v130
	v_lshrrev_b32_e32 v131, 8, v168
	v_lshl_add_u32 v130, v131, 2, v130
	v_lshlrev_b32_e32 v130, 14, v130
	v_and_b32_e32 v131, 63, v168
	v_lshl_or_b32 v142, v131, 4, v130
	v_and_b32_e32 v131, 1, v155
	v_lshl_or_b32 v142, v131, 3, v142
	v_add_u32_e32 v0, 0x2000, v142
	global_load_dwordx2 v[198:199], v142, s[8:9] offset:2048
	global_load_dwordx2 v[200:201], v142, s[10:11] offset:2048
	global_load_dwordx2 v[202:203], v142, s[42:43] offset:2048
	global_load_dwordx2 v[204:205], v142, s[44:45] offset:2048
	global_load_dwordx2 v[206:207], v142, s[8:9] offset:3072
	global_load_dwordx2 v[208:209], v142, s[10:11] offset:3072
	global_load_dwordx2 v[210:211], v142, s[42:43] offset:3072
	global_load_dwordx2 v[212:213], v142, s[44:45] offset:3072
	global_load_dwordx2 v[214:215], v0, s[8:9] offset:0
	global_load_dwordx2 v[216:217], v0, s[10:11] offset:0
	global_load_dwordx2 v[218:219], v0, s[42:43] offset:0
	global_load_dwordx2 v[220:221], v0, s[44:45] offset:0
	global_load_dwordx2 v[222:223], v0, s[8:9] offset:1024
	global_load_dwordx2 v[224:225], v0, s[10:11] offset:1024
	global_load_dwordx2 v[226:227], v0, s[42:43] offset:1024
	global_load_dwordx2 v[228:229], v0, s[44:45] offset:1024
	global_load_dwordx2 v[182:183], v0, s[8:9] offset:2048
	global_load_dwordx2 v[184:185], v0, s[10:11] offset:2048
	global_load_dwordx2 v[186:187], v0, s[42:43] offset:2048
	global_load_dwordx2 v[188:189], v0, s[44:45] offset:2048
	global_load_dwordx2 v[190:191], v0, s[8:9] offset:3072
	global_load_dwordx2 v[192:193], v0, s[10:11] offset:3072
	global_load_dwordx2 v[194:195], v0, s[42:43] offset:3072
	global_load_dwordx2 v[196:197], v0, s[44:45] offset:3072
	s_waitcnt vmcnt(24)
	v_mul_f32_e32 v170, 0xbfb8aa3b, v170
	v_mul_f32_e32 v252, 0xbfb8aa3b, v252
	v_mul_f32_e32 v253, 0xbfb8aa3b, v253
	v_mul_f32_e32 v162, 0xbfb8aa3b, v162
	v_fmamk_f32 v158, v158, 0xbfb8aa3b, v170
	v_exp_f32_e32 v158, v158
	v_fmamk_f32 v159, v159, 0xbfb8aa3b, v170
	v_exp_f32_e32 v159, v159
	v_fmamk_f32 v160, v160, 0xbfb8aa3b, v170
	v_exp_f32_e32 v160, v160
	v_fmamk_f32 v161, v161, 0xbfb8aa3b, v170
	v_exp_f32_e32 v161, v161
	v_fmamk_f32 v150, v150, 0xbfb8aa3b, v252
	v_exp_f32_e32 v150, v150
	v_fmamk_f32 v151, v151, 0xbfb8aa3b, v252
	v_exp_f32_e32 v151, v151
	v_fmamk_f32 v152, v152, 0xbfb8aa3b, v252
	v_exp_f32_e32 v152, v152
	v_fmamk_f32 v153, v153, 0xbfb8aa3b, v252
	v_exp_f32_e32 v153, v153
	v_fmamk_f32 v110, v110, 0xbfb8aa3b, v253
	v_exp_f32_e32 v110, v110
	v_fmamk_f32 v111, v111, 0xbfb8aa3b, v253
	v_exp_f32_e32 v111, v111
	v_fmamk_f32 v112, v112, 0xbfb8aa3b, v253
	v_exp_f32_e32 v112, v112
	v_fmamk_f32 v113, v113, 0xbfb8aa3b, v253
	v_exp_f32_e32 v113, v113
	v_fmamk_f32 v106, v106, 0xbfb8aa3b, v162
	v_exp_f32_e32 v106, v106
	v_fmamk_f32 v107, v107, 0xbfb8aa3b, v162
	v_exp_f32_e32 v107, v107
	v_fmamk_f32 v108, v108, 0xbfb8aa3b, v162
	v_exp_f32_e32 v108, v108
	v_fmamk_f32 v109, v109, 0xbfb8aa3b, v162
	v_exp_f32_e32 v109, v109
	v_add_f32_e32 v158, 1.0, v158
	v_add_f32_e32 v159, 1.0, v159
	v_lshlrev_b32_e32 v156, 16, v230
	v_and_b32_e32 v157, 0xffff0000, v230
	v_rcp_f32_e32 v158, v158
	v_rcp_f32_e32 v159, v159
	v_add_f32_e32 v160, 1.0, v160
	v_add_f32_e32 v161, 1.0, v161
	v_lshlrev_b32_e32 v164, 16, v231
	v_and_b32_e32 v165, 0xffff0000, v231
	v_rcp_f32_e32 v160, v160
	v_rcp_f32_e32 v161, v161
	v_mul_f32_e32 v158, v158, v156
	v_mul_f32_e32 v159, v159, v157
	v_mul_f32_e32 v160, v160, v164
	v_mul_f32_e32 v161, v161, v165
	v_add_f32_e32 v150, 1.0, v150
	v_add_f32_e32 v151, 1.0, v151
	v_lshlrev_b32_e32 v156, 16, v232
	v_and_b32_e32 v157, 0xffff0000, v232
	v_rcp_f32_e32 v150, v150
	v_rcp_f32_e32 v151, v151
	v_add_f32_e32 v152, 1.0, v152
	v_add_f32_e32 v153, 1.0, v153
	v_lshlrev_b32_e32 v164, 16, v233
	v_and_b32_e32 v165, 0xffff0000, v233
	v_rcp_f32_e32 v152, v152
	v_rcp_f32_e32 v153, v153
	v_fmac_f32_e32 v158, v150, v156
	v_fmac_f32_e32 v159, v151, v157
	v_fmac_f32_e32 v160, v152, v164
	v_fmac_f32_e32 v161, v153, v165
	v_add_f32_e32 v110, 1.0, v110
	v_add_f32_e32 v111, 1.0, v111
	v_lshlrev_b32_e32 v156, 16, v234
	v_and_b32_e32 v157, 0xffff0000, v234
	v_rcp_f32_e32 v110, v110
	v_rcp_f32_e32 v111, v111
	v_add_f32_e32 v112, 1.0, v112
	v_add_f32_e32 v113, 1.0, v113
	v_lshlrev_b32_e32 v164, 16, v235
	v_and_b32_e32 v165, 0xffff0000, v235
	v_rcp_f32_e32 v112, v112
	v_rcp_f32_e32 v113, v113
	v_fmac_f32_e32 v158, v110, v156
	v_fmac_f32_e32 v159, v111, v157
	v_fmac_f32_e32 v160, v112, v164
	v_fmac_f32_e32 v161, v113, v165
	v_add_f32_e32 v106, 1.0, v106
	v_add_f32_e32 v107, 1.0, v107
	v_lshlrev_b32_e32 v156, 16, v236
	v_and_b32_e32 v157, 0xffff0000, v236
	v_rcp_f32_e32 v106, v106
	v_rcp_f32_e32 v107, v107
	v_add_f32_e32 v108, 1.0, v108
	v_add_f32_e32 v109, 1.0, v109
	v_lshlrev_b32_e32 v164, 16, v237
	v_and_b32_e32 v165, 0xffff0000, v237
	v_rcp_f32_e32 v108, v108
	v_rcp_f32_e32 v109, v109
	v_fmac_f32_e32 v158, v106, v156
	v_fmac_f32_e32 v159, v107, v157
	v_fmac_f32_e32 v160, v108, v164
	v_fmac_f32_e32 v161, v109, v165
	s_waitcnt vmcnt(24)
; DI float sigm(float x) { return 1.f / (1.f + __expf(-x)); }
; DI u32x4 pack8(const float* f) { u32x4 o; o.x = pack2(f[0], f[1]); o.y = pack2(f[2], f[3]); o.z = pack2(f[4], f[5]); o.w = pack2(f[6], f[7]); return o; }
; DI void gate_reg(PREF p, int l, int n, f32x4 (&acc)[2][2][4][2], int dt) {
;     ...
;       for (int m = 0; m < 4; ++m) {
;         float b[8]; unpack8(bn[m], b);
;         float v[8];
; #pragma unroll
;         for (int nn = 0; nn < 2; ++nn)
; #pragma unroll
;           for (int j = 0; j < 4; ++j) v[nn * 4 + j] = sigm(acc[ai][bj][m][nn][j] + bias[bj][nn]) * b[nn * 4 + j];
;         if (n > 0) {
;           float o[8]; unpack8(pv[m], o);
; #pragma unroll
;           for (int e = 0; e < 8; ++e) v[e] += o[e];
;         }
;         if (n < 3) ssum[((ai * 2 + bj) * 4 + m) * 64] = pack8(v);
; #pragma unroll
;         for (int nn = 0; nn < 2; ++nn)
; #pragma unroll
;           for (int j = 0; j < 4; ++j) acc[ai][bj][m][nn][j] = v[nn * 4 + j];
	v_fmamk_f32 v146, v146, 0xbfb8aa3b, v170
	v_exp_f32_e32 v146, v146
	v_fmamk_f32 v147, v147, 0xbfb8aa3b, v170
	v_exp_f32_e32 v147, v147
	v_fmamk_f32 v148, v148, 0xbfb8aa3b, v170
	v_exp_f32_e32 v148, v148
	v_fmamk_f32 v149, v149, 0xbfb8aa3b, v170
	v_exp_f32_e32 v149, v149
	v_fmamk_f32 v138, v138, 0xbfb8aa3b, v252
	v_exp_f32_e32 v138, v138
	v_fmamk_f32 v139, v139, 0xbfb8aa3b, v252
	v_exp_f32_e32 v139, v139
	v_fmamk_f32 v140, v140, 0xbfb8aa3b, v252
	v_exp_f32_e32 v140, v140
	v_fmamk_f32 v141, v141, 0xbfb8aa3b, v252
	v_exp_f32_e32 v141, v141
	v_fmamk_f32 v102, v102, 0xbfb8aa3b, v253
	v_exp_f32_e32 v102, v102
	v_fmamk_f32 v103, v103, 0xbfb8aa3b, v253
	v_exp_f32_e32 v103, v103
	v_fmamk_f32 v104, v104, 0xbfb8aa3b, v253
	v_exp_f32_e32 v104, v104
	v_fmamk_f32 v105, v105, 0xbfb8aa3b, v253
	v_exp_f32_e32 v105, v105
	v_fmamk_f32 v98, v98, 0xbfb8aa3b, v162
	v_exp_f32_e32 v98, v98
	v_fmamk_f32 v99, v99, 0xbfb8aa3b, v162
	v_exp_f32_e32 v99, v99
	v_fmamk_f32 v100, v100, 0xbfb8aa3b, v162
	v_exp_f32_e32 v100, v100
	v_fmamk_f32 v101, v101, 0xbfb8aa3b, v162
	v_exp_f32_e32 v101, v101
	v_add_f32_e32 v146, 1.0, v146
	v_add_f32_e32 v147, 1.0, v147
	v_lshlrev_b32_e32 v156, 16, v238
	v_and_b32_e32 v157, 0xffff0000, v238
	v_rcp_f32_e32 v146, v146
	v_rcp_f32_e32 v147, v147
	v_add_f32_e32 v148, 1.0, v148
	v_add_f32_e32 v149, 1.0, v149
	v_lshlrev_b32_e32 v164, 16, v239
	v_and_b32_e32 v165, 0xffff0000, v239
	v_rcp_f32_e32 v148, v148
	v_rcp_f32_e32 v149, v149
	v_mul_f32_e32 v146, v146, v156
	v_mul_f32_e32 v147, v147, v157
	v_mul_f32_e32 v148, v148, v164
	v_mul_f32_e32 v149, v149, v165
	v_add_f32_e32 v138, 1.0, v138
	v_add_f32_e32 v139, 1.0, v139
	v_lshlrev_b32_e32 v156, 16, v240
	v_and_b32_e32 v157, 0xffff0000, v240
	v_rcp_f32_e32 v138, v138
	v_rcp_f32_e32 v139, v139
	v_add_f32_e32 v140, 1.0, v140
	v_add_f32_e32 v141, 1.0, v141
	v_lshlrev_b32_e32 v164, 16, v241
	v_and_b32_e32 v165, 0xffff0000, v241
	v_rcp_f32_e32 v140, v140
	v_rcp_f32_e32 v141, v141
	v_fmac_f32_e32 v146, v138, v156
	v_fmac_f32_e32 v147, v139, v157
	v_fmac_f32_e32 v148, v140, v164
	v_fmac_f32_e32 v149, v141, v165
	v_add_f32_e32 v102, 1.0, v102
	v_add_f32_e32 v103, 1.0, v103
	v_lshlrev_b32_e32 v156, 16, v242
	v_and_b32_e32 v157, 0xffff0000, v242
	v_rcp_f32_e32 v102, v102
	v_rcp_f32_e32 v103, v103
	v_add_f32_e32 v104, 1.0, v104
	v_add_f32_e32 v105, 1.0, v105
	v_lshlrev_b32_e32 v164, 16, v243
	v_and_b32_e32 v165, 0xffff0000, v243
	v_rcp_f32_e32 v104, v104
	v_rcp_f32_e32 v105, v105
	v_fmac_f32_e32 v146, v102, v156
	v_fmac_f32_e32 v147, v103, v157
	v_fmac_f32_e32 v148, v104, v164
	v_fmac_f32_e32 v149, v105, v165
	v_add_f32_e32 v98, 1.0, v98
	v_add_f32_e32 v99, 1.0, v99
	v_lshlrev_b32_e32 v156, 16, v244
	v_and_b32_e32 v157, 0xffff0000, v244
	v_rcp_f32_e32 v98, v98
	v_rcp_f32_e32 v99, v99
	v_add_f32_e32 v100, 1.0, v100
	v_add_f32_e32 v101, 1.0, v101
	v_lshlrev_b32_e32 v164, 16, v245
	v_and_b32_e32 v165, 0xffff0000, v245
	v_rcp_f32_e32 v100, v100
	v_rcp_f32_e32 v101, v101
	v_fmac_f32_e32 v146, v98, v156
	v_fmac_f32_e32 v147, v99, v157
	v_fmac_f32_e32 v148, v100, v164
	v_fmac_f32_e32 v149, v101, v165
	s_waitcnt vmcnt(20)
	v_fmamk_f32 v134, v134, 0xbfb8aa3b, v170
	v_exp_f32_e32 v134, v134
	v_fmamk_f32 v135, v135, 0xbfb8aa3b, v170
	v_exp_f32_e32 v135, v135
	v_fmamk_f32 v136, v136, 0xbfb8aa3b, v170
	v_exp_f32_e32 v136, v136
	v_fmamk_f32 v137, v137, 0xbfb8aa3b, v170
	v_exp_f32_e32 v137, v137
	v_fmamk_f32 v126, v126, 0xbfb8aa3b, v252
	v_exp_f32_e32 v126, v126
	v_fmamk_f32 v127, v127, 0xbfb8aa3b, v252
	v_exp_f32_e32 v127, v127
	v_fmamk_f32 v128, v128, 0xbfb8aa3b, v252
	v_exp_f32_e32 v128, v128
	v_fmamk_f32 v129, v129, 0xbfb8aa3b, v252
	v_exp_f32_e32 v129, v129
	v_fmamk_f32 v94, v94, 0xbfb8aa3b, v253
	v_exp_f32_e32 v94, v94
	v_fmamk_f32 v95, v95, 0xbfb8aa3b, v253
	v_exp_f32_e32 v95, v95
	v_fmamk_f32 v96, v96, 0xbfb8aa3b, v253
	v_exp_f32_e32 v96, v96
	v_fmamk_f32 v97, v97, 0xbfb8aa3b, v253
	v_exp_f32_e32 v97, v97
	v_fmamk_f32 v90, v90, 0xbfb8aa3b, v162
	v_exp_f32_e32 v90, v90
	v_fmamk_f32 v91, v91, 0xbfb8aa3b, v162
	v_exp_f32_e32 v91, v91
	v_fmamk_f32 v92, v92, 0xbfb8aa3b, v162
	v_exp_f32_e32 v92, v92
	v_fmamk_f32 v93, v93, 0xbfb8aa3b, v162
	v_exp_f32_e32 v93, v93
	v_add_f32_e32 v134, 1.0, v134
	v_add_f32_e32 v135, 1.0, v135
	v_lshlrev_b32_e32 v156, 16, v198
	v_and_b32_e32 v157, 0xffff0000, v198
	v_rcp_f32_e32 v134, v134
	v_rcp_f32_e32 v135, v135
	v_add_f32_e32 v136, 1.0, v136
	v_add_f32_e32 v137, 1.0, v137
	v_lshlrev_b32_e32 v164, 16, v199
	v_and_b32_e32 v165, 0xffff0000, v199
	v_rcp_f32_e32 v136, v136
	v_rcp_f32_e32 v137, v137
	v_mul_f32_e32 v134, v134, v156
	v_mul_f32_e32 v135, v135, v157
	v_mul_f32_e32 v136, v136, v164
	v_mul_f32_e32 v137, v137, v165
	v_add_f32_e32 v126, 1.0, v126
	v_add_f32_e32 v127, 1.0, v127
	v_lshlrev_b32_e32 v156, 16, v200
	v_and_b32_e32 v157, 0xffff0000, v200
	v_rcp_f32_e32 v126, v126
	v_rcp_f32_e32 v127, v127
	v_add_f32_e32 v128, 1.0, v128
	v_add_f32_e32 v129, 1.0, v129
	v_lshlrev_b32_e32 v164, 16, v201
	v_and_b32_e32 v165, 0xffff0000, v201
	v_rcp_f32_e32 v128, v128
	v_rcp_f32_e32 v129, v129
	v_fmac_f32_e32 v134, v126, v156
	v_fmac_f32_e32 v135, v127, v157
	v_fmac_f32_e32 v136, v128, v164
	v_fmac_f32_e32 v137, v129, v165
	v_add_f32_e32 v94, 1.0, v94
	v_add_f32_e32 v95, 1.0, v95
	v_lshlrev_b32_e32 v156, 16, v202
	v_and_b32_e32 v157, 0xffff0000, v202
	v_rcp_f32_e32 v94, v94
	v_rcp_f32_e32 v95, v95
	v_add_f32_e32 v96, 1.0, v96
	v_add_f32_e32 v97, 1.0, v97
	v_lshlrev_b32_e32 v164, 16, v203
	v_and_b32_e32 v165, 0xffff0000, v203
	v_rcp_f32_e32 v96, v96
	v_rcp_f32_e32 v97, v97
	v_fmac_f32_e32 v134, v94, v156
	v_fmac_f32_e32 v135, v95, v157
	v_fmac_f32_e32 v136, v96, v164
	v_fmac_f32_e32 v137, v97, v165
	v_add_f32_e32 v90, 1.0, v90
	v_add_f32_e32 v91, 1.0, v91
	v_lshlrev_b32_e32 v156, 16, v204
	v_and_b32_e32 v157, 0xffff0000, v204
	v_rcp_f32_e32 v90, v90
	v_rcp_f32_e32 v91, v91
	v_add_f32_e32 v92, 1.0, v92
	v_add_f32_e32 v93, 1.0, v93
	v_lshlrev_b32_e32 v164, 16, v205
	v_and_b32_e32 v165, 0xffff0000, v205
	v_rcp_f32_e32 v92, v92
	v_rcp_f32_e32 v93, v93
	v_fmac_f32_e32 v134, v90, v156
	v_fmac_f32_e32 v135, v91, v157
	v_fmac_f32_e32 v136, v92, v164
	v_fmac_f32_e32 v137, v93, v165
	s_waitcnt vmcnt(16)
; DI float sigm(float x) { return 1.f / (1.f + __expf(-x)); }
; DI u32x4 pack8(const float* f) { u32x4 o; o.x = pack2(f[0], f[1]); o.y = pack2(f[2], f[3]); o.z = pack2(f[4], f[5]); o.w = pack2(f[6], f[7]); return o; }
; DI void gate_reg(PREF p, int l, int n, f32x4 (&acc)[2][2][4][2], int dt) {
;     ...
;       for (int m = 0; m < 4; ++m) {
;         float b[8]; unpack8(bn[m], b);
;         float v[8];
; #pragma unroll
;         for (int nn = 0; nn < 2; ++nn)
; #pragma unroll
;           for (int j = 0; j < 4; ++j) v[nn * 4 + j] = sigm(acc[ai][bj][m][nn][j] + bias[bj][nn]) * b[nn * 4 + j];
;         if (n > 0) {
;           float o[8]; unpack8(pv[m], o);
; #pragma unroll
;           for (int e = 0; e < 8; ++e) v[e] += o[e];
;         }
;         if (n < 3) ssum[((ai * 2 + bj) * 4 + m) * 64] = pack8(v);
; #pragma unroll
;         for (int nn = 0; nn < 2; ++nn)
; #pragma unroll
;           for (int j = 0; j < 4; ++j) acc[ai][bj][m][nn][j] = v[nn * 4 + j];
	v_fmamk_f32 v122, v122, 0xbfb8aa3b, v170
	v_exp_f32_e32 v122, v122
	v_fmamk_f32 v123, v123, 0xbfb8aa3b, v170
	v_exp_f32_e32 v123, v123
	v_fmamk_f32 v124, v124, 0xbfb8aa3b, v170
	v_exp_f32_e32 v124, v124
	v_fmamk_f32 v125, v125, 0xbfb8aa3b, v170
	v_exp_f32_e32 v125, v125
	v_fmamk_f32 v114, v114, 0xbfb8aa3b, v252
	v_exp_f32_e32 v114, v114
	v_fmamk_f32 v115, v115, 0xbfb8aa3b, v252
	v_exp_f32_e32 v115, v115
	v_fmamk_f32 v116, v116, 0xbfb8aa3b, v252
	v_exp_f32_e32 v116, v116
	v_fmamk_f32 v117, v117, 0xbfb8aa3b, v252
	v_exp_f32_e32 v117, v117
	v_fmamk_f32 v86, v86, 0xbfb8aa3b, v253
	v_exp_f32_e32 v86, v86
	v_fmamk_f32 v87, v87, 0xbfb8aa3b, v253
	v_exp_f32_e32 v87, v87
	v_fmamk_f32 v88, v88, 0xbfb8aa3b, v253
	v_exp_f32_e32 v88, v88
	v_fmamk_f32 v89, v89, 0xbfb8aa3b, v253
	v_exp_f32_e32 v89, v89
	v_fmamk_f32 v82, v82, 0xbfb8aa3b, v162
	v_exp_f32_e32 v82, v82
	v_fmamk_f32 v83, v83, 0xbfb8aa3b, v162
	v_exp_f32_e32 v83, v83
	v_fmamk_f32 v84, v84, 0xbfb8aa3b, v162
	v_exp_f32_e32 v84, v84
	v_fmamk_f32 v85, v85, 0xbfb8aa3b, v162
	v_exp_f32_e32 v85, v85
	v_add_f32_e32 v122, 1.0, v122
	v_add_f32_e32 v123, 1.0, v123
	v_lshlrev_b32_e32 v156, 16, v206
	v_and_b32_e32 v157, 0xffff0000, v206
	v_rcp_f32_e32 v122, v122
	v_rcp_f32_e32 v123, v123
	v_add_f32_e32 v124, 1.0, v124
	v_add_f32_e32 v125, 1.0, v125
	v_lshlrev_b32_e32 v164, 16, v207
	v_and_b32_e32 v165, 0xffff0000, v207
	v_rcp_f32_e32 v124, v124
	v_rcp_f32_e32 v125, v125
	v_mul_f32_e32 v122, v122, v156
	v_mul_f32_e32 v123, v123, v157
	v_mul_f32_e32 v124, v124, v164
	v_mul_f32_e32 v125, v125, v165
	v_add_f32_e32 v114, 1.0, v114
	v_add_f32_e32 v115, 1.0, v115
	v_lshlrev_b32_e32 v156, 16, v208
	v_and_b32_e32 v157, 0xffff0000, v208
	v_rcp_f32_e32 v114, v114
	v_rcp_f32_e32 v115, v115
	v_add_f32_e32 v116, 1.0, v116
	v_add_f32_e32 v117, 1.0, v117
	v_lshlrev_b32_e32 v164, 16, v209
	v_and_b32_e32 v165, 0xffff0000, v209
	v_rcp_f32_e32 v116, v116
	v_rcp_f32_e32 v117, v117
	v_fmac_f32_e32 v122, v114, v156
	v_fmac_f32_e32 v123, v115, v157
	v_fmac_f32_e32 v124, v116, v164
	v_fmac_f32_e32 v125, v117, v165
	v_add_f32_e32 v86, 1.0, v86
	v_add_f32_e32 v87, 1.0, v87
	v_lshlrev_b32_e32 v156, 16, v210
	v_and_b32_e32 v157, 0xffff0000, v210
	v_rcp_f32_e32 v86, v86
	v_rcp_f32_e32 v87, v87
	v_add_f32_e32 v88, 1.0, v88
	v_add_f32_e32 v89, 1.0, v89
	v_lshlrev_b32_e32 v164, 16, v211
	v_and_b32_e32 v165, 0xffff0000, v211
	v_rcp_f32_e32 v88, v88
	v_rcp_f32_e32 v89, v89
	v_fmac_f32_e32 v122, v86, v156
	v_fmac_f32_e32 v123, v87, v157
	v_fmac_f32_e32 v124, v88, v164
	v_fmac_f32_e32 v125, v89, v165
	v_add_f32_e32 v82, 1.0, v82
	v_add_f32_e32 v83, 1.0, v83
	v_lshlrev_b32_e32 v156, 16, v212
	v_and_b32_e32 v157, 0xffff0000, v212
	v_rcp_f32_e32 v82, v82
	v_rcp_f32_e32 v83, v83
	v_add_f32_e32 v84, 1.0, v84
	v_add_f32_e32 v85, 1.0, v85
	v_lshlrev_b32_e32 v164, 16, v213
	v_and_b32_e32 v165, 0xffff0000, v213
	v_rcp_f32_e32 v84, v84
	v_rcp_f32_e32 v85, v85
	v_fmac_f32_e32 v122, v82, v156
	v_fmac_f32_e32 v123, v83, v157
	v_fmac_f32_e32 v124, v84, v164
	v_fmac_f32_e32 v125, v85, v165
	s_waitcnt vmcnt(12)
	v_fmamk_f32 v78, v78, 0xbfb8aa3b, v170
	v_exp_f32_e32 v78, v78
	v_fmamk_f32 v79, v79, 0xbfb8aa3b, v170
	v_exp_f32_e32 v79, v79
	v_fmamk_f32 v80, v80, 0xbfb8aa3b, v170
	v_exp_f32_e32 v80, v80
	v_fmamk_f32 v81, v81, 0xbfb8aa3b, v170
	v_exp_f32_e32 v81, v81
	v_fmamk_f32 v74, v74, 0xbfb8aa3b, v252
	v_exp_f32_e32 v74, v74
	v_fmamk_f32 v75, v75, 0xbfb8aa3b, v252
	v_exp_f32_e32 v75, v75
	v_fmamk_f32 v76, v76, 0xbfb8aa3b, v252
	v_exp_f32_e32 v76, v76
	v_fmamk_f32 v77, v77, 0xbfb8aa3b, v252
	v_exp_f32_e32 v77, v77
	v_fmamk_f32 v46, v46, 0xbfb8aa3b, v253
	v_exp_f32_e32 v46, v46
	v_fmamk_f32 v47, v47, 0xbfb8aa3b, v253
	v_exp_f32_e32 v47, v47
	v_fmamk_f32 v48, v48, 0xbfb8aa3b, v253
	v_exp_f32_e32 v48, v48
	v_fmamk_f32 v49, v49, 0xbfb8aa3b, v253
	v_exp_f32_e32 v49, v49
	v_fmamk_f32 v38, v38, 0xbfb8aa3b, v162
	v_exp_f32_e32 v38, v38
	v_fmamk_f32 v39, v39, 0xbfb8aa3b, v162
	v_exp_f32_e32 v39, v39
	v_fmamk_f32 v40, v40, 0xbfb8aa3b, v162
	v_exp_f32_e32 v40, v40
	v_fmamk_f32 v41, v41, 0xbfb8aa3b, v162
	v_exp_f32_e32 v41, v41
	v_add_f32_e32 v78, 1.0, v78
	v_add_f32_e32 v79, 1.0, v79
	v_lshlrev_b32_e32 v156, 16, v214
	v_and_b32_e32 v157, 0xffff0000, v214
	v_rcp_f32_e32 v78, v78
	v_rcp_f32_e32 v79, v79
	v_add_f32_e32 v80, 1.0, v80
	v_add_f32_e32 v81, 1.0, v81
	v_lshlrev_b32_e32 v164, 16, v215
	v_and_b32_e32 v165, 0xffff0000, v215
	v_rcp_f32_e32 v80, v80
	v_rcp_f32_e32 v81, v81
	v_mul_f32_e32 v78, v78, v156
	v_mul_f32_e32 v79, v79, v157
	v_mul_f32_e32 v80, v80, v164
	v_mul_f32_e32 v81, v81, v165
	v_add_f32_e32 v74, 1.0, v74
	v_add_f32_e32 v75, 1.0, v75
	v_lshlrev_b32_e32 v156, 16, v216
	v_and_b32_e32 v157, 0xffff0000, v216
	v_rcp_f32_e32 v74, v74
	v_rcp_f32_e32 v75, v75
	v_add_f32_e32 v76, 1.0, v76
	v_add_f32_e32 v77, 1.0, v77
	v_lshlrev_b32_e32 v164, 16, v217
	v_and_b32_e32 v165, 0xffff0000, v217
	v_rcp_f32_e32 v76, v76
	v_rcp_f32_e32 v77, v77
	v_fmac_f32_e32 v78, v74, v156
	v_fmac_f32_e32 v79, v75, v157
	v_fmac_f32_e32 v80, v76, v164
	v_fmac_f32_e32 v81, v77, v165
	v_add_f32_e32 v46, 1.0, v46
	v_add_f32_e32 v47, 1.0, v47
	v_lshlrev_b32_e32 v156, 16, v218
	v_and_b32_e32 v157, 0xffff0000, v218
	v_rcp_f32_e32 v46, v46
	v_rcp_f32_e32 v47, v47
	v_add_f32_e32 v48, 1.0, v48
	v_add_f32_e32 v49, 1.0, v49
	v_lshlrev_b32_e32 v164, 16, v219
	v_and_b32_e32 v165, 0xffff0000, v219
	v_rcp_f32_e32 v48, v48
	v_rcp_f32_e32 v49, v49
	v_fmac_f32_e32 v78, v46, v156
	v_fmac_f32_e32 v79, v47, v157
	v_fmac_f32_e32 v80, v48, v164
	v_fmac_f32_e32 v81, v49, v165
	v_add_f32_e32 v38, 1.0, v38
	v_add_f32_e32 v39, 1.0, v39
	v_lshlrev_b32_e32 v156, 16, v220
	v_and_b32_e32 v157, 0xffff0000, v220
	v_rcp_f32_e32 v38, v38
	v_rcp_f32_e32 v39, v39
	v_add_f32_e32 v40, 1.0, v40
	v_add_f32_e32 v41, 1.0, v41
	v_lshlrev_b32_e32 v164, 16, v221
	v_and_b32_e32 v165, 0xffff0000, v221
	v_rcp_f32_e32 v40, v40
	v_rcp_f32_e32 v41, v41
	v_fmac_f32_e32 v78, v38, v156
	v_fmac_f32_e32 v79, v39, v157
	v_fmac_f32_e32 v80, v40, v164
	v_fmac_f32_e32 v81, v41, v165
	s_waitcnt vmcnt(8)
; DI float sigm(float x) { return 1.f / (1.f + __expf(-x)); }
; DI u32x4 pack8(const float* f) { u32x4 o; o.x = pack2(f[0], f[1]); o.y = pack2(f[2], f[3]); o.z = pack2(f[4], f[5]); o.w = pack2(f[6], f[7]); return o; }
; DI void gate_reg(PREF p, int l, int n, f32x4 (&acc)[2][2][4][2], int dt) {
;     ...
;       for (int m = 0; m < 4; ++m) {
;         float b[8]; unpack8(bn[m], b);
;         float v[8];
; #pragma unroll
;         for (int nn = 0; nn < 2; ++nn)
; #pragma unroll
;           for (int j = 0; j < 4; ++j) v[nn * 4 + j] = sigm(acc[ai][bj][m][nn][j] + bias[bj][nn]) * b[nn * 4 + j];
;         if (n > 0) {
;           float o[8]; unpack8(pv[m], o);
; #pragma unroll
;           for (int e = 0; e < 8; ++e) v[e] += o[e];
;         }
;         if (n < 3) ssum[((ai * 2 + bj) * 4 + m) * 64] = pack8(v);
; #pragma unroll
;         for (int nn = 0; nn < 2; ++nn)
; #pragma unroll
;           for (int j = 0; j < 4; ++j) acc[ai][bj][m][nn][j] = v[nn * 4 + j];
	v_fmamk_f32 v70, v70, 0xbfb8aa3b, v170
	v_exp_f32_e32 v70, v70
	v_fmamk_f32 v71, v71, 0xbfb8aa3b, v170
	v_exp_f32_e32 v71, v71
	v_fmamk_f32 v72, v72, 0xbfb8aa3b, v170
	v_exp_f32_e32 v72, v72
	v_fmamk_f32 v73, v73, 0xbfb8aa3b, v170
	v_exp_f32_e32 v73, v73
	v_fmamk_f32 v66, v66, 0xbfb8aa3b, v252
	v_exp_f32_e32 v66, v66
	v_fmamk_f32 v67, v67, 0xbfb8aa3b, v252
	v_exp_f32_e32 v67, v67
	v_fmamk_f32 v68, v68, 0xbfb8aa3b, v252
	v_exp_f32_e32 v68, v68
	v_fmamk_f32 v69, v69, 0xbfb8aa3b, v252
	v_exp_f32_e32 v69, v69
	v_fmamk_f32 v34, v34, 0xbfb8aa3b, v253
	v_exp_f32_e32 v34, v34
	v_fmamk_f32 v35, v35, 0xbfb8aa3b, v253
	v_exp_f32_e32 v35, v35
	v_fmamk_f32 v36, v36, 0xbfb8aa3b, v253
	v_exp_f32_e32 v36, v36
	v_fmamk_f32 v37, v37, 0xbfb8aa3b, v253
	v_exp_f32_e32 v37, v37
	v_fmamk_f32 v26, v26, 0xbfb8aa3b, v162
	v_exp_f32_e32 v26, v26
	v_fmamk_f32 v27, v27, 0xbfb8aa3b, v162
	v_exp_f32_e32 v27, v27
	v_fmamk_f32 v28, v28, 0xbfb8aa3b, v162
	v_exp_f32_e32 v28, v28
	v_fmamk_f32 v29, v29, 0xbfb8aa3b, v162
	v_exp_f32_e32 v29, v29
	v_add_f32_e32 v70, 1.0, v70
	v_add_f32_e32 v71, 1.0, v71
	v_lshlrev_b32_e32 v156, 16, v222
	v_and_b32_e32 v157, 0xffff0000, v222
	v_rcp_f32_e32 v70, v70
	v_rcp_f32_e32 v71, v71
	v_add_f32_e32 v72, 1.0, v72
	v_add_f32_e32 v73, 1.0, v73
	v_lshlrev_b32_e32 v164, 16, v223
	v_and_b32_e32 v165, 0xffff0000, v223
	v_rcp_f32_e32 v72, v72
	v_rcp_f32_e32 v73, v73
	v_mul_f32_e32 v70, v70, v156
	v_mul_f32_e32 v71, v71, v157
	v_mul_f32_e32 v72, v72, v164
	v_mul_f32_e32 v73, v73, v165
	v_add_f32_e32 v66, 1.0, v66
	v_add_f32_e32 v67, 1.0, v67
	v_lshlrev_b32_e32 v156, 16, v224
	v_and_b32_e32 v157, 0xffff0000, v224
	v_rcp_f32_e32 v66, v66
	v_rcp_f32_e32 v67, v67
	v_add_f32_e32 v68, 1.0, v68
	v_add_f32_e32 v69, 1.0, v69
	v_lshlrev_b32_e32 v164, 16, v225
	v_and_b32_e32 v165, 0xffff0000, v225
	v_rcp_f32_e32 v68, v68
	v_rcp_f32_e32 v69, v69
	v_fmac_f32_e32 v70, v66, v156
	v_fmac_f32_e32 v71, v67, v157
	v_fmac_f32_e32 v72, v68, v164
	v_fmac_f32_e32 v73, v69, v165
	v_add_f32_e32 v34, 1.0, v34
	v_add_f32_e32 v35, 1.0, v35
	v_lshlrev_b32_e32 v156, 16, v226
	v_and_b32_e32 v157, 0xffff0000, v226
	v_rcp_f32_e32 v34, v34
	v_rcp_f32_e32 v35, v35
	v_add_f32_e32 v36, 1.0, v36
	v_add_f32_e32 v37, 1.0, v37
	v_lshlrev_b32_e32 v164, 16, v227
	v_and_b32_e32 v165, 0xffff0000, v227
	v_rcp_f32_e32 v36, v36
	v_rcp_f32_e32 v37, v37
	v_fmac_f32_e32 v70, v34, v156
	v_fmac_f32_e32 v71, v35, v157
	v_fmac_f32_e32 v72, v36, v164
	v_fmac_f32_e32 v73, v37, v165
	v_add_f32_e32 v26, 1.0, v26
	v_add_f32_e32 v27, 1.0, v27
	v_lshlrev_b32_e32 v156, 16, v228
	v_and_b32_e32 v157, 0xffff0000, v228
	v_rcp_f32_e32 v26, v26
	v_rcp_f32_e32 v27, v27
	v_add_f32_e32 v28, 1.0, v28
	v_add_f32_e32 v29, 1.0, v29
	v_lshlrev_b32_e32 v164, 16, v229
	v_and_b32_e32 v165, 0xffff0000, v229
	v_rcp_f32_e32 v28, v28
	v_rcp_f32_e32 v29, v29
	v_fmac_f32_e32 v70, v26, v156
	v_fmac_f32_e32 v71, v27, v157
	v_fmac_f32_e32 v72, v28, v164
	v_fmac_f32_e32 v73, v29, v165
	s_waitcnt vmcnt(4)
	v_fmamk_f32 v62, v62, 0xbfb8aa3b, v170
	v_exp_f32_e32 v62, v62
	v_fmamk_f32 v63, v63, 0xbfb8aa3b, v170
	v_exp_f32_e32 v63, v63
	v_fmamk_f32 v64, v64, 0xbfb8aa3b, v170
	v_exp_f32_e32 v64, v64
	v_fmamk_f32 v65, v65, 0xbfb8aa3b, v170
	v_exp_f32_e32 v65, v65
	v_fmamk_f32 v58, v58, 0xbfb8aa3b, v252
	v_exp_f32_e32 v58, v58
	v_fmamk_f32 v59, v59, 0xbfb8aa3b, v252
	v_exp_f32_e32 v59, v59
	v_fmamk_f32 v60, v60, 0xbfb8aa3b, v252
	v_exp_f32_e32 v60, v60
	v_fmamk_f32 v61, v61, 0xbfb8aa3b, v252
	v_exp_f32_e32 v61, v61
	v_fmamk_f32 v22, v22, 0xbfb8aa3b, v253
	v_exp_f32_e32 v22, v22
	v_fmamk_f32 v23, v23, 0xbfb8aa3b, v253
	v_exp_f32_e32 v23, v23
	v_fmamk_f32 v24, v24, 0xbfb8aa3b, v253
	v_exp_f32_e32 v24, v24
	v_fmamk_f32 v25, v25, 0xbfb8aa3b, v253
	v_exp_f32_e32 v25, v25
	v_fmamk_f32 v14, v14, 0xbfb8aa3b, v162
	v_exp_f32_e32 v14, v14
	v_fmamk_f32 v15, v15, 0xbfb8aa3b, v162
	v_exp_f32_e32 v15, v15
	v_fmamk_f32 v16, v16, 0xbfb8aa3b, v162
	v_exp_f32_e32 v16, v16
	v_fmamk_f32 v17, v17, 0xbfb8aa3b, v162
	v_exp_f32_e32 v17, v17
	v_add_f32_e32 v62, 1.0, v62
	v_add_f32_e32 v63, 1.0, v63
	v_lshlrev_b32_e32 v156, 16, v182
	v_and_b32_e32 v157, 0xffff0000, v182
	v_rcp_f32_e32 v62, v62
	v_rcp_f32_e32 v63, v63
	v_add_f32_e32 v64, 1.0, v64
	v_add_f32_e32 v65, 1.0, v65
	v_lshlrev_b32_e32 v164, 16, v183
	v_and_b32_e32 v165, 0xffff0000, v183
	v_rcp_f32_e32 v64, v64
	v_rcp_f32_e32 v65, v65
	v_mul_f32_e32 v62, v62, v156
	v_mul_f32_e32 v63, v63, v157
	v_mul_f32_e32 v64, v64, v164
	v_mul_f32_e32 v65, v65, v165
	v_add_f32_e32 v58, 1.0, v58
	v_add_f32_e32 v59, 1.0, v59
	v_lshlrev_b32_e32 v156, 16, v184
	v_and_b32_e32 v157, 0xffff0000, v184
	v_rcp_f32_e32 v58, v58
	v_rcp_f32_e32 v59, v59
	v_add_f32_e32 v60, 1.0, v60
	v_add_f32_e32 v61, 1.0, v61
	v_lshlrev_b32_e32 v164, 16, v185
	v_and_b32_e32 v165, 0xffff0000, v185
	v_rcp_f32_e32 v60, v60
	v_rcp_f32_e32 v61, v61
	v_fmac_f32_e32 v62, v58, v156
	v_fmac_f32_e32 v63, v59, v157
	v_fmac_f32_e32 v64, v60, v164
	v_fmac_f32_e32 v65, v61, v165
	v_add_f32_e32 v22, 1.0, v22
	v_add_f32_e32 v23, 1.0, v23
	v_lshlrev_b32_e32 v156, 16, v186
	v_and_b32_e32 v157, 0xffff0000, v186
	v_rcp_f32_e32 v22, v22
	v_rcp_f32_e32 v23, v23
	v_add_f32_e32 v24, 1.0, v24
	v_add_f32_e32 v25, 1.0, v25
	v_lshlrev_b32_e32 v164, 16, v187
	v_and_b32_e32 v165, 0xffff0000, v187
	v_rcp_f32_e32 v24, v24
	v_rcp_f32_e32 v25, v25
	v_fmac_f32_e32 v62, v22, v156
	v_fmac_f32_e32 v63, v23, v157
	v_fmac_f32_e32 v64, v24, v164
	v_fmac_f32_e32 v65, v25, v165
	v_add_f32_e32 v14, 1.0, v14
	v_add_f32_e32 v15, 1.0, v15
	v_lshlrev_b32_e32 v156, 16, v188
	v_and_b32_e32 v157, 0xffff0000, v188
	v_rcp_f32_e32 v14, v14
	v_rcp_f32_e32 v15, v15
	v_add_f32_e32 v16, 1.0, v16
	v_add_f32_e32 v17, 1.0, v17
	v_lshlrev_b32_e32 v164, 16, v189
	v_and_b32_e32 v165, 0xffff0000, v189
	v_rcp_f32_e32 v16, v16
	v_rcp_f32_e32 v17, v17
	v_fmac_f32_e32 v62, v14, v156
	v_fmac_f32_e32 v63, v15, v157
	v_fmac_f32_e32 v64, v16, v164
	v_fmac_f32_e32 v65, v17, v165
	s_waitcnt vmcnt(0)
; DI float sigm(float x) { return 1.f / (1.f + __expf(-x)); }
; DI u32x4 pack8(const float* f) { u32x4 o; o.x = pack2(f[0], f[1]); o.y = pack2(f[2], f[3]); o.z = pack2(f[4], f[5]); o.w = pack2(f[6], f[7]); return o; }
; DI int tid512() { int t = threadIdx.x; asm volatile("" : "+v"(t)); return t; }
; DI void gate_reg(PREF p, int l, int n, f32x4 (&acc)[2][2][4][2], int dt) {
;     ...
;       for (int m = 0; m < 4; ++m) {
;         float b[8]; unpack8(bn[m], b);
;         float v[8];
; #pragma unroll
;         for (int nn = 0; nn < 2; ++nn)
; #pragma unroll
;           for (int j = 0; j < 4; ++j) v[nn * 4 + j] = sigm(acc[ai][bj][m][nn][j] + bias[bj][nn]) * b[nn * 4 + j];
;         if (n > 0) {
;           float o[8]; unpack8(pv[m], o);
; #pragma unroll
;           for (int e = 0; e < 8; ++e) v[e] += o[e];
;         }
;         if (n < 3) ssum[((ai * 2 + bj) * 4 + m) * 64] = pack8(v);
; #pragma unroll
;         for (int nn = 0; nn < 2; ++nn)
; #pragma unroll
;           for (int j = 0; j < 4; ++j) acc[ai][bj][m][nn][j] = v[nn * 4 + j];
; template <int AI, int BJ>
; DI void mg_quadrant(PREF p, const f32x4 (&acc)[2][2][4][2], int mt, int dt, float* Cs) {
;   const int t = tid512();
;   const int row0 = mt * 256 + AI * 128, col0 = dt * 256 + BJ * 128;
;   stage_q<AI, BJ>(acc, Cs);
; #pragma unroll
;   for (int q = 0; q < 4; ++q) {
;     int r = (t >> 4) + 32 * q, c = (t & 15) * 8;
;     float v[8]; ld8(Cs + r * CST + c, v);
;     *(u32x4*)(p.mg + (size_t)(row0 + r) * 1024 + col0 + c) = pack8(v);
;   }
; }
	v_fmamk_f32 v54, v54, 0xbfb8aa3b, v170
	v_exp_f32_e32 v54, v54
	v_fmamk_f32 v55, v55, 0xbfb8aa3b, v170
	v_exp_f32_e32 v55, v55
	v_fmamk_f32 v56, v56, 0xbfb8aa3b, v170
	v_exp_f32_e32 v56, v56
	v_fmamk_f32 v57, v57, 0xbfb8aa3b, v170
	v_exp_f32_e32 v57, v57
	v_fmamk_f32 v50, v50, 0xbfb8aa3b, v252
	v_exp_f32_e32 v50, v50
	v_fmamk_f32 v51, v51, 0xbfb8aa3b, v252
	v_exp_f32_e32 v51, v51
	v_fmamk_f32 v52, v52, 0xbfb8aa3b, v252
	v_exp_f32_e32 v52, v52
	v_fmamk_f32 v53, v53, 0xbfb8aa3b, v252
	v_exp_f32_e32 v53, v53
	v_fmamk_f32 v10, v10, 0xbfb8aa3b, v253
	v_exp_f32_e32 v10, v10
	v_fmamk_f32 v11, v11, 0xbfb8aa3b, v253
	v_exp_f32_e32 v11, v11
	v_fmamk_f32 v12, v12, 0xbfb8aa3b, v253
	v_exp_f32_e32 v12, v12
	v_fmamk_f32 v13, v13, 0xbfb8aa3b, v253
	v_exp_f32_e32 v13, v13
	v_fmamk_f32 v2, v2, 0xbfb8aa3b, v162
	v_exp_f32_e32 v2, v2
	v_fmamk_f32 v3, v3, 0xbfb8aa3b, v162
	v_exp_f32_e32 v3, v3
	v_fmamk_f32 v4, v4, 0xbfb8aa3b, v162
	v_exp_f32_e32 v4, v4
	v_fmamk_f32 v5, v5, 0xbfb8aa3b, v162
	v_exp_f32_e32 v5, v5
	v_add_f32_e32 v54, 1.0, v54
	v_add_f32_e32 v55, 1.0, v55
	v_lshlrev_b32_e32 v156, 16, v190
	v_and_b32_e32 v157, 0xffff0000, v190
	v_rcp_f32_e32 v54, v54
	v_rcp_f32_e32 v55, v55
	v_add_f32_e32 v56, 1.0, v56
	v_add_f32_e32 v57, 1.0, v57
	v_lshlrev_b32_e32 v164, 16, v191
	v_and_b32_e32 v165, 0xffff0000, v191
	v_rcp_f32_e32 v56, v56
	v_rcp_f32_e32 v57, v57
	v_mul_f32_e32 v54, v54, v156
	v_mul_f32_e32 v55, v55, v157
	v_mul_f32_e32 v56, v56, v164
	v_mul_f32_e32 v57, v57, v165
	v_add_f32_e32 v50, 1.0, v50
	v_add_f32_e32 v51, 1.0, v51
	v_lshlrev_b32_e32 v156, 16, v192
	v_and_b32_e32 v157, 0xffff0000, v192
	v_rcp_f32_e32 v50, v50
	v_rcp_f32_e32 v51, v51
	v_add_f32_e32 v52, 1.0, v52
	v_add_f32_e32 v53, 1.0, v53
	v_lshlrev_b32_e32 v164, 16, v193
	v_and_b32_e32 v165, 0xffff0000, v193
	v_rcp_f32_e32 v52, v52
	v_rcp_f32_e32 v53, v53
	v_fmac_f32_e32 v54, v50, v156
	v_fmac_f32_e32 v55, v51, v157
	v_fmac_f32_e32 v56, v52, v164
	v_fmac_f32_e32 v57, v53, v165
	v_add_f32_e32 v10, 1.0, v10
	v_add_f32_e32 v11, 1.0, v11
	v_lshlrev_b32_e32 v156, 16, v194
	v_and_b32_e32 v157, 0xffff0000, v194
	v_rcp_f32_e32 v10, v10
	v_rcp_f32_e32 v11, v11
	v_add_f32_e32 v12, 1.0, v12
	v_add_f32_e32 v13, 1.0, v13
	v_lshlrev_b32_e32 v164, 16, v195
	v_and_b32_e32 v165, 0xffff0000, v195
	v_rcp_f32_e32 v12, v12
	v_rcp_f32_e32 v13, v13
	v_fmac_f32_e32 v54, v10, v156
	v_fmac_f32_e32 v55, v11, v157
	v_fmac_f32_e32 v56, v12, v164
	v_fmac_f32_e32 v57, v13, v165
	v_add_f32_e32 v2, 1.0, v2
	v_add_f32_e32 v3, 1.0, v3
	v_lshlrev_b32_e32 v156, 16, v196
	v_and_b32_e32 v157, 0xffff0000, v196
	v_rcp_f32_e32 v2, v2
	v_rcp_f32_e32 v3, v3
	v_add_f32_e32 v4, 1.0, v4
	v_add_f32_e32 v5, 1.0, v5
	v_lshlrev_b32_e32 v164, 16, v197
	v_and_b32_e32 v165, 0xffff0000, v197
	v_rcp_f32_e32 v4, v4
	v_rcp_f32_e32 v5, v5
	v_fmac_f32_e32 v54, v2, v156
	v_fmac_f32_e32 v55, v3, v157
	v_fmac_f32_e32 v56, v4, v164
	v_fmac_f32_e32 v57, v5, v165
	v_lshrrev_b32_e32 v156, 8, v168
	v_lshlrev_b32_e32 v156, 6, v156
	v_bfe_u32 v157, v168, 4, 2
	v_lshl_add_u32 v156, v157, 2, v156
	v_mul_u32_u24_e32 v156, 0x84, v156
	v_lshlrev_b32_e32 v157, 4, v155
	v_and_b32_e32 v164, 15, v168
	v_add3_u32 v156, v156, v157, v164
	v_lshlrev_b32_e32 v156, 2, v156
	v_lshrrev_b32_e32 v157, 3, v168
	v_lshlrev_b32_e32 v165, 11, v157
	v_mul_u32_u24_e32 v157, 0x84, v157
	v_and_b32_e32 v164, 7, v168
	v_lshl_add_u32 v157, v164, 3, v157
	v_lshlrev_b32_e32 v157, 2, v157
	v_lshl_add_u32 v165, v164, 4, v165
	v_mov_b32_e32 v164, v165
	s_waitcnt lgkmcnt(0)
	s_barrier
	ds_write_b32 v156, v158 offset:0
	ds_write_b32 v156, v159 offset:528
	ds_write_b32 v156, v160 offset:1056
	ds_write_b32 v156, v161 offset:1584
	ds_write_b32 v156, v146 offset:8448
	ds_write_b32 v156, v147 offset:8976
	ds_write_b32 v156, v148 offset:9504
	ds_write_b32 v156, v149 offset:10032
	ds_write_b32 v156, v134 offset:16896
	ds_write_b32 v156, v135 offset:17424
	ds_write_b32 v156, v136 offset:17952
	ds_write_b32 v156, v137 offset:18480
	ds_write_b32 v156, v122 offset:25344
	ds_write_b32 v156, v123 offset:25872
	ds_write_b32 v156, v124 offset:26400
	ds_write_b32 v156, v125 offset:26928
	s_waitcnt lgkmcnt(0)
	s_barrier
	s_add_i32 s0, s12, 0
	s_lshl_b32 s0, s0, 11
	s_lshl_b32 s1, s23, 7
	s_add_u32 s0, s0, s1
	s_add_u32 s0, s36, s0
	s_addc_u32 s1, s37, 0
	ds_read_b128 v[230:233], v157 offset:0
	ds_read_b128 v[234:237], v157 offset:16
	ds_read_b128 v[238:241], v157 offset:33792
	ds_read_b128 v[242:245], v157 offset:33808
	s_waitcnt lgkmcnt(2)
	v_cvt_pk_bf16_f32 v230, v230, v231
	v_cvt_pk_bf16_f32 v231, v232, v233
	v_cvt_pk_bf16_f32 v232, v234, v235
	v_cvt_pk_bf16_f32 v233, v236, v237
	global_store_dwordx4 v164, v[230:233], s[0:1]
	s_waitcnt lgkmcnt(0)
	v_cvt_pk_bf16_f32 v238, v238, v239
	v_cvt_pk_bf16_f32 v239, v240, v241
	v_cvt_pk_bf16_f32 v240, v242, v243
	v_cvt_pk_bf16_f32 v241, v244, v245
	v_add_u32_e32 v164, 0x20000, v164
	global_store_dwordx4 v164, v[238:241], s[0:1]
	v_mov_b32_e32 v164, v165
	s_waitcnt lgkmcnt(0)
	s_barrier
	ds_write_b32 v156, v78 offset:0
	ds_write_b32 v156, v79 offset:528
	ds_write_b32 v156, v80 offset:1056
	ds_write_b32 v156, v81 offset:1584
	ds_write_b32 v156, v70 offset:8448
	ds_write_b32 v156, v71 offset:8976
	ds_write_b32 v156, v72 offset:9504
	ds_write_b32 v156, v73 offset:10032
	ds_write_b32 v156, v62 offset:16896
	ds_write_b32 v156, v63 offset:17424
	ds_write_b32 v156, v64 offset:17952
	ds_write_b32 v156, v65 offset:18480
	ds_write_b32 v156, v54 offset:25344
	ds_write_b32 v156, v55 offset:25872
	ds_write_b32 v156, v56 offset:26400
	ds_write_b32 v156, v57 offset:26928
	s_waitcnt lgkmcnt(0)
	s_barrier
	s_add_i32 s0, s12, 128
	s_lshl_b32 s0, s0, 11
	s_lshl_b32 s1, s23, 7
	s_add_u32 s0, s0, s1
	s_add_u32 s0, s36, s0
	s_addc_u32 s1, s37, 0
	ds_read_b128 v[230:233], v157 offset:0
	ds_read_b128 v[234:237], v157 offset:16
	ds_read_b128 v[238:241], v157 offset:33792
	ds_read_b128 v[242:245], v157 offset:33808
	s_waitcnt lgkmcnt(2)
	v_cvt_pk_bf16_f32 v230, v230, v231
	v_cvt_pk_bf16_f32 v231, v232, v233
	v_cvt_pk_bf16_f32 v232, v234, v235
	v_cvt_pk_bf16_f32 v233, v236, v237
	global_store_dwordx4 v164, v[230:233], s[0:1]
	s_waitcnt lgkmcnt(0)
	v_cvt_pk_bf16_f32 v238, v238, v239
	v_cvt_pk_bf16_f32 v239, v240, v241
	v_cvt_pk_bf16_f32 v240, v242, v243
	v_cvt_pk_bf16_f32 v241, v244, v245
	v_add_u32_e32 v164, 0x20000, v164
	global_store_dwordx4 v164, v[238:241], s[0:1]
	s_branch .LBB0_101

; DI void lds_barrier() { asm volatile("s_waitcnt lgkmcnt(0)\n\ts_barrier" ::: "memory"); }
; DI int tid512() { int t = threadIdx.x; asm volatile("" : "+v"(t)); return t; }
; #define G_LDA(dst, b, h)                                                                                                  \
;   _Pragma("unroll") for (int m = 0; m < 4; ++m) _Pragma("unroll") for (int k = 0; k < 2; ++k)                             \
;       dst[m][k] = *(const bf16x8*)((const char*)G_SA(b, h) + ((wr * 4 + m) * 2 + k) * 1024 + rdo)
; #define G_LDB(dst, b, h)                                                                                                  \
;   _Pragma("unroll") for (int n = 0; n < 2; ++n) _Pragma("unroll") for (int k = 0; k < 2; ++k)                             \
;       dst[n][k] = *(const bf16x8*)((const char*)G_SB(b, h) + ((wc * 2 + n) * 2 + k) * 1024 + rdo)
; #define G_WAIT_V(n) asm volatile("s_waitcnt vmcnt(" #n ")" ::: "memory")
; #define G_BAR __builtin_amdgcn_s_barrier()
; #define G_SCHED __builtin_amdgcn_sched_barrier(0)
;     ...
;   const int t = tid512();
;   const int wid = t >> 6, lane = t & 63, wr = wid >> 2, wc = wid & 3, fr = lane & 15, fq = lane >> 4;
;   int r0, c0, r1, c1;
;   g_stage_rc(t * 16, r0, c0); g_stage_rc(t * 16 + 8192, r1, c1);
;   const int oa0 = r0 * LDA + c0, oa1 = r1 * LDA + c1, ob0 = r0 * LDB + c0, ob1 = r1 * LDB + c1;
;   const int obr = fr * 64 + fq * 16, rdo = obr ^ (((obr >> 9) & 1) << 5);
;   bf16x8 At[4][2], B0[2][2], B1[2][2];
;   constexpr int nt = K / 64;
;   lds_barrier();
;   G_STAGE(G_SB(0, 0), B, ob0, ob1, LDB, 0, KB(0)); G_STAGE(G_SA(0, 0), A, oa0, oa1, LDA, 0, KA(0));
;   G_STAGE(G_SB(0, 1), B, ob0, ob1, LDB, 128, KB(0)); G_STAGE(G_SA(0, 1), A, oa0, oa1, LDA, 128, KA(0));
;   if (wr == 1) G_BAR;
;   G_WAIT_V(4); G_BAR;
;   G_STAGE(G_SB(1, 0), B, ob0, ob1, LDB, 0, KB(1)); G_STAGE(G_SA(1, 0), A, oa0, oa1, LDA, 0, KA(1)); G_STAGE(G_SB(1, 1), B, ob0, ob1, LDB, 128, KB(1));
;   G_WAIT_V(6); G_BAR;
;   for (int tt = 0; tt < nt - 2; tt += 2) {
;     G_LDB(B0, 0, 0); G_SCHED; G_LDA(At, 0, 0); G_STAGE(G_SA(1, 1), A, oa0, oa1, LDA, 128, KA(tt + 1));
.LBB0_215:
	s_ashr_i32 s14, s24, 1
	s_ashr_i32 s15, s14, 31
	s_and_b32 s25, s24, 1
	s_lshl_b64 s[0:1], s[14:15], 17
	v_mov_b32_e32 v0, v168
	s_add_u32 s16, s12, s0
	s_addc_u32 s17, s13, s1
	v_lshlrev_b32_e32 v18, 4, v0
	s_nop 0
	v_readfirstlane_b32 s32, v18
	v_and_b32_e32 v2, 32, v0
	s_lshl_b32 s0, s25, 17
	v_bitop3_b32 v2, v18, v2, 48 bitop3:0x6c
	s_add_u32 s18, s22, s0
	v_lshrrev_b32_e32 v3, 3, v0
	v_bfe_u32 v4, v0, 2, 4
	s_mov_b32 s0, 0xfffff0
	v_lshrrev_b32_e32 v5, 1, v0
	v_lshrrev_b32_e32 v2, 1, v2
	v_add_u32_e32 v19, 0x2000, v18
	v_and_or_b32 v3, v3, s0, v4
	v_and_or_b32 v5, v5, 32, v2
	v_lshrrev_b32_e32 v2, 7, v19
	v_and_or_b32 v4, v2, s0, v4
	v_lshl_or_b32 v2, v3, 8, v5
	v_lshl_or_b32 v4, v4, 8, v5
	v_ashrrev_i32_e32 v3, 31, v2
	s_addc_u32 s19, s23, 0
	v_lshlrev_b64 v[2:3], 1, v[2:3]
	v_ashrrev_i32_e32 v5, 31, v4
	s_waitcnt lgkmcnt(0)
	s_barrier
	v_lshl_add_u64 v[6:7], s[18:19], 0, v[2:3]
	s_add_u32 m0, s32, 0x10000
	v_lshlrev_b64 v[4:5], 1, v[4:5]
	global_load_lds_dwordx4 v[6:7], off
	v_lshl_add_u64 v[8:9], s[18:19], 0, v[4:5]
	s_add_u32 m0, s32, 0x12000
	s_nop 0
	global_load_lds_dwordx4 v[8:9], off
	v_lshl_add_u64 v[10:11], s[16:17], 0, v[2:3]
	s_mov_b32 m0, s32
	s_nop 0
	global_load_lds_dwordx4 v[10:11], off
	s_add_u32 m0, s32, 0x2000
	s_add_u32 s0, s18, 0x10000
	v_lshl_add_u64 v[14:15], s[16:17], 0, v[4:5]
	s_addc_u32 s1, s19, 0
	global_load_lds_dwordx4 v[14:15], off
	v_lshl_add_u64 v[16:17], s[0:1], 0, v[2:3]
	s_add_u32 m0, s32, 0x14000
	s_nop 0
	global_load_lds_dwordx4 v[16:17], off
	v_lshl_add_u64 v[16:17], s[0:1], 0, v[4:5]
	s_add_u32 m0, s32, 0x16000
	s_add_u32 s0, s16, 0x10000
	global_load_lds_dwordx4 v[16:17], off
	v_add_u32_e32 v16, 0x4000, v18
	s_addc_u32 s1, s17, 0
	v_readfirstlane_b32 s15, v16
	v_lshl_add_u64 v[24:25], s[0:1], 0, v[2:3]
	s_add_u32 m0, s32, 0x4000
	v_add_u32_e32 v17, 0x6000, v18
	global_load_lds_dwordx4 v[24:25], off
	v_lshl_add_u64 v[24:25], s[0:1], 0, v[4:5]
	v_readfirstlane_b32 s0, v17
	s_add_u32 m0, s32, 0x6000
	v_ashrrev_i32_e32 v12, 8, v0
	global_load_lds_dwordx4 v[24:25], off
	v_cmp_eq_u32_e32 vcc, 1, v12
	s_and_saveexec_b64 s[20:21], vcc
	s_cbranch_execz .LBB0_217
	s_barrier
.LBB0_217:
	s_or_b64 exec, exec, s[20:21]
	v_add_u32_e32 v13, 0x18000, v18
	v_lshl_add_u64 v[24:25], v[6:7], 0, s[76:77]
	v_readfirstlane_b32 s27, v13
	v_add_u32_e32 v13, 0x1a000, v18
	s_mov_b32 m0, s27
	v_readfirstlane_b32 s28, v13
	v_add_u32_e32 v13, 0x8000, v18
	s_waitcnt vmcnt(4)
	s_barrier
	global_load_lds_dwordx4 v[24:25], off
	v_lshl_add_u64 v[24:25], v[8:9], 0, s[76:77]
	s_mov_b32 m0, s28
	v_readfirstlane_b32 s21, v13
	v_add_u32_e32 v13, 0xa000, v18
	global_load_lds_dwordx4 v[24:25], off
	v_lshl_add_u64 v[24:25], v[10:11], 0, s[76:77]
	s_mov_b32 m0, s21
	v_readfirstlane_b32 s26, v13
	s_add_u32 s0, s18, 0x10080
	v_add_u32_e32 v13, 0x1c000, v18
	global_load_lds_dwordx4 v[24:25], off
	v_lshl_add_u64 v[24:25], v[14:15], 0, s[76:77]
	s_mov_b32 m0, s26
	s_addc_u32 s1, s19, 0
	v_readfirstlane_b32 s15, v13
	v_add_u32_e32 v13, 0x1e000, v18
	global_load_lds_dwordx4 v[24:25], off
	v_lshl_add_u64 v[24:25], s[0:1], 0, v[2:3]
	s_mov_b32 m0, s15
	v_readfirstlane_b32 s20, v13
	global_load_lds_dwordx4 v[24:25], off
	v_lshl_add_u64 v[24:25], s[0:1], 0, v[4:5]
	s_mov_b32 m0, s20
	v_lshlrev_b32_e32 v26, 2, v0
	global_load_lds_dwordx4 v[24:25], off
	v_lshlrev_b32_e32 v24, 6, v0
	v_and_b32_e32 v13, 48, v0
	v_and_b32_e32 v25, 0x3c0, v24
	v_and_b32_e32 v41, 32, v26
	v_or_b32_e32 v40, v25, v13
	v_bitop3_b32 v13, v25, v41, v13 bitop3:0x36
	s_movk_i32 s0, 0x3000
	v_and_or_b32 v162, v24, s0, v13
	s_add_u32 s0, s16, 0x10080
	s_addc_u32 s1, s17, 0
	v_lshl_add_u64 v[72:73], s[0:1], 0, v[2:3]
	v_lshl_add_u64 v[74:75], s[0:1], 0, v[4:5]
	s_add_u32 s0, s18, 0x10100
	s_addc_u32 s1, s19, 0
	v_or_b32_e32 v230, 0x10000, v162
	v_or_b32_e32 v232, 0x10800, v162
	s_waitcnt vmcnt(6)
	s_barrier
	v_lshl_add_u64 v[160:161], s[0:1], 0, v[2:3]
	v_lshl_add_u64 v[194:195], s[0:1], 0, v[4:5]
	s_add_u32 s0, s16, 0x10100
	v_or_b32_e32 v231, 0x10400, v162
	ds_read_b128 v[24:27], v230
	ds_read_b128 v[28:31], v231
	v_or_b32_e32 v233, 0x10c00, v162
	ds_read_b128 v[32:35], v232
	ds_read_b128 v[36:39], v233
	s_addc_u32 s1, s17, 0
	v_lshl_add_u64 v[214:215], s[0:1], 0, v[2:3]
	v_lshl_add_u64 v[216:217], s[0:1], 0, v[4:5]
	s_add_u32 s0, s18, 0x10180
	s_addc_u32 s1, s19, 0
	v_lshlrev_b32_e32 v42, 13, v12
	v_lshl_add_u64 v[120:121], v[6:7], 0, s[82:83]
	v_lshl_add_u64 v[122:123], v[8:9], 0, s[82:83]
	v_lshl_add_u64 v[152:153], v[10:11], 0, s[82:83]
	v_lshl_add_u64 v[226:227], v[6:7], 0, s[90:91]
	v_lshl_add_u64 v[228:229], v[8:9], 0, s[90:91]
	v_lshl_add_u64 v[12:13], v[10:11], 0, s[90:91]
	v_lshl_add_u64 v[10:11], v[14:15], 0, s[90:91]
	v_lshl_add_u64 v[8:9], s[0:1], 0, v[2:3]
	v_lshl_add_u64 v[6:7], s[0:1], 0, v[4:5]
	v_lshl_add_u64 v[154:155], v[14:15], 0, s[82:83]
	v_add_u32_e32 v14, 0xc000, v18
	v_bitop3_b32 v242, v40, v42, v41 bitop3:0xde
	v_readfirstlane_b32 s19, v14
	v_add_u32_e32 v14, 0xe000, v18
	s_mov_b32 m0, s19
	v_readfirstlane_b32 s18, v14
	ds_read_b128 v[40:43], v242
	ds_read_b128 v[44:47], v242 offset:1024
	ds_read_b128 v[48:51], v242 offset:2048
	ds_read_b128 v[52:55], v242 offset:3072
	ds_read_b128 v[56:59], v242 offset:4096
	ds_read_b128 v[60:63], v242 offset:5120
	ds_read_b128 v[64:67], v242 offset:6144
	ds_read_b128 v[68:71], v242 offset:7168
	global_load_lds_dwordx4 v[72:73], off
	s_mov_b32 m0, s18
	s_nop 0
	global_load_lds_dwordx4 v[74:75], off
	s_waitcnt lgkmcnt(8)
	s_barrier
; #define G_LDA(dst, b, h)                                                                                                  \
;   _Pragma("unroll") for (int m = 0; m < 4; ++m) _Pragma("unroll") for (int k = 0; k < 2; ++k)                             \
;       dst[m][k] = *(const bf16x8*)((const char*)G_SA(b, h) + ((wr * 4 + m) * 2 + k) * 1024 + rdo)
; #define G_LDB(dst, b, h)                                                                                                  \
;   _Pragma("unroll") for (int n = 0; n < 2; ++n) _Pragma("unroll") for (int k = 0; k < 2; ++k)                             \
;       dst[n][k] = *(const bf16x8*)((const char*)G_SB(b, h) + ((wc * 2 + n) * 2 + k) * 1024 + rdo)
; #define G_WAIT_V(n) asm volatile("s_waitcnt vmcnt(" #n ")" ::: "memory")
; #define G_WAIT_L(n) asm volatile("s_waitcnt lgkmcnt(" #n ")" ::: "memory")
; #define G_BAR __builtin_amdgcn_s_barrier()
; #define G_SCHED __builtin_amdgcn_sched_barrier(0)
;     ...
;   for (int tt = 0; tt < nt - 2; tt += 2) {
;     G_LDB(B0, 0, 0); G_SCHED; G_LDA(At, 0, 0); G_STAGE(G_SA(1, 1), A, oa0, oa1, LDA, 128, KA(tt + 1));
;     G_WAIT_L(8); G_BAR; G_WAIT_L(0); G_MMA(0, 0, At, B0); G_BAR; G_SCHED;
;     G_LDB(B1, 0, 1); G_STAGE(G_SB(0, 0), B, ob0, ob1, LDB, 0, KB(tt + 2));
;     G_BAR; G_WAIT_L(0); G_MMA(0, 1, At, B1); G_BAR;
;     G_LDA(At, 0, 1); G_STAGE(G_SA(0, 0), A, oa0, oa1, LDA, 0, KA(tt + 2));
;     G_BAR; G_WAIT_L(0); G_MMA(1, 0, At, B0); G_BAR; G_SCHED;
;     G_STAGE(G_SB(0, 1), B, ob0, ob1, LDB, 128, KB(tt + 2));
;     G_WAIT_V(6); G_BAR; G_MMA(1, 1, At, B1); G_BAR;
	s_waitcnt lgkmcnt(0)
	v_mfma_f32_16x16x32_bf16 v[72:75], v[40:43], v[24:27], 0
	v_mfma_f32_16x16x32_bf16 v[76:79], v[40:43], v[32:35], 0
	v_mfma_f32_16x16x32_bf16 v[80:83], v[48:51], v[24:27], 0
	v_mfma_f32_16x16x32_bf16 v[84:87], v[48:51], v[32:35], 0
	v_mfma_f32_16x16x32_bf16 v[88:91], v[56:59], v[24:27], 0
	v_mfma_f32_16x16x32_bf16 v[92:95], v[56:59], v[32:35], 0
	v_mfma_f32_16x16x32_bf16 v[96:99], v[64:67], v[24:27], 0
	v_mfma_f32_16x16x32_bf16 v[100:103], v[64:67], v[32:35], 0
	v_mfma_f32_16x16x32_bf16 v[72:75], v[44:47], v[28:31], v[72:75]
	v_mfma_f32_16x16x32_bf16 v[76:79], v[44:47], v[36:39], v[76:79]
	v_mfma_f32_16x16x32_bf16 v[80:83], v[52:55], v[28:31], v[80:83]
	v_mfma_f32_16x16x32_bf16 v[84:87], v[52:55], v[36:39], v[84:87]
	v_mfma_f32_16x16x32_bf16 v[88:91], v[60:63], v[28:31], v[88:91]
	v_mfma_f32_16x16x32_bf16 v[92:95], v[60:63], v[36:39], v[92:95]
	v_mfma_f32_16x16x32_bf16 v[96:99], v[68:71], v[28:31], v[96:99]
	v_mfma_f32_16x16x32_bf16 v[100:103], v[68:71], v[36:39], v[100:103]
	s_barrier
	v_or_b32_e32 v234, 0x14000, v162
	v_or_b32_e32 v236, 0x14800, v162
	s_add_u32 m0, s32, 0x10000
	v_or_b32_e32 v235, 0x14400, v162
	ds_read_b128 v[104:107], v234
	ds_read_b128 v[108:111], v235
	v_or_b32_e32 v237, 0x14c00, v162
	ds_read_b128 v[112:115], v236
	ds_read_b128 v[116:119], v237
	global_load_lds_dwordx4 v[120:121], off
	s_add_u32 m0, s32, 0x12000
	s_nop 0
	global_load_lds_dwordx4 v[122:123], off
	s_barrier
	s_waitcnt lgkmcnt(0)
	v_mfma_f32_16x16x32_bf16 v[120:123], v[40:43], v[104:107], 0
	v_mfma_f32_16x16x32_bf16 v[40:43], v[40:43], v[112:115], 0
	v_mfma_f32_16x16x32_bf16 v[120:123], v[44:47], v[108:111], v[120:123]
	v_mfma_f32_16x16x32_bf16 v[40:43], v[44:47], v[116:119], v[40:43]
	v_mfma_f32_16x16x32_bf16 v[44:47], v[48:51], v[104:107], 0
	v_mfma_f32_16x16x32_bf16 v[48:51], v[48:51], v[112:115], 0
	v_mfma_f32_16x16x32_bf16 v[44:47], v[52:55], v[108:111], v[44:47]
	v_mfma_f32_16x16x32_bf16 v[48:51], v[52:55], v[116:119], v[48:51]
	v_mfma_f32_16x16x32_bf16 v[52:55], v[56:59], v[104:107], 0
	v_mfma_f32_16x16x32_bf16 v[56:59], v[56:59], v[112:115], 0
	v_mfma_f32_16x16x32_bf16 v[52:55], v[60:63], v[108:111], v[52:55]
	v_mfma_f32_16x16x32_bf16 v[56:59], v[60:63], v[116:119], v[56:59]
	v_mfma_f32_16x16x32_bf16 v[60:63], v[64:67], v[104:107], 0
	v_mfma_f32_16x16x32_bf16 v[64:67], v[64:67], v[112:115], 0
	v_mfma_f32_16x16x32_bf16 v[60:63], v[68:71], v[108:111], v[60:63]
	v_mfma_f32_16x16x32_bf16 v[64:67], v[68:71], v[116:119], v[64:67]
	s_mov_b32 m0, s32
	s_barrier
	ds_read_b128 v[68:71], v242 offset:16384
	ds_read_b128 v[124:127], v242 offset:17408
	ds_read_b128 v[128:131], v242 offset:18432
	ds_read_b128 v[132:135], v242 offset:19456
	ds_read_b128 v[136:139], v242 offset:20480
	ds_read_b128 v[140:143], v242 offset:21504
	ds_read_b128 v[144:147], v242 offset:22528
	ds_read_b128 v[148:151], v242 offset:23552
	global_load_lds_dwordx4 v[152:153], off
	s_add_u32 m0, s32, 0x2000
	s_nop 0
	global_load_lds_dwordx4 v[154:155], off
	s_barrier
	s_waitcnt lgkmcnt(0)
	v_mfma_f32_16x16x32_bf16 v[152:155], v[68:71], v[24:27], 0
	v_mfma_f32_16x16x32_bf16 v[164:167], v[128:131], v[24:27], 0
	v_mfma_f32_16x16x32_bf16 v[186:189], v[136:139], v[24:27], 0
	v_mfma_f32_16x16x32_bf16 v[22:25], v[144:147], v[24:27], 0
	v_mfma_f32_16x16x32_bf16 v[152:155], v[124:127], v[28:31], v[152:155]
	v_mfma_f32_16x16x32_bf16 v[164:167], v[132:135], v[28:31], v[164:167]
	v_mfma_f32_16x16x32_bf16 v[186:189], v[140:143], v[28:31], v[186:189]
	v_mfma_f32_16x16x32_bf16 v[22:25], v[148:151], v[28:31], v[22:25]
	v_mfma_f32_16x16x32_bf16 v[26:29], v[144:147], v[32:35], 0
	v_mfma_f32_16x16x32_bf16 v[156:159], v[68:71], v[32:35], 0
	v_mfma_f32_16x16x32_bf16 v[182:185], v[128:131], v[32:35], 0
	v_mfma_f32_16x16x32_bf16 v[190:193], v[136:139], v[32:35], 0
	v_mfma_f32_16x16x32_bf16 v[26:29], v[148:151], v[36:39], v[26:29]
	v_mfma_f32_16x16x32_bf16 v[156:159], v[124:127], v[36:39], v[156:159]
	v_mfma_f32_16x16x32_bf16 v[182:185], v[132:135], v[36:39], v[182:185]
	v_mfma_f32_16x16x32_bf16 v[190:193], v[140:143], v[36:39], v[190:193]
	s_barrier
	s_add_u32 m0, s32, 0x14000
	s_nop 0
	global_load_lds_dwordx4 v[160:161], off
	s_add_u32 m0, s32, 0x16000
	s_nop 0
	global_load_lds_dwordx4 v[194:195], off
	s_waitcnt vmcnt(6)
	s_barrier
	v_mfma_f32_16x16x32_bf16 v[18:21], v[68:71], v[104:107], 0
	v_mfma_f32_16x16x32_bf16 v[30:33], v[68:71], v[112:115], 0
	v_mfma_f32_16x16x32_bf16 v[18:21], v[124:127], v[108:111], v[18:21]
	v_mfma_f32_16x16x32_bf16 v[30:33], v[124:127], v[116:119], v[30:33]
	v_mfma_f32_16x16x32_bf16 v[34:37], v[128:131], v[104:107], 0
	v_mfma_f32_16x16x32_bf16 v[124:127], v[136:139], v[104:107], 0
	v_mfma_f32_16x16x32_bf16 v[104:107], v[144:147], v[104:107], 0
	v_mfma_f32_16x16x32_bf16 v[34:37], v[132:135], v[108:111], v[34:37]
	v_mfma_f32_16x16x32_bf16 v[68:71], v[128:131], v[112:115], 0
	v_mfma_f32_16x16x32_bf16 v[124:127], v[140:143], v[108:111], v[124:127]
	v_mfma_f32_16x16x32_bf16 v[128:131], v[136:139], v[112:115], 0
	v_mfma_f32_16x16x32_bf16 v[104:107], v[148:151], v[108:111], v[104:107]
	v_mfma_f32_16x16x32_bf16 v[108:111], v[144:147], v[112:115], 0
	v_mfma_f32_16x16x32_bf16 v[68:71], v[132:135], v[116:119], v[68:71]
	v_mfma_f32_16x16x32_bf16 v[128:131], v[140:143], v[116:119], v[128:131]
	v_mfma_f32_16x16x32_bf16 v[108:111], v[148:151], v[116:119], v[108:111]
	v_or_b32_e32 v160, 0x18000, v162
	v_or_b32_e32 v238, 0x18800, v162
	s_barrier
; #define G_LDA(dst, b, h)                                                                                                  \
;   _Pragma("unroll") for (int m = 0; m < 4; ++m) _Pragma("unroll") for (int k = 0; k < 2; ++k)                             \
;       dst[m][k] = *(const bf16x8*)((const char*)G_SA(b, h) + ((wr * 4 + m) * 2 + k) * 1024 + rdo)
; #define G_LDB(dst, b, h)                                                                                                  \
;   _Pragma("unroll") for (int n = 0; n < 2; ++n) _Pragma("unroll") for (int k = 0; k < 2; ++k)                             \
;       dst[n][k] = *(const bf16x8*)((const char*)G_SB(b, h) + ((wc * 2 + n) * 2 + k) * 1024 + rdo)
; #define G_WAIT_L(n) asm volatile("s_waitcnt lgkmcnt(" #n ")" ::: "memory")
; #define G_BAR __builtin_amdgcn_s_barrier()
; #define G_SCHED __builtin_amdgcn_sched_barrier(0)
;     ...
;     G_LDB(B0, 1, 0); G_SCHED; G_LDA(At, 1, 0); G_STAGE(G_SA(0, 1), A, oa0, oa1, LDA, 128, KA(tt + 2));
;     G_WAIT_L(8); G_BAR; G_WAIT_L(0); G_MMA(0, 0, At, B0); G_BAR; G_SCHED;
;     G_LDB(B1, 1, 1); G_STAGE(G_SB(1, 0), B, ob0, ob1, LDB, 0, KB(tt + 3));
;     G_BAR; G_WAIT_L(0); G_MMA(0, 1, At, B1); G_BAR;
;     G_LDA(At, 1, 1); G_STAGE(G_SA(1, 0), A, oa0, oa1, LDA, 0, KA(tt + 3));
;     G_BAR; G_WAIT_L(0); G_MMA(1, 0, At, B0); G_BAR; G_SCHED;
;     G_STAGE(G_SB(1, 1), B, ob0, ob1, LDB, 128, KB(tt + 3));
	v_or_b32_e32 v161, 0x18400, v162
	ds_read_b128 v[112:115], v160
	ds_read_b128 v[116:119], v161
	v_or_b32_e32 v239, 0x18c00, v162
	ds_read_b128 v[132:135], v238
	ds_read_b128 v[136:139], v239
	v_readfirstlane_b32 s0, v16
	s_mov_b32 m0, s0
	v_readfirstlane_b32 s0, v17
	ds_read_b128 v[140:143], v242 offset:32768
	ds_read_b128 v[144:147], v242 offset:33792
	ds_read_b128 v[148:151], v242 offset:34816
	ds_read_b128 v[194:197], v242 offset:35840
	ds_read_b128 v[198:201], v242 offset:36864
	ds_read_b128 v[202:205], v242 offset:37888
	ds_read_b128 v[206:209], v242 offset:38912
	ds_read_b128 v[210:213], v242 offset:39936
	global_load_lds_dwordx4 v[214:215], off
	s_mov_b32 m0, s0
	s_nop 0
	global_load_lds_dwordx4 v[216:217], off
	s_waitcnt lgkmcnt(8)
	s_barrier
	s_waitcnt lgkmcnt(0)
	v_mfma_f32_16x16x32_bf16 v[14:17], v[140:143], v[112:115], v[72:75]
	v_mfma_f32_16x16x32_bf16 v[72:75], v[140:143], v[132:135], v[76:79]
	v_mfma_f32_16x16x32_bf16 v[76:79], v[148:151], v[112:115], v[80:83]
	v_mfma_f32_16x16x32_bf16 v[80:83], v[148:151], v[132:135], v[84:87]
	v_mfma_f32_16x16x32_bf16 v[84:87], v[198:201], v[112:115], v[88:91]
	v_mfma_f32_16x16x32_bf16 v[88:91], v[198:201], v[132:135], v[92:95]
	v_mfma_f32_16x16x32_bf16 v[92:95], v[206:209], v[112:115], v[96:99]
	v_mfma_f32_16x16x32_bf16 v[96:99], v[206:209], v[132:135], v[100:103]
	v_mfma_f32_16x16x32_bf16 v[14:17], v[144:147], v[116:119], v[14:17]
	v_mfma_f32_16x16x32_bf16 v[72:75], v[144:147], v[136:139], v[72:75]
	v_mfma_f32_16x16x32_bf16 v[76:79], v[194:197], v[116:119], v[76:79]
	v_mfma_f32_16x16x32_bf16 v[80:83], v[194:197], v[136:139], v[80:83]
	v_mfma_f32_16x16x32_bf16 v[84:87], v[202:205], v[116:119], v[84:87]
	v_mfma_f32_16x16x32_bf16 v[88:91], v[202:205], v[136:139], v[88:91]
	v_mfma_f32_16x16x32_bf16 v[92:95], v[210:213], v[116:119], v[92:95]
	v_mfma_f32_16x16x32_bf16 v[96:99], v[210:213], v[136:139], v[96:99]
	s_barrier
	v_or_b32_e32 v240, 0x1c000, v162
	v_or_b32_e32 v243, 0x1c800, v162
	s_mov_b32 m0, s27
	v_or_b32_e32 v241, 0x1c400, v162
	ds_read_b128 v[100:103], v240
	ds_read_b128 v[214:217], v241
	v_or_b32_e32 v162, 0x1cc00, v162
	ds_read_b128 v[218:221], v243
	ds_read_b128 v[222:225], v162
	global_load_lds_dwordx4 v[226:227], off
	s_mov_b32 m0, s28
	s_nop 0
	global_load_lds_dwordx4 v[228:229], off
	s_barrier
	s_waitcnt lgkmcnt(0)
	v_mfma_f32_16x16x32_bf16 v[120:123], v[140:143], v[100:103], v[120:123]
	v_mfma_f32_16x16x32_bf16 v[38:41], v[140:143], v[218:221], v[40:43]
	v_mfma_f32_16x16x32_bf16 v[42:45], v[148:151], v[100:103], v[44:47]
	v_mfma_f32_16x16x32_bf16 v[46:49], v[148:151], v[218:221], v[48:51]
	v_mfma_f32_16x16x32_bf16 v[50:53], v[198:201], v[100:103], v[52:55]
	v_mfma_f32_16x16x32_bf16 v[54:57], v[198:201], v[218:221], v[56:59]
	v_mfma_f32_16x16x32_bf16 v[58:61], v[206:209], v[100:103], v[60:63]
	v_mfma_f32_16x16x32_bf16 v[62:65], v[206:209], v[218:221], v[64:67]
	v_mfma_f32_16x16x32_bf16 v[120:123], v[144:147], v[214:217], v[120:123]
	v_mfma_f32_16x16x32_bf16 v[38:41], v[144:147], v[222:225], v[38:41]
	v_mfma_f32_16x16x32_bf16 v[42:45], v[194:197], v[214:217], v[42:45]
	v_mfma_f32_16x16x32_bf16 v[46:49], v[194:197], v[222:225], v[46:49]
	v_mfma_f32_16x16x32_bf16 v[50:53], v[202:205], v[214:217], v[50:53]
	v_mfma_f32_16x16x32_bf16 v[54:57], v[202:205], v[222:225], v[54:57]
	v_mfma_f32_16x16x32_bf16 v[58:61], v[210:213], v[214:217], v[58:61]
	v_mfma_f32_16x16x32_bf16 v[62:65], v[210:213], v[222:225], v[62:65]
	s_mov_b32 m0, s21
	s_barrier
	ds_read_b128 v[140:143], v242 offset:49152
	ds_read_b128 v[144:147], v242 offset:50176
	ds_read_b128 v[148:151], v242 offset:51200
	ds_read_b128 v[194:197], v242 offset:52224
	ds_read_b128 v[198:201], v242 offset:53248
	ds_read_b128 v[202:205], v242 offset:54272
	ds_read_b128 v[206:209], v242 offset:55296
	ds_read_b128 v[210:213], v242 offset:56320
	global_load_lds_dwordx4 v[12:13], off
	s_mov_b32 m0, s26
	s_nop 0
	global_load_lds_dwordx4 v[10:11], off
	s_barrier
	s_waitcnt lgkmcnt(0)
	v_mfma_f32_16x16x32_bf16 v[10:13], v[140:143], v[112:115], v[152:155]
	v_mfma_f32_16x16x32_bf16 v[22:25], v[206:209], v[112:115], v[22:25]
	v_mfma_f32_16x16x32_bf16 v[26:29], v[206:209], v[132:135], v[26:29]
	v_mfma_f32_16x16x32_bf16 v[10:13], v[144:147], v[116:119], v[10:13]
	v_mfma_f32_16x16x32_bf16 v[152:155], v[140:143], v[132:135], v[156:159]
	v_mfma_f32_16x16x32_bf16 v[156:159], v[148:151], v[112:115], v[164:167]
	v_mfma_f32_16x16x32_bf16 v[164:167], v[148:151], v[132:135], v[182:185]
	v_mfma_f32_16x16x32_bf16 v[182:185], v[198:201], v[112:115], v[186:189]
	v_mfma_f32_16x16x32_bf16 v[186:189], v[198:201], v[132:135], v[190:193]
	v_mfma_f32_16x16x32_bf16 v[22:25], v[210:213], v[116:119], v[22:25]
	v_mfma_f32_16x16x32_bf16 v[26:29], v[210:213], v[136:139], v[26:29]
	v_mfma_f32_16x16x32_bf16 v[152:155], v[144:147], v[136:139], v[152:155]
	v_mfma_f32_16x16x32_bf16 v[156:159], v[194:197], v[116:119], v[156:159]
	v_mfma_f32_16x16x32_bf16 v[164:167], v[194:197], v[136:139], v[164:167]
	v_mfma_f32_16x16x32_bf16 v[182:185], v[202:205], v[116:119], v[182:185]
	v_mfma_f32_16x16x32_bf16 v[186:189], v[202:205], v[136:139], v[186:189]
	s_barrier
	s_mov_b32 m0, s15
	s_nop 0
	global_load_lds_dwordx4 v[8:9], off
	s_mov_b32 m0, s20
	s_nop 0
	global_load_lds_dwordx4 v[6:7], off
	s_waitcnt vmcnt(6)
	s_barrier
; #define G_LDA(dst, b, h)                                                                                                  \
;   _Pragma("unroll") for (int m = 0; m < 4; ++m) _Pragma("unroll") for (int k = 0; k < 2; ++k)                             \
;       dst[m][k] = *(const bf16x8*)((const char*)G_SA(b, h) + ((wr * 4 + m) * 2 + k) * 1024 + rdo)
; #define G_LDB(dst, b, h)                                                                                                  \
;   _Pragma("unroll") for (int n = 0; n < 2; ++n) _Pragma("unroll") for (int k = 0; k < 2; ++k)                             \
;       dst[n][k] = *(const bf16x8*)((const char*)G_SB(b, h) + ((wc * 2 + n) * 2 + k) * 1024 + rdo)
; #define G_WAIT_V(n) asm volatile("s_waitcnt vmcnt(" #n ")" ::: "memory")
; #define G_WAIT_L(n) asm volatile("s_waitcnt lgkmcnt(" #n ")" ::: "memory")
; #define G_BAR __builtin_amdgcn_s_barrier()
; DI void br_flush(PREF p, f32x4 (&acc)[2][2][4][2], int slot) { br_store(p, acc, slot); zero_acc256(acc); }
;     ...
;     G_WAIT_V(6); G_BAR; G_MMA(1, 1, At, B1); G_BAR;
;     if (MODE && ((tt + 1) & 3) == 3) br_flush(p, acc, (tt + 1) >> 2);
;   }
;   {
;     G_LDB(B0, 0, 0); G_LDA(At, 0, 0); G_STAGE(G_SA(1, 1), A, oa0, oa1, LDA, 128, KA(nt - 1));
;     G_BAR; G_WAIT_L(0); G_MMA(0, 0, At, B0); G_BAR;
;     G_LDB(B1, 0, 1); G_BAR; G_WAIT_L(0); G_MMA(0, 1, At, B1); G_BAR;
;     G_LDA(At, 0, 1); G_WAIT_V(4); G_BAR; G_WAIT_L(0); G_MMA(1, 0, At, B0); G_MMA(1, 1, At, B1); G_BAR;
	v_mfma_f32_16x16x32_bf16 v[6:9], v[140:143], v[100:103], v[18:21]
	v_mfma_f32_16x16x32_bf16 v[18:21], v[140:143], v[218:221], v[30:33]
	v_mfma_f32_16x16x32_bf16 v[30:33], v[148:151], v[100:103], v[34:37]
	v_mfma_f32_16x16x32_bf16 v[34:37], v[148:151], v[218:221], v[68:71]
	v_mfma_f32_16x16x32_bf16 v[66:69], v[198:201], v[100:103], v[124:127]
	v_mfma_f32_16x16x32_bf16 v[112:115], v[198:201], v[218:221], v[128:131]
	v_mfma_f32_16x16x32_bf16 v[100:103], v[206:209], v[100:103], v[104:107]
	v_mfma_f32_16x16x32_bf16 v[104:107], v[206:209], v[218:221], v[108:111]
	v_mfma_f32_16x16x32_bf16 v[6:9], v[144:147], v[214:217], v[6:9]
	v_mfma_f32_16x16x32_bf16 v[18:21], v[144:147], v[222:225], v[18:21]
	v_mfma_f32_16x16x32_bf16 v[30:33], v[194:197], v[214:217], v[30:33]
	v_mfma_f32_16x16x32_bf16 v[34:37], v[194:197], v[222:225], v[34:37]
	v_mfma_f32_16x16x32_bf16 v[66:69], v[202:205], v[214:217], v[66:69]
	v_mfma_f32_16x16x32_bf16 v[112:115], v[202:205], v[222:225], v[112:115]
	v_mfma_f32_16x16x32_bf16 v[100:103], v[210:213], v[214:217], v[100:103]
	v_mfma_f32_16x16x32_bf16 v[104:107], v[210:213], v[222:225], v[104:107]
	s_add_u32 s0, s16, 0x10180
	s_addc_u32 s1, s17, 0
	s_mov_b32 m0, s19
	v_lshl_add_u64 v[2:3], s[0:1], 0, v[2:3]
	s_barrier
	ds_read_b128 v[108:111], v230
	ds_read_b128 v[116:119], v231
	ds_read_b128 v[124:127], v232
	ds_read_b128 v[128:131], v233
	ds_read_b128 v[132:135], v242
	ds_read_b128 v[136:139], v242 offset:1024
	ds_read_b128 v[140:143], v242 offset:2048
	ds_read_b128 v[144:147], v242 offset:3072
	ds_read_b128 v[148:151], v242 offset:4096
	ds_read_b128 v[190:193], v242 offset:5120
	ds_read_b128 v[194:197], v242 offset:6144
	ds_read_b128 v[198:201], v242 offset:7168
	global_load_lds_dwordx4 v[2:3], off
	s_mov_b32 m0, s18
	v_lshl_add_u64 v[2:3], s[0:1], 0, v[4:5]
	global_load_lds_dwordx4 v[2:3], off
	s_barrier
	s_waitcnt lgkmcnt(0)
	v_mfma_f32_16x16x32_bf16 v[2:5], v[132:135], v[108:111], v[14:17]
	v_mfma_f32_16x16x32_bf16 v[14:17], v[132:135], v[124:127], v[72:75]
	v_mfma_f32_16x16x32_bf16 v[70:73], v[140:143], v[108:111], v[76:79]
	v_mfma_f32_16x16x32_bf16 v[74:77], v[140:143], v[124:127], v[80:83]
	v_mfma_f32_16x16x32_bf16 v[78:81], v[148:151], v[108:111], v[84:87]
	v_mfma_f32_16x16x32_bf16 v[82:85], v[148:151], v[124:127], v[88:91]
	v_mfma_f32_16x16x32_bf16 v[86:89], v[194:197], v[108:111], v[92:95]
	v_mfma_f32_16x16x32_bf16 v[90:93], v[194:197], v[124:127], v[96:99]
	v_mfma_f32_16x16x32_bf16 v[2:5], v[136:139], v[116:119], v[2:5]
	v_mfma_f32_16x16x32_bf16 v[14:17], v[136:139], v[128:131], v[14:17]
	v_mfma_f32_16x16x32_bf16 v[70:73], v[144:147], v[116:119], v[70:73]
	v_mfma_f32_16x16x32_bf16 v[74:77], v[144:147], v[128:131], v[74:77]
	v_mfma_f32_16x16x32_bf16 v[78:81], v[190:193], v[116:119], v[78:81]
	v_mfma_f32_16x16x32_bf16 v[82:85], v[190:193], v[128:131], v[82:85]
	v_mfma_f32_16x16x32_bf16 v[86:89], v[198:201], v[116:119], v[86:89]
	v_mfma_f32_16x16x32_bf16 v[90:93], v[198:201], v[128:131], v[90:93]
	s_barrier
	ds_read_b128 v[94:97], v234
	ds_read_b128 v[202:205], v235
	ds_read_b128 v[206:209], v236
	ds_read_b128 v[210:213], v237
	s_barrier
	s_waitcnt lgkmcnt(0)
	v_mfma_f32_16x16x32_bf16 v[38:41], v[132:135], v[206:209], v[38:41]
	v_mfma_f32_16x16x32_bf16 v[42:45], v[140:143], v[94:97], v[42:45]
	v_mfma_f32_16x16x32_bf16 v[46:49], v[140:143], v[206:209], v[46:49]
	v_mfma_f32_16x16x32_bf16 v[50:53], v[148:151], v[94:97], v[50:53]
	v_mfma_f32_16x16x32_bf16 v[54:57], v[148:151], v[206:209], v[54:57]
	v_mfma_f32_16x16x32_bf16 v[58:61], v[194:197], v[94:97], v[58:61]
	v_mfma_f32_16x16x32_bf16 v[62:65], v[194:197], v[206:209], v[62:65]
	v_mfma_f32_16x16x32_bf16 v[120:123], v[132:135], v[94:97], v[120:123]
	v_mfma_f32_16x16x32_bf16 v[38:41], v[136:139], v[210:213], v[38:41]
	v_mfma_f32_16x16x32_bf16 v[42:45], v[144:147], v[202:205], v[42:45]
	v_mfma_f32_16x16x32_bf16 v[46:49], v[144:147], v[210:213], v[46:49]
	v_mfma_f32_16x16x32_bf16 v[50:53], v[190:193], v[202:205], v[50:53]
	v_mfma_f32_16x16x32_bf16 v[54:57], v[190:193], v[210:213], v[54:57]
	v_mfma_f32_16x16x32_bf16 v[58:61], v[198:201], v[202:205], v[58:61]
	v_mfma_f32_16x16x32_bf16 v[62:65], v[198:201], v[210:213], v[62:65]
	v_mfma_f32_16x16x32_bf16 v[214:217], v[136:139], v[202:205], v[120:123]
	s_barrier
	s_nop 0
	ds_read_b128 v[120:123], v242 offset:16384
	ds_read_b128 v[132:135], v242 offset:17408
	ds_read_b128 v[136:139], v242 offset:18432
	ds_read_b128 v[140:143], v242 offset:19456
	ds_read_b128 v[144:147], v242 offset:20480
	ds_read_b128 v[148:151], v242 offset:21504
	ds_read_b128 v[190:193], v242 offset:22528
	ds_read_b128 v[194:197], v242 offset:23552
	s_waitcnt vmcnt(4)
	s_barrier
; #define G_LDA(dst, b, h)                                                                                                  \
;   _Pragma("unroll") for (int m = 0; m < 4; ++m) _Pragma("unroll") for (int k = 0; k < 2; ++k)                             \
;       dst[m][k] = *(const bf16x8*)((const char*)G_SA(b, h) + ((wr * 4 + m) * 2 + k) * 1024 + rdo)
; #define G_LDB(dst, b, h)                                                                                                  \
;   _Pragma("unroll") for (int n = 0; n < 2; ++n) _Pragma("unroll") for (int k = 0; k < 2; ++k)                             \
;       dst[n][k] = *(const bf16x8*)((const char*)G_SB(b, h) + ((wc * 2 + n) * 2 + k) * 1024 + rdo)
; #define G_WAIT_V(n) asm volatile("s_waitcnt vmcnt(" #n ")" ::: "memory")
; #define G_WAIT_L(n) asm volatile("s_waitcnt lgkmcnt(" #n ")" ::: "memory")
; #define G_BAR __builtin_amdgcn_s_barrier()
;     ...
;     G_LDA(At, 0, 1); G_WAIT_V(4); G_BAR; G_WAIT_L(0); G_MMA(1, 0, At, B0); G_MMA(1, 1, At, B1); G_BAR;
;   }
;   {
;     G_LDB(B0, 1, 0); G_LDA(At, 1, 0); G_WAIT_V(2); G_BAR; G_WAIT_L(0); G_MMA(0, 0, At, B0); G_BAR;
;     G_LDB(B1, 1, 1); G_WAIT_V(0); G_BAR; G_WAIT_L(0); G_MMA(0, 1, At, B1); G_BAR;
	s_waitcnt lgkmcnt(0)
	v_mfma_f32_16x16x32_bf16 v[10:13], v[120:123], v[108:111], v[10:13]
	v_mfma_f32_16x16x32_bf16 v[22:25], v[190:193], v[108:111], v[22:25]
	v_mfma_f32_16x16x32_bf16 v[26:29], v[190:193], v[124:127], v[26:29]
	v_mfma_f32_16x16x32_bf16 v[10:13], v[132:135], v[116:119], v[10:13]
	v_mfma_f32_16x16x32_bf16 v[152:155], v[120:123], v[124:127], v[152:155]
	v_mfma_f32_16x16x32_bf16 v[156:159], v[136:139], v[108:111], v[156:159]
	v_mfma_f32_16x16x32_bf16 v[164:167], v[136:139], v[124:127], v[164:167]
	v_mfma_f32_16x16x32_bf16 v[182:185], v[144:147], v[108:111], v[182:185]
	v_mfma_f32_16x16x32_bf16 v[186:189], v[144:147], v[124:127], v[186:189]
	v_mfma_f32_16x16x32_bf16 v[22:25], v[194:197], v[116:119], v[22:25]
	v_mfma_f32_16x16x32_bf16 v[26:29], v[194:197], v[128:131], v[26:29]
	v_mfma_f32_16x16x32_bf16 v[152:155], v[132:135], v[128:131], v[152:155]
	v_mfma_f32_16x16x32_bf16 v[156:159], v[140:143], v[116:119], v[156:159]
	v_mfma_f32_16x16x32_bf16 v[164:167], v[140:143], v[128:131], v[164:167]
	v_mfma_f32_16x16x32_bf16 v[182:185], v[148:151], v[116:119], v[182:185]
	v_mfma_f32_16x16x32_bf16 v[186:189], v[148:151], v[128:131], v[186:189]
	v_mfma_f32_16x16x32_bf16 v[30:33], v[136:139], v[94:97], v[30:33]
	v_mfma_f32_16x16x32_bf16 v[6:9], v[120:123], v[94:97], v[6:9]
	v_mfma_f32_16x16x32_bf16 v[18:21], v[120:123], v[206:209], v[18:21]
	v_mfma_f32_16x16x32_bf16 v[118:121], v[140:143], v[202:205], v[30:33]
	v_mfma_f32_16x16x32_bf16 v[30:33], v[136:139], v[206:209], v[34:37]
	v_mfma_f32_16x16x32_bf16 v[138:141], v[140:143], v[210:213], v[30:33]
	v_mfma_f32_16x16x32_bf16 v[30:33], v[144:147], v[94:97], v[66:69]
	v_mfma_f32_16x16x32_bf16 v[198:201], v[148:151], v[202:205], v[30:33]
	v_mfma_f32_16x16x32_bf16 v[30:33], v[144:147], v[206:209], v[112:115]
	v_mfma_f32_16x16x32_bf16 v[142:145], v[148:151], v[210:213], v[30:33]
	v_mfma_f32_16x16x32_bf16 v[30:33], v[190:193], v[94:97], v[100:103]
	v_mfma_f32_16x16x32_bf16 v[6:9], v[132:135], v[202:205], v[6:9]
	v_mfma_f32_16x16x32_bf16 v[18:21], v[132:135], v[210:213], v[18:21]
	v_mfma_f32_16x16x32_bf16 v[98:101], v[194:197], v[202:205], v[30:33]
	v_mfma_f32_16x16x32_bf16 v[30:33], v[190:193], v[206:209], v[104:107]
	v_mfma_f32_16x16x32_bf16 v[146:149], v[194:197], v[210:213], v[30:33]
	s_barrier
	s_nop 4
	s_nop 0
	ds_read_b128 v[30:33], v160
	ds_read_b128 v[34:37], v161
	ds_read_b128 v[190:193], v238
	ds_read_b128 v[194:197], v239
	ds_read_b128 v[66:69], v242 offset:32768
	ds_read_b128 v[94:97], v242 offset:33792
	ds_read_b128 v[202:205], v242 offset:34816
	ds_read_b128 v[206:209], v242 offset:35840
	ds_read_b128 v[210:213], v242 offset:36864
	ds_read_b128 v[218:221], v242 offset:37888
	ds_read_b128 v[222:225], v242 offset:38912
	ds_read_b128 v[226:229], v242 offset:39936
	s_waitcnt vmcnt(2)
	s_barrier
	s_waitcnt lgkmcnt(0)
	v_mfma_f32_16x16x32_bf16 v[2:5], v[66:69], v[30:33], v[2:5]
	v_mfma_f32_16x16x32_bf16 v[126:129], v[94:97], v[34:37], v[2:5]
	v_mfma_f32_16x16x32_bf16 v[2:5], v[66:69], v[190:193], v[14:17]
	v_mfma_f32_16x16x32_bf16 v[134:137], v[94:97], v[194:197], v[2:5]
	v_mfma_f32_16x16x32_bf16 v[2:5], v[202:205], v[30:33], v[70:73]
	v_mfma_f32_16x16x32_bf16 v[122:125], v[206:209], v[34:37], v[2:5]
	v_mfma_f32_16x16x32_bf16 v[2:5], v[202:205], v[190:193], v[74:77]
	v_mfma_f32_16x16x32_bf16 v[130:133], v[206:209], v[194:197], v[2:5]
	v_mfma_f32_16x16x32_bf16 v[2:5], v[210:213], v[30:33], v[78:81]
	v_mfma_f32_16x16x32_bf16 v[110:113], v[218:221], v[34:37], v[2:5]
	v_mfma_f32_16x16x32_bf16 v[2:5], v[210:213], v[190:193], v[82:85]
	v_mfma_f32_16x16x32_bf16 v[114:117], v[218:221], v[194:197], v[2:5]
	v_mfma_f32_16x16x32_bf16 v[2:5], v[222:225], v[30:33], v[86:89]
	v_mfma_f32_16x16x32_bf16 v[102:105], v[226:229], v[34:37], v[2:5]
	v_mfma_f32_16x16x32_bf16 v[2:5], v[222:225], v[190:193], v[90:93]
	v_mfma_f32_16x16x32_bf16 v[106:109], v[226:229], v[194:197], v[2:5]
	s_barrier
; #define G_LDA(dst, b, h)                                                                                                  \
;   _Pragma("unroll") for (int m = 0; m < 4; ++m) _Pragma("unroll") for (int k = 0; k < 2; ++k)                             \
;       dst[m][k] = *(const bf16x8*)((const char*)G_SA(b, h) + ((wr * 4 + m) * 2 + k) * 1024 + rdo)
; #define G_LDB(dst, b, h)                                                                                                  \
;   _Pragma("unroll") for (int n = 0; n < 2; ++n) _Pragma("unroll") for (int k = 0; k < 2; ++k)                             \
;       dst[n][k] = *(const bf16x8*)((const char*)G_SB(b, h) + ((wc * 2 + n) * 2 + k) * 1024 + rdo)
; #define G_WAIT_V(n) asm volatile("s_waitcnt vmcnt(" #n ")" ::: "memory")
; #define G_WAIT_L(n) asm volatile("s_waitcnt lgkmcnt(" #n ")" ::: "memory")
; #define G_BAR __builtin_amdgcn_s_barrier()
;     ...
;     G_LDB(B1, 1, 1); G_WAIT_V(0); G_BAR; G_WAIT_L(0); G_MMA(0, 1, At, B1); G_BAR;
;     G_LDA(At, 1, 1); G_BAR; G_WAIT_L(0); G_MMA(1, 0, At, B0); G_MMA(1, 1, At, B1); G_BAR;
;   }
;   if (wr == 0) G_BAR;
	s_nop 4
	s_nop 0
	ds_read_b128 v[2:5], v240
	ds_read_b128 v[230:233], v241
	ds_read_b128 v[234:237], v243
	ds_read_b128 v[238:241], v162
	s_waitcnt vmcnt(0)
	s_barrier
	s_waitcnt lgkmcnt(0)
	v_mfma_f32_16x16x32_bf16 v[14:17], v[66:69], v[2:5], v[214:217]
	v_mfma_f32_16x16x32_bf16 v[86:89], v[94:97], v[230:233], v[14:17]
	v_mfma_f32_16x16x32_bf16 v[14:17], v[66:69], v[234:237], v[38:41]
	v_mfma_f32_16x16x32_bf16 v[94:97], v[94:97], v[238:241], v[14:17]
	v_mfma_f32_16x16x32_bf16 v[14:17], v[202:205], v[2:5], v[42:45]
	v_mfma_f32_16x16x32_bf16 v[82:85], v[206:209], v[230:233], v[14:17]
	v_mfma_f32_16x16x32_bf16 v[14:17], v[202:205], v[234:237], v[46:49]
	v_mfma_f32_16x16x32_bf16 v[90:93], v[206:209], v[238:241], v[14:17]
	v_mfma_f32_16x16x32_bf16 v[14:17], v[210:213], v[2:5], v[50:53]
	v_mfma_f32_16x16x32_bf16 v[74:77], v[218:221], v[230:233], v[14:17]
	v_mfma_f32_16x16x32_bf16 v[14:17], v[210:213], v[234:237], v[54:57]
	v_mfma_f32_16x16x32_bf16 v[78:81], v[218:221], v[238:241], v[14:17]
	v_mfma_f32_16x16x32_bf16 v[14:17], v[222:225], v[2:5], v[58:61]
	v_mfma_f32_16x16x32_bf16 v[66:69], v[226:229], v[230:233], v[14:17]
	v_mfma_f32_16x16x32_bf16 v[14:17], v[222:225], v[234:237], v[62:65]
	v_mfma_f32_16x16x32_bf16 v[70:73], v[226:229], v[238:241], v[14:17]
	s_barrier
	s_nop 4
	s_nop 0
	ds_read_b128 v[14:17], v242 offset:49152
	ds_read_b128 v[202:205], v242 offset:50176
	ds_read_b128 v[206:209], v242 offset:51200
	ds_read_b128 v[210:213], v242 offset:52224
	ds_read_b128 v[214:217], v242 offset:53248
	ds_read_b128 v[218:221], v242 offset:54272
	ds_read_b128 v[222:225], v242 offset:55296
	ds_read_b128 v[226:229], v242 offset:56320
	s_barrier
	s_waitcnt lgkmcnt(0)
	v_mfma_f32_16x16x32_bf16 v[10:13], v[14:17], v[30:33], v[10:13]
	v_mfma_f32_16x16x32_bf16 v[54:57], v[202:205], v[34:37], v[10:13]
	v_mfma_f32_16x16x32_bf16 v[10:13], v[14:17], v[190:193], v[152:155]
	v_mfma_f32_16x16x32_bf16 v[62:65], v[202:205], v[194:197], v[10:13]
	v_mfma_f32_16x16x32_bf16 v[10:13], v[206:209], v[30:33], v[156:159]
	v_mfma_f32_16x16x32_bf16 v[50:53], v[210:213], v[34:37], v[10:13]
	v_mfma_f32_16x16x32_bf16 v[10:13], v[206:209], v[190:193], v[164:167]
	v_mfma_f32_16x16x32_bf16 v[58:61], v[210:213], v[194:197], v[10:13]
	v_mfma_f32_16x16x32_bf16 v[10:13], v[214:217], v[30:33], v[182:185]
	v_mfma_f32_16x16x32_bf16 v[42:45], v[218:221], v[34:37], v[10:13]
	v_mfma_f32_16x16x32_bf16 v[10:13], v[214:217], v[190:193], v[186:189]
	v_mfma_f32_16x16x32_bf16 v[46:49], v[218:221], v[194:197], v[10:13]
	v_mfma_f32_16x16x32_bf16 v[10:13], v[222:225], v[30:33], v[22:25]
	v_mfma_f32_16x16x32_bf16 v[34:37], v[226:229], v[34:37], v[10:13]
	v_mfma_f32_16x16x32_bf16 v[10:13], v[222:225], v[190:193], v[26:29]
	v_mfma_f32_16x16x32_bf16 v[38:41], v[226:229], v[194:197], v[10:13]
	v_mfma_f32_16x16x32_bf16 v[6:9], v[14:17], v[2:5], v[6:9]
	v_mfma_f32_16x16x32_bf16 v[22:25], v[202:205], v[230:233], v[6:9]
	v_mfma_f32_16x16x32_bf16 v[6:9], v[14:17], v[234:237], v[18:21]
	v_mfma_f32_16x16x32_bf16 v[30:33], v[202:205], v[238:241], v[6:9]
	v_mfma_f32_16x16x32_bf16 v[6:9], v[206:209], v[2:5], v[118:121]
	v_mfma_f32_16x16x32_bf16 v[18:21], v[210:213], v[230:233], v[6:9]
	v_mfma_f32_16x16x32_bf16 v[6:9], v[206:209], v[234:237], v[138:141]
	v_mfma_f32_16x16x32_bf16 v[26:29], v[210:213], v[238:241], v[6:9]
	v_mfma_f32_16x16x32_bf16 v[6:9], v[214:217], v[2:5], v[198:201]
	v_mfma_f32_16x16x32_bf16 v[10:13], v[218:221], v[230:233], v[6:9]
	v_mfma_f32_16x16x32_bf16 v[6:9], v[214:217], v[234:237], v[142:145]
	v_mfma_f32_16x16x32_bf16 v[14:17], v[218:221], v[238:241], v[6:9]
	v_mfma_f32_16x16x32_bf16 v[2:5], v[222:225], v[2:5], v[98:101]
	v_mfma_f32_16x16x32_bf16 v[6:9], v[222:225], v[234:237], v[146:149]
	v_mfma_f32_16x16x32_bf16 v[2:5], v[226:229], v[230:233], v[2:5]
	v_mfma_f32_16x16x32_bf16 v[6:9], v[226:229], v[238:241], v[6:9]
	v_cmp_gt_u32_e32 vcc, s67, v0
	s_barrier
	s_and_saveexec_b64 s[16:17], vcc
	s_cbranch_execz .LBB0_214
	s_barrier
	s_branch .LBB0_214

; DI void lds_barrier() { asm volatile("s_waitcnt lgkmcnt(0)\n\ts_barrier" ::: "memory"); }
; DI int tid512() { int t = threadIdx.x; asm volatile("" : "+v"(t)); return t; }
; #define G_WAIT_V(n) asm volatile("s_waitcnt vmcnt(" #n ")" ::: "memory")
; #define G_BAR __builtin_amdgcn_s_barrier()
;     ...
;   const int t = tid512();
;   const int wid = t >> 6, lane = t & 63, wr = wid >> 2, wc = wid & 3, fr = lane & 15, fq = lane >> 4;
;   int r0, c0, r1, c1;
;   g_stage_rc(t * 16, r0, c0); g_stage_rc(t * 16 + 8192, r1, c1);
;   const int oa0 = r0 * LDA + c0, oa1 = r1 * LDA + c1, ob0 = r0 * LDB + c0, ob1 = r1 * LDB + c1;
;   const int obr = fr * 64 + fq * 16, rdo = obr ^ (((obr >> 9) & 1) << 5);
;   bf16x8 At[4][2], B0[2][2], B1[2][2];
;   constexpr int nt = K / 64;
;   lds_barrier();
;   G_STAGE(G_SB(0, 0), B, ob0, ob1, LDB, 0, KB(0)); G_STAGE(G_SA(0, 0), A, oa0, oa1, LDA, 0, KA(0));
;   G_STAGE(G_SB(0, 1), B, ob0, ob1, LDB, 128, KB(0)); G_STAGE(G_SA(0, 1), A, oa0, oa1, LDA, 128, KA(0));
;   if (wr == 1) G_BAR;
;   G_WAIT_V(4); G_BAR;
;   G_STAGE(G_SB(1, 0), B, ob0, ob1, LDB, 0, KB(1)); G_STAGE(G_SA(1, 0), A, oa0, oa1, LDA, 0, KA(1)); G_STAGE(G_SB(1, 1), B, ob0, ob1, LDB, 128, KB(1));
;   G_WAIT_V(6); G_BAR;
; DI void zero_acc256(f32x4 (&a)[2][2][4][2]) {
; #pragma unroll
;   for (int i = 0; i < 2; ++i)
; #pragma unroll
;     for (int j = 0; j < 2; ++j)
; #pragma unroll
;       for (int m = 0; m < 4; ++m)
; #pragma unroll
;         for (int n = 0; n < 2; ++n)
; #pragma unroll
;           for (int e = 0; e < 4; ++e) a[i][j][m][n][e] = 0.f;
; }
.LBB0_450:
	v_mov_b32_e32 v0, v168
	s_ashr_i32 s17, s16, 31
	s_lshl_b64 s[22:23], s[16:17], 19
	v_lshlrev_b32_e32 v144, 4, v0
	s_nop 0
	v_readfirstlane_b32 s32, v144
	v_and_b32_e32 v2, 32, v0
	v_lshrrev_b32_e32 v4, 1, v0
	v_bitop3_b32 v2, v144, v2, 48 bitop3:0x6c
	s_add_u32 s18, s8, s22
	v_ashrrev_i32_e32 v10, 3, v0
	v_bfe_u32 v13, v0, 2, 4
	s_mov_b32 s0, 0x3ffff0
	v_and_b32_e32 v11, 32, v4
	v_lshrrev_b32_e32 v12, 1, v2
	v_add_u32_e32 v145, 0x2000, v144
	s_addc_u32 s19, s9, s23
	s_ashr_i32 s15, s14, 31
	v_and_or_b32 v3, v10, s0, v13
	v_or_b32_e32 v2, v12, v11
	v_ashrrev_i32_e32 v15, 7, v145
	s_lshl_b64 s[20:21], s[14:15], 19
	v_and_or_b32 v4, v15, s0, v13
	v_lshl_or_b32 v132, v3, 10, v2
	s_add_u32 s24, s28, s20
	v_lshl_or_b32 v130, v4, 10, v2
	v_ashrrev_i32_e32 v133, 31, v132
	s_addc_u32 s25, s29, s21
	v_lshlrev_b64 v[16:17], 1, v[132:133]
	v_ashrrev_i32_e32 v131, 31, v130
	s_waitcnt lgkmcnt(0)
	s_barrier
	v_lshl_add_u64 v[2:3], s[24:25], 0, v[16:17]
	s_add_u32 m0, s32, 0x10000
	v_lshlrev_b64 v[18:19], 1, v[130:131]
	global_load_lds_dwordx4 v[2:3], off
	v_lshl_add_u64 v[6:7], s[24:25], 0, v[18:19]
	s_add_u32 m0, s32, 0x12000
	s_nop 0
	global_load_lds_dwordx4 v[6:7], off
	v_lshl_add_u64 v[8:9], s[18:19], 0, v[16:17]
	s_mov_b32 m0, s32
	s_nop 0
	global_load_lds_dwordx4 v[8:9], off
	s_add_u32 m0, s32, 0x2000
	s_add_u32 s0, s24, 0x40000
	v_lshl_add_u64 v[4:5], s[18:19], 0, v[18:19]
	s_addc_u32 s1, s25, 0
	global_load_lds_dwordx4 v[4:5], off
	v_lshl_add_u64 v[20:21], s[0:1], 0, v[16:17]
	s_add_u32 m0, s32, 0x14000
	s_nop 0
	global_load_lds_dwordx4 v[20:21], off
	v_lshl_add_u64 v[20:21], s[0:1], 0, v[18:19]
	s_add_u32 m0, s32, 0x16000
	s_add_u32 s0, s18, 0x40000
	v_add_u32_e32 v152, 0x4000, v144
	s_addc_u32 s1, s19, 0
	v_readfirstlane_b32 s15, v152
	global_load_lds_dwordx4 v[20:21], off
	v_lshl_add_u64 v[16:17], s[0:1], 0, v[16:17]
	s_add_u32 m0, s32, 0x4000
	v_add_u32_e32 v153, 0x6000, v144
	global_load_lds_dwordx4 v[16:17], off
	v_lshl_add_u64 v[16:17], s[0:1], 0, v[18:19]
	v_readfirstlane_b32 s0, v153
	s_add_u32 m0, s32, 0x6000
	v_ashrrev_i32_e32 v14, 8, v0
	global_load_lds_dwordx4 v[16:17], off
	v_cmp_eq_u32_e32 vcc, 1, v14
	s_and_saveexec_b64 s[26:27], vcc
	s_cbranch_execz .LBB0_452
	s_barrier
.LBB0_452:
	s_or_b64 exec, exec, s[26:27]
	v_lshl_add_u64 v[2:3], v[2:3], 0, s[76:77]
	s_add_u32 m0, s32, 0x18000
	s_waitcnt vmcnt(4)
	s_barrier
	global_load_lds_dwordx4 v[2:3], off
	v_lshl_add_u64 v[2:3], v[6:7], 0, s[76:77]
	s_add_u32 m0, s32, 0x1a000
	s_nop 0
	global_load_lds_dwordx4 v[2:3], off
	v_lshl_add_u64 v[2:3], v[8:9], 0, s[76:77]
	s_add_u32 m0, s32, 0x8000
	s_nop 0
	global_load_lds_dwordx4 v[2:3], off
	s_add_u32 m0, s32, 0xa000
	s_add_u32 s0, s24, 0x40080
	v_lshl_add_u64 v[2:3], v[4:5], 0, s[76:77]
	s_addc_u32 s1, s25, 0
	global_load_lds_dwordx4 v[2:3], off
	v_lshl_add_u64 v[2:3], v[132:133], 1, s[0:1]
	s_add_u32 m0, s32, 0x1c000
	s_nop 0
	global_load_lds_dwordx4 v[2:3], off
	v_lshl_add_u64 v[2:3], v[130:131], 1, s[0:1]
	s_add_u32 m0, s32, 0x1e000
	v_lshlrev_b32_e32 v17, 6, v0
	global_load_lds_dwordx4 v[2:3], off
	v_and_b32_e32 v16, 48, v0
	v_and_b32_e32 v18, 0x3c0, v17
	v_lshlrev_b32_e32 v20, 2, v0
	v_lshlrev_b32_e32 v2, 10, v15
	v_lshlrev_b32_e32 v5, 10, v10
	v_or_b32_e32 v19, v18, v16
	v_and_b32_e32 v20, 32, v20
	s_mov_b32 s0, 0x14000
	v_and_b32_e32 v2, 0xffffc000, v2
	v_lshlrev_b32_e32 v4, 10, v13
	v_and_b32_e32 v5, 0xffffc000, v5
	v_bitop3_b32 v8, v19, s0, v20 bitop3:0xde
	s_mov_b32 s0, 0x18000
	v_or3_b32 v2, v12, v2, v4
	v_or3_b32 v4, v12, v5, v4
	v_bitop3_b32 v9, v19, s0, v20 bitop3:0xde
	s_mov_b32 s0, 0x1c000
	v_add_u32_e32 v2, v2, v11
	v_add_u32_e32 v4, v4, v11
	v_lshlrev_b32_e32 v7, 13, v14
	v_bitop3_b32 v14, v19, s0, v20 bitop3:0xde
	v_ashrrev_i32_e32 v3, 31, v2
	s_add_u32 s0, s8, s22
	v_ashrrev_i32_e32 v5, 31, v4
	v_lshlrev_b64 v[2:3], 1, v[2:3]
	s_addc_u32 s1, s9, s23
	v_lshlrev_b64 v[4:5], 1, v[4:5]
	v_lshl_add_u64 v[134:135], s[0:1], 0, v[2:3]
	v_lshl_add_u64 v[136:137], s[0:1], 0, v[4:5]
	s_add_u32 s0, s28, s20
	s_waitcnt vmcnt(6)
	s_addc_u32 s1, s29, s21
	v_bitop3_b32 v16, v18, v20, v16 bitop3:0x36
	v_bitop3_b32 v6, v19, s88, v20 bitop3:0xde
	v_and_b32_e32 v17, 0x3000, v17
	v_lshl_add_u64 v[138:139], s[0:1], 0, v[2:3]
	v_mov_b32_e32 v2, 0
	v_lshl_add_u64 v[140:141], s[0:1], 0, v[4:5]
	s_mov_b32 s15, -2
	s_mov_b64 s[20:21], 0
	v_add_u32_e32 v161, v6, v17
	v_add_u32_e32 v143, v16, v7
	v_add_u32_e32 v159, v8, v17
	v_add_u32_e32 v150, v9, v17
	v_add_u32_e32 v146, v14, v17
	v_mov_b32_e32 v3, v2
	v_mov_b32_e32 v4, v2
	v_mov_b32_e32 v5, v2
	v_mov_b32_e32 v6, v2
	v_mov_b32_e32 v7, v2
	v_mov_b32_e32 v8, v2
	v_mov_b32_e32 v9, v2
	v_mov_b32_e32 v10, v2
	v_mov_b32_e32 v11, v2
	v_mov_b32_e32 v12, v2
	v_mov_b32_e32 v13, v2
	v_mov_b32_e32 v14, v2
	v_mov_b32_e32 v15, v2
	v_mov_b32_e32 v16, v2
	v_mov_b32_e32 v17, v2
	v_mov_b32_e32 v18, v2
	v_mov_b32_e32 v19, v2
	v_mov_b32_e32 v20, v2
	v_mov_b32_e32 v21, v2
	v_mov_b32_e32 v22, v2
	v_mov_b32_e32 v23, v2
	v_mov_b32_e32 v24, v2
	v_mov_b32_e32 v25, v2
	v_mov_b32_e32 v26, v2
	v_mov_b32_e32 v27, v2
	v_mov_b32_e32 v28, v2
	v_mov_b32_e32 v29, v2
	v_mov_b32_e32 v30, v2
	v_mov_b32_e32 v31, v2
	v_mov_b32_e32 v32, v2
	v_mov_b32_e32 v33, v2
	v_mov_b32_e32 v34, v2
	v_mov_b32_e32 v35, v2
	v_mov_b32_e32 v36, v2
	v_mov_b32_e32 v37, v2
	v_mov_b32_e32 v38, v2
	v_mov_b32_e32 v39, v2
	v_mov_b32_e32 v40, v2
	v_mov_b32_e32 v41, v2
	v_mov_b32_e32 v42, v2
	v_mov_b32_e32 v43, v2
	v_mov_b32_e32 v44, v2
	v_mov_b32_e32 v45, v2
	v_mov_b32_e32 v46, v2
	v_mov_b32_e32 v47, v2
	v_mov_b32_e32 v48, v2
	v_mov_b32_e32 v49, v2
	v_mov_b32_e32 v50, v2
	v_mov_b32_e32 v51, v2
	v_mov_b32_e32 v52, v2
	v_mov_b32_e32 v53, v2
; #define G_LDA(dst, b, h)                                                                                                  \
;   _Pragma("unroll") for (int m = 0; m < 4; ++m) _Pragma("unroll") for (int k = 0; k < 2; ++k)                             \
;       dst[m][k] = *(const bf16x8*)((const char*)G_SA(b, h) + ((wr * 4 + m) * 2 + k) * 1024 + rdo)
; #define G_LDB(dst, b, h)                                                                                                  \
;   _Pragma("unroll") for (int n = 0; n < 2; ++n) _Pragma("unroll") for (int k = 0; k < 2; ++k)                             \
;       dst[n][k] = *(const bf16x8*)((const char*)G_SB(b, h) + ((wc * 2 + n) * 2 + k) * 1024 + rdo)
; #define G_WAIT_V(n) asm volatile("s_waitcnt vmcnt(" #n ")" ::: "memory")
; #define G_WAIT_L(n) asm volatile("s_waitcnt lgkmcnt(" #n ")" ::: "memory")
; #define G_BAR __builtin_amdgcn_s_barrier()
; #define G_SCHED __builtin_amdgcn_sched_barrier(0)
;     ...
;   G_WAIT_V(6); G_BAR;
;   for (int tt = 0; tt < nt - 2; tt += 2) {
;     G_LDB(B0, 0, 0); G_SCHED; G_LDA(At, 0, 0); G_STAGE(G_SA(1, 1), A, oa0, oa1, LDA, 128, KA(tt + 1));
;     G_WAIT_L(8); G_BAR; G_WAIT_L(0); G_MMA(0, 0, At, B0); G_BAR; G_SCHED;
;     G_LDB(B1, 0, 1); G_STAGE(G_SB(0, 0), B, ob0, ob1, LDB, 0, KB(tt + 2));
;     G_BAR; G_WAIT_L(0); G_MMA(0, 1, At, B1); G_BAR;
; DI void zero_acc256(f32x4 (&a)[2][2][4][2]) {
; #pragma unroll
;   for (int i = 0; i < 2; ++i)
; #pragma unroll
;     for (int j = 0; j < 2; ++j)
; #pragma unroll
;       for (int m = 0; m < 4; ++m)
; #pragma unroll
;         for (int n = 0; n < 2; ++n)
; #pragma unroll
;           for (int e = 0; e < 4; ++e) a[i][j][m][n][e] = 0.f;
; }
	v_mov_b32_e32 v54, v2
	v_mov_b32_e32 v55, v2
	v_mov_b32_e32 v56, v2
	v_mov_b32_e32 v57, v2
	v_mov_b32_e32 v58, v2
	v_mov_b32_e32 v59, v2
	v_mov_b32_e32 v60, v2
	v_mov_b32_e32 v61, v2
	v_mov_b32_e32 v70, v2
	v_mov_b32_e32 v71, v2
	v_mov_b32_e32 v72, v2
	v_mov_b32_e32 v73, v2
	v_mov_b32_e32 v86, v2
	v_mov_b32_e32 v87, v2
	v_mov_b32_e32 v88, v2
	v_mov_b32_e32 v89, v2
	v_mov_b32_e32 v94, v2
	v_mov_b32_e32 v95, v2
	v_mov_b32_e32 v96, v2
	v_mov_b32_e32 v97, v2
	v_mov_b32_e32 v98, v2
	v_mov_b32_e32 v99, v2
	v_mov_b32_e32 v100, v2
	v_mov_b32_e32 v101, v2
	v_mov_b32_e32 v102, v2
	v_mov_b32_e32 v103, v2
	v_mov_b32_e32 v104, v2
	v_mov_b32_e32 v105, v2
	v_mov_b32_e32 v106, v2
	v_mov_b32_e32 v107, v2
	v_mov_b32_e32 v108, v2
	v_mov_b32_e32 v109, v2
	v_mov_b32_e32 v110, v2
	v_mov_b32_e32 v111, v2
	v_mov_b32_e32 v112, v2
	v_mov_b32_e32 v113, v2
	v_mov_b32_e32 v114, v2
	v_mov_b32_e32 v115, v2
	v_mov_b32_e32 v116, v2
	v_mov_b32_e32 v117, v2
	v_mov_b32_e32 v118, v2
	v_mov_b32_e32 v119, v2
	v_mov_b32_e32 v120, v2
	v_mov_b32_e32 v121, v2
	v_mov_b32_e32 v122, v2
	v_mov_b32_e32 v123, v2
	v_mov_b32_e32 v124, v2
	v_mov_b32_e32 v125, v2
	v_mov_b32_e32 v126, v2
	v_mov_b32_e32 v127, v2
	v_mov_b32_e32 v128, v2
	v_mov_b32_e32 v129, v2
	v_mov_b32_e32 v62, v2
	v_mov_b32_e32 v63, v2
	v_mov_b32_e32 v64, v2
	v_mov_b32_e32 v65, v2
	v_mov_b32_e32 v66, v2
	v_mov_b32_e32 v67, v2
	v_mov_b32_e32 v68, v2
	v_mov_b32_e32 v69, v2
	v_mov_b32_e32 v74, v2
	v_mov_b32_e32 v75, v2
	v_mov_b32_e32 v76, v2
	v_mov_b32_e32 v77, v2
	v_mov_b32_e32 v78, v2
	v_mov_b32_e32 v79, v2
	v_mov_b32_e32 v80, v2
	v_mov_b32_e32 v81, v2
	v_mov_b32_e32 v82, v2
	v_mov_b32_e32 v83, v2
	v_mov_b32_e32 v84, v2
	v_mov_b32_e32 v85, v2
	v_mov_b32_e32 v90, v2
	v_mov_b32_e32 v91, v2
	v_mov_b32_e32 v92, v2
	v_mov_b32_e32 v93, v2
	s_barrier
.LBB0_453:
	ds_read_b128 v[182:185], v161
	ds_read_b128 v[186:189], v161 offset:1024
	ds_read_b128 v[190:193], v161 offset:2048
	ds_read_b128 v[194:197], v161 offset:3072
	v_lshl_add_u64 v[166:167], v[136:137], 0, s[20:21]
	v_lshl_add_u64 v[164:165], v[166:167], 0, s[78:79]
	s_add_u32 m0, s32, 0xc000
	ds_read_b128 v[198:201], v143
	ds_read_b128 v[202:205], v143 offset:1024
	ds_read_b128 v[206:209], v143 offset:2048
	ds_read_b128 v[210:213], v143 offset:3072
	ds_read_b128 v[214:217], v143 offset:4096
	ds_read_b128 v[218:221], v143 offset:5120
	ds_read_b128 v[222:225], v143 offset:6144
	ds_read_b128 v[226:229], v143 offset:7168
	global_load_lds_dwordx4 v[164:165], off
	v_lshl_add_u64 v[246:247], v[134:135], 0, s[20:21]
	s_add_u32 m0, s32, 0xe000
	v_lshl_add_u64 v[230:231], v[246:247], 0, s[78:79]
	global_load_lds_dwordx4 v[230:231], off
	s_waitcnt lgkmcnt(8)
	s_barrier
	s_waitcnt lgkmcnt(0)
	v_mfma_f32_16x16x32_bf16 v[126:129], v[198:201], v[182:185], v[126:129]
	v_mfma_f32_16x16x32_bf16 v[122:125], v[198:201], v[190:193], v[122:125]
	v_mfma_f32_16x16x32_bf16 v[118:121], v[206:209], v[182:185], v[118:121]
	v_mfma_f32_16x16x32_bf16 v[114:117], v[206:209], v[190:193], v[114:117]
	v_mfma_f32_16x16x32_bf16 v[110:113], v[214:217], v[182:185], v[110:113]
	v_mfma_f32_16x16x32_bf16 v[106:109], v[214:217], v[190:193], v[106:109]
	v_mfma_f32_16x16x32_bf16 v[102:105], v[222:225], v[182:185], v[102:105]
	v_mfma_f32_16x16x32_bf16 v[98:101], v[222:225], v[190:193], v[98:101]
	v_mfma_f32_16x16x32_bf16 v[126:129], v[202:205], v[186:189], v[126:129]
	v_mfma_f32_16x16x32_bf16 v[122:125], v[202:205], v[194:197], v[122:125]
	v_mfma_f32_16x16x32_bf16 v[118:121], v[210:213], v[186:189], v[118:121]
	v_mfma_f32_16x16x32_bf16 v[114:117], v[210:213], v[194:197], v[114:117]
	v_mfma_f32_16x16x32_bf16 v[110:113], v[218:221], v[186:189], v[110:113]
	v_mfma_f32_16x16x32_bf16 v[106:109], v[218:221], v[194:197], v[106:109]
	v_mfma_f32_16x16x32_bf16 v[102:105], v[226:229], v[186:189], v[102:105]
	v_mfma_f32_16x16x32_bf16 v[98:101], v[226:229], v[194:197], v[98:101]
	s_barrier
	v_lshl_add_u64 v[248:249], v[140:141], 0, s[20:21]
	v_lshl_add_u64 v[250:251], v[248:249], 0, s[82:83]
	s_add_u32 m0, s32, 0x10000
	ds_read_b128 v[230:233], v159
	ds_read_b128 v[234:237], v159 offset:1024
	ds_read_b128 v[238:241], v159 offset:2048
	ds_read_b128 v[242:245], v159 offset:3072
	global_load_lds_dwordx4 v[250:251], off
	v_lshl_add_u64 v[250:251], v[138:139], 0, s[20:21]
	s_add_u32 m0, s32, 0x12000
	v_lshl_add_u64 v[252:253], v[250:251], 0, s[82:83]
	global_load_lds_dwordx4 v[252:253], off
	s_barrier
	s_waitcnt lgkmcnt(0)
	v_mfma_f32_16x16x32_bf16 v[94:97], v[198:201], v[230:233], v[94:97]
	v_mfma_f32_16x16x32_bf16 v[86:89], v[198:201], v[238:241], v[86:89]
	v_mfma_f32_16x16x32_bf16 v[70:73], v[206:209], v[230:233], v[70:73]
	v_mfma_f32_16x16x32_bf16 v[58:61], v[206:209], v[238:241], v[58:61]
	v_mfma_f32_16x16x32_bf16 v[54:57], v[214:217], v[230:233], v[54:57]
	v_mfma_f32_16x16x32_bf16 v[50:53], v[214:217], v[238:241], v[50:53]
	v_mfma_f32_16x16x32_bf16 v[46:49], v[222:225], v[230:233], v[46:49]
	v_mfma_f32_16x16x32_bf16 v[42:45], v[222:225], v[238:241], v[42:45]
	v_mfma_f32_16x16x32_bf16 v[94:97], v[202:205], v[234:237], v[94:97]
	v_mfma_f32_16x16x32_bf16 v[86:89], v[202:205], v[242:245], v[86:89]
	v_mfma_f32_16x16x32_bf16 v[70:73], v[210:213], v[234:237], v[70:73]
	v_mfma_f32_16x16x32_bf16 v[58:61], v[210:213], v[242:245], v[58:61]
	v_mfma_f32_16x16x32_bf16 v[54:57], v[218:221], v[234:237], v[54:57]
	v_mfma_f32_16x16x32_bf16 v[50:53], v[218:221], v[242:245], v[50:53]
	v_mfma_f32_16x16x32_bf16 v[46:49], v[226:229], v[234:237], v[46:49]
	v_mfma_f32_16x16x32_bf16 v[42:45], v[226:229], v[242:245], v[42:45]
	v_lshl_add_u64 v[252:253], v[166:167], 0, s[82:83]
	s_mov_b32 m0, s32
	s_barrier
; #define G_LDA(dst, b, h)                                                                                                  \
;   _Pragma("unroll") for (int m = 0; m < 4; ++m) _Pragma("unroll") for (int k = 0; k < 2; ++k)                             \
;       dst[m][k] = *(const bf16x8*)((const char*)G_SA(b, h) + ((wr * 4 + m) * 2 + k) * 1024 + rdo)
; #define G_LDB(dst, b, h)                                                                                                  \
;   _Pragma("unroll") for (int n = 0; n < 2; ++n) _Pragma("unroll") for (int k = 0; k < 2; ++k)                             \
;       dst[n][k] = *(const bf16x8*)((const char*)G_SB(b, h) + ((wc * 2 + n) * 2 + k) * 1024 + rdo)
; #define G_WAIT_V(n) asm volatile("s_waitcnt vmcnt(" #n ")" ::: "memory")
; #define G_WAIT_L(n) asm volatile("s_waitcnt lgkmcnt(" #n ")" ::: "memory")
; #define G_BAR __builtin_amdgcn_s_barrier()
; #define G_SCHED __builtin_amdgcn_sched_barrier(0)
;     ...
;     G_LDA(At, 0, 1); G_STAGE(G_SA(0, 0), A, oa0, oa1, LDA, 0, KA(tt + 2));
;     G_BAR; G_WAIT_L(0); G_MMA(1, 0, At, B0); G_BAR; G_SCHED;
;     G_STAGE(G_SB(0, 1), B, ob0, ob1, LDB, 128, KB(tt + 2));
;     G_WAIT_V(6); G_BAR; G_MMA(1, 1, At, B1); G_BAR;
;     G_LDB(B0, 1, 0); G_SCHED; G_LDA(At, 1, 0); G_STAGE(G_SA(0, 1), A, oa0, oa1, LDA, 128, KA(tt + 2));
;     G_WAIT_L(8); G_BAR; G_WAIT_L(0); G_MMA(0, 0, At, B0); G_BAR; G_SCHED;
;     G_LDB(B1, 1, 1); G_STAGE(G_SB(1, 0), B, ob0, ob1, LDB, 0, KB(tt + 3));
	ds_read_b128 v[198:201], v143 offset:16384
	ds_read_b128 v[202:205], v143 offset:17408
	ds_read_b128 v[206:209], v143 offset:18432
	ds_read_b128 v[210:213], v143 offset:19456
	ds_read_b128 v[214:217], v143 offset:20480
	ds_read_b128 v[218:221], v143 offset:21504
	ds_read_b128 v[222:225], v143 offset:22528
	ds_read_b128 v[226:229], v143 offset:23552
	global_load_lds_dwordx4 v[252:253], off
	s_add_u32 m0, s32, 0x2000
	v_lshl_add_u64 v[252:253], v[246:247], 0, s[82:83]
	global_load_lds_dwordx4 v[252:253], off
	s_barrier
	s_waitcnt lgkmcnt(0)
	v_mfma_f32_16x16x32_bf16 v[38:41], v[198:201], v[182:185], v[38:41]
	v_mfma_f32_16x16x32_bf16 v[34:37], v[198:201], v[190:193], v[34:37]
	v_mfma_f32_16x16x32_bf16 v[30:33], v[206:209], v[182:185], v[30:33]
	v_mfma_f32_16x16x32_bf16 v[26:29], v[206:209], v[190:193], v[26:29]
	v_mfma_f32_16x16x32_bf16 v[22:25], v[214:217], v[182:185], v[22:25]
	v_mfma_f32_16x16x32_bf16 v[18:21], v[214:217], v[190:193], v[18:21]
	v_mfma_f32_16x16x32_bf16 v[14:17], v[222:225], v[182:185], v[14:17]
	v_mfma_f32_16x16x32_bf16 v[10:13], v[222:225], v[190:193], v[10:13]
	v_mfma_f32_16x16x32_bf16 v[38:41], v[202:205], v[186:189], v[38:41]
	v_mfma_f32_16x16x32_bf16 v[34:37], v[202:205], v[194:197], v[34:37]
	v_mfma_f32_16x16x32_bf16 v[30:33], v[210:213], v[186:189], v[30:33]
	v_mfma_f32_16x16x32_bf16 v[26:29], v[210:213], v[194:197], v[26:29]
	v_mfma_f32_16x16x32_bf16 v[22:25], v[218:221], v[186:189], v[22:25]
	v_mfma_f32_16x16x32_bf16 v[18:21], v[218:221], v[194:197], v[18:21]
	v_mfma_f32_16x16x32_bf16 v[14:17], v[226:229], v[186:189], v[14:17]
	v_mfma_f32_16x16x32_bf16 v[10:13], v[226:229], v[194:197], v[10:13]
	s_barrier
	v_lshl_add_u64 v[182:183], v[248:249], 0, s[86:87]
	s_add_u32 m0, s32, 0x14000
	s_nop 0
	global_load_lds_dwordx4 v[182:183], off
	s_add_u32 m0, s32, 0x16000
	v_lshl_add_u64 v[182:183], v[250:251], 0, s[86:87]
	global_load_lds_dwordx4 v[182:183], off
	s_waitcnt vmcnt(6)
	s_barrier
	v_mfma_f32_16x16x32_bf16 v[6:9], v[198:201], v[230:233], v[6:9]
	v_mfma_f32_16x16x32_bf16 v[2:5], v[198:201], v[238:241], v[2:5]
	v_mfma_f32_16x16x32_bf16 v[62:65], v[206:209], v[230:233], v[62:65]
	v_mfma_f32_16x16x32_bf16 v[66:69], v[206:209], v[238:241], v[66:69]
	v_mfma_f32_16x16x32_bf16 v[74:77], v[214:217], v[230:233], v[74:77]
	v_mfma_f32_16x16x32_bf16 v[78:81], v[214:217], v[238:241], v[78:81]
	v_mfma_f32_16x16x32_bf16 v[82:85], v[222:225], v[230:233], v[82:85]
	v_mfma_f32_16x16x32_bf16 v[90:93], v[222:225], v[238:241], v[90:93]
	v_mfma_f32_16x16x32_bf16 v[6:9], v[202:205], v[234:237], v[6:9]
	v_mfma_f32_16x16x32_bf16 v[2:5], v[202:205], v[242:245], v[2:5]
	v_mfma_f32_16x16x32_bf16 v[62:65], v[210:213], v[234:237], v[62:65]
	v_mfma_f32_16x16x32_bf16 v[66:69], v[210:213], v[242:245], v[66:69]
	v_mfma_f32_16x16x32_bf16 v[74:77], v[218:221], v[234:237], v[74:77]
	v_mfma_f32_16x16x32_bf16 v[78:81], v[218:221], v[242:245], v[78:81]
	v_mfma_f32_16x16x32_bf16 v[82:85], v[226:229], v[234:237], v[82:85]
	v_mfma_f32_16x16x32_bf16 v[90:93], v[226:229], v[242:245], v[90:93]
	s_barrier
	ds_read_b128 v[182:185], v150
	ds_read_b128 v[186:189], v150 offset:1024
	ds_read_b128 v[190:193], v150 offset:2048
	ds_read_b128 v[194:197], v150 offset:3072
	v_lshl_add_u64 v[230:231], v[166:167], 0, s[86:87]
	s_add_u32 m0, s32, 0x4000
	ds_read_b128 v[198:201], v143 offset:32768
	ds_read_b128 v[202:205], v143 offset:33792
	ds_read_b128 v[206:209], v143 offset:34816
	ds_read_b128 v[210:213], v143 offset:35840
	ds_read_b128 v[214:217], v143 offset:36864
	ds_read_b128 v[218:221], v143 offset:37888
	ds_read_b128 v[222:225], v143 offset:38912
	ds_read_b128 v[226:229], v143 offset:39936
	global_load_lds_dwordx4 v[230:231], off
	s_add_u32 m0, s32, 0x6000
	v_lshl_add_u64 v[230:231], v[246:247], 0, s[86:87]
	global_load_lds_dwordx4 v[230:231], off
	s_waitcnt lgkmcnt(8)
	s_barrier
	s_waitcnt lgkmcnt(0)
	v_mfma_f32_16x16x32_bf16 v[126:129], v[198:201], v[182:185], v[126:129]
	v_mfma_f32_16x16x32_bf16 v[122:125], v[198:201], v[190:193], v[122:125]
	v_mfma_f32_16x16x32_bf16 v[118:121], v[206:209], v[182:185], v[118:121]
	v_mfma_f32_16x16x32_bf16 v[114:117], v[206:209], v[190:193], v[114:117]
	v_mfma_f32_16x16x32_bf16 v[110:113], v[214:217], v[182:185], v[110:113]
	v_mfma_f32_16x16x32_bf16 v[106:109], v[214:217], v[190:193], v[106:109]
	v_mfma_f32_16x16x32_bf16 v[102:105], v[222:225], v[182:185], v[102:105]
	v_mfma_f32_16x16x32_bf16 v[98:101], v[222:225], v[190:193], v[98:101]
	v_mfma_f32_16x16x32_bf16 v[126:129], v[202:205], v[186:189], v[126:129]
	v_mfma_f32_16x16x32_bf16 v[122:125], v[202:205], v[194:197], v[122:125]
	v_mfma_f32_16x16x32_bf16 v[118:121], v[210:213], v[186:189], v[118:121]
	v_mfma_f32_16x16x32_bf16 v[114:117], v[210:213], v[194:197], v[114:117]
	v_mfma_f32_16x16x32_bf16 v[110:113], v[218:221], v[186:189], v[110:113]
	v_mfma_f32_16x16x32_bf16 v[106:109], v[218:221], v[194:197], v[106:109]
	v_mfma_f32_16x16x32_bf16 v[102:105], v[226:229], v[186:189], v[102:105]
	v_mfma_f32_16x16x32_bf16 v[98:101], v[226:229], v[194:197], v[98:101]
	s_barrier
	v_lshl_add_u64 v[252:253], v[248:249], 0, s[90:91]
	s_add_u32 m0, s32, 0x18000
	ds_read_b128 v[230:233], v146
	ds_read_b128 v[234:237], v146 offset:1024
	ds_read_b128 v[238:241], v146 offset:2048
	ds_read_b128 v[242:245], v146 offset:3072
	global_load_lds_dwordx4 v[252:253], off
	s_add_u32 m0, s32, 0x1a000
	v_lshl_add_u64 v[252:253], v[250:251], 0, s[90:91]
	global_load_lds_dwordx4 v[252:253], off
	s_barrier
; #define G_LDA(dst, b, h)                                                                                                  \
;   _Pragma("unroll") for (int m = 0; m < 4; ++m) _Pragma("unroll") for (int k = 0; k < 2; ++k)                             \
;       dst[m][k] = *(const bf16x8*)((const char*)G_SA(b, h) + ((wr * 4 + m) * 2 + k) * 1024 + rdo)
; #define G_LDB(dst, b, h)                                                                                                  \
;   _Pragma("unroll") for (int n = 0; n < 2; ++n) _Pragma("unroll") for (int k = 0; k < 2; ++k)                             \
;       dst[n][k] = *(const bf16x8*)((const char*)G_SB(b, h) + ((wc * 2 + n) * 2 + k) * 1024 + rdo)
; #define G_WAIT_V(n) asm volatile("s_waitcnt vmcnt(" #n ")" ::: "memory")
; #define G_WAIT_L(n) asm volatile("s_waitcnt lgkmcnt(" #n ")" ::: "memory")
; #define G_BAR __builtin_amdgcn_s_barrier()
; #define G_SCHED __builtin_amdgcn_sched_barrier(0)
; DI void br_flush(PREF p, f32x4 (&acc)[2][2][4][2], int slot) { br_store(p, acc, slot); zero_acc256(acc); }
;     ...
;     G_BAR; G_WAIT_L(0); G_MMA(0, 1, At, B1); G_BAR;
;     G_LDA(At, 1, 1); G_STAGE(G_SA(1, 0), A, oa0, oa1, LDA, 0, KA(tt + 3));
;     G_BAR; G_WAIT_L(0); G_MMA(1, 0, At, B0); G_BAR; G_SCHED;
;     G_STAGE(G_SB(1, 1), B, ob0, ob1, LDB, 128, KB(tt + 3));
;     G_WAIT_V(6); G_BAR; G_MMA(1, 1, At, B1); G_BAR;
;     if (MODE && ((tt + 1) & 3) == 3) br_flush(p, acc, (tt + 1) >> 2);
;   }
;   {
;     G_LDB(B0, 0, 0); G_LDA(At, 0, 0); G_STAGE(G_SA(1, 1), A, oa0, oa1, LDA, 128, KA(nt - 1));
	s_waitcnt lgkmcnt(0)
	v_mfma_f32_16x16x32_bf16 v[94:97], v[198:201], v[230:233], v[94:97]
	v_mfma_f32_16x16x32_bf16 v[86:89], v[198:201], v[238:241], v[86:89]
	v_mfma_f32_16x16x32_bf16 v[70:73], v[206:209], v[230:233], v[70:73]
	v_mfma_f32_16x16x32_bf16 v[58:61], v[206:209], v[238:241], v[58:61]
	v_mfma_f32_16x16x32_bf16 v[54:57], v[214:217], v[230:233], v[54:57]
	v_mfma_f32_16x16x32_bf16 v[50:53], v[214:217], v[238:241], v[50:53]
	v_mfma_f32_16x16x32_bf16 v[46:49], v[222:225], v[230:233], v[46:49]
	v_mfma_f32_16x16x32_bf16 v[42:45], v[222:225], v[238:241], v[42:45]
	v_mfma_f32_16x16x32_bf16 v[94:97], v[202:205], v[234:237], v[94:97]
	v_mfma_f32_16x16x32_bf16 v[86:89], v[202:205], v[242:245], v[86:89]
	v_mfma_f32_16x16x32_bf16 v[70:73], v[210:213], v[234:237], v[70:73]
	v_mfma_f32_16x16x32_bf16 v[58:61], v[210:213], v[242:245], v[58:61]
	v_mfma_f32_16x16x32_bf16 v[54:57], v[218:221], v[234:237], v[54:57]
	v_mfma_f32_16x16x32_bf16 v[50:53], v[218:221], v[242:245], v[50:53]
	v_mfma_f32_16x16x32_bf16 v[46:49], v[226:229], v[234:237], v[46:49]
	v_mfma_f32_16x16x32_bf16 v[42:45], v[226:229], v[242:245], v[42:45]
	v_lshl_add_u64 v[166:167], v[166:167], 0, s[90:91]
	s_add_u32 m0, s32, 0x8000
	s_barrier
	ds_read_b128 v[198:201], v143 offset:49152
	ds_read_b128 v[202:205], v143 offset:50176
	ds_read_b128 v[206:209], v143 offset:51200
	ds_read_b128 v[210:213], v143 offset:52224
	ds_read_b128 v[214:217], v143 offset:53248
	ds_read_b128 v[218:221], v143 offset:54272
	ds_read_b128 v[222:225], v143 offset:55296
	ds_read_b128 v[226:229], v143 offset:56320
	global_load_lds_dwordx4 v[166:167], off
	s_add_u32 m0, s32, 0xa000
	v_lshl_add_u64 v[166:167], v[246:247], 0, s[90:91]
	global_load_lds_dwordx4 v[166:167], off
	s_barrier
	s_waitcnt lgkmcnt(0)
	v_mfma_f32_16x16x32_bf16 v[38:41], v[198:201], v[182:185], v[38:41]
	v_mfma_f32_16x16x32_bf16 v[34:37], v[198:201], v[190:193], v[34:37]
	v_mfma_f32_16x16x32_bf16 v[30:33], v[206:209], v[182:185], v[30:33]
	v_mfma_f32_16x16x32_bf16 v[26:29], v[206:209], v[190:193], v[26:29]
	v_mfma_f32_16x16x32_bf16 v[22:25], v[214:217], v[182:185], v[22:25]
	v_mfma_f32_16x16x32_bf16 v[18:21], v[214:217], v[190:193], v[18:21]
	v_mfma_f32_16x16x32_bf16 v[14:17], v[222:225], v[182:185], v[14:17]
	v_mfma_f32_16x16x32_bf16 v[10:13], v[222:225], v[190:193], v[10:13]
	v_mfma_f32_16x16x32_bf16 v[38:41], v[202:205], v[186:189], v[38:41]
	v_mfma_f32_16x16x32_bf16 v[34:37], v[202:205], v[194:197], v[34:37]
	v_mfma_f32_16x16x32_bf16 v[30:33], v[210:213], v[186:189], v[30:33]
	v_mfma_f32_16x16x32_bf16 v[26:29], v[210:213], v[194:197], v[26:29]
	v_mfma_f32_16x16x32_bf16 v[22:25], v[218:221], v[186:189], v[22:25]
	v_mfma_f32_16x16x32_bf16 v[18:21], v[218:221], v[194:197], v[18:21]
	v_mfma_f32_16x16x32_bf16 v[14:17], v[226:229], v[186:189], v[14:17]
	v_mfma_f32_16x16x32_bf16 v[10:13], v[226:229], v[194:197], v[10:13]
	s_barrier
	v_lshl_add_u64 v[166:167], v[248:249], 0, s[6:7]
	s_add_u32 m0, s32, 0x1c000
	s_nop 0
	global_load_lds_dwordx4 v[166:167], off
	s_add_u32 m0, s32, 0x1e000
	v_lshl_add_u64 v[166:167], v[250:251], 0, s[6:7]
	global_load_lds_dwordx4 v[166:167], off
	s_waitcnt vmcnt(6)
	s_barrier
	v_mfma_f32_16x16x32_bf16 v[6:9], v[198:201], v[230:233], v[6:9]
	v_mfma_f32_16x16x32_bf16 v[2:5], v[198:201], v[238:241], v[2:5]
	v_mfma_f32_16x16x32_bf16 v[62:65], v[206:209], v[230:233], v[62:65]
	v_mfma_f32_16x16x32_bf16 v[66:69], v[206:209], v[238:241], v[66:69]
	v_mfma_f32_16x16x32_bf16 v[74:77], v[214:217], v[230:233], v[74:77]
	v_mfma_f32_16x16x32_bf16 v[78:81], v[214:217], v[238:241], v[78:81]
	v_mfma_f32_16x16x32_bf16 v[82:85], v[222:225], v[230:233], v[82:85]
	v_mfma_f32_16x16x32_bf16 v[90:93], v[222:225], v[238:241], v[90:93]
	v_mfma_f32_16x16x32_bf16 v[6:9], v[202:205], v[234:237], v[6:9]
	v_mfma_f32_16x16x32_bf16 v[2:5], v[202:205], v[242:245], v[2:5]
	v_mfma_f32_16x16x32_bf16 v[62:65], v[210:213], v[234:237], v[62:65]
	v_mfma_f32_16x16x32_bf16 v[66:69], v[210:213], v[242:245], v[66:69]
	v_mfma_f32_16x16x32_bf16 v[74:77], v[218:221], v[234:237], v[74:77]
	v_mfma_f32_16x16x32_bf16 v[78:81], v[218:221], v[242:245], v[78:81]
	v_mfma_f32_16x16x32_bf16 v[82:85], v[226:229], v[234:237], v[82:85]
	v_mfma_f32_16x16x32_bf16 v[90:93], v[226:229], v[242:245], v[90:93]
	s_add_i32 s15, s15, 2
	s_add_u32 s20, s20, 0x100
	s_addc_u32 s21, s21, 0
	s_cmp_lt_u32 s15, 12
	s_barrier
	s_cbranch_scc1 .LBB0_453
	s_add_u32 s0, s18, 0x40780
	s_addc_u32 s1, s19, 0
	v_lshl_add_u64 v[132:133], v[132:133], 1, s[0:1]
	s_add_u32 m0, s32, 0xc000
	v_lshl_add_u64 v[130:131], v[130:131], 1, s[0:1]
	ds_read_b128 v[134:137], v161
	ds_read_b128 v[138:141], v161 offset:1024
	ds_read_b128 v[152:155], v161 offset:2048
	ds_read_b128 v[182:185], v161 offset:3072
	ds_read_b128 v[186:189], v143
	ds_read_b128 v[190:193], v143 offset:1024
	ds_read_b128 v[194:197], v143 offset:2048
	ds_read_b128 v[198:201], v143 offset:3072
	ds_read_b128 v[202:205], v143 offset:4096
	ds_read_b128 v[206:209], v143 offset:5120
	ds_read_b128 v[210:213], v143 offset:6144
	ds_read_b128 v[214:217], v143 offset:7168
	global_load_lds_dwordx4 v[132:133], off
	s_add_u32 m0, s32, 0xe000
	s_nop 0
	global_load_lds_dwordx4 v[130:131], off
	s_barrier
; #define G_LDA(dst, b, h)                                                                                                  \
;   _Pragma("unroll") for (int m = 0; m < 4; ++m) _Pragma("unroll") for (int k = 0; k < 2; ++k)                             \
;       dst[m][k] = *(const bf16x8*)((const char*)G_SA(b, h) + ((wr * 4 + m) * 2 + k) * 1024 + rdo)
; #define G_LDB(dst, b, h)                                                                                                  \
;   _Pragma("unroll") for (int n = 0; n < 2; ++n) _Pragma("unroll") for (int k = 0; k < 2; ++k)                             \
;       dst[n][k] = *(const bf16x8*)((const char*)G_SB(b, h) + ((wc * 2 + n) * 2 + k) * 1024 + rdo)
; #define G_WAIT_V(n) asm volatile("s_waitcnt vmcnt(" #n ")" ::: "memory")
; #define G_WAIT_L(n) asm volatile("s_waitcnt lgkmcnt(" #n ")" ::: "memory")
; #define G_BAR __builtin_amdgcn_s_barrier()
;     ...
;     G_BAR; G_WAIT_L(0); G_MMA(0, 0, At, B0); G_BAR;
;     G_LDB(B1, 0, 1); G_BAR; G_WAIT_L(0); G_MMA(0, 1, At, B1); G_BAR;
;     G_LDA(At, 0, 1); G_WAIT_V(4); G_BAR; G_WAIT_L(0); G_MMA(1, 0, At, B0); G_MMA(1, 1, At, B1); G_BAR;
;   }
;   {
;     G_LDB(B0, 1, 0); G_LDA(At, 1, 0); G_WAIT_V(2); G_BAR; G_WAIT_L(0); G_MMA(0, 0, At, B0); G_BAR;
	s_waitcnt lgkmcnt(0)
	v_mfma_f32_16x16x32_bf16 v[126:129], v[186:189], v[134:137], v[126:129]
	v_mfma_f32_16x16x32_bf16 v[122:125], v[186:189], v[152:155], v[122:125]
	v_mfma_f32_16x16x32_bf16 v[110:113], v[202:205], v[134:137], v[110:113]
	v_mfma_f32_16x16x32_bf16 v[102:105], v[210:213], v[134:137], v[102:105]
	v_mfma_f32_16x16x32_bf16 v[126:129], v[190:193], v[138:141], v[126:129]
	v_mfma_f32_16x16x32_bf16 v[122:125], v[190:193], v[182:185], v[122:125]
	v_mfma_f32_16x16x32_bf16 v[118:121], v[194:197], v[134:137], v[118:121]
	v_mfma_f32_16x16x32_bf16 v[114:117], v[194:197], v[152:155], v[114:117]
	v_mfma_f32_16x16x32_bf16 v[110:113], v[206:209], v[138:141], v[110:113]
	v_mfma_f32_16x16x32_bf16 v[106:109], v[202:205], v[152:155], v[106:109]
	v_mfma_f32_16x16x32_bf16 v[102:105], v[214:217], v[138:141], v[102:105]
	v_mfma_f32_16x16x32_bf16 v[98:101], v[210:213], v[152:155], v[98:101]
	v_mfma_f32_16x16x32_bf16 v[130:133], v[198:201], v[138:141], v[118:121]
	v_mfma_f32_16x16x32_bf16 v[164:167], v[198:201], v[182:185], v[114:117]
	v_mfma_f32_16x16x32_bf16 v[218:221], v[206:209], v[182:185], v[106:109]
	v_mfma_f32_16x16x32_bf16 v[222:225], v[214:217], v[182:185], v[98:101]
	s_barrier
	s_nop 1
	s_nop 0
	ds_read_b128 v[98:101], v159
	ds_read_b128 v[106:109], v159 offset:1024
	ds_read_b128 v[114:117], v159 offset:2048
	ds_read_b128 v[118:121], v159 offset:3072
	s_barrier
	s_waitcnt lgkmcnt(0)
	v_mfma_f32_16x16x32_bf16 v[94:97], v[186:189], v[98:101], v[94:97]
	v_mfma_f32_16x16x32_bf16 v[70:73], v[194:197], v[98:101], v[70:73]
	v_mfma_f32_16x16x32_bf16 v[58:61], v[194:197], v[114:117], v[58:61]
	v_mfma_f32_16x16x32_bf16 v[54:57], v[202:205], v[98:101], v[54:57]
	v_mfma_f32_16x16x32_bf16 v[50:53], v[202:205], v[114:117], v[50:53]
	v_mfma_f32_16x16x32_bf16 v[46:49], v[210:213], v[98:101], v[46:49]
	v_mfma_f32_16x16x32_bf16 v[42:45], v[210:213], v[114:117], v[42:45]
	v_mfma_f32_16x16x32_bf16 v[94:97], v[190:193], v[106:109], v[94:97]
	v_mfma_f32_16x16x32_bf16 v[86:89], v[186:189], v[114:117], v[86:89]
	v_mfma_f32_16x16x32_bf16 v[70:73], v[198:201], v[106:109], v[70:73]
	v_mfma_f32_16x16x32_bf16 v[58:61], v[198:201], v[118:121], v[58:61]
	v_mfma_f32_16x16x32_bf16 v[54:57], v[206:209], v[106:109], v[54:57]
	v_mfma_f32_16x16x32_bf16 v[50:53], v[206:209], v[118:121], v[50:53]
	v_mfma_f32_16x16x32_bf16 v[46:49], v[214:217], v[106:109], v[46:49]
	v_mfma_f32_16x16x32_bf16 v[42:45], v[214:217], v[118:121], v[42:45]
	v_mfma_f32_16x16x32_bf16 v[156:159], v[190:193], v[118:121], v[86:89]
	s_barrier
	s_nop 0
	ds_read_b128 v[86:89], v143 offset:16384
	ds_read_b128 v[186:189], v143 offset:17408
	ds_read_b128 v[190:193], v143 offset:18432
	ds_read_b128 v[194:197], v143 offset:19456
	ds_read_b128 v[198:201], v143 offset:20480
	ds_read_b128 v[202:205], v143 offset:21504
	ds_read_b128 v[206:209], v143 offset:22528
	ds_read_b128 v[210:213], v143 offset:23552
	s_waitcnt vmcnt(4)
	s_barrier
	s_waitcnt lgkmcnt(0)
	v_mfma_f32_16x16x32_bf16 v[38:41], v[86:89], v[134:137], v[38:41]
	v_mfma_f32_16x16x32_bf16 v[34:37], v[86:89], v[152:155], v[34:37]
	v_mfma_f32_16x16x32_bf16 v[30:33], v[190:193], v[134:137], v[30:33]
	v_mfma_f32_16x16x32_bf16 v[26:29], v[190:193], v[152:155], v[26:29]
	v_mfma_f32_16x16x32_bf16 v[22:25], v[198:201], v[134:137], v[22:25]
	v_mfma_f32_16x16x32_bf16 v[18:21], v[198:201], v[152:155], v[18:21]
	v_mfma_f32_16x16x32_bf16 v[14:17], v[206:209], v[134:137], v[14:17]
	v_mfma_f32_16x16x32_bf16 v[10:13], v[206:209], v[152:155], v[10:13]
	v_mfma_f32_16x16x32_bf16 v[38:41], v[186:189], v[138:141], v[38:41]
	v_mfma_f32_16x16x32_bf16 v[34:37], v[186:189], v[182:185], v[34:37]
	v_mfma_f32_16x16x32_bf16 v[30:33], v[194:197], v[138:141], v[30:33]
	v_mfma_f32_16x16x32_bf16 v[26:29], v[194:197], v[182:185], v[26:29]
	v_mfma_f32_16x16x32_bf16 v[22:25], v[202:205], v[138:141], v[22:25]
	v_mfma_f32_16x16x32_bf16 v[18:21], v[202:205], v[182:185], v[18:21]
	v_mfma_f32_16x16x32_bf16 v[14:17], v[210:213], v[138:141], v[14:17]
	v_mfma_f32_16x16x32_bf16 v[10:13], v[210:213], v[182:185], v[10:13]
	v_mfma_f32_16x16x32_bf16 v[62:65], v[190:193], v[98:101], v[62:65]
	v_mfma_f32_16x16x32_bf16 v[134:137], v[194:197], v[106:109], v[62:65]
	v_mfma_f32_16x16x32_bf16 v[62:65], v[190:193], v[114:117], v[66:69]
	v_mfma_f32_16x16x32_bf16 v[138:141], v[194:197], v[118:121], v[62:65]
	v_mfma_f32_16x16x32_bf16 v[62:65], v[198:201], v[98:101], v[74:77]
	v_mfma_f32_16x16x32_bf16 v[152:155], v[202:205], v[106:109], v[62:65]
	v_mfma_f32_16x16x32_bf16 v[62:65], v[198:201], v[114:117], v[78:81]
	v_mfma_f32_16x16x32_bf16 v[6:9], v[86:89], v[98:101], v[6:9]
	v_mfma_f32_16x16x32_bf16 v[2:5], v[86:89], v[114:117], v[2:5]
	v_mfma_f32_16x16x32_bf16 v[182:185], v[202:205], v[118:121], v[62:65]
	v_mfma_f32_16x16x32_bf16 v[62:65], v[206:209], v[98:101], v[82:85]
	v_mfma_f32_16x16x32_bf16 v[6:9], v[186:189], v[106:109], v[6:9]
	v_mfma_f32_16x16x32_bf16 v[2:5], v[186:189], v[118:121], v[2:5]
	v_mfma_f32_16x16x32_bf16 v[186:189], v[210:213], v[106:109], v[62:65]
	v_mfma_f32_16x16x32_bf16 v[62:65], v[206:209], v[114:117], v[90:93]
	v_mfma_f32_16x16x32_bf16 v[190:193], v[210:213], v[118:121], v[62:65]
	s_barrier
	ds_read_b128 v[194:197], v150
	ds_read_b128 v[198:201], v150 offset:1024
	ds_read_b128 v[202:205], v150 offset:2048
	ds_read_b128 v[148:151], v150 offset:3072
	s_nop 0
	s_nop 0
	ds_read_b128 v[62:65], v143 offset:32768
	ds_read_b128 v[66:69], v143 offset:33792
	ds_read_b128 v[74:77], v143 offset:34816
	ds_read_b128 v[78:81], v143 offset:35840
	ds_read_b128 v[206:209], v143 offset:36864
	ds_read_b128 v[210:213], v143 offset:37888
	ds_read_b128 v[214:217], v143 offset:38912
	ds_read_b128 v[226:229], v143 offset:39936
	s_waitcnt vmcnt(2)
	s_barrier
; #define G_LDA(dst, b, h)                                                                                                  \
;   _Pragma("unroll") for (int m = 0; m < 4; ++m) _Pragma("unroll") for (int k = 0; k < 2; ++k)                             \
;       dst[m][k] = *(const bf16x8*)((const char*)G_SA(b, h) + ((wr * 4 + m) * 2 + k) * 1024 + rdo)
; #define G_LDB(dst, b, h)                                                                                                  \
;   _Pragma("unroll") for (int n = 0; n < 2; ++n) _Pragma("unroll") for (int k = 0; k < 2; ++k)                             \
;       dst[n][k] = *(const bf16x8*)((const char*)G_SB(b, h) + ((wc * 2 + n) * 2 + k) * 1024 + rdo)
; #define G_WAIT_V(n) asm volatile("s_waitcnt vmcnt(" #n ")" ::: "memory")
; #define G_WAIT_L(n) asm volatile("s_waitcnt lgkmcnt(" #n ")" ::: "memory")
; #define G_BAR __builtin_amdgcn_s_barrier()
;     ...
;     G_LDB(B0, 1, 0); G_LDA(At, 1, 0); G_WAIT_V(2); G_BAR; G_WAIT_L(0); G_MMA(0, 0, At, B0); G_BAR;
;     G_LDB(B1, 1, 1); G_WAIT_V(0); G_BAR; G_WAIT_L(0); G_MMA(0, 1, At, B1); G_BAR;
;     G_LDA(At, 1, 1); G_BAR; G_WAIT_L(0); G_MMA(1, 0, At, B0); G_MMA(1, 1, At, B1); G_BAR;
;   }
;   if (wr == 0) G_BAR;
	s_waitcnt lgkmcnt(0)
	v_mfma_f32_16x16x32_bf16 v[82:85], v[62:65], v[194:197], v[126:129]
	v_mfma_f32_16x16x32_bf16 v[118:121], v[66:69], v[198:201], v[82:85]
	v_mfma_f32_16x16x32_bf16 v[82:85], v[62:65], v[202:205], v[122:125]
	v_mfma_f32_16x16x32_bf16 v[126:129], v[66:69], v[148:151], v[82:85]
	v_mfma_f32_16x16x32_bf16 v[82:85], v[74:77], v[194:197], v[130:133]
	v_mfma_f32_16x16x32_bf16 v[114:117], v[78:81], v[198:201], v[82:85]
	v_mfma_f32_16x16x32_bf16 v[82:85], v[74:77], v[202:205], v[164:167]
	v_mfma_f32_16x16x32_bf16 v[122:125], v[78:81], v[148:151], v[82:85]
	v_mfma_f32_16x16x32_bf16 v[82:85], v[206:209], v[194:197], v[110:113]
	v_mfma_f32_16x16x32_bf16 v[106:109], v[210:213], v[198:201], v[82:85]
	v_mfma_f32_16x16x32_bf16 v[82:85], v[206:209], v[202:205], v[218:221]
	v_mfma_f32_16x16x32_bf16 v[110:113], v[210:213], v[148:151], v[82:85]
	v_mfma_f32_16x16x32_bf16 v[82:85], v[214:217], v[194:197], v[102:105]
	v_mfma_f32_16x16x32_bf16 v[98:101], v[226:229], v[198:201], v[82:85]
	v_mfma_f32_16x16x32_bf16 v[82:85], v[214:217], v[202:205], v[222:225]
	v_mfma_f32_16x16x32_bf16 v[102:105], v[226:229], v[148:151], v[82:85]
	s_barrier
	ds_read_b128 v[130:133], v146
	ds_read_b128 v[164:167], v146 offset:1024
	ds_read_b128 v[218:221], v146 offset:2048
	ds_read_b128 v[144:147], v146 offset:3072
	s_waitcnt vmcnt(0)
	s_barrier
	s_waitcnt lgkmcnt(0)
	v_mfma_f32_16x16x32_bf16 v[82:85], v[62:65], v[130:133], v[94:97]
	v_mfma_f32_16x16x32_bf16 v[62:65], v[62:65], v[218:221], v[156:159]
	v_mfma_f32_16x16x32_bf16 v[94:97], v[66:69], v[144:147], v[62:65]
	v_mfma_f32_16x16x32_bf16 v[62:65], v[74:77], v[130:133], v[70:73]
	v_mfma_f32_16x16x32_bf16 v[58:61], v[74:77], v[218:221], v[58:61]
	v_mfma_f32_16x16x32_bf16 v[54:57], v[206:209], v[130:133], v[54:57]
	v_mfma_f32_16x16x32_bf16 v[50:53], v[206:209], v[218:221], v[50:53]
	v_mfma_f32_16x16x32_bf16 v[46:49], v[214:217], v[130:133], v[46:49]
	v_mfma_f32_16x16x32_bf16 v[42:45], v[214:217], v[218:221], v[42:45]
	v_mfma_f32_16x16x32_bf16 v[86:89], v[66:69], v[164:167], v[82:85]
	v_mfma_f32_16x16x32_bf16 v[82:85], v[78:81], v[164:167], v[62:65]
	v_mfma_f32_16x16x32_bf16 v[90:93], v[78:81], v[144:147], v[58:61]
	v_mfma_f32_16x16x32_bf16 v[74:77], v[210:213], v[164:167], v[54:57]
	v_mfma_f32_16x16x32_bf16 v[78:81], v[210:213], v[144:147], v[50:53]
	v_mfma_f32_16x16x32_bf16 v[66:69], v[226:229], v[164:167], v[46:49]
	v_mfma_f32_16x16x32_bf16 v[70:73], v[226:229], v[144:147], v[42:45]
	s_barrier
	ds_read_b128 v[156:159], v143 offset:49152
	ds_read_b128 v[206:209], v143 offset:50176
	ds_read_b128 v[210:213], v143 offset:51200
	ds_read_b128 v[214:217], v143 offset:52224
	ds_read_b128 v[222:225], v143 offset:53248
	ds_read_b128 v[226:229], v143 offset:54272
	ds_read_b128 v[230:233], v143 offset:55296
	ds_read_b128 v[234:237], v143 offset:56320
	s_barrier
	s_waitcnt lgkmcnt(0)
	v_mfma_f32_16x16x32_bf16 v[38:41], v[156:159], v[194:197], v[38:41]
	v_mfma_f32_16x16x32_bf16 v[34:37], v[156:159], v[202:205], v[34:37]
	v_mfma_f32_16x16x32_bf16 v[30:33], v[210:213], v[194:197], v[30:33]
	v_mfma_f32_16x16x32_bf16 v[26:29], v[210:213], v[202:205], v[26:29]
	v_mfma_f32_16x16x32_bf16 v[22:25], v[222:225], v[194:197], v[22:25]
	v_mfma_f32_16x16x32_bf16 v[18:21], v[222:225], v[202:205], v[18:21]
	v_mfma_f32_16x16x32_bf16 v[14:17], v[230:233], v[194:197], v[14:17]
	v_mfma_f32_16x16x32_bf16 v[10:13], v[230:233], v[202:205], v[10:13]
	v_mfma_f32_16x16x32_bf16 v[54:57], v[206:209], v[198:201], v[38:41]
	v_mfma_f32_16x16x32_bf16 v[62:65], v[206:209], v[148:151], v[34:37]
	v_mfma_f32_16x16x32_bf16 v[50:53], v[214:217], v[198:201], v[30:33]
	v_mfma_f32_16x16x32_bf16 v[58:61], v[214:217], v[148:151], v[26:29]
	v_mfma_f32_16x16x32_bf16 v[42:45], v[226:229], v[198:201], v[22:25]
	v_mfma_f32_16x16x32_bf16 v[46:49], v[226:229], v[148:151], v[18:21]
	v_mfma_f32_16x16x32_bf16 v[34:37], v[234:237], v[198:201], v[14:17]
	v_mfma_f32_16x16x32_bf16 v[38:41], v[234:237], v[148:151], v[10:13]
	v_mfma_f32_16x16x32_bf16 v[2:5], v[156:159], v[218:221], v[2:5]
	v_mfma_f32_16x16x32_bf16 v[30:33], v[206:209], v[144:147], v[2:5]
	v_mfma_f32_16x16x32_bf16 v[2:5], v[210:213], v[130:133], v[134:137]
	v_mfma_f32_16x16x32_bf16 v[18:21], v[214:217], v[164:167], v[2:5]
	v_mfma_f32_16x16x32_bf16 v[2:5], v[210:213], v[218:221], v[138:141]
	v_mfma_f32_16x16x32_bf16 v[26:29], v[214:217], v[144:147], v[2:5]
	v_mfma_f32_16x16x32_bf16 v[2:5], v[222:225], v[130:133], v[152:155]
	v_mfma_f32_16x16x32_bf16 v[6:9], v[156:159], v[130:133], v[6:9]
	v_mfma_f32_16x16x32_bf16 v[10:13], v[226:229], v[164:167], v[2:5]
	v_mfma_f32_16x16x32_bf16 v[2:5], v[222:225], v[218:221], v[182:185]
	v_mfma_f32_16x16x32_bf16 v[22:25], v[206:209], v[164:167], v[6:9]
	v_mfma_f32_16x16x32_bf16 v[14:17], v[226:229], v[144:147], v[2:5]
	v_mfma_f32_16x16x32_bf16 v[2:5], v[230:233], v[130:133], v[186:189]
	v_mfma_f32_16x16x32_bf16 v[6:9], v[230:233], v[218:221], v[190:193]
	v_mfma_f32_16x16x32_bf16 v[2:5], v[234:237], v[164:167], v[2:5]
	v_mfma_f32_16x16x32_bf16 v[6:9], v[234:237], v[144:147], v[6:9]
	v_cmp_gt_u32_e32 vcc, s67, v0
	s_barrier
	s_and_saveexec_b64 s[18:19], vcc
	s_cbranch_execz .LBB0_456
	s_barrier
